# GEMM compute segment: priority is dropped in the shadow of the second-to-last MFMA, so nothing sits between the last MFMA and the barrier and the wave is already at priority 0 when released
# speedup vs baseline: 1.0006x; 1.0006x over previous
.Lpk354_peel:
	ds_read_b128 v[166:169], v139
	ds_read_b128 v[170:173], v139 offset:1024
	ds_read_b128 v[178:181], v139 offset:2048
	ds_read_b128 v[182:185], v139 offset:3072
	ds_read_b128 v[186:189], v164
	ds_read_b128 v[190:193], v164 offset:1024
	ds_read_b128 v[194:197], v164 offset:2048
	ds_read_b128 v[198:201], v164 offset:3072
	s_add_u32 s2, s26, 0xfffc0080
	s_addc_u32 s3, s27, -1
	s_cmp_eq_u32 s52, 12
	s_cselect_b32 s3, s11, s3
	s_cselect_b32 s2, s13, s2
	s_cselect_b32 s29, s44, s47
	s_cselect_b32 s28, s45, s46
	v_lshl_add_u64 v[148:149], s[26:27], 0, v[142:143]
	s_add_i32 m0, s34, 0xc000
	ds_read_b128 v[202:205], v165
	ds_read_b128 v[206:209], v165 offset:1024
	ds_read_b128 v[210:213], v165 offset:2048
	ds_read_b128 v[214:217], v165 offset:3072
	ds_read_b128 v[218:221], v165 offset:4096
	ds_read_b128 v[222:225], v165 offset:5120
	ds_read_b128 v[226:229], v165 offset:6144
	ds_read_b128 v[230:233], v165 offset:7168
	global_load_lds_dwordx4 v[148:149], off
	v_lshl_add_u64 v[148:149], s[26:27], 0, v[144:145]
	s_add_i32 m0, s34, 0xe000
	s_nop 0
	global_load_lds_dwordx4 v[148:149], off
	s_waitcnt vmcnt(8)
	s_waitcnt lgkmcnt(0)
	s_setprio 1
	s_barrier
	v_mfma_f32_16x16x32_bf16 v[126:129], v[166:169], v[202:205], 0
	v_mfma_f32_16x16x32_bf16 v[122:125], v[178:181], v[202:205], 0
	v_mfma_f32_16x16x32_bf16 v[110:113], v[166:169], v[210:213], 0
	v_mfma_f32_16x16x32_bf16 v[106:109], v[178:181], v[210:213], 0
	v_mfma_f32_16x16x32_bf16 v[94:97], v[166:169], v[218:221], 0
	v_mfma_f32_16x16x32_bf16 v[90:93], v[178:181], v[218:221], 0
	v_mfma_f32_16x16x32_bf16 v[78:81], v[166:169], v[226:229], 0
	v_mfma_f32_16x16x32_bf16 v[74:77], v[178:181], v[226:229], 0
	v_mfma_f32_16x16x32_bf16 v[126:129], v[170:173], v[206:209], v[126:129]
	v_mfma_f32_16x16x32_bf16 v[122:125], v[182:185], v[206:209], v[122:125]
	v_mfma_f32_16x16x32_bf16 v[110:113], v[170:173], v[214:217], v[110:113]
	v_mfma_f32_16x16x32_bf16 v[106:109], v[182:185], v[214:217], v[106:109]
	v_mfma_f32_16x16x32_bf16 v[94:97], v[170:173], v[222:225], v[94:97]
	v_mfma_f32_16x16x32_bf16 v[90:93], v[182:185], v[222:225], v[90:93]
	v_mfma_f32_16x16x32_bf16 v[78:81], v[170:173], v[230:233], v[78:81]
	v_mfma_f32_16x16x32_bf16 v[74:77], v[182:185], v[230:233], v[74:77]
	v_mfma_f32_16x16x32_bf16 v[118:121], v[186:189], v[202:205], 0
	v_mfma_f32_16x16x32_bf16 v[114:117], v[194:197], v[202:205], 0
	v_mfma_f32_16x16x32_bf16 v[102:105], v[186:189], v[210:213], 0
	v_mfma_f32_16x16x32_bf16 v[98:101], v[194:197], v[210:213], 0
	v_mfma_f32_16x16x32_bf16 v[86:89], v[186:189], v[218:221], 0
	v_mfma_f32_16x16x32_bf16 v[82:85], v[194:197], v[218:221], 0
	v_mfma_f32_16x16x32_bf16 v[70:73], v[186:189], v[226:229], 0
	v_mfma_f32_16x16x32_bf16 v[66:69], v[194:197], v[226:229], 0
	v_mfma_f32_16x16x32_bf16 v[118:121], v[190:193], v[206:209], v[118:121]
	v_mfma_f32_16x16x32_bf16 v[114:117], v[198:201], v[206:209], v[114:117]
	v_mfma_f32_16x16x32_bf16 v[102:105], v[190:193], v[214:217], v[102:105]
	v_mfma_f32_16x16x32_bf16 v[98:101], v[198:201], v[214:217], v[98:101]
	v_mfma_f32_16x16x32_bf16 v[86:89], v[190:193], v[222:225], v[86:89]
	v_mfma_f32_16x16x32_bf16 v[82:85], v[198:201], v[222:225], v[82:85]
	v_mfma_f32_16x16x32_bf16 v[70:73], v[190:193], v[230:233], v[70:73]
	s_setprio 0
	v_mfma_f32_16x16x32_bf16 v[66:69], v[198:201], v[230:233], v[66:69]
	s_barrier
	s_add_i32 s53, s41, s30
	v_lshl_add_u64 v[148:149], s[28:29], 0, v[132:133]
	s_mov_b32 m0, s53
	ds_read_b128 v[202:205], v165 offset:16384
	ds_read_b128 v[206:209], v165 offset:17408
	ds_read_b128 v[210:213], v165 offset:18432
	ds_read_b128 v[214:217], v165 offset:19456
	ds_read_b128 v[218:221], v165 offset:20480
	ds_read_b128 v[222:225], v165 offset:21504
	ds_read_b128 v[226:229], v165 offset:22528
	ds_read_b128 v[230:233], v165 offset:23552
	global_load_lds_dwordx4 v[148:149], off
	s_add_i32 m0, s53, 0x2000
	s_add_u32 s54, s28, 0x40000
	v_lshl_add_u64 v[174:175], s[28:29], 0, v[136:137]
	s_addc_u32 s55, s29, 0
	s_add_i32 s53, s42, s30
	global_load_lds_dwordx4 v[174:175], off
	v_lshl_add_u64 v[234:235], s[54:55], 0, v[132:133]
	s_mov_b32 m0, s53
	v_lshl_add_u64 v[236:237], s[2:3], 0, v[134:135]
	global_load_lds_dwordx4 v[234:235], off
	v_lshl_add_u64 v[234:235], s[54:55], 0, v[136:137]
	s_add_i32 m0, s53, 0x2000
	s_nop 0
	global_load_lds_dwordx4 v[234:235], off
	v_lshl_add_u64 v[234:235], s[2:3], 0, v[130:131]
	s_mov_b32 m0, s34
	s_nop 0
	global_load_lds_dwordx4 v[234:235], off
	s_mov_b32 m0, s25
	s_nop 0
	global_load_lds_dwordx4 v[236:237], off
	s_waitcnt vmcnt(8)
	s_waitcnt lgkmcnt(0)
	s_setprio 1
	s_barrier
	v_mfma_f32_16x16x32_bf16 v[62:65], v[166:169], v[202:205], 0
	v_mfma_f32_16x16x32_bf16 v[58:61], v[178:181], v[202:205], 0
	v_mfma_f32_16x16x32_bf16 v[46:49], v[166:169], v[210:213], 0
	v_mfma_f32_16x16x32_bf16 v[42:45], v[178:181], v[210:213], 0
	v_mfma_f32_16x16x32_bf16 v[30:33], v[166:169], v[218:221], 0
	v_mfma_f32_16x16x32_bf16 v[26:29], v[178:181], v[218:221], 0
	v_mfma_f32_16x16x32_bf16 v[14:17], v[166:169], v[226:229], 0
	v_mfma_f32_16x16x32_bf16 v[10:13], v[178:181], v[226:229], 0
	v_mfma_f32_16x16x32_bf16 v[62:65], v[170:173], v[206:209], v[62:65]
	v_mfma_f32_16x16x32_bf16 v[58:61], v[182:185], v[206:209], v[58:61]
	v_mfma_f32_16x16x32_bf16 v[46:49], v[170:173], v[214:217], v[46:49]
	v_mfma_f32_16x16x32_bf16 v[42:45], v[182:185], v[214:217], v[42:45]
	v_mfma_f32_16x16x32_bf16 v[30:33], v[170:173], v[222:225], v[30:33]
	v_mfma_f32_16x16x32_bf16 v[26:29], v[182:185], v[222:225], v[26:29]
	v_mfma_f32_16x16x32_bf16 v[14:17], v[170:173], v[230:233], v[14:17]
	v_mfma_f32_16x16x32_bf16 v[10:13], v[182:185], v[230:233], v[10:13]
	v_mfma_f32_16x16x32_bf16 v[54:57], v[186:189], v[202:205], 0
	v_mfma_f32_16x16x32_bf16 v[50:53], v[194:197], v[202:205], 0
	v_mfma_f32_16x16x32_bf16 v[38:41], v[186:189], v[210:213], 0
	v_mfma_f32_16x16x32_bf16 v[34:37], v[194:197], v[210:213], 0
	v_mfma_f32_16x16x32_bf16 v[22:25], v[186:189], v[218:221], 0
	v_mfma_f32_16x16x32_bf16 v[18:21], v[194:197], v[218:221], 0
	v_mfma_f32_16x16x32_bf16 v[6:9], v[186:189], v[226:229], 0
	v_mfma_f32_16x16x32_bf16 v[2:5], v[194:197], v[226:229], 0
	v_mfma_f32_16x16x32_bf16 v[54:57], v[190:193], v[206:209], v[54:57]
	v_mfma_f32_16x16x32_bf16 v[50:53], v[198:201], v[206:209], v[50:53]
	v_mfma_f32_16x16x32_bf16 v[38:41], v[190:193], v[214:217], v[38:41]
	v_mfma_f32_16x16x32_bf16 v[34:37], v[198:201], v[214:217], v[34:37]
	v_mfma_f32_16x16x32_bf16 v[22:25], v[190:193], v[222:225], v[22:25]
	v_mfma_f32_16x16x32_bf16 v[18:21], v[198:201], v[222:225], v[18:21]
	v_mfma_f32_16x16x32_bf16 v[6:9], v[190:193], v[230:233], v[6:9]
	s_setprio 0
	v_mfma_f32_16x16x32_bf16 v[2:5], v[198:201], v[230:233], v[2:5]
	s_barrier
	s_add_i32 s53, 0, 0x18000
	v_add_u32_e32 v176, s53, v163
	s_add_i32 s54, 0, 0x1c000
	ds_read_b128 v[166:169], v176
	ds_read_b128 v[170:173], v176 offset:1024
	ds_read_b128 v[178:181], v176 offset:2048
	ds_read_b128 v[182:185], v176 offset:3072
	v_add_u32_e32 v176, s54, v163
	ds_read_b128 v[186:189], v176
	ds_read_b128 v[190:193], v176 offset:1024
	ds_read_b128 v[194:197], v176 offset:2048
	ds_read_b128 v[198:201], v176 offset:3072
	s_add_u32 s2, s2, 0x40000
	s_addc_u32 s3, s3, 0
	s_mov_b32 m0, s35
	v_lshl_add_u64 v[238:239], s[2:3], 0, v[130:131]
	ds_read_b128 v[202:205], v165 offset:32768
	ds_read_b128 v[206:209], v165 offset:33792
	ds_read_b128 v[210:213], v165 offset:34816
	ds_read_b128 v[214:217], v165 offset:35840
	ds_read_b128 v[218:221], v165 offset:36864
	ds_read_b128 v[222:225], v165 offset:37888
	ds_read_b128 v[226:229], v165 offset:38912
	ds_read_b128 v[230:233], v165 offset:39936
	global_load_lds_dwordx4 v[238:239], off
	v_lshl_add_u64 v[238:239], s[2:3], 0, v[134:135]
	s_mov_b32 m0, s36
	s_nop 0
	global_load_lds_dwordx4 v[238:239], off
	s_waitcnt vmcnt(8)
	s_waitcnt lgkmcnt(0)
	s_setprio 1
	s_barrier
	v_mfma_f32_16x16x32_bf16 v[126:129], v[166:169], v[202:205], v[126:129]
	v_mfma_f32_16x16x32_bf16 v[122:125], v[178:181], v[202:205], v[122:125]
	v_mfma_f32_16x16x32_bf16 v[110:113], v[166:169], v[210:213], v[110:113]
	v_mfma_f32_16x16x32_bf16 v[106:109], v[178:181], v[210:213], v[106:109]
	v_mfma_f32_16x16x32_bf16 v[94:97], v[166:169], v[218:221], v[94:97]
	v_mfma_f32_16x16x32_bf16 v[90:93], v[178:181], v[218:221], v[90:93]
	v_mfma_f32_16x16x32_bf16 v[78:81], v[166:169], v[226:229], v[78:81]
	v_mfma_f32_16x16x32_bf16 v[74:77], v[178:181], v[226:229], v[74:77]
	v_mfma_f32_16x16x32_bf16 v[126:129], v[170:173], v[206:209], v[126:129]
	v_mfma_f32_16x16x32_bf16 v[122:125], v[182:185], v[206:209], v[122:125]
	v_mfma_f32_16x16x32_bf16 v[110:113], v[170:173], v[214:217], v[110:113]
	v_mfma_f32_16x16x32_bf16 v[106:109], v[182:185], v[214:217], v[106:109]
	v_mfma_f32_16x16x32_bf16 v[94:97], v[170:173], v[222:225], v[94:97]
	v_mfma_f32_16x16x32_bf16 v[90:93], v[182:185], v[222:225], v[90:93]
	v_mfma_f32_16x16x32_bf16 v[78:81], v[170:173], v[230:233], v[78:81]
	v_mfma_f32_16x16x32_bf16 v[74:77], v[182:185], v[230:233], v[74:77]
	v_mfma_f32_16x16x32_bf16 v[118:121], v[186:189], v[202:205], v[118:121]
	v_mfma_f32_16x16x32_bf16 v[114:117], v[194:197], v[202:205], v[114:117]
	v_mfma_f32_16x16x32_bf16 v[102:105], v[186:189], v[210:213], v[102:105]
	v_mfma_f32_16x16x32_bf16 v[98:101], v[194:197], v[210:213], v[98:101]
	v_mfma_f32_16x16x32_bf16 v[86:89], v[186:189], v[218:221], v[86:89]
	v_mfma_f32_16x16x32_bf16 v[82:85], v[194:197], v[218:221], v[82:85]
	v_mfma_f32_16x16x32_bf16 v[70:73], v[186:189], v[226:229], v[70:73]
	v_mfma_f32_16x16x32_bf16 v[66:69], v[194:197], v[226:229], v[66:69]
	v_mfma_f32_16x16x32_bf16 v[118:121], v[190:193], v[206:209], v[118:121]
	v_mfma_f32_16x16x32_bf16 v[114:117], v[198:201], v[206:209], v[114:117]
	v_mfma_f32_16x16x32_bf16 v[102:105], v[190:193], v[214:217], v[102:105]
	v_mfma_f32_16x16x32_bf16 v[98:101], v[198:201], v[214:217], v[98:101]
	v_mfma_f32_16x16x32_bf16 v[86:89], v[190:193], v[222:225], v[86:89]
	v_mfma_f32_16x16x32_bf16 v[82:85], v[198:201], v[222:225], v[82:85]
	v_mfma_f32_16x16x32_bf16 v[70:73], v[190:193], v[230:233], v[70:73]
	s_setprio 0
	v_mfma_f32_16x16x32_bf16 v[66:69], v[198:201], v[230:233], v[66:69]
	s_barrier
	s_add_i32 s2, s53, s30
	v_lshl_add_u64 v[148:149], v[148:149], 0, s[6:7]
	s_mov_b32 m0, s2
	ds_read_b128 v[202:205], v165 offset:49152
	ds_read_b128 v[206:209], v165 offset:50176
	ds_read_b128 v[210:213], v165 offset:51200
	ds_read_b128 v[214:217], v165 offset:52224
	ds_read_b128 v[218:221], v165 offset:53248
	ds_read_b128 v[222:225], v165 offset:54272
	ds_read_b128 v[226:229], v165 offset:55296
	ds_read_b128 v[230:233], v165 offset:56320
	global_load_lds_dwordx4 v[148:149], off
	s_add_i32 m0, s2, 0x2000
	s_add_u32 s2, s28, 0x40080
	v_lshl_add_u64 v[148:149], v[174:175], 0, s[6:7]
	s_addc_u32 s3, s29, 0
	s_add_i32 s28, s54, s30
	global_load_lds_dwordx4 v[148:149], off
	v_lshl_add_u64 v[148:149], s[2:3], 0, v[132:133]
	s_mov_b32 m0, s28
	s_nop 0
	global_load_lds_dwordx4 v[148:149], off
	v_lshl_add_u64 v[148:149], s[2:3], 0, v[136:137]
	s_add_i32 m0, s28, 0x2000
	s_nop 0
	global_load_lds_dwordx4 v[148:149], off
	v_lshl_add_u64 v[148:149], v[234:235], 0, s[6:7]
	s_mov_b32 m0, s38
	s_nop 0
	global_load_lds_dwordx4 v[148:149], off
	v_lshl_add_u64 v[148:149], v[236:237], 0, s[6:7]
	s_mov_b32 m0, s39
	s_nop 0
	global_load_lds_dwordx4 v[148:149], off
	s_waitcnt vmcnt(8)
	s_waitcnt lgkmcnt(0)
	s_setprio 1
	s_barrier
	v_mfma_f32_16x16x32_bf16 v[62:65], v[166:169], v[202:205], v[62:65]
	v_mfma_f32_16x16x32_bf16 v[58:61], v[178:181], v[202:205], v[58:61]
	v_mfma_f32_16x16x32_bf16 v[46:49], v[166:169], v[210:213], v[46:49]
	v_mfma_f32_16x16x32_bf16 v[42:45], v[178:181], v[210:213], v[42:45]
	v_mfma_f32_16x16x32_bf16 v[30:33], v[166:169], v[218:221], v[30:33]
	v_mfma_f32_16x16x32_bf16 v[26:29], v[178:181], v[218:221], v[26:29]
	v_mfma_f32_16x16x32_bf16 v[14:17], v[166:169], v[226:229], v[14:17]
	v_mfma_f32_16x16x32_bf16 v[10:13], v[178:181], v[226:229], v[10:13]
	v_mfma_f32_16x16x32_bf16 v[62:65], v[170:173], v[206:209], v[62:65]
	v_mfma_f32_16x16x32_bf16 v[58:61], v[182:185], v[206:209], v[58:61]
	v_mfma_f32_16x16x32_bf16 v[46:49], v[170:173], v[214:217], v[46:49]
	v_mfma_f32_16x16x32_bf16 v[42:45], v[182:185], v[214:217], v[42:45]
	v_mfma_f32_16x16x32_bf16 v[30:33], v[170:173], v[222:225], v[30:33]
	v_mfma_f32_16x16x32_bf16 v[26:29], v[182:185], v[222:225], v[26:29]
	v_mfma_f32_16x16x32_bf16 v[14:17], v[170:173], v[230:233], v[14:17]
	v_mfma_f32_16x16x32_bf16 v[10:13], v[182:185], v[230:233], v[10:13]
	v_mfma_f32_16x16x32_bf16 v[54:57], v[186:189], v[202:205], v[54:57]
	v_mfma_f32_16x16x32_bf16 v[50:53], v[194:197], v[202:205], v[50:53]
	v_mfma_f32_16x16x32_bf16 v[38:41], v[186:189], v[210:213], v[38:41]
	v_mfma_f32_16x16x32_bf16 v[34:37], v[194:197], v[210:213], v[34:37]
	v_mfma_f32_16x16x32_bf16 v[22:25], v[186:189], v[218:221], v[22:25]
	v_mfma_f32_16x16x32_bf16 v[18:21], v[194:197], v[218:221], v[18:21]
	v_mfma_f32_16x16x32_bf16 v[6:9], v[186:189], v[226:229], v[6:9]
	v_mfma_f32_16x16x32_bf16 v[2:5], v[194:197], v[226:229], v[2:5]
	v_mfma_f32_16x16x32_bf16 v[54:57], v[190:193], v[206:209], v[54:57]
	v_mfma_f32_16x16x32_bf16 v[50:53], v[198:201], v[206:209], v[50:53]
	v_mfma_f32_16x16x32_bf16 v[38:41], v[190:193], v[214:217], v[38:41]
	v_mfma_f32_16x16x32_bf16 v[34:37], v[198:201], v[214:217], v[34:37]
	v_mfma_f32_16x16x32_bf16 v[22:25], v[190:193], v[222:225], v[22:25]
	v_mfma_f32_16x16x32_bf16 v[18:21], v[198:201], v[222:225], v[18:21]
	v_mfma_f32_16x16x32_bf16 v[6:9], v[190:193], v[230:233], v[6:9]
	s_setprio 0
	v_mfma_f32_16x16x32_bf16 v[2:5], v[198:201], v[230:233], v[2:5]
	s_barrier
	s_add_i32 s52, s52, 2
	s_add_u32 s26, s26, 0x100
	s_addc_u32 s27, s27, 0
	s_add_u32 s46, s46, 0x100
	s_addc_u32 s47, s47, 0
	s_cmp_gt_u32 s52, 13
	s_cbranch_scc0 .LBB0_354
	s_branch .Lpk354_exit
.LBB0_354:
	ds_read_b128 v[166:169], v139
	ds_read_b128 v[170:173], v139 offset:1024
	ds_read_b128 v[178:181], v139 offset:2048
	ds_read_b128 v[182:185], v139 offset:3072
	ds_read_b128 v[186:189], v164
	ds_read_b128 v[190:193], v164 offset:1024
	ds_read_b128 v[194:197], v164 offset:2048
	ds_read_b128 v[198:201], v164 offset:3072
	s_add_u32 s2, s26, 0xfffc0080
	s_addc_u32 s3, s27, -1
	s_cmp_eq_u32 s52, 12
	s_cselect_b32 s3, s11, s3
	s_cselect_b32 s2, s13, s2
	s_cselect_b32 s29, s44, s47
	s_cselect_b32 s28, s45, s46
	v_lshl_add_u64 v[148:149], s[26:27], 0, v[142:143]
	s_add_i32 m0, s34, 0xc000
	ds_read_b128 v[202:205], v165
	ds_read_b128 v[206:209], v165 offset:1024
	ds_read_b128 v[210:213], v165 offset:2048
	ds_read_b128 v[214:217], v165 offset:3072
	ds_read_b128 v[218:221], v165 offset:4096
	ds_read_b128 v[222:225], v165 offset:5120
	ds_read_b128 v[226:229], v165 offset:6144
	ds_read_b128 v[230:233], v165 offset:7168
	global_load_lds_dwordx4 v[148:149], off
	v_lshl_add_u64 v[148:149], s[26:27], 0, v[144:145]
	s_add_i32 m0, s34, 0xe000
	s_nop 0
	global_load_lds_dwordx4 v[148:149], off
	s_waitcnt vmcnt(8)
	s_waitcnt lgkmcnt(0)
	s_setprio 1
	s_barrier
	v_mfma_f32_16x16x32_bf16 v[126:129], v[166:169], v[202:205], v[126:129]
	v_mfma_f32_16x16x32_bf16 v[122:125], v[178:181], v[202:205], v[122:125]
	v_mfma_f32_16x16x32_bf16 v[110:113], v[166:169], v[210:213], v[110:113]
	v_mfma_f32_16x16x32_bf16 v[106:109], v[178:181], v[210:213], v[106:109]
	v_mfma_f32_16x16x32_bf16 v[94:97], v[166:169], v[218:221], v[94:97]
	v_mfma_f32_16x16x32_bf16 v[90:93], v[178:181], v[218:221], v[90:93]
	v_mfma_f32_16x16x32_bf16 v[78:81], v[166:169], v[226:229], v[78:81]
	v_mfma_f32_16x16x32_bf16 v[74:77], v[178:181], v[226:229], v[74:77]
	v_mfma_f32_16x16x32_bf16 v[126:129], v[170:173], v[206:209], v[126:129]
	v_mfma_f32_16x16x32_bf16 v[122:125], v[182:185], v[206:209], v[122:125]
	v_mfma_f32_16x16x32_bf16 v[110:113], v[170:173], v[214:217], v[110:113]
	v_mfma_f32_16x16x32_bf16 v[106:109], v[182:185], v[214:217], v[106:109]
	v_mfma_f32_16x16x32_bf16 v[94:97], v[170:173], v[222:225], v[94:97]
	v_mfma_f32_16x16x32_bf16 v[90:93], v[182:185], v[222:225], v[90:93]
	v_mfma_f32_16x16x32_bf16 v[78:81], v[170:173], v[230:233], v[78:81]
	v_mfma_f32_16x16x32_bf16 v[74:77], v[182:185], v[230:233], v[74:77]
	v_mfma_f32_16x16x32_bf16 v[118:121], v[186:189], v[202:205], v[118:121]
	v_mfma_f32_16x16x32_bf16 v[114:117], v[194:197], v[202:205], v[114:117]
	v_mfma_f32_16x16x32_bf16 v[102:105], v[186:189], v[210:213], v[102:105]
	v_mfma_f32_16x16x32_bf16 v[98:101], v[194:197], v[210:213], v[98:101]
	v_mfma_f32_16x16x32_bf16 v[86:89], v[186:189], v[218:221], v[86:89]
	v_mfma_f32_16x16x32_bf16 v[82:85], v[194:197], v[218:221], v[82:85]
	v_mfma_f32_16x16x32_bf16 v[70:73], v[186:189], v[226:229], v[70:73]
	v_mfma_f32_16x16x32_bf16 v[66:69], v[194:197], v[226:229], v[66:69]
	v_mfma_f32_16x16x32_bf16 v[118:121], v[190:193], v[206:209], v[118:121]
	v_mfma_f32_16x16x32_bf16 v[114:117], v[198:201], v[206:209], v[114:117]
	v_mfma_f32_16x16x32_bf16 v[102:105], v[190:193], v[214:217], v[102:105]
	v_mfma_f32_16x16x32_bf16 v[98:101], v[198:201], v[214:217], v[98:101]
	v_mfma_f32_16x16x32_bf16 v[86:89], v[190:193], v[222:225], v[86:89]
	v_mfma_f32_16x16x32_bf16 v[82:85], v[198:201], v[222:225], v[82:85]
	v_mfma_f32_16x16x32_bf16 v[70:73], v[190:193], v[230:233], v[70:73]
	s_setprio 0
	v_mfma_f32_16x16x32_bf16 v[66:69], v[198:201], v[230:233], v[66:69]
	s_barrier
	s_add_i32 s53, s41, s30
	v_lshl_add_u64 v[148:149], s[28:29], 0, v[132:133]
	s_mov_b32 m0, s53
	ds_read_b128 v[202:205], v165 offset:16384
	ds_read_b128 v[206:209], v165 offset:17408
	ds_read_b128 v[210:213], v165 offset:18432
	ds_read_b128 v[214:217], v165 offset:19456
	ds_read_b128 v[218:221], v165 offset:20480
	ds_read_b128 v[222:225], v165 offset:21504
	ds_read_b128 v[226:229], v165 offset:22528
	ds_read_b128 v[230:233], v165 offset:23552
	global_load_lds_dwordx4 v[148:149], off
	s_add_i32 m0, s53, 0x2000
	s_add_u32 s54, s28, 0x40000
	v_lshl_add_u64 v[174:175], s[28:29], 0, v[136:137]
	s_addc_u32 s55, s29, 0
	s_add_i32 s53, s42, s30
	global_load_lds_dwordx4 v[174:175], off
	v_lshl_add_u64 v[234:235], s[54:55], 0, v[132:133]
	s_mov_b32 m0, s53
	v_lshl_add_u64 v[236:237], s[2:3], 0, v[134:135]
	global_load_lds_dwordx4 v[234:235], off
	v_lshl_add_u64 v[234:235], s[54:55], 0, v[136:137]
	s_add_i32 m0, s53, 0x2000
	s_nop 0
	global_load_lds_dwordx4 v[234:235], off
	v_lshl_add_u64 v[234:235], s[2:3], 0, v[130:131]
	s_mov_b32 m0, s34
	s_nop 0
	global_load_lds_dwordx4 v[234:235], off
	s_mov_b32 m0, s25
	s_nop 0
	global_load_lds_dwordx4 v[236:237], off
	s_waitcnt vmcnt(8)
	s_waitcnt lgkmcnt(0)
	s_setprio 1
	s_barrier
	v_mfma_f32_16x16x32_bf16 v[62:65], v[166:169], v[202:205], v[62:65]
	v_mfma_f32_16x16x32_bf16 v[58:61], v[178:181], v[202:205], v[58:61]
	v_mfma_f32_16x16x32_bf16 v[46:49], v[166:169], v[210:213], v[46:49]
	v_mfma_f32_16x16x32_bf16 v[42:45], v[178:181], v[210:213], v[42:45]
	v_mfma_f32_16x16x32_bf16 v[30:33], v[166:169], v[218:221], v[30:33]
	v_mfma_f32_16x16x32_bf16 v[26:29], v[178:181], v[218:221], v[26:29]
	v_mfma_f32_16x16x32_bf16 v[14:17], v[166:169], v[226:229], v[14:17]
	v_mfma_f32_16x16x32_bf16 v[10:13], v[178:181], v[226:229], v[10:13]
	v_mfma_f32_16x16x32_bf16 v[62:65], v[170:173], v[206:209], v[62:65]
	v_mfma_f32_16x16x32_bf16 v[58:61], v[182:185], v[206:209], v[58:61]
	v_mfma_f32_16x16x32_bf16 v[46:49], v[170:173], v[214:217], v[46:49]
	v_mfma_f32_16x16x32_bf16 v[42:45], v[182:185], v[214:217], v[42:45]
	v_mfma_f32_16x16x32_bf16 v[30:33], v[170:173], v[222:225], v[30:33]
	v_mfma_f32_16x16x32_bf16 v[26:29], v[182:185], v[222:225], v[26:29]
	v_mfma_f32_16x16x32_bf16 v[14:17], v[170:173], v[230:233], v[14:17]
	v_mfma_f32_16x16x32_bf16 v[10:13], v[182:185], v[230:233], v[10:13]
	v_mfma_f32_16x16x32_bf16 v[54:57], v[186:189], v[202:205], v[54:57]
	v_mfma_f32_16x16x32_bf16 v[50:53], v[194:197], v[202:205], v[50:53]
	v_mfma_f32_16x16x32_bf16 v[38:41], v[186:189], v[210:213], v[38:41]
	v_mfma_f32_16x16x32_bf16 v[34:37], v[194:197], v[210:213], v[34:37]
	v_mfma_f32_16x16x32_bf16 v[22:25], v[186:189], v[218:221], v[22:25]
	v_mfma_f32_16x16x32_bf16 v[18:21], v[194:197], v[218:221], v[18:21]
	v_mfma_f32_16x16x32_bf16 v[6:9], v[186:189], v[226:229], v[6:9]
	v_mfma_f32_16x16x32_bf16 v[2:5], v[194:197], v[226:229], v[2:5]
	v_mfma_f32_16x16x32_bf16 v[54:57], v[190:193], v[206:209], v[54:57]
	v_mfma_f32_16x16x32_bf16 v[50:53], v[198:201], v[206:209], v[50:53]
	v_mfma_f32_16x16x32_bf16 v[38:41], v[190:193], v[214:217], v[38:41]
	v_mfma_f32_16x16x32_bf16 v[34:37], v[198:201], v[214:217], v[34:37]
	v_mfma_f32_16x16x32_bf16 v[22:25], v[190:193], v[222:225], v[22:25]
	v_mfma_f32_16x16x32_bf16 v[18:21], v[198:201], v[222:225], v[18:21]
	v_mfma_f32_16x16x32_bf16 v[6:9], v[190:193], v[230:233], v[6:9]
	s_setprio 0
	v_mfma_f32_16x16x32_bf16 v[2:5], v[198:201], v[230:233], v[2:5]
	s_barrier
	s_add_i32 s53, 0, 0x18000
	v_add_u32_e32 v176, s53, v163
	s_add_i32 s54, 0, 0x1c000
	ds_read_b128 v[166:169], v176
	ds_read_b128 v[170:173], v176 offset:1024
	ds_read_b128 v[178:181], v176 offset:2048
	ds_read_b128 v[182:185], v176 offset:3072
	v_add_u32_e32 v176, s54, v163
	ds_read_b128 v[186:189], v176
	ds_read_b128 v[190:193], v176 offset:1024
	ds_read_b128 v[194:197], v176 offset:2048
	ds_read_b128 v[198:201], v176 offset:3072
	s_add_u32 s2, s2, 0x40000
	s_addc_u32 s3, s3, 0
	s_mov_b32 m0, s35
	v_lshl_add_u64 v[238:239], s[2:3], 0, v[130:131]
	ds_read_b128 v[202:205], v165 offset:32768
	ds_read_b128 v[206:209], v165 offset:33792
	ds_read_b128 v[210:213], v165 offset:34816
	ds_read_b128 v[214:217], v165 offset:35840
	ds_read_b128 v[218:221], v165 offset:36864
	ds_read_b128 v[222:225], v165 offset:37888
	ds_read_b128 v[226:229], v165 offset:38912
	ds_read_b128 v[230:233], v165 offset:39936
	global_load_lds_dwordx4 v[238:239], off
	v_lshl_add_u64 v[238:239], s[2:3], 0, v[134:135]
	s_mov_b32 m0, s36
	s_nop 0
	global_load_lds_dwordx4 v[238:239], off
	s_waitcnt vmcnt(8)
	s_waitcnt lgkmcnt(0)
	s_setprio 1
	s_barrier
	v_mfma_f32_16x16x32_bf16 v[126:129], v[166:169], v[202:205], v[126:129]
	v_mfma_f32_16x16x32_bf16 v[122:125], v[178:181], v[202:205], v[122:125]
	v_mfma_f32_16x16x32_bf16 v[110:113], v[166:169], v[210:213], v[110:113]
	v_mfma_f32_16x16x32_bf16 v[106:109], v[178:181], v[210:213], v[106:109]
	v_mfma_f32_16x16x32_bf16 v[94:97], v[166:169], v[218:221], v[94:97]
	v_mfma_f32_16x16x32_bf16 v[90:93], v[178:181], v[218:221], v[90:93]
	v_mfma_f32_16x16x32_bf16 v[78:81], v[166:169], v[226:229], v[78:81]
	v_mfma_f32_16x16x32_bf16 v[74:77], v[178:181], v[226:229], v[74:77]
	v_mfma_f32_16x16x32_bf16 v[126:129], v[170:173], v[206:209], v[126:129]
	v_mfma_f32_16x16x32_bf16 v[122:125], v[182:185], v[206:209], v[122:125]
	v_mfma_f32_16x16x32_bf16 v[110:113], v[170:173], v[214:217], v[110:113]
	v_mfma_f32_16x16x32_bf16 v[106:109], v[182:185], v[214:217], v[106:109]
	v_mfma_f32_16x16x32_bf16 v[94:97], v[170:173], v[222:225], v[94:97]
	v_mfma_f32_16x16x32_bf16 v[90:93], v[182:185], v[222:225], v[90:93]
	v_mfma_f32_16x16x32_bf16 v[78:81], v[170:173], v[230:233], v[78:81]
	v_mfma_f32_16x16x32_bf16 v[74:77], v[182:185], v[230:233], v[74:77]
	v_mfma_f32_16x16x32_bf16 v[118:121], v[186:189], v[202:205], v[118:121]
	v_mfma_f32_16x16x32_bf16 v[114:117], v[194:197], v[202:205], v[114:117]
	v_mfma_f32_16x16x32_bf16 v[102:105], v[186:189], v[210:213], v[102:105]
	v_mfma_f32_16x16x32_bf16 v[98:101], v[194:197], v[210:213], v[98:101]
	v_mfma_f32_16x16x32_bf16 v[86:89], v[186:189], v[218:221], v[86:89]
	v_mfma_f32_16x16x32_bf16 v[82:85], v[194:197], v[218:221], v[82:85]
	v_mfma_f32_16x16x32_bf16 v[70:73], v[186:189], v[226:229], v[70:73]
	v_mfma_f32_16x16x32_bf16 v[66:69], v[194:197], v[226:229], v[66:69]
	v_mfma_f32_16x16x32_bf16 v[118:121], v[190:193], v[206:209], v[118:121]
	v_mfma_f32_16x16x32_bf16 v[114:117], v[198:201], v[206:209], v[114:117]
	v_mfma_f32_16x16x32_bf16 v[102:105], v[190:193], v[214:217], v[102:105]
	v_mfma_f32_16x16x32_bf16 v[98:101], v[198:201], v[214:217], v[98:101]
	v_mfma_f32_16x16x32_bf16 v[86:89], v[190:193], v[222:225], v[86:89]
	v_mfma_f32_16x16x32_bf16 v[82:85], v[198:201], v[222:225], v[82:85]
	v_mfma_f32_16x16x32_bf16 v[70:73], v[190:193], v[230:233], v[70:73]
	s_setprio 0
	v_mfma_f32_16x16x32_bf16 v[66:69], v[198:201], v[230:233], v[66:69]
	s_barrier
	s_add_i32 s2, s53, s30
	v_lshl_add_u64 v[148:149], v[148:149], 0, s[6:7]
	s_mov_b32 m0, s2
	ds_read_b128 v[202:205], v165 offset:49152
	ds_read_b128 v[206:209], v165 offset:50176
	ds_read_b128 v[210:213], v165 offset:51200
	ds_read_b128 v[214:217], v165 offset:52224
	ds_read_b128 v[218:221], v165 offset:53248
	ds_read_b128 v[222:225], v165 offset:54272
	ds_read_b128 v[226:229], v165 offset:55296
	ds_read_b128 v[230:233], v165 offset:56320
	global_load_lds_dwordx4 v[148:149], off
	s_add_i32 m0, s2, 0x2000
	s_add_u32 s2, s28, 0x40080
	v_lshl_add_u64 v[148:149], v[174:175], 0, s[6:7]
	s_addc_u32 s3, s29, 0
	s_add_i32 s28, s54, s30
	global_load_lds_dwordx4 v[148:149], off
	v_lshl_add_u64 v[148:149], s[2:3], 0, v[132:133]
	s_mov_b32 m0, s28
	s_nop 0
	global_load_lds_dwordx4 v[148:149], off
	v_lshl_add_u64 v[148:149], s[2:3], 0, v[136:137]
	s_add_i32 m0, s28, 0x2000
	s_nop 0
	global_load_lds_dwordx4 v[148:149], off
	v_lshl_add_u64 v[148:149], v[234:235], 0, s[6:7]
	s_mov_b32 m0, s38
	s_nop 0
	global_load_lds_dwordx4 v[148:149], off
	v_lshl_add_u64 v[148:149], v[236:237], 0, s[6:7]
	s_mov_b32 m0, s39
	s_nop 0
	global_load_lds_dwordx4 v[148:149], off
	s_waitcnt vmcnt(8)
	s_waitcnt lgkmcnt(0)
	s_setprio 1
	s_barrier
	v_mfma_f32_16x16x32_bf16 v[62:65], v[166:169], v[202:205], v[62:65]
	v_mfma_f32_16x16x32_bf16 v[58:61], v[178:181], v[202:205], v[58:61]
	v_mfma_f32_16x16x32_bf16 v[46:49], v[166:169], v[210:213], v[46:49]
	v_mfma_f32_16x16x32_bf16 v[42:45], v[178:181], v[210:213], v[42:45]
	v_mfma_f32_16x16x32_bf16 v[30:33], v[166:169], v[218:221], v[30:33]
	v_mfma_f32_16x16x32_bf16 v[26:29], v[178:181], v[218:221], v[26:29]
	v_mfma_f32_16x16x32_bf16 v[14:17], v[166:169], v[226:229], v[14:17]
	v_mfma_f32_16x16x32_bf16 v[10:13], v[178:181], v[226:229], v[10:13]
	v_mfma_f32_16x16x32_bf16 v[62:65], v[170:173], v[206:209], v[62:65]
	v_mfma_f32_16x16x32_bf16 v[58:61], v[182:185], v[206:209], v[58:61]
	v_mfma_f32_16x16x32_bf16 v[46:49], v[170:173], v[214:217], v[46:49]
	v_mfma_f32_16x16x32_bf16 v[42:45], v[182:185], v[214:217], v[42:45]
	v_mfma_f32_16x16x32_bf16 v[30:33], v[170:173], v[222:225], v[30:33]
	v_mfma_f32_16x16x32_bf16 v[26:29], v[182:185], v[222:225], v[26:29]
	v_mfma_f32_16x16x32_bf16 v[14:17], v[170:173], v[230:233], v[14:17]
	v_mfma_f32_16x16x32_bf16 v[10:13], v[182:185], v[230:233], v[10:13]
	v_mfma_f32_16x16x32_bf16 v[54:57], v[186:189], v[202:205], v[54:57]
	v_mfma_f32_16x16x32_bf16 v[50:53], v[194:197], v[202:205], v[50:53]
	v_mfma_f32_16x16x32_bf16 v[38:41], v[186:189], v[210:213], v[38:41]
	v_mfma_f32_16x16x32_bf16 v[34:37], v[194:197], v[210:213], v[34:37]
	v_mfma_f32_16x16x32_bf16 v[22:25], v[186:189], v[218:221], v[22:25]
	v_mfma_f32_16x16x32_bf16 v[18:21], v[194:197], v[218:221], v[18:21]
	v_mfma_f32_16x16x32_bf16 v[6:9], v[186:189], v[226:229], v[6:9]
	v_mfma_f32_16x16x32_bf16 v[2:5], v[194:197], v[226:229], v[2:5]
	v_mfma_f32_16x16x32_bf16 v[54:57], v[190:193], v[206:209], v[54:57]
	v_mfma_f32_16x16x32_bf16 v[50:53], v[198:201], v[206:209], v[50:53]
	v_mfma_f32_16x16x32_bf16 v[38:41], v[190:193], v[214:217], v[38:41]
	v_mfma_f32_16x16x32_bf16 v[34:37], v[198:201], v[214:217], v[34:37]
	v_mfma_f32_16x16x32_bf16 v[22:25], v[190:193], v[222:225], v[22:25]
	v_mfma_f32_16x16x32_bf16 v[18:21], v[198:201], v[222:225], v[18:21]
	v_mfma_f32_16x16x32_bf16 v[6:9], v[190:193], v[230:233], v[6:9]
	s_setprio 0
	v_mfma_f32_16x16x32_bf16 v[2:5], v[198:201], v[230:233], v[2:5]
	s_barrier
	s_add_i32 s52, s52, 2
	s_add_u32 s26, s26, 0x100
	s_addc_u32 s27, s27, 0
	s_add_u32 s46, s46, 0x100
	s_addc_u32 s47, s47, 0
	s_cmp_gt_u32 s52, 13
	s_cbranch_scc0 .LBB0_354

.LBB0_437:
	ds_read_b128 v[160:163], v133
	ds_read_b128 v[164:167], v133 offset:1024
	ds_read_b128 v[168:171], v133 offset:2048
	ds_read_b128 v[172:175], v133 offset:3072
	ds_read_b128 v[178:181], v135
	ds_read_b128 v[182:185], v135 offset:1024
	ds_read_b128 v[186:189], v135 offset:2048
	ds_read_b128 v[190:193], v135 offset:3072
	s_cmp_lg_u32 s8, 0x160000
	s_cselect_b32 s13, s8, 0
	s_cselect_b32 s12, s9, 0
	s_add_u32 s2, s6, s13
	s_addc_u32 s3, s7, s12
	s_add_u32 s14, s0, s13
	s_addc_u32 s15, s1, s12
	s_add_u32 s12, s2, 0x8000
	s_addc_u32 s13, s3, 0
	v_lshl_add_u64 v[226:227], v[148:149], 0, s[8:9]
	s_mov_b32 m0, s27
	v_lshl_add_u64 v[226:227], v[226:227], 0, s[10:11]
	ds_read_b128 v[194:197], v137
	ds_read_b128 v[198:201], v137 offset:1024
	ds_read_b128 v[202:205], v137 offset:2048
	ds_read_b128 v[206:209], v137 offset:3072
	ds_read_b128 v[210:213], v137 offset:4096
	ds_read_b128 v[214:217], v137 offset:5120
	ds_read_b128 v[218:221], v137 offset:6144
	ds_read_b128 v[222:225], v137 offset:7168
	global_load_lds_dwordx4 v[226:227], off
	v_lshl_add_u64 v[226:227], v[150:151], 0, s[8:9]
	v_lshl_add_u64 v[226:227], v[226:227], 0, s[10:11]
	s_mov_b32 m0, s28
	s_nop 0
	global_load_lds_dwordx4 v[226:227], off
	s_waitcnt vmcnt(8)
	s_waitcnt lgkmcnt(0)
	s_setprio 1
	s_barrier
	v_mfma_f32_16x16x32_bf16 v[126:129], v[160:163], v[194:197], v[126:129]
	v_mfma_f32_16x16x32_bf16 v[122:125], v[168:171], v[194:197], v[122:125]
	v_mfma_f32_16x16x32_bf16 v[114:117], v[160:163], v[202:205], v[114:117]
	v_mfma_f32_16x16x32_bf16 v[106:109], v[168:171], v[202:205], v[106:109]
	v_mfma_f32_16x16x32_bf16 v[98:101], v[160:163], v[210:213], v[98:101]
	v_mfma_f32_16x16x32_bf16 v[90:93], v[168:171], v[210:213], v[90:93]
	v_mfma_f32_16x16x32_bf16 v[82:85], v[160:163], v[218:221], v[82:85]
	v_mfma_f32_16x16x32_bf16 v[74:77], v[168:171], v[218:221], v[74:77]
	v_mfma_f32_16x16x32_bf16 v[126:129], v[164:167], v[198:201], v[126:129]
	v_mfma_f32_16x16x32_bf16 v[122:125], v[172:175], v[198:201], v[122:125]
	v_mfma_f32_16x16x32_bf16 v[114:117], v[164:167], v[206:209], v[114:117]
	v_mfma_f32_16x16x32_bf16 v[106:109], v[172:175], v[206:209], v[106:109]
	v_mfma_f32_16x16x32_bf16 v[98:101], v[164:167], v[214:217], v[98:101]
	v_mfma_f32_16x16x32_bf16 v[90:93], v[172:175], v[214:217], v[90:93]
	v_mfma_f32_16x16x32_bf16 v[82:85], v[164:167], v[222:225], v[82:85]
	v_mfma_f32_16x16x32_bf16 v[74:77], v[172:175], v[222:225], v[74:77]
	v_mfma_f32_16x16x32_bf16 v[118:121], v[178:181], v[194:197], v[118:121]
	v_mfma_f32_16x16x32_bf16 v[110:113], v[186:189], v[194:197], v[110:113]
	v_mfma_f32_16x16x32_bf16 v[102:105], v[178:181], v[202:205], v[102:105]
	v_mfma_f32_16x16x32_bf16 v[94:97], v[186:189], v[202:205], v[94:97]
	v_mfma_f32_16x16x32_bf16 v[86:89], v[178:181], v[210:213], v[86:89]
	v_mfma_f32_16x16x32_bf16 v[78:81], v[186:189], v[210:213], v[78:81]
	v_mfma_f32_16x16x32_bf16 v[70:73], v[178:181], v[218:221], v[70:73]
	v_mfma_f32_16x16x32_bf16 v[66:69], v[186:189], v[218:221], v[66:69]
	v_mfma_f32_16x16x32_bf16 v[118:121], v[182:185], v[198:201], v[118:121]
	v_mfma_f32_16x16x32_bf16 v[110:113], v[190:193], v[198:201], v[110:113]
	v_mfma_f32_16x16x32_bf16 v[102:105], v[182:185], v[206:209], v[102:105]
	v_mfma_f32_16x16x32_bf16 v[94:97], v[190:193], v[206:209], v[94:97]
	v_mfma_f32_16x16x32_bf16 v[86:89], v[182:185], v[214:217], v[86:89]
	v_mfma_f32_16x16x32_bf16 v[78:81], v[190:193], v[214:217], v[78:81]
	v_mfma_f32_16x16x32_bf16 v[70:73], v[182:185], v[222:225], v[70:73]
	s_setprio 0
	v_mfma_f32_16x16x32_bf16 v[66:69], v[190:193], v[222:225], v[66:69]
	s_barrier
	s_mov_b32 m0, s29
	v_lshl_add_u64 v[226:227], s[14:15], 0, v[142:143]
	s_add_u32 s40, s14, 0x4000
	ds_read_b128 v[194:197], v137 offset:16384
	ds_read_b128 v[198:201], v137 offset:17408
	ds_read_b128 v[202:205], v137 offset:18432
	ds_read_b128 v[206:209], v137 offset:19456
	ds_read_b128 v[210:213], v137 offset:20480
	ds_read_b128 v[214:217], v137 offset:21504
	ds_read_b128 v[218:221], v137 offset:22528
	ds_read_b128 v[222:225], v137 offset:23552
	global_load_lds_dwordx4 v[226:227], off
	v_lshl_add_u64 v[226:227], s[14:15], 0, v[146:147]
	s_mov_b32 m0, s30
	s_addc_u32 s41, s15, 0
	global_load_lds_dwordx4 v[226:227], off
	v_lshl_add_u64 v[226:227], s[40:41], 0, v[142:143]
	s_mov_b32 m0, s31
	s_nop 0
	global_load_lds_dwordx4 v[226:227], off
	v_lshl_add_u64 v[226:227], s[40:41], 0, v[146:147]
	s_mov_b32 m0, s34
	s_nop 0
	global_load_lds_dwordx4 v[226:227], off
	v_lshl_add_u64 v[226:227], s[2:3], 0, v[140:141]
	s_mov_b32 m0, s19
	s_nop 0
	global_load_lds_dwordx4 v[226:227], off
	v_lshl_add_u64 v[226:227], s[2:3], 0, v[144:145]
	s_mov_b32 m0, s20
	s_nop 0
	global_load_lds_dwordx4 v[226:227], off
	s_waitcnt vmcnt(8)
	s_waitcnt lgkmcnt(0)
	s_setprio 1
	s_barrier
	v_mfma_f32_16x16x32_bf16 v[62:65], v[160:163], v[194:197], v[62:65]
	v_mfma_f32_16x16x32_bf16 v[58:61], v[168:171], v[194:197], v[58:61]
	v_mfma_f32_16x16x32_bf16 v[50:53], v[160:163], v[202:205], v[50:53]
	v_mfma_f32_16x16x32_bf16 v[42:45], v[168:171], v[202:205], v[42:45]
	v_mfma_f32_16x16x32_bf16 v[34:37], v[160:163], v[210:213], v[34:37]
	v_mfma_f32_16x16x32_bf16 v[26:29], v[168:171], v[210:213], v[26:29]
	v_mfma_f32_16x16x32_bf16 v[18:21], v[160:163], v[218:221], v[18:21]
	v_mfma_f32_16x16x32_bf16 v[10:13], v[168:171], v[218:221], v[10:13]
	v_mfma_f32_16x16x32_bf16 v[62:65], v[164:167], v[198:201], v[62:65]
	v_mfma_f32_16x16x32_bf16 v[58:61], v[172:175], v[198:201], v[58:61]
	v_mfma_f32_16x16x32_bf16 v[50:53], v[164:167], v[206:209], v[50:53]
	v_mfma_f32_16x16x32_bf16 v[42:45], v[172:175], v[206:209], v[42:45]
	v_mfma_f32_16x16x32_bf16 v[34:37], v[164:167], v[214:217], v[34:37]
	v_mfma_f32_16x16x32_bf16 v[26:29], v[172:175], v[214:217], v[26:29]
	v_mfma_f32_16x16x32_bf16 v[18:21], v[164:167], v[222:225], v[18:21]
	v_mfma_f32_16x16x32_bf16 v[10:13], v[172:175], v[222:225], v[10:13]
	v_mfma_f32_16x16x32_bf16 v[54:57], v[178:181], v[194:197], v[54:57]
	v_mfma_f32_16x16x32_bf16 v[46:49], v[186:189], v[194:197], v[46:49]
	v_mfma_f32_16x16x32_bf16 v[38:41], v[178:181], v[202:205], v[38:41]
	v_mfma_f32_16x16x32_bf16 v[30:33], v[186:189], v[202:205], v[30:33]
	v_mfma_f32_16x16x32_bf16 v[22:25], v[178:181], v[210:213], v[22:25]
	v_mfma_f32_16x16x32_bf16 v[14:17], v[186:189], v[210:213], v[14:17]
	v_mfma_f32_16x16x32_bf16 v[6:9], v[178:181], v[218:221], v[6:9]
	v_mfma_f32_16x16x32_bf16 v[2:5], v[186:189], v[218:221], v[2:5]
	v_mfma_f32_16x16x32_bf16 v[54:57], v[182:185], v[198:201], v[54:57]
	v_mfma_f32_16x16x32_bf16 v[46:49], v[190:193], v[198:201], v[46:49]
	v_mfma_f32_16x16x32_bf16 v[38:41], v[182:185], v[206:209], v[38:41]
	v_mfma_f32_16x16x32_bf16 v[30:33], v[190:193], v[206:209], v[30:33]
	v_mfma_f32_16x16x32_bf16 v[22:25], v[182:185], v[214:217], v[22:25]
	v_mfma_f32_16x16x32_bf16 v[14:17], v[190:193], v[214:217], v[14:17]
	v_mfma_f32_16x16x32_bf16 v[6:9], v[182:185], v[222:225], v[6:9]
	s_setprio 0
	v_mfma_f32_16x16x32_bf16 v[2:5], v[190:193], v[222:225], v[2:5]
	s_barrier
	ds_read_b128 v[160:163], v139
	ds_read_b128 v[164:167], v139 offset:1024
	ds_read_b128 v[168:171], v139 offset:2048
	ds_read_b128 v[172:175], v139 offset:3072
	ds_read_b128 v[178:181], v159
	ds_read_b128 v[182:185], v159 offset:1024
	ds_read_b128 v[186:189], v159 offset:2048
	ds_read_b128 v[190:193], v159 offset:3072
	s_add_u32 s2, s2, 0x4000
	s_addc_u32 s3, s3, 0
	s_mov_b32 m0, s21
	v_lshl_add_u64 v[226:227], s[2:3], 0, v[140:141]
	ds_read_b128 v[194:197], v137 offset:32768
	ds_read_b128 v[198:201], v137 offset:33792
	ds_read_b128 v[202:205], v137 offset:34816
	ds_read_b128 v[206:209], v137 offset:35840
	ds_read_b128 v[210:213], v137 offset:36864
	ds_read_b128 v[214:217], v137 offset:37888
	ds_read_b128 v[218:221], v137 offset:38912
	ds_read_b128 v[222:225], v137 offset:39936
	global_load_lds_dwordx4 v[226:227], off
	v_lshl_add_u64 v[226:227], s[2:3], 0, v[144:145]
	s_mov_b32 m0, s22
	s_nop 0
	global_load_lds_dwordx4 v[226:227], off
	s_waitcnt vmcnt(8)
	s_waitcnt lgkmcnt(0)
	s_setprio 1
	s_barrier
	v_mfma_f32_16x16x32_bf16 v[126:129], v[160:163], v[194:197], v[126:129]
	v_mfma_f32_16x16x32_bf16 v[122:125], v[168:171], v[194:197], v[122:125]
	v_mfma_f32_16x16x32_bf16 v[114:117], v[160:163], v[202:205], v[114:117]
	v_mfma_f32_16x16x32_bf16 v[106:109], v[168:171], v[202:205], v[106:109]
	v_mfma_f32_16x16x32_bf16 v[98:101], v[160:163], v[210:213], v[98:101]
	v_mfma_f32_16x16x32_bf16 v[90:93], v[168:171], v[210:213], v[90:93]
	v_mfma_f32_16x16x32_bf16 v[82:85], v[160:163], v[218:221], v[82:85]
	v_mfma_f32_16x16x32_bf16 v[74:77], v[168:171], v[218:221], v[74:77]
	v_mfma_f32_16x16x32_bf16 v[126:129], v[164:167], v[198:201], v[126:129]
	v_mfma_f32_16x16x32_bf16 v[122:125], v[172:175], v[198:201], v[122:125]
	v_mfma_f32_16x16x32_bf16 v[114:117], v[164:167], v[206:209], v[114:117]
	v_mfma_f32_16x16x32_bf16 v[106:109], v[172:175], v[206:209], v[106:109]
	v_mfma_f32_16x16x32_bf16 v[98:101], v[164:167], v[214:217], v[98:101]
	v_mfma_f32_16x16x32_bf16 v[90:93], v[172:175], v[214:217], v[90:93]
	v_mfma_f32_16x16x32_bf16 v[82:85], v[164:167], v[222:225], v[82:85]
	v_mfma_f32_16x16x32_bf16 v[74:77], v[172:175], v[222:225], v[74:77]
	v_mfma_f32_16x16x32_bf16 v[118:121], v[178:181], v[194:197], v[118:121]
	v_mfma_f32_16x16x32_bf16 v[110:113], v[186:189], v[194:197], v[110:113]
	v_mfma_f32_16x16x32_bf16 v[102:105], v[178:181], v[202:205], v[102:105]
	v_mfma_f32_16x16x32_bf16 v[94:97], v[186:189], v[202:205], v[94:97]
	v_mfma_f32_16x16x32_bf16 v[86:89], v[178:181], v[210:213], v[86:89]
	v_mfma_f32_16x16x32_bf16 v[78:81], v[186:189], v[210:213], v[78:81]
	v_mfma_f32_16x16x32_bf16 v[70:73], v[178:181], v[218:221], v[70:73]
	v_mfma_f32_16x16x32_bf16 v[66:69], v[186:189], v[218:221], v[66:69]
	v_mfma_f32_16x16x32_bf16 v[118:121], v[182:185], v[198:201], v[118:121]
	v_mfma_f32_16x16x32_bf16 v[110:113], v[190:193], v[198:201], v[110:113]
	v_mfma_f32_16x16x32_bf16 v[102:105], v[182:185], v[206:209], v[102:105]
	v_mfma_f32_16x16x32_bf16 v[94:97], v[190:193], v[206:209], v[94:97]
	v_mfma_f32_16x16x32_bf16 v[86:89], v[182:185], v[214:217], v[86:89]
	v_mfma_f32_16x16x32_bf16 v[78:81], v[190:193], v[214:217], v[78:81]
	v_mfma_f32_16x16x32_bf16 v[70:73], v[182:185], v[222:225], v[70:73]
	s_setprio 0
	v_mfma_f32_16x16x32_bf16 v[66:69], v[190:193], v[222:225], v[66:69]
	s_barrier
	s_add_u32 s2, s14, 0x8000
	s_addc_u32 s3, s15, 0
	s_mov_b32 m0, s35
	v_lshl_add_u64 v[226:227], s[2:3], 0, v[142:143]
	ds_read_b128 v[194:197], v137 offset:49152
	ds_read_b128 v[198:201], v137 offset:50176
	ds_read_b128 v[202:205], v137 offset:51200
	ds_read_b128 v[206:209], v137 offset:52224
	ds_read_b128 v[210:213], v137 offset:53248
	ds_read_b128 v[214:217], v137 offset:54272
	ds_read_b128 v[218:221], v137 offset:55296
	ds_read_b128 v[222:225], v137 offset:56320
	global_load_lds_dwordx4 v[226:227], off
	v_lshl_add_u64 v[226:227], s[2:3], 0, v[146:147]
	s_add_u32 s2, s14, 0xc000
	s_mov_b32 m0, s36
	s_addc_u32 s3, s15, 0
	global_load_lds_dwordx4 v[226:227], off
	v_lshl_add_u64 v[226:227], s[2:3], 0, v[142:143]
	s_mov_b32 m0, s37
	s_nop 0
	global_load_lds_dwordx4 v[226:227], off
	v_lshl_add_u64 v[226:227], s[2:3], 0, v[146:147]
	s_mov_b32 m0, s38
	s_nop 0
	global_load_lds_dwordx4 v[226:227], off
	v_lshl_add_u64 v[226:227], s[12:13], 0, v[140:141]
	s_mov_b32 m0, s24
	s_nop 0
	global_load_lds_dwordx4 v[226:227], off
	v_lshl_add_u64 v[226:227], s[12:13], 0, v[144:145]
	s_mov_b32 m0, s25
	s_nop 0
	global_load_lds_dwordx4 v[226:227], off
	s_waitcnt vmcnt(8)
	s_waitcnt lgkmcnt(0)
	s_setprio 1
	s_barrier
	v_mfma_f32_16x16x32_bf16 v[62:65], v[160:163], v[194:197], v[62:65]
	v_mfma_f32_16x16x32_bf16 v[58:61], v[168:171], v[194:197], v[58:61]
	v_mfma_f32_16x16x32_bf16 v[50:53], v[160:163], v[202:205], v[50:53]
	v_mfma_f32_16x16x32_bf16 v[42:45], v[168:171], v[202:205], v[42:45]
	v_mfma_f32_16x16x32_bf16 v[34:37], v[160:163], v[210:213], v[34:37]
	v_mfma_f32_16x16x32_bf16 v[26:29], v[168:171], v[210:213], v[26:29]
	v_mfma_f32_16x16x32_bf16 v[18:21], v[160:163], v[218:221], v[18:21]
	v_mfma_f32_16x16x32_bf16 v[10:13], v[168:171], v[218:221], v[10:13]
	v_mfma_f32_16x16x32_bf16 v[62:65], v[164:167], v[198:201], v[62:65]
	v_mfma_f32_16x16x32_bf16 v[58:61], v[172:175], v[198:201], v[58:61]
	v_mfma_f32_16x16x32_bf16 v[50:53], v[164:167], v[206:209], v[50:53]
	v_mfma_f32_16x16x32_bf16 v[42:45], v[172:175], v[206:209], v[42:45]
	v_mfma_f32_16x16x32_bf16 v[34:37], v[164:167], v[214:217], v[34:37]
	v_mfma_f32_16x16x32_bf16 v[26:29], v[172:175], v[214:217], v[26:29]
	v_mfma_f32_16x16x32_bf16 v[18:21], v[164:167], v[222:225], v[18:21]
	v_mfma_f32_16x16x32_bf16 v[10:13], v[172:175], v[222:225], v[10:13]
	v_mfma_f32_16x16x32_bf16 v[54:57], v[178:181], v[194:197], v[54:57]
	v_mfma_f32_16x16x32_bf16 v[46:49], v[186:189], v[194:197], v[46:49]
	v_mfma_f32_16x16x32_bf16 v[38:41], v[178:181], v[202:205], v[38:41]
	v_mfma_f32_16x16x32_bf16 v[30:33], v[186:189], v[202:205], v[30:33]
	v_mfma_f32_16x16x32_bf16 v[22:25], v[178:181], v[210:213], v[22:25]
	v_mfma_f32_16x16x32_bf16 v[14:17], v[186:189], v[210:213], v[14:17]
	v_mfma_f32_16x16x32_bf16 v[6:9], v[178:181], v[218:221], v[6:9]
	v_mfma_f32_16x16x32_bf16 v[2:5], v[186:189], v[218:221], v[2:5]
	v_mfma_f32_16x16x32_bf16 v[54:57], v[182:185], v[198:201], v[54:57]
	v_mfma_f32_16x16x32_bf16 v[46:49], v[190:193], v[198:201], v[46:49]
	v_mfma_f32_16x16x32_bf16 v[38:41], v[182:185], v[206:209], v[38:41]
	v_mfma_f32_16x16x32_bf16 v[30:33], v[190:193], v[206:209], v[30:33]
	v_mfma_f32_16x16x32_bf16 v[22:25], v[182:185], v[214:217], v[22:25]
	v_mfma_f32_16x16x32_bf16 v[14:17], v[190:193], v[214:217], v[14:17]
	v_mfma_f32_16x16x32_bf16 v[6:9], v[182:185], v[222:225], v[6:9]
	s_setprio 0
	v_mfma_f32_16x16x32_bf16 v[2:5], v[190:193], v[222:225], v[2:5]
	s_barrier
	s_add_i32 s26, s26, 2
	s_add_u32 s8, s8, 0x10000
	s_addc_u32 s9, s9, 0
	s_cmp_gt_u32 s26, 41
	s_cbranch_scc0 .LBB0_437
	s_cmpk_lt_u32 s16, 0x100
	s_cbranch_scc0 .LBB0_440
	s_barrier

.Lpk451_peel:
	ds_read_b128 v[152:155], v149
	ds_read_b128 v[156:159], v149 offset:1024
	ds_read_b128 v[160:163], v149 offset:2048
	ds_read_b128 v[164:167], v149 offset:3072
	ds_read_b128 v[168:171], v150
	ds_read_b128 v[172:175], v150 offset:1024
	ds_read_b128 v[178:181], v150 offset:2048
	ds_read_b128 v[182:185], v150 offset:3072
	s_add_u32 s2, s28, 0xfffc0080
	s_addc_u32 s3, s29, -1
	s_cmp_eq_u32 s52, 12
	s_cselect_b32 s3, s11, s3
	s_cselect_b32 s2, s13, s2
	s_cselect_b32 s31, s44, s47
	s_cselect_b32 s30, s45, s46
	v_lshl_add_u64 v[146:147], s[28:29], 0, v[140:141]
	s_add_i32 m0, s25, 0xc000
	ds_read_b128 v[186:189], v151
	ds_read_b128 v[190:193], v151 offset:1024
	ds_read_b128 v[194:197], v151 offset:2048
	ds_read_b128 v[198:201], v151 offset:3072
	ds_read_b128 v[202:205], v151 offset:4096
	ds_read_b128 v[206:209], v151 offset:5120
	ds_read_b128 v[210:213], v151 offset:6144
	ds_read_b128 v[214:217], v151 offset:7168
	global_load_lds_dwordx4 v[146:147], off
	v_lshl_add_u64 v[146:147], s[28:29], 0, v[142:143]
	s_add_i32 m0, s25, 0xe000
	s_nop 0
	global_load_lds_dwordx4 v[146:147], off
	s_waitcnt vmcnt(8)
	s_waitcnt lgkmcnt(0)
	s_setprio 1
	s_barrier
	v_mfma_f32_16x16x32_bf16 v[126:129], v[152:155], v[186:189], 0
	v_mfma_f32_16x16x32_bf16 v[122:125], v[160:163], v[186:189], 0
	v_mfma_f32_16x16x32_bf16 v[110:113], v[152:155], v[194:197], 0
	v_mfma_f32_16x16x32_bf16 v[106:109], v[160:163], v[194:197], 0
	v_mfma_f32_16x16x32_bf16 v[94:97], v[152:155], v[202:205], 0
	v_mfma_f32_16x16x32_bf16 v[90:93], v[160:163], v[202:205], 0
	v_mfma_f32_16x16x32_bf16 v[78:81], v[152:155], v[210:213], 0
	v_mfma_f32_16x16x32_bf16 v[74:77], v[160:163], v[210:213], 0
	v_mfma_f32_16x16x32_bf16 v[126:129], v[156:159], v[190:193], v[126:129]
	v_mfma_f32_16x16x32_bf16 v[122:125], v[164:167], v[190:193], v[122:125]
	v_mfma_f32_16x16x32_bf16 v[110:113], v[156:159], v[198:201], v[110:113]
	v_mfma_f32_16x16x32_bf16 v[106:109], v[164:167], v[198:201], v[106:109]
	v_mfma_f32_16x16x32_bf16 v[94:97], v[156:159], v[206:209], v[94:97]
	v_mfma_f32_16x16x32_bf16 v[90:93], v[164:167], v[206:209], v[90:93]
	v_mfma_f32_16x16x32_bf16 v[78:81], v[156:159], v[214:217], v[78:81]
	v_mfma_f32_16x16x32_bf16 v[74:77], v[164:167], v[214:217], v[74:77]
	v_mfma_f32_16x16x32_bf16 v[118:121], v[168:171], v[186:189], 0
	v_mfma_f32_16x16x32_bf16 v[114:117], v[178:181], v[186:189], 0
	v_mfma_f32_16x16x32_bf16 v[102:105], v[168:171], v[194:197], 0
	v_mfma_f32_16x16x32_bf16 v[98:101], v[178:181], v[194:197], 0
	v_mfma_f32_16x16x32_bf16 v[86:89], v[168:171], v[202:205], 0
	v_mfma_f32_16x16x32_bf16 v[82:85], v[178:181], v[202:205], 0
	v_mfma_f32_16x16x32_bf16 v[70:73], v[168:171], v[210:213], 0
	v_mfma_f32_16x16x32_bf16 v[66:69], v[178:181], v[210:213], 0
	v_mfma_f32_16x16x32_bf16 v[118:121], v[172:175], v[190:193], v[118:121]
	v_mfma_f32_16x16x32_bf16 v[114:117], v[182:185], v[190:193], v[114:117]
	v_mfma_f32_16x16x32_bf16 v[102:105], v[172:175], v[198:201], v[102:105]
	v_mfma_f32_16x16x32_bf16 v[98:101], v[182:185], v[198:201], v[98:101]
	v_mfma_f32_16x16x32_bf16 v[86:89], v[172:175], v[206:209], v[86:89]
	v_mfma_f32_16x16x32_bf16 v[82:85], v[182:185], v[206:209], v[82:85]
	v_mfma_f32_16x16x32_bf16 v[70:73], v[172:175], v[214:217], v[70:73]
	s_setprio 0
	v_mfma_f32_16x16x32_bf16 v[66:69], v[182:185], v[214:217], v[66:69]
	s_barrier
	s_add_i32 s53, s42, s34
	v_lshl_add_u64 v[146:147], s[30:31], 0, v[132:133]
	s_mov_b32 m0, s53
	ds_read_b128 v[186:189], v151 offset:16384
	ds_read_b128 v[190:193], v151 offset:17408
	ds_read_b128 v[194:197], v151 offset:18432
	ds_read_b128 v[198:201], v151 offset:19456
	ds_read_b128 v[202:205], v151 offset:20480
	ds_read_b128 v[206:209], v151 offset:21504
	ds_read_b128 v[210:213], v151 offset:22528
	ds_read_b128 v[214:217], v151 offset:23552
	global_load_lds_dwordx4 v[146:147], off
	s_add_i32 m0, s53, 0x2000
	s_add_u32 s54, s30, 0x40000
	v_lshl_add_u64 v[218:219], s[30:31], 0, v[136:137]
	s_addc_u32 s55, s31, 0
	s_add_i32 s53, s43, s34
	global_load_lds_dwordx4 v[218:219], off
	v_lshl_add_u64 v[220:221], s[54:55], 0, v[132:133]
	s_mov_b32 m0, s53
	v_lshl_add_u64 v[222:223], s[2:3], 0, v[134:135]
	global_load_lds_dwordx4 v[220:221], off
	v_lshl_add_u64 v[220:221], s[54:55], 0, v[136:137]
	s_add_i32 m0, s53, 0x2000
	s_nop 0
	global_load_lds_dwordx4 v[220:221], off
	v_lshl_add_u64 v[220:221], s[2:3], 0, v[130:131]
	s_mov_b32 m0, s25
	s_nop 0
	global_load_lds_dwordx4 v[220:221], off
	s_mov_b32 m0, s27
	s_nop 0
	global_load_lds_dwordx4 v[222:223], off
	s_waitcnt vmcnt(8)
	s_waitcnt lgkmcnt(0)
	s_setprio 1
	s_barrier
	v_mfma_f32_16x16x32_bf16 v[62:65], v[152:155], v[186:189], 0
	v_mfma_f32_16x16x32_bf16 v[58:61], v[160:163], v[186:189], 0
	v_mfma_f32_16x16x32_bf16 v[46:49], v[152:155], v[194:197], 0
	v_mfma_f32_16x16x32_bf16 v[42:45], v[160:163], v[194:197], 0
	v_mfma_f32_16x16x32_bf16 v[30:33], v[152:155], v[202:205], 0
	v_mfma_f32_16x16x32_bf16 v[26:29], v[160:163], v[202:205], 0
	v_mfma_f32_16x16x32_bf16 v[14:17], v[152:155], v[210:213], 0
	v_mfma_f32_16x16x32_bf16 v[10:13], v[160:163], v[210:213], 0
	v_mfma_f32_16x16x32_bf16 v[62:65], v[156:159], v[190:193], v[62:65]
	v_mfma_f32_16x16x32_bf16 v[58:61], v[164:167], v[190:193], v[58:61]
	v_mfma_f32_16x16x32_bf16 v[46:49], v[156:159], v[198:201], v[46:49]
	v_mfma_f32_16x16x32_bf16 v[42:45], v[164:167], v[198:201], v[42:45]
	v_mfma_f32_16x16x32_bf16 v[30:33], v[156:159], v[206:209], v[30:33]
	v_mfma_f32_16x16x32_bf16 v[26:29], v[164:167], v[206:209], v[26:29]
	v_mfma_f32_16x16x32_bf16 v[14:17], v[156:159], v[214:217], v[14:17]
	v_mfma_f32_16x16x32_bf16 v[10:13], v[164:167], v[214:217], v[10:13]
	v_mfma_f32_16x16x32_bf16 v[54:57], v[168:171], v[186:189], 0
	v_mfma_f32_16x16x32_bf16 v[50:53], v[178:181], v[186:189], 0
	v_mfma_f32_16x16x32_bf16 v[38:41], v[168:171], v[194:197], 0
	v_mfma_f32_16x16x32_bf16 v[34:37], v[178:181], v[194:197], 0
	v_mfma_f32_16x16x32_bf16 v[22:25], v[168:171], v[202:205], 0
	v_mfma_f32_16x16x32_bf16 v[18:21], v[178:181], v[202:205], 0
	v_mfma_f32_16x16x32_bf16 v[6:9], v[168:171], v[210:213], 0
	v_mfma_f32_16x16x32_bf16 v[2:5], v[178:181], v[210:213], 0
	v_mfma_f32_16x16x32_bf16 v[54:57], v[172:175], v[190:193], v[54:57]
	v_mfma_f32_16x16x32_bf16 v[50:53], v[182:185], v[190:193], v[50:53]
	v_mfma_f32_16x16x32_bf16 v[38:41], v[172:175], v[198:201], v[38:41]
	v_mfma_f32_16x16x32_bf16 v[34:37], v[182:185], v[198:201], v[34:37]
	v_mfma_f32_16x16x32_bf16 v[22:25], v[172:175], v[206:209], v[22:25]
	v_mfma_f32_16x16x32_bf16 v[18:21], v[182:185], v[206:209], v[18:21]
	v_mfma_f32_16x16x32_bf16 v[6:9], v[172:175], v[214:217], v[6:9]
	s_setprio 0
	v_mfma_f32_16x16x32_bf16 v[2:5], v[182:185], v[214:217], v[2:5]
	s_barrier
	s_add_i32 s53, 0, 0x18000
	s_add_i32 s54, 0, 0x1c000
	v_add_u32_e32 v164, s53, v148
	v_add_u32_e32 v176, s54, v148
	ds_read_b128 v[152:155], v164
	ds_read_b128 v[156:159], v164 offset:1024
	ds_read_b128 v[160:163], v164 offset:2048
	ds_read_b128 v[164:167], v164 offset:3072
	ds_read_b128 v[168:171], v176
	ds_read_b128 v[172:175], v176 offset:1024
	ds_read_b128 v[178:181], v176 offset:2048
	ds_read_b128 v[182:185], v176 offset:3072
	s_add_u32 s2, s2, 0x40000
	s_addc_u32 s3, s3, 0
	s_mov_b32 m0, s36
	v_lshl_add_u64 v[224:225], s[2:3], 0, v[130:131]
	ds_read_b128 v[186:189], v151 offset:32768
	ds_read_b128 v[190:193], v151 offset:33792
	ds_read_b128 v[194:197], v151 offset:34816
	ds_read_b128 v[198:201], v151 offset:35840
	ds_read_b128 v[202:205], v151 offset:36864
	ds_read_b128 v[206:209], v151 offset:37888
	ds_read_b128 v[210:213], v151 offset:38912
	ds_read_b128 v[214:217], v151 offset:39936
	global_load_lds_dwordx4 v[224:225], off
	v_lshl_add_u64 v[224:225], s[2:3], 0, v[134:135]
	s_mov_b32 m0, s37
	s_nop 0
	global_load_lds_dwordx4 v[224:225], off
	s_waitcnt vmcnt(8)
	s_waitcnt lgkmcnt(0)
	s_setprio 1
	s_barrier
	v_mfma_f32_16x16x32_bf16 v[126:129], v[152:155], v[186:189], v[126:129]
	v_mfma_f32_16x16x32_bf16 v[122:125], v[160:163], v[186:189], v[122:125]
	v_mfma_f32_16x16x32_bf16 v[110:113], v[152:155], v[194:197], v[110:113]
	v_mfma_f32_16x16x32_bf16 v[106:109], v[160:163], v[194:197], v[106:109]
	v_mfma_f32_16x16x32_bf16 v[94:97], v[152:155], v[202:205], v[94:97]
	v_mfma_f32_16x16x32_bf16 v[90:93], v[160:163], v[202:205], v[90:93]
	v_mfma_f32_16x16x32_bf16 v[78:81], v[152:155], v[210:213], v[78:81]
	v_mfma_f32_16x16x32_bf16 v[74:77], v[160:163], v[210:213], v[74:77]
	v_mfma_f32_16x16x32_bf16 v[126:129], v[156:159], v[190:193], v[126:129]
	v_mfma_f32_16x16x32_bf16 v[122:125], v[164:167], v[190:193], v[122:125]
	v_mfma_f32_16x16x32_bf16 v[110:113], v[156:159], v[198:201], v[110:113]
	v_mfma_f32_16x16x32_bf16 v[106:109], v[164:167], v[198:201], v[106:109]
	v_mfma_f32_16x16x32_bf16 v[94:97], v[156:159], v[206:209], v[94:97]
	v_mfma_f32_16x16x32_bf16 v[90:93], v[164:167], v[206:209], v[90:93]
	v_mfma_f32_16x16x32_bf16 v[78:81], v[156:159], v[214:217], v[78:81]
	v_mfma_f32_16x16x32_bf16 v[74:77], v[164:167], v[214:217], v[74:77]
	v_mfma_f32_16x16x32_bf16 v[118:121], v[168:171], v[186:189], v[118:121]
	v_mfma_f32_16x16x32_bf16 v[114:117], v[178:181], v[186:189], v[114:117]
	v_mfma_f32_16x16x32_bf16 v[102:105], v[168:171], v[194:197], v[102:105]
	v_mfma_f32_16x16x32_bf16 v[98:101], v[178:181], v[194:197], v[98:101]
	v_mfma_f32_16x16x32_bf16 v[86:89], v[168:171], v[202:205], v[86:89]
	v_mfma_f32_16x16x32_bf16 v[82:85], v[178:181], v[202:205], v[82:85]
	v_mfma_f32_16x16x32_bf16 v[70:73], v[168:171], v[210:213], v[70:73]
	v_mfma_f32_16x16x32_bf16 v[66:69], v[178:181], v[210:213], v[66:69]
	v_mfma_f32_16x16x32_bf16 v[118:121], v[172:175], v[190:193], v[118:121]
	v_mfma_f32_16x16x32_bf16 v[114:117], v[182:185], v[190:193], v[114:117]
	v_mfma_f32_16x16x32_bf16 v[102:105], v[172:175], v[198:201], v[102:105]
	v_mfma_f32_16x16x32_bf16 v[98:101], v[182:185], v[198:201], v[98:101]
	v_mfma_f32_16x16x32_bf16 v[86:89], v[172:175], v[206:209], v[86:89]
	v_mfma_f32_16x16x32_bf16 v[82:85], v[182:185], v[206:209], v[82:85]
	v_mfma_f32_16x16x32_bf16 v[70:73], v[172:175], v[214:217], v[70:73]
	s_setprio 0
	v_mfma_f32_16x16x32_bf16 v[66:69], v[182:185], v[214:217], v[66:69]
	s_barrier
	s_add_i32 s2, s53, s34
	v_lshl_add_u64 v[146:147], v[146:147], 0, s[6:7]
	s_mov_b32 m0, s2
	ds_read_b128 v[186:189], v151 offset:49152
	ds_read_b128 v[190:193], v151 offset:50176
	ds_read_b128 v[194:197], v151 offset:51200
	ds_read_b128 v[198:201], v151 offset:52224
	ds_read_b128 v[202:205], v151 offset:53248
	ds_read_b128 v[206:209], v151 offset:54272
	ds_read_b128 v[210:213], v151 offset:55296
	ds_read_b128 v[214:217], v151 offset:56320
	global_load_lds_dwordx4 v[146:147], off
	s_add_i32 m0, s2, 0x2000
	s_add_u32 s2, s30, 0x40080
	v_lshl_add_u64 v[146:147], v[218:219], 0, s[6:7]
	s_addc_u32 s3, s31, 0
	s_add_i32 s30, s54, s34
	global_load_lds_dwordx4 v[146:147], off
	v_lshl_add_u64 v[146:147], s[2:3], 0, v[132:133]
	s_mov_b32 m0, s30
	s_nop 0
	global_load_lds_dwordx4 v[146:147], off
	v_lshl_add_u64 v[146:147], s[2:3], 0, v[136:137]
	s_add_i32 m0, s30, 0x2000
	s_nop 0
	global_load_lds_dwordx4 v[146:147], off
	v_lshl_add_u64 v[146:147], v[220:221], 0, s[6:7]
	s_mov_b32 m0, s39
	s_nop 0
	global_load_lds_dwordx4 v[146:147], off
	v_lshl_add_u64 v[146:147], v[222:223], 0, s[6:7]
	s_mov_b32 m0, s40
	s_nop 0
	global_load_lds_dwordx4 v[146:147], off
	s_waitcnt vmcnt(8)
	s_waitcnt lgkmcnt(0)
	s_setprio 1
	s_barrier
	v_mfma_f32_16x16x32_bf16 v[62:65], v[152:155], v[186:189], v[62:65]
	v_mfma_f32_16x16x32_bf16 v[58:61], v[160:163], v[186:189], v[58:61]
	v_mfma_f32_16x16x32_bf16 v[46:49], v[152:155], v[194:197], v[46:49]
	v_mfma_f32_16x16x32_bf16 v[42:45], v[160:163], v[194:197], v[42:45]
	v_mfma_f32_16x16x32_bf16 v[30:33], v[152:155], v[202:205], v[30:33]
	v_mfma_f32_16x16x32_bf16 v[26:29], v[160:163], v[202:205], v[26:29]
	v_mfma_f32_16x16x32_bf16 v[14:17], v[152:155], v[210:213], v[14:17]
	v_mfma_f32_16x16x32_bf16 v[10:13], v[160:163], v[210:213], v[10:13]
	v_mfma_f32_16x16x32_bf16 v[62:65], v[156:159], v[190:193], v[62:65]
	v_mfma_f32_16x16x32_bf16 v[58:61], v[164:167], v[190:193], v[58:61]
	v_mfma_f32_16x16x32_bf16 v[46:49], v[156:159], v[198:201], v[46:49]
	v_mfma_f32_16x16x32_bf16 v[42:45], v[164:167], v[198:201], v[42:45]
	v_mfma_f32_16x16x32_bf16 v[30:33], v[156:159], v[206:209], v[30:33]
	v_mfma_f32_16x16x32_bf16 v[26:29], v[164:167], v[206:209], v[26:29]
	v_mfma_f32_16x16x32_bf16 v[14:17], v[156:159], v[214:217], v[14:17]
	v_mfma_f32_16x16x32_bf16 v[10:13], v[164:167], v[214:217], v[10:13]
	v_mfma_f32_16x16x32_bf16 v[54:57], v[168:171], v[186:189], v[54:57]
	v_mfma_f32_16x16x32_bf16 v[50:53], v[178:181], v[186:189], v[50:53]
	v_mfma_f32_16x16x32_bf16 v[38:41], v[168:171], v[194:197], v[38:41]
	v_mfma_f32_16x16x32_bf16 v[34:37], v[178:181], v[194:197], v[34:37]
	v_mfma_f32_16x16x32_bf16 v[22:25], v[168:171], v[202:205], v[22:25]
	v_mfma_f32_16x16x32_bf16 v[18:21], v[178:181], v[202:205], v[18:21]
	v_mfma_f32_16x16x32_bf16 v[6:9], v[168:171], v[210:213], v[6:9]
	v_mfma_f32_16x16x32_bf16 v[2:5], v[178:181], v[210:213], v[2:5]
	v_mfma_f32_16x16x32_bf16 v[54:57], v[172:175], v[190:193], v[54:57]
	v_mfma_f32_16x16x32_bf16 v[50:53], v[182:185], v[190:193], v[50:53]
	v_mfma_f32_16x16x32_bf16 v[38:41], v[172:175], v[198:201], v[38:41]
	v_mfma_f32_16x16x32_bf16 v[34:37], v[182:185], v[198:201], v[34:37]
	v_mfma_f32_16x16x32_bf16 v[22:25], v[172:175], v[206:209], v[22:25]
	v_mfma_f32_16x16x32_bf16 v[18:21], v[182:185], v[206:209], v[18:21]
	v_mfma_f32_16x16x32_bf16 v[6:9], v[172:175], v[214:217], v[6:9]
	s_setprio 0
	v_mfma_f32_16x16x32_bf16 v[2:5], v[182:185], v[214:217], v[2:5]
	s_barrier
	s_add_i32 s52, s52, 2
	s_add_u32 s28, s28, 0x100
	s_addc_u32 s29, s29, 0
	s_add_u32 s46, s46, 0x100
	s_addc_u32 s47, s47, 0
	s_cmp_gt_u32 s52, 13
	s_cbranch_scc0 .LBB0_451
	s_branch .Lpk451_exit
.LBB0_451:
	ds_read_b128 v[152:155], v149
	ds_read_b128 v[156:159], v149 offset:1024
	ds_read_b128 v[160:163], v149 offset:2048
	ds_read_b128 v[164:167], v149 offset:3072
	ds_read_b128 v[168:171], v150
	ds_read_b128 v[172:175], v150 offset:1024
	ds_read_b128 v[178:181], v150 offset:2048
	ds_read_b128 v[182:185], v150 offset:3072
	s_add_u32 s2, s28, 0xfffc0080
	s_addc_u32 s3, s29, -1
	s_cmp_eq_u32 s52, 12
	s_cselect_b32 s3, s11, s3
	s_cselect_b32 s2, s13, s2
	s_cselect_b32 s31, s44, s47
	s_cselect_b32 s30, s45, s46
	v_lshl_add_u64 v[146:147], s[28:29], 0, v[140:141]
	s_add_i32 m0, s25, 0xc000
	ds_read_b128 v[186:189], v151
	ds_read_b128 v[190:193], v151 offset:1024
	ds_read_b128 v[194:197], v151 offset:2048
	ds_read_b128 v[198:201], v151 offset:3072
	ds_read_b128 v[202:205], v151 offset:4096
	ds_read_b128 v[206:209], v151 offset:5120
	ds_read_b128 v[210:213], v151 offset:6144
	ds_read_b128 v[214:217], v151 offset:7168
	global_load_lds_dwordx4 v[146:147], off
	v_lshl_add_u64 v[146:147], s[28:29], 0, v[142:143]
	s_add_i32 m0, s25, 0xe000
	s_nop 0
	global_load_lds_dwordx4 v[146:147], off
	s_waitcnt vmcnt(8)
	s_waitcnt lgkmcnt(0)
	s_setprio 1
	s_barrier
	v_mfma_f32_16x16x32_bf16 v[126:129], v[152:155], v[186:189], v[126:129]
	v_mfma_f32_16x16x32_bf16 v[122:125], v[160:163], v[186:189], v[122:125]
	v_mfma_f32_16x16x32_bf16 v[110:113], v[152:155], v[194:197], v[110:113]
	v_mfma_f32_16x16x32_bf16 v[106:109], v[160:163], v[194:197], v[106:109]
	v_mfma_f32_16x16x32_bf16 v[94:97], v[152:155], v[202:205], v[94:97]
	v_mfma_f32_16x16x32_bf16 v[90:93], v[160:163], v[202:205], v[90:93]
	v_mfma_f32_16x16x32_bf16 v[78:81], v[152:155], v[210:213], v[78:81]
	v_mfma_f32_16x16x32_bf16 v[74:77], v[160:163], v[210:213], v[74:77]
	v_mfma_f32_16x16x32_bf16 v[126:129], v[156:159], v[190:193], v[126:129]
	v_mfma_f32_16x16x32_bf16 v[122:125], v[164:167], v[190:193], v[122:125]
	v_mfma_f32_16x16x32_bf16 v[110:113], v[156:159], v[198:201], v[110:113]
	v_mfma_f32_16x16x32_bf16 v[106:109], v[164:167], v[198:201], v[106:109]
	v_mfma_f32_16x16x32_bf16 v[94:97], v[156:159], v[206:209], v[94:97]
	v_mfma_f32_16x16x32_bf16 v[90:93], v[164:167], v[206:209], v[90:93]
	v_mfma_f32_16x16x32_bf16 v[78:81], v[156:159], v[214:217], v[78:81]
	v_mfma_f32_16x16x32_bf16 v[74:77], v[164:167], v[214:217], v[74:77]
	v_mfma_f32_16x16x32_bf16 v[118:121], v[168:171], v[186:189], v[118:121]
	v_mfma_f32_16x16x32_bf16 v[114:117], v[178:181], v[186:189], v[114:117]
	v_mfma_f32_16x16x32_bf16 v[102:105], v[168:171], v[194:197], v[102:105]
	v_mfma_f32_16x16x32_bf16 v[98:101], v[178:181], v[194:197], v[98:101]
	v_mfma_f32_16x16x32_bf16 v[86:89], v[168:171], v[202:205], v[86:89]
	v_mfma_f32_16x16x32_bf16 v[82:85], v[178:181], v[202:205], v[82:85]
	v_mfma_f32_16x16x32_bf16 v[70:73], v[168:171], v[210:213], v[70:73]
	v_mfma_f32_16x16x32_bf16 v[66:69], v[178:181], v[210:213], v[66:69]
	v_mfma_f32_16x16x32_bf16 v[118:121], v[172:175], v[190:193], v[118:121]
	v_mfma_f32_16x16x32_bf16 v[114:117], v[182:185], v[190:193], v[114:117]
	v_mfma_f32_16x16x32_bf16 v[102:105], v[172:175], v[198:201], v[102:105]
	v_mfma_f32_16x16x32_bf16 v[98:101], v[182:185], v[198:201], v[98:101]
	v_mfma_f32_16x16x32_bf16 v[86:89], v[172:175], v[206:209], v[86:89]
	v_mfma_f32_16x16x32_bf16 v[82:85], v[182:185], v[206:209], v[82:85]
	v_mfma_f32_16x16x32_bf16 v[70:73], v[172:175], v[214:217], v[70:73]
	s_setprio 0
	v_mfma_f32_16x16x32_bf16 v[66:69], v[182:185], v[214:217], v[66:69]
	s_barrier
	s_add_i32 s53, s42, s34
	v_lshl_add_u64 v[146:147], s[30:31], 0, v[132:133]
	s_mov_b32 m0, s53
	ds_read_b128 v[186:189], v151 offset:16384
	ds_read_b128 v[190:193], v151 offset:17408
	ds_read_b128 v[194:197], v151 offset:18432
	ds_read_b128 v[198:201], v151 offset:19456
	ds_read_b128 v[202:205], v151 offset:20480
	ds_read_b128 v[206:209], v151 offset:21504
	ds_read_b128 v[210:213], v151 offset:22528
	ds_read_b128 v[214:217], v151 offset:23552
	global_load_lds_dwordx4 v[146:147], off
	s_add_i32 m0, s53, 0x2000
	s_add_u32 s54, s30, 0x40000
	v_lshl_add_u64 v[218:219], s[30:31], 0, v[136:137]
	s_addc_u32 s55, s31, 0
	s_add_i32 s53, s43, s34
	global_load_lds_dwordx4 v[218:219], off
	v_lshl_add_u64 v[220:221], s[54:55], 0, v[132:133]
	s_mov_b32 m0, s53
	v_lshl_add_u64 v[222:223], s[2:3], 0, v[134:135]
	global_load_lds_dwordx4 v[220:221], off
	v_lshl_add_u64 v[220:221], s[54:55], 0, v[136:137]
	s_add_i32 m0, s53, 0x2000
	s_nop 0
	global_load_lds_dwordx4 v[220:221], off
	v_lshl_add_u64 v[220:221], s[2:3], 0, v[130:131]
	s_mov_b32 m0, s25
	s_nop 0
	global_load_lds_dwordx4 v[220:221], off
	s_mov_b32 m0, s27
	s_nop 0
	global_load_lds_dwordx4 v[222:223], off
	s_waitcnt vmcnt(8)
	s_waitcnt lgkmcnt(0)
	s_setprio 1
	s_barrier
	v_mfma_f32_16x16x32_bf16 v[62:65], v[152:155], v[186:189], v[62:65]
	v_mfma_f32_16x16x32_bf16 v[58:61], v[160:163], v[186:189], v[58:61]
	v_mfma_f32_16x16x32_bf16 v[46:49], v[152:155], v[194:197], v[46:49]
	v_mfma_f32_16x16x32_bf16 v[42:45], v[160:163], v[194:197], v[42:45]
	v_mfma_f32_16x16x32_bf16 v[30:33], v[152:155], v[202:205], v[30:33]
	v_mfma_f32_16x16x32_bf16 v[26:29], v[160:163], v[202:205], v[26:29]
	v_mfma_f32_16x16x32_bf16 v[14:17], v[152:155], v[210:213], v[14:17]
	v_mfma_f32_16x16x32_bf16 v[10:13], v[160:163], v[210:213], v[10:13]
	v_mfma_f32_16x16x32_bf16 v[62:65], v[156:159], v[190:193], v[62:65]
	v_mfma_f32_16x16x32_bf16 v[58:61], v[164:167], v[190:193], v[58:61]
	v_mfma_f32_16x16x32_bf16 v[46:49], v[156:159], v[198:201], v[46:49]
	v_mfma_f32_16x16x32_bf16 v[42:45], v[164:167], v[198:201], v[42:45]
	v_mfma_f32_16x16x32_bf16 v[30:33], v[156:159], v[206:209], v[30:33]
	v_mfma_f32_16x16x32_bf16 v[26:29], v[164:167], v[206:209], v[26:29]
	v_mfma_f32_16x16x32_bf16 v[14:17], v[156:159], v[214:217], v[14:17]
	v_mfma_f32_16x16x32_bf16 v[10:13], v[164:167], v[214:217], v[10:13]
	v_mfma_f32_16x16x32_bf16 v[54:57], v[168:171], v[186:189], v[54:57]
	v_mfma_f32_16x16x32_bf16 v[50:53], v[178:181], v[186:189], v[50:53]
	v_mfma_f32_16x16x32_bf16 v[38:41], v[168:171], v[194:197], v[38:41]
	v_mfma_f32_16x16x32_bf16 v[34:37], v[178:181], v[194:197], v[34:37]
	v_mfma_f32_16x16x32_bf16 v[22:25], v[168:171], v[202:205], v[22:25]
	v_mfma_f32_16x16x32_bf16 v[18:21], v[178:181], v[202:205], v[18:21]
	v_mfma_f32_16x16x32_bf16 v[6:9], v[168:171], v[210:213], v[6:9]
	v_mfma_f32_16x16x32_bf16 v[2:5], v[178:181], v[210:213], v[2:5]
	v_mfma_f32_16x16x32_bf16 v[54:57], v[172:175], v[190:193], v[54:57]
	v_mfma_f32_16x16x32_bf16 v[50:53], v[182:185], v[190:193], v[50:53]
	v_mfma_f32_16x16x32_bf16 v[38:41], v[172:175], v[198:201], v[38:41]
	v_mfma_f32_16x16x32_bf16 v[34:37], v[182:185], v[198:201], v[34:37]
	v_mfma_f32_16x16x32_bf16 v[22:25], v[172:175], v[206:209], v[22:25]
	v_mfma_f32_16x16x32_bf16 v[18:21], v[182:185], v[206:209], v[18:21]
	v_mfma_f32_16x16x32_bf16 v[6:9], v[172:175], v[214:217], v[6:9]
	s_setprio 0
	v_mfma_f32_16x16x32_bf16 v[2:5], v[182:185], v[214:217], v[2:5]
	s_barrier
	s_add_i32 s53, 0, 0x18000
	s_add_i32 s54, 0, 0x1c000
	v_add_u32_e32 v164, s53, v148
	v_add_u32_e32 v176, s54, v148
	ds_read_b128 v[152:155], v164
	ds_read_b128 v[156:159], v164 offset:1024
	ds_read_b128 v[160:163], v164 offset:2048
	ds_read_b128 v[164:167], v164 offset:3072
	ds_read_b128 v[168:171], v176
	ds_read_b128 v[172:175], v176 offset:1024
	ds_read_b128 v[178:181], v176 offset:2048
	ds_read_b128 v[182:185], v176 offset:3072
	s_add_u32 s2, s2, 0x40000
	s_addc_u32 s3, s3, 0
	s_mov_b32 m0, s36
	v_lshl_add_u64 v[224:225], s[2:3], 0, v[130:131]
	ds_read_b128 v[186:189], v151 offset:32768
	ds_read_b128 v[190:193], v151 offset:33792
	ds_read_b128 v[194:197], v151 offset:34816
	ds_read_b128 v[198:201], v151 offset:35840
	ds_read_b128 v[202:205], v151 offset:36864
	ds_read_b128 v[206:209], v151 offset:37888
	ds_read_b128 v[210:213], v151 offset:38912
	ds_read_b128 v[214:217], v151 offset:39936
	global_load_lds_dwordx4 v[224:225], off
	v_lshl_add_u64 v[224:225], s[2:3], 0, v[134:135]
	s_mov_b32 m0, s37
	s_nop 0
	global_load_lds_dwordx4 v[224:225], off
	s_waitcnt vmcnt(8)
	s_waitcnt lgkmcnt(0)
	s_setprio 1
	s_barrier
	v_mfma_f32_16x16x32_bf16 v[126:129], v[152:155], v[186:189], v[126:129]
	v_mfma_f32_16x16x32_bf16 v[122:125], v[160:163], v[186:189], v[122:125]
	v_mfma_f32_16x16x32_bf16 v[110:113], v[152:155], v[194:197], v[110:113]
	v_mfma_f32_16x16x32_bf16 v[106:109], v[160:163], v[194:197], v[106:109]
	v_mfma_f32_16x16x32_bf16 v[94:97], v[152:155], v[202:205], v[94:97]
	v_mfma_f32_16x16x32_bf16 v[90:93], v[160:163], v[202:205], v[90:93]
	v_mfma_f32_16x16x32_bf16 v[78:81], v[152:155], v[210:213], v[78:81]
	v_mfma_f32_16x16x32_bf16 v[74:77], v[160:163], v[210:213], v[74:77]
	v_mfma_f32_16x16x32_bf16 v[126:129], v[156:159], v[190:193], v[126:129]
	v_mfma_f32_16x16x32_bf16 v[122:125], v[164:167], v[190:193], v[122:125]
	v_mfma_f32_16x16x32_bf16 v[110:113], v[156:159], v[198:201], v[110:113]
	v_mfma_f32_16x16x32_bf16 v[106:109], v[164:167], v[198:201], v[106:109]
	v_mfma_f32_16x16x32_bf16 v[94:97], v[156:159], v[206:209], v[94:97]
	v_mfma_f32_16x16x32_bf16 v[90:93], v[164:167], v[206:209], v[90:93]
	v_mfma_f32_16x16x32_bf16 v[78:81], v[156:159], v[214:217], v[78:81]
	v_mfma_f32_16x16x32_bf16 v[74:77], v[164:167], v[214:217], v[74:77]
	v_mfma_f32_16x16x32_bf16 v[118:121], v[168:171], v[186:189], v[118:121]
	v_mfma_f32_16x16x32_bf16 v[114:117], v[178:181], v[186:189], v[114:117]
	v_mfma_f32_16x16x32_bf16 v[102:105], v[168:171], v[194:197], v[102:105]
	v_mfma_f32_16x16x32_bf16 v[98:101], v[178:181], v[194:197], v[98:101]
	v_mfma_f32_16x16x32_bf16 v[86:89], v[168:171], v[202:205], v[86:89]
	v_mfma_f32_16x16x32_bf16 v[82:85], v[178:181], v[202:205], v[82:85]
	v_mfma_f32_16x16x32_bf16 v[70:73], v[168:171], v[210:213], v[70:73]
	v_mfma_f32_16x16x32_bf16 v[66:69], v[178:181], v[210:213], v[66:69]
	v_mfma_f32_16x16x32_bf16 v[118:121], v[172:175], v[190:193], v[118:121]
	v_mfma_f32_16x16x32_bf16 v[114:117], v[182:185], v[190:193], v[114:117]
	v_mfma_f32_16x16x32_bf16 v[102:105], v[172:175], v[198:201], v[102:105]
	v_mfma_f32_16x16x32_bf16 v[98:101], v[182:185], v[198:201], v[98:101]
	v_mfma_f32_16x16x32_bf16 v[86:89], v[172:175], v[206:209], v[86:89]
	v_mfma_f32_16x16x32_bf16 v[82:85], v[182:185], v[206:209], v[82:85]
	v_mfma_f32_16x16x32_bf16 v[70:73], v[172:175], v[214:217], v[70:73]
	s_setprio 0
	v_mfma_f32_16x16x32_bf16 v[66:69], v[182:185], v[214:217], v[66:69]
	s_barrier
	s_add_i32 s2, s53, s34
	v_lshl_add_u64 v[146:147], v[146:147], 0, s[6:7]
	s_mov_b32 m0, s2
	ds_read_b128 v[186:189], v151 offset:49152
	ds_read_b128 v[190:193], v151 offset:50176
	ds_read_b128 v[194:197], v151 offset:51200
	ds_read_b128 v[198:201], v151 offset:52224
	ds_read_b128 v[202:205], v151 offset:53248
	ds_read_b128 v[206:209], v151 offset:54272
	ds_read_b128 v[210:213], v151 offset:55296
	ds_read_b128 v[214:217], v151 offset:56320
	global_load_lds_dwordx4 v[146:147], off
	s_add_i32 m0, s2, 0x2000
	s_add_u32 s2, s30, 0x40080
	v_lshl_add_u64 v[146:147], v[218:219], 0, s[6:7]
	s_addc_u32 s3, s31, 0
	s_add_i32 s30, s54, s34
	global_load_lds_dwordx4 v[146:147], off
	v_lshl_add_u64 v[146:147], s[2:3], 0, v[132:133]
	s_mov_b32 m0, s30
	s_nop 0
	global_load_lds_dwordx4 v[146:147], off
	v_lshl_add_u64 v[146:147], s[2:3], 0, v[136:137]
	s_add_i32 m0, s30, 0x2000
	s_nop 0
	global_load_lds_dwordx4 v[146:147], off
	v_lshl_add_u64 v[146:147], v[220:221], 0, s[6:7]
	s_mov_b32 m0, s39
	s_nop 0
	global_load_lds_dwordx4 v[146:147], off
	v_lshl_add_u64 v[146:147], v[222:223], 0, s[6:7]
	s_mov_b32 m0, s40
	s_nop 0
	global_load_lds_dwordx4 v[146:147], off
	s_waitcnt vmcnt(8)
	s_waitcnt lgkmcnt(0)
	s_setprio 1
	s_barrier
	v_mfma_f32_16x16x32_bf16 v[62:65], v[152:155], v[186:189], v[62:65]
	v_mfma_f32_16x16x32_bf16 v[58:61], v[160:163], v[186:189], v[58:61]
	v_mfma_f32_16x16x32_bf16 v[46:49], v[152:155], v[194:197], v[46:49]
	v_mfma_f32_16x16x32_bf16 v[42:45], v[160:163], v[194:197], v[42:45]
	v_mfma_f32_16x16x32_bf16 v[30:33], v[152:155], v[202:205], v[30:33]
	v_mfma_f32_16x16x32_bf16 v[26:29], v[160:163], v[202:205], v[26:29]
	v_mfma_f32_16x16x32_bf16 v[14:17], v[152:155], v[210:213], v[14:17]
	v_mfma_f32_16x16x32_bf16 v[10:13], v[160:163], v[210:213], v[10:13]
	v_mfma_f32_16x16x32_bf16 v[62:65], v[156:159], v[190:193], v[62:65]
	v_mfma_f32_16x16x32_bf16 v[58:61], v[164:167], v[190:193], v[58:61]
	v_mfma_f32_16x16x32_bf16 v[46:49], v[156:159], v[198:201], v[46:49]
	v_mfma_f32_16x16x32_bf16 v[42:45], v[164:167], v[198:201], v[42:45]
	v_mfma_f32_16x16x32_bf16 v[30:33], v[156:159], v[206:209], v[30:33]
	v_mfma_f32_16x16x32_bf16 v[26:29], v[164:167], v[206:209], v[26:29]
	v_mfma_f32_16x16x32_bf16 v[14:17], v[156:159], v[214:217], v[14:17]
	v_mfma_f32_16x16x32_bf16 v[10:13], v[164:167], v[214:217], v[10:13]
	v_mfma_f32_16x16x32_bf16 v[54:57], v[168:171], v[186:189], v[54:57]
	v_mfma_f32_16x16x32_bf16 v[50:53], v[178:181], v[186:189], v[50:53]
	v_mfma_f32_16x16x32_bf16 v[38:41], v[168:171], v[194:197], v[38:41]
	v_mfma_f32_16x16x32_bf16 v[34:37], v[178:181], v[194:197], v[34:37]
	v_mfma_f32_16x16x32_bf16 v[22:25], v[168:171], v[202:205], v[22:25]
	v_mfma_f32_16x16x32_bf16 v[18:21], v[178:181], v[202:205], v[18:21]
	v_mfma_f32_16x16x32_bf16 v[6:9], v[168:171], v[210:213], v[6:9]
	v_mfma_f32_16x16x32_bf16 v[2:5], v[178:181], v[210:213], v[2:5]
	v_mfma_f32_16x16x32_bf16 v[54:57], v[172:175], v[190:193], v[54:57]
	v_mfma_f32_16x16x32_bf16 v[50:53], v[182:185], v[190:193], v[50:53]
	v_mfma_f32_16x16x32_bf16 v[38:41], v[172:175], v[198:201], v[38:41]
	v_mfma_f32_16x16x32_bf16 v[34:37], v[182:185], v[198:201], v[34:37]
	v_mfma_f32_16x16x32_bf16 v[22:25], v[172:175], v[206:209], v[22:25]
	v_mfma_f32_16x16x32_bf16 v[18:21], v[182:185], v[206:209], v[18:21]
	v_mfma_f32_16x16x32_bf16 v[6:9], v[172:175], v[214:217], v[6:9]
	s_setprio 0
	v_mfma_f32_16x16x32_bf16 v[2:5], v[182:185], v[214:217], v[2:5]
	s_barrier
	s_add_i32 s52, s52, 2
	s_add_u32 s28, s28, 0x100
	s_addc_u32 s29, s29, 0
	s_add_u32 s46, s46, 0x100
	s_addc_u32 s47, s47, 0
	s_cmp_gt_u32 s52, 13
	s_cbranch_scc0 .LBB0_451

.Lpk495_peel:
	ds_read_b128 v[152:155], v149
	ds_read_b128 v[156:159], v149 offset:1024
	ds_read_b128 v[160:163], v149 offset:2048
	ds_read_b128 v[164:167], v149 offset:3072
	ds_read_b128 v[168:171], v150
	ds_read_b128 v[172:175], v150 offset:1024
	ds_read_b128 v[178:181], v150 offset:2048
	ds_read_b128 v[182:185], v150 offset:3072
	s_add_u32 s2, s18, 0x4000
	s_addc_u32 s3, s19, 0
	s_cmp_eq_u32 s50, 40
	s_cselect_b32 s2, s45, s2
	s_cselect_b32 s3, s44, s3
	s_cselect_b32 s23, s46, s49
	s_cselect_b32 s22, s47, s48
	s_add_u32 s20, s2, 0x8000
	s_addc_u32 s21, s3, 0
	v_lshl_add_u64 v[144:145], s[18:19], 0, v[138:139]
	s_add_i32 m0, s29, 0xc000
	ds_read_b128 v[186:189], v151
	ds_read_b128 v[190:193], v151 offset:1024
	ds_read_b128 v[194:197], v151 offset:2048
	ds_read_b128 v[198:201], v151 offset:3072
	ds_read_b128 v[202:205], v151 offset:4096
	ds_read_b128 v[206:209], v151 offset:5120
	ds_read_b128 v[210:213], v151 offset:6144
	ds_read_b128 v[214:217], v151 offset:7168
	global_load_lds_dwordx4 v[144:145], off
	v_lshl_add_u64 v[144:145], s[18:19], 0, v[140:141]
	s_add_i32 m0, s29, 0xe000
	s_nop 0
	global_load_lds_dwordx4 v[144:145], off
	s_waitcnt vmcnt(8)
	s_waitcnt lgkmcnt(0)
	s_setprio 1
	s_barrier
	v_mfma_f32_16x16x32_bf16 v[126:129], v[152:155], v[186:189], 0
	v_mfma_f32_16x16x32_bf16 v[122:125], v[160:163], v[186:189], 0
	v_mfma_f32_16x16x32_bf16 v[114:117], v[152:155], v[194:197], 0
	v_mfma_f32_16x16x32_bf16 v[106:109], v[160:163], v[194:197], 0
	v_mfma_f32_16x16x32_bf16 v[98:101], v[152:155], v[202:205], 0
	v_mfma_f32_16x16x32_bf16 v[90:93], v[160:163], v[202:205], 0
	v_mfma_f32_16x16x32_bf16 v[82:85], v[152:155], v[210:213], 0
	v_mfma_f32_16x16x32_bf16 v[74:77], v[160:163], v[210:213], 0
	v_mfma_f32_16x16x32_bf16 v[126:129], v[156:159], v[190:193], v[126:129]
	v_mfma_f32_16x16x32_bf16 v[122:125], v[164:167], v[190:193], v[122:125]
	v_mfma_f32_16x16x32_bf16 v[114:117], v[156:159], v[198:201], v[114:117]
	v_mfma_f32_16x16x32_bf16 v[106:109], v[164:167], v[198:201], v[106:109]
	v_mfma_f32_16x16x32_bf16 v[98:101], v[156:159], v[206:209], v[98:101]
	v_mfma_f32_16x16x32_bf16 v[90:93], v[164:167], v[206:209], v[90:93]
	v_mfma_f32_16x16x32_bf16 v[82:85], v[156:159], v[214:217], v[82:85]
	v_mfma_f32_16x16x32_bf16 v[74:77], v[164:167], v[214:217], v[74:77]
	v_mfma_f32_16x16x32_bf16 v[118:121], v[168:171], v[186:189], 0
	v_mfma_f32_16x16x32_bf16 v[110:113], v[178:181], v[186:189], 0
	v_mfma_f32_16x16x32_bf16 v[102:105], v[168:171], v[194:197], 0
	v_mfma_f32_16x16x32_bf16 v[94:97], v[178:181], v[194:197], 0
	v_mfma_f32_16x16x32_bf16 v[86:89], v[168:171], v[202:205], 0
	v_mfma_f32_16x16x32_bf16 v[78:81], v[178:181], v[202:205], 0
	v_mfma_f32_16x16x32_bf16 v[70:73], v[168:171], v[210:213], 0
	v_mfma_f32_16x16x32_bf16 v[66:69], v[178:181], v[210:213], 0
	v_mfma_f32_16x16x32_bf16 v[118:121], v[172:175], v[190:193], v[118:121]
	v_mfma_f32_16x16x32_bf16 v[110:113], v[182:185], v[190:193], v[110:113]
	v_mfma_f32_16x16x32_bf16 v[102:105], v[172:175], v[198:201], v[102:105]
	v_mfma_f32_16x16x32_bf16 v[94:97], v[182:185], v[198:201], v[94:97]
	v_mfma_f32_16x16x32_bf16 v[86:89], v[172:175], v[206:209], v[86:89]
	v_mfma_f32_16x16x32_bf16 v[78:81], v[182:185], v[206:209], v[78:81]
	v_mfma_f32_16x16x32_bf16 v[70:73], v[172:175], v[214:217], v[70:73]
	s_setprio 0
	v_mfma_f32_16x16x32_bf16 v[66:69], v[182:185], v[214:217], v[66:69]
	s_barrier
	s_add_i32 s51, s38, s28
	v_lshl_add_u64 v[144:145], s[22:23], 0, v[132:133]
	s_mov_b32 m0, s51
	ds_read_b128 v[186:189], v151 offset:16384
	ds_read_b128 v[190:193], v151 offset:17408
	ds_read_b128 v[194:197], v151 offset:18432
	ds_read_b128 v[198:201], v151 offset:19456
	ds_read_b128 v[202:205], v151 offset:20480
	ds_read_b128 v[206:209], v151 offset:21504
	ds_read_b128 v[210:213], v151 offset:22528
	ds_read_b128 v[214:217], v151 offset:23552
	global_load_lds_dwordx4 v[144:145], off
	s_add_i32 m0, s51, 0x2000
	s_add_u32 s52, s22, 0x4000
	v_lshl_add_u64 v[144:145], s[22:23], 0, v[136:137]
	s_addc_u32 s53, s23, 0
	s_add_i32 s51, s39, s28
	global_load_lds_dwordx4 v[144:145], off
	v_lshl_add_u64 v[144:145], s[52:53], 0, v[132:133]
	s_mov_b32 m0, s51
	s_nop 0
	global_load_lds_dwordx4 v[144:145], off
	v_lshl_add_u64 v[144:145], s[52:53], 0, v[136:137]
	s_add_i32 m0, s51, 0x2000
	s_nop 0
	global_load_lds_dwordx4 v[144:145], off
	v_lshl_add_u64 v[144:145], s[2:3], 0, v[130:131]
	s_mov_b32 m0, s29
	s_nop 0
	global_load_lds_dwordx4 v[144:145], off
	v_lshl_add_u64 v[144:145], s[2:3], 0, v[134:135]
	s_mov_b32 m0, s30
	s_nop 0
	global_load_lds_dwordx4 v[144:145], off
	s_waitcnt vmcnt(8)
	s_waitcnt lgkmcnt(0)
	s_setprio 1
	s_barrier
	v_mfma_f32_16x16x32_bf16 v[62:65], v[152:155], v[186:189], 0
	v_mfma_f32_16x16x32_bf16 v[58:61], v[160:163], v[186:189], 0
	v_mfma_f32_16x16x32_bf16 v[50:53], v[152:155], v[194:197], 0
	v_mfma_f32_16x16x32_bf16 v[42:45], v[160:163], v[194:197], 0
	v_mfma_f32_16x16x32_bf16 v[34:37], v[152:155], v[202:205], 0
	v_mfma_f32_16x16x32_bf16 v[26:29], v[160:163], v[202:205], 0
	v_mfma_f32_16x16x32_bf16 v[18:21], v[152:155], v[210:213], 0
	v_mfma_f32_16x16x32_bf16 v[10:13], v[160:163], v[210:213], 0
	v_mfma_f32_16x16x32_bf16 v[62:65], v[156:159], v[190:193], v[62:65]
	v_mfma_f32_16x16x32_bf16 v[58:61], v[164:167], v[190:193], v[58:61]
	v_mfma_f32_16x16x32_bf16 v[50:53], v[156:159], v[198:201], v[50:53]
	v_mfma_f32_16x16x32_bf16 v[42:45], v[164:167], v[198:201], v[42:45]
	v_mfma_f32_16x16x32_bf16 v[34:37], v[156:159], v[206:209], v[34:37]
	v_mfma_f32_16x16x32_bf16 v[26:29], v[164:167], v[206:209], v[26:29]
	v_mfma_f32_16x16x32_bf16 v[18:21], v[156:159], v[214:217], v[18:21]
	v_mfma_f32_16x16x32_bf16 v[10:13], v[164:167], v[214:217], v[10:13]
	v_mfma_f32_16x16x32_bf16 v[54:57], v[168:171], v[186:189], 0
	v_mfma_f32_16x16x32_bf16 v[46:49], v[178:181], v[186:189], 0
	v_mfma_f32_16x16x32_bf16 v[38:41], v[168:171], v[194:197], 0
	v_mfma_f32_16x16x32_bf16 v[30:33], v[178:181], v[194:197], 0
	v_mfma_f32_16x16x32_bf16 v[22:25], v[168:171], v[202:205], 0
	v_mfma_f32_16x16x32_bf16 v[14:17], v[178:181], v[202:205], 0
	v_mfma_f32_16x16x32_bf16 v[6:9], v[168:171], v[210:213], 0
	v_mfma_f32_16x16x32_bf16 v[2:5], v[178:181], v[210:213], 0
	v_mfma_f32_16x16x32_bf16 v[54:57], v[172:175], v[190:193], v[54:57]
	v_mfma_f32_16x16x32_bf16 v[46:49], v[182:185], v[190:193], v[46:49]
	v_mfma_f32_16x16x32_bf16 v[38:41], v[172:175], v[198:201], v[38:41]
	v_mfma_f32_16x16x32_bf16 v[30:33], v[182:185], v[198:201], v[30:33]
	v_mfma_f32_16x16x32_bf16 v[22:25], v[172:175], v[206:209], v[22:25]
	v_mfma_f32_16x16x32_bf16 v[14:17], v[182:185], v[206:209], v[14:17]
	v_mfma_f32_16x16x32_bf16 v[6:9], v[172:175], v[214:217], v[6:9]
	s_setprio 0
	v_mfma_f32_16x16x32_bf16 v[2:5], v[182:185], v[214:217], v[2:5]
	s_barrier
	s_add_i32 s51, 0, 0x18000
	v_add_u32_e32 v144, s51, v147
	s_add_i32 s52, 0, 0x1c000
	ds_read_b128 v[152:155], v144
	ds_read_b128 v[156:159], v144 offset:1024
	ds_read_b128 v[160:163], v144 offset:2048
	ds_read_b128 v[164:167], v144 offset:3072
	v_add_u32_e32 v144, s52, v147
	ds_read_b128 v[168:171], v144
	ds_read_b128 v[172:175], v144 offset:1024
	ds_read_b128 v[178:181], v144 offset:2048
	ds_read_b128 v[182:185], v144 offset:3072
	s_add_u32 s2, s2, 0x4000
	s_addc_u32 s3, s3, 0
	s_mov_b32 m0, s31
	v_lshl_add_u64 v[144:145], s[2:3], 0, v[130:131]
	ds_read_b128 v[186:189], v151 offset:32768
	ds_read_b128 v[190:193], v151 offset:33792
	ds_read_b128 v[194:197], v151 offset:34816
	ds_read_b128 v[198:201], v151 offset:35840
	ds_read_b128 v[202:205], v151 offset:36864
	ds_read_b128 v[206:209], v151 offset:37888
	ds_read_b128 v[210:213], v151 offset:38912
	ds_read_b128 v[214:217], v151 offset:39936
	global_load_lds_dwordx4 v[144:145], off
	v_lshl_add_u64 v[144:145], s[2:3], 0, v[134:135]
	s_mov_b32 m0, s34
	s_nop 0
	global_load_lds_dwordx4 v[144:145], off
	s_waitcnt vmcnt(8)
	s_waitcnt lgkmcnt(0)
	s_setprio 1
	s_barrier
	v_mfma_f32_16x16x32_bf16 v[126:129], v[152:155], v[186:189], v[126:129]
	v_mfma_f32_16x16x32_bf16 v[122:125], v[160:163], v[186:189], v[122:125]
	v_mfma_f32_16x16x32_bf16 v[114:117], v[152:155], v[194:197], v[114:117]
	v_mfma_f32_16x16x32_bf16 v[106:109], v[160:163], v[194:197], v[106:109]
	v_mfma_f32_16x16x32_bf16 v[98:101], v[152:155], v[202:205], v[98:101]
	v_mfma_f32_16x16x32_bf16 v[90:93], v[160:163], v[202:205], v[90:93]
	v_mfma_f32_16x16x32_bf16 v[82:85], v[152:155], v[210:213], v[82:85]
	v_mfma_f32_16x16x32_bf16 v[74:77], v[160:163], v[210:213], v[74:77]
	v_mfma_f32_16x16x32_bf16 v[126:129], v[156:159], v[190:193], v[126:129]
	v_mfma_f32_16x16x32_bf16 v[122:125], v[164:167], v[190:193], v[122:125]
	v_mfma_f32_16x16x32_bf16 v[114:117], v[156:159], v[198:201], v[114:117]
	v_mfma_f32_16x16x32_bf16 v[106:109], v[164:167], v[198:201], v[106:109]
	v_mfma_f32_16x16x32_bf16 v[98:101], v[156:159], v[206:209], v[98:101]
	v_mfma_f32_16x16x32_bf16 v[90:93], v[164:167], v[206:209], v[90:93]
	v_mfma_f32_16x16x32_bf16 v[82:85], v[156:159], v[214:217], v[82:85]
	v_mfma_f32_16x16x32_bf16 v[74:77], v[164:167], v[214:217], v[74:77]
	v_mfma_f32_16x16x32_bf16 v[118:121], v[168:171], v[186:189], v[118:121]
	v_mfma_f32_16x16x32_bf16 v[110:113], v[178:181], v[186:189], v[110:113]
	v_mfma_f32_16x16x32_bf16 v[102:105], v[168:171], v[194:197], v[102:105]
	v_mfma_f32_16x16x32_bf16 v[94:97], v[178:181], v[194:197], v[94:97]
	v_mfma_f32_16x16x32_bf16 v[86:89], v[168:171], v[202:205], v[86:89]
	v_mfma_f32_16x16x32_bf16 v[78:81], v[178:181], v[202:205], v[78:81]
	v_mfma_f32_16x16x32_bf16 v[70:73], v[168:171], v[210:213], v[70:73]
	v_mfma_f32_16x16x32_bf16 v[66:69], v[178:181], v[210:213], v[66:69]
	v_mfma_f32_16x16x32_bf16 v[118:121], v[172:175], v[190:193], v[118:121]
	v_mfma_f32_16x16x32_bf16 v[110:113], v[182:185], v[190:193], v[110:113]
	v_mfma_f32_16x16x32_bf16 v[102:105], v[172:175], v[198:201], v[102:105]
	v_mfma_f32_16x16x32_bf16 v[94:97], v[182:185], v[198:201], v[94:97]
	v_mfma_f32_16x16x32_bf16 v[86:89], v[172:175], v[206:209], v[86:89]
	v_mfma_f32_16x16x32_bf16 v[78:81], v[182:185], v[206:209], v[78:81]
	v_mfma_f32_16x16x32_bf16 v[70:73], v[172:175], v[214:217], v[70:73]
	s_setprio 0
	v_mfma_f32_16x16x32_bf16 v[66:69], v[182:185], v[214:217], v[66:69]
	s_barrier
	s_add_u32 s2, s22, 0x8000
	s_addc_u32 s3, s23, 0
	s_add_i32 s51, s51, s28
	v_lshl_add_u64 v[144:145], s[2:3], 0, v[132:133]
	s_mov_b32 m0, s51
	ds_read_b128 v[186:189], v151 offset:49152
	ds_read_b128 v[190:193], v151 offset:50176
	ds_read_b128 v[194:197], v151 offset:51200
	ds_read_b128 v[198:201], v151 offset:52224
	ds_read_b128 v[202:205], v151 offset:53248
	ds_read_b128 v[206:209], v151 offset:54272
	ds_read_b128 v[210:213], v151 offset:55296
	ds_read_b128 v[214:217], v151 offset:56320
	global_load_lds_dwordx4 v[144:145], off
	s_add_i32 m0, s51, 0x2000
	v_lshl_add_u64 v[144:145], s[2:3], 0, v[136:137]
	s_add_u32 s2, s22, 0xc000
	s_addc_u32 s3, s23, 0
	s_add_i32 s22, s52, s28
	global_load_lds_dwordx4 v[144:145], off
	v_lshl_add_u64 v[144:145], s[2:3], 0, v[132:133]
	s_mov_b32 m0, s22
	s_nop 0
	global_load_lds_dwordx4 v[144:145], off
	v_lshl_add_u64 v[144:145], s[2:3], 0, v[136:137]
	s_add_i32 m0, s22, 0x2000
	s_nop 0
	global_load_lds_dwordx4 v[144:145], off
	v_lshl_add_u64 v[144:145], s[20:21], 0, v[130:131]
	s_mov_b32 m0, s36
	s_nop 0
	global_load_lds_dwordx4 v[144:145], off
	v_lshl_add_u64 v[144:145], s[20:21], 0, v[134:135]
	s_mov_b32 m0, s37
	s_nop 0
	global_load_lds_dwordx4 v[144:145], off
	s_waitcnt vmcnt(8)
	s_waitcnt lgkmcnt(0)
	s_setprio 1
	s_barrier
	v_mfma_f32_16x16x32_bf16 v[62:65], v[152:155], v[186:189], v[62:65]
	v_mfma_f32_16x16x32_bf16 v[58:61], v[160:163], v[186:189], v[58:61]
	v_mfma_f32_16x16x32_bf16 v[50:53], v[152:155], v[194:197], v[50:53]
	v_mfma_f32_16x16x32_bf16 v[42:45], v[160:163], v[194:197], v[42:45]
	v_mfma_f32_16x16x32_bf16 v[34:37], v[152:155], v[202:205], v[34:37]
	v_mfma_f32_16x16x32_bf16 v[26:29], v[160:163], v[202:205], v[26:29]
	v_mfma_f32_16x16x32_bf16 v[18:21], v[152:155], v[210:213], v[18:21]
	v_mfma_f32_16x16x32_bf16 v[10:13], v[160:163], v[210:213], v[10:13]
	v_mfma_f32_16x16x32_bf16 v[62:65], v[156:159], v[190:193], v[62:65]
	v_mfma_f32_16x16x32_bf16 v[58:61], v[164:167], v[190:193], v[58:61]
	v_mfma_f32_16x16x32_bf16 v[50:53], v[156:159], v[198:201], v[50:53]
	v_mfma_f32_16x16x32_bf16 v[42:45], v[164:167], v[198:201], v[42:45]
	v_mfma_f32_16x16x32_bf16 v[34:37], v[156:159], v[206:209], v[34:37]
	v_mfma_f32_16x16x32_bf16 v[26:29], v[164:167], v[206:209], v[26:29]
	v_mfma_f32_16x16x32_bf16 v[18:21], v[156:159], v[214:217], v[18:21]
	v_mfma_f32_16x16x32_bf16 v[10:13], v[164:167], v[214:217], v[10:13]
	v_mfma_f32_16x16x32_bf16 v[54:57], v[168:171], v[186:189], v[54:57]
	v_mfma_f32_16x16x32_bf16 v[46:49], v[178:181], v[186:189], v[46:49]
	v_mfma_f32_16x16x32_bf16 v[38:41], v[168:171], v[194:197], v[38:41]
	v_mfma_f32_16x16x32_bf16 v[30:33], v[178:181], v[194:197], v[30:33]
	v_mfma_f32_16x16x32_bf16 v[22:25], v[168:171], v[202:205], v[22:25]
	v_mfma_f32_16x16x32_bf16 v[14:17], v[178:181], v[202:205], v[14:17]
	v_mfma_f32_16x16x32_bf16 v[6:9], v[168:171], v[210:213], v[6:9]
	v_mfma_f32_16x16x32_bf16 v[2:5], v[178:181], v[210:213], v[2:5]
	v_mfma_f32_16x16x32_bf16 v[54:57], v[172:175], v[190:193], v[54:57]
	v_mfma_f32_16x16x32_bf16 v[46:49], v[182:185], v[190:193], v[46:49]
	v_mfma_f32_16x16x32_bf16 v[38:41], v[172:175], v[198:201], v[38:41]
	v_mfma_f32_16x16x32_bf16 v[30:33], v[182:185], v[198:201], v[30:33]
	v_mfma_f32_16x16x32_bf16 v[22:25], v[172:175], v[206:209], v[22:25]
	v_mfma_f32_16x16x32_bf16 v[14:17], v[182:185], v[206:209], v[14:17]
	v_mfma_f32_16x16x32_bf16 v[6:9], v[172:175], v[214:217], v[6:9]
	s_setprio 0
	v_mfma_f32_16x16x32_bf16 v[2:5], v[182:185], v[214:217], v[2:5]
	s_barrier
	s_add_i32 s50, s50, 2
	s_add_u32 s18, s18, 0x10000
	s_addc_u32 s19, s19, 0
	s_add_u32 s48, s48, 0x10000
	s_addc_u32 s49, s49, 0
	s_cmp_gt_u32 s50, 41
	s_cbranch_scc0 .LBB0_495
	s_branch .Lpk495_exit
.LBB0_495:
	ds_read_b128 v[152:155], v149
	ds_read_b128 v[156:159], v149 offset:1024
	ds_read_b128 v[160:163], v149 offset:2048
	ds_read_b128 v[164:167], v149 offset:3072
	ds_read_b128 v[168:171], v150
	ds_read_b128 v[172:175], v150 offset:1024
	ds_read_b128 v[178:181], v150 offset:2048
	ds_read_b128 v[182:185], v150 offset:3072
	s_add_u32 s2, s18, 0x4000
	s_addc_u32 s3, s19, 0
	s_cmp_eq_u32 s50, 40
	s_cselect_b32 s2, s45, s2
	s_cselect_b32 s3, s44, s3
	s_cselect_b32 s23, s46, s49
	s_cselect_b32 s22, s47, s48
	s_add_u32 s20, s2, 0x8000
	s_addc_u32 s21, s3, 0
	v_lshl_add_u64 v[144:145], s[18:19], 0, v[138:139]
	s_add_i32 m0, s29, 0xc000
	ds_read_b128 v[186:189], v151
	ds_read_b128 v[190:193], v151 offset:1024
	ds_read_b128 v[194:197], v151 offset:2048
	ds_read_b128 v[198:201], v151 offset:3072
	ds_read_b128 v[202:205], v151 offset:4096
	ds_read_b128 v[206:209], v151 offset:5120
	ds_read_b128 v[210:213], v151 offset:6144
	ds_read_b128 v[214:217], v151 offset:7168
	global_load_lds_dwordx4 v[144:145], off
	v_lshl_add_u64 v[144:145], s[18:19], 0, v[140:141]
	s_add_i32 m0, s29, 0xe000
	s_nop 0
	global_load_lds_dwordx4 v[144:145], off
	s_waitcnt vmcnt(8)
	s_waitcnt lgkmcnt(0)
	s_setprio 1
	s_barrier
	v_mfma_f32_16x16x32_bf16 v[126:129], v[152:155], v[186:189], v[126:129]
	v_mfma_f32_16x16x32_bf16 v[122:125], v[160:163], v[186:189], v[122:125]
	v_mfma_f32_16x16x32_bf16 v[114:117], v[152:155], v[194:197], v[114:117]
	v_mfma_f32_16x16x32_bf16 v[106:109], v[160:163], v[194:197], v[106:109]
	v_mfma_f32_16x16x32_bf16 v[98:101], v[152:155], v[202:205], v[98:101]
	v_mfma_f32_16x16x32_bf16 v[90:93], v[160:163], v[202:205], v[90:93]
	v_mfma_f32_16x16x32_bf16 v[82:85], v[152:155], v[210:213], v[82:85]
	v_mfma_f32_16x16x32_bf16 v[74:77], v[160:163], v[210:213], v[74:77]
	v_mfma_f32_16x16x32_bf16 v[126:129], v[156:159], v[190:193], v[126:129]
	v_mfma_f32_16x16x32_bf16 v[122:125], v[164:167], v[190:193], v[122:125]
	v_mfma_f32_16x16x32_bf16 v[114:117], v[156:159], v[198:201], v[114:117]
	v_mfma_f32_16x16x32_bf16 v[106:109], v[164:167], v[198:201], v[106:109]
	v_mfma_f32_16x16x32_bf16 v[98:101], v[156:159], v[206:209], v[98:101]
	v_mfma_f32_16x16x32_bf16 v[90:93], v[164:167], v[206:209], v[90:93]
	v_mfma_f32_16x16x32_bf16 v[82:85], v[156:159], v[214:217], v[82:85]
	v_mfma_f32_16x16x32_bf16 v[74:77], v[164:167], v[214:217], v[74:77]
	v_mfma_f32_16x16x32_bf16 v[118:121], v[168:171], v[186:189], v[118:121]
	v_mfma_f32_16x16x32_bf16 v[110:113], v[178:181], v[186:189], v[110:113]
	v_mfma_f32_16x16x32_bf16 v[102:105], v[168:171], v[194:197], v[102:105]
	v_mfma_f32_16x16x32_bf16 v[94:97], v[178:181], v[194:197], v[94:97]
	v_mfma_f32_16x16x32_bf16 v[86:89], v[168:171], v[202:205], v[86:89]
	v_mfma_f32_16x16x32_bf16 v[78:81], v[178:181], v[202:205], v[78:81]
	v_mfma_f32_16x16x32_bf16 v[70:73], v[168:171], v[210:213], v[70:73]
	v_mfma_f32_16x16x32_bf16 v[66:69], v[178:181], v[210:213], v[66:69]
	v_mfma_f32_16x16x32_bf16 v[118:121], v[172:175], v[190:193], v[118:121]
	v_mfma_f32_16x16x32_bf16 v[110:113], v[182:185], v[190:193], v[110:113]
	v_mfma_f32_16x16x32_bf16 v[102:105], v[172:175], v[198:201], v[102:105]
	v_mfma_f32_16x16x32_bf16 v[94:97], v[182:185], v[198:201], v[94:97]
	v_mfma_f32_16x16x32_bf16 v[86:89], v[172:175], v[206:209], v[86:89]
	v_mfma_f32_16x16x32_bf16 v[78:81], v[182:185], v[206:209], v[78:81]
	v_mfma_f32_16x16x32_bf16 v[70:73], v[172:175], v[214:217], v[70:73]
	s_setprio 0
	v_mfma_f32_16x16x32_bf16 v[66:69], v[182:185], v[214:217], v[66:69]
	s_barrier
	s_add_i32 s51, s38, s28
	v_lshl_add_u64 v[144:145], s[22:23], 0, v[132:133]
	s_mov_b32 m0, s51
	ds_read_b128 v[186:189], v151 offset:16384
	ds_read_b128 v[190:193], v151 offset:17408
	ds_read_b128 v[194:197], v151 offset:18432
	ds_read_b128 v[198:201], v151 offset:19456
	ds_read_b128 v[202:205], v151 offset:20480
	ds_read_b128 v[206:209], v151 offset:21504
	ds_read_b128 v[210:213], v151 offset:22528
	ds_read_b128 v[214:217], v151 offset:23552
	global_load_lds_dwordx4 v[144:145], off
	s_add_i32 m0, s51, 0x2000
	s_add_u32 s52, s22, 0x4000
	v_lshl_add_u64 v[144:145], s[22:23], 0, v[136:137]
	s_addc_u32 s53, s23, 0
	s_add_i32 s51, s39, s28
	global_load_lds_dwordx4 v[144:145], off
	v_lshl_add_u64 v[144:145], s[52:53], 0, v[132:133]
	s_mov_b32 m0, s51
	s_nop 0
	global_load_lds_dwordx4 v[144:145], off
	v_lshl_add_u64 v[144:145], s[52:53], 0, v[136:137]
	s_add_i32 m0, s51, 0x2000
	s_nop 0
	global_load_lds_dwordx4 v[144:145], off
	v_lshl_add_u64 v[144:145], s[2:3], 0, v[130:131]
	s_mov_b32 m0, s29
	s_nop 0
	global_load_lds_dwordx4 v[144:145], off
	v_lshl_add_u64 v[144:145], s[2:3], 0, v[134:135]
	s_mov_b32 m0, s30
	s_nop 0
	global_load_lds_dwordx4 v[144:145], off
	s_waitcnt vmcnt(8)
	s_waitcnt lgkmcnt(0)
	s_setprio 1
	s_barrier
	v_mfma_f32_16x16x32_bf16 v[62:65], v[152:155], v[186:189], v[62:65]
	v_mfma_f32_16x16x32_bf16 v[58:61], v[160:163], v[186:189], v[58:61]
	v_mfma_f32_16x16x32_bf16 v[50:53], v[152:155], v[194:197], v[50:53]
	v_mfma_f32_16x16x32_bf16 v[42:45], v[160:163], v[194:197], v[42:45]
	v_mfma_f32_16x16x32_bf16 v[34:37], v[152:155], v[202:205], v[34:37]
	v_mfma_f32_16x16x32_bf16 v[26:29], v[160:163], v[202:205], v[26:29]
	v_mfma_f32_16x16x32_bf16 v[18:21], v[152:155], v[210:213], v[18:21]
	v_mfma_f32_16x16x32_bf16 v[10:13], v[160:163], v[210:213], v[10:13]
	v_mfma_f32_16x16x32_bf16 v[62:65], v[156:159], v[190:193], v[62:65]
	v_mfma_f32_16x16x32_bf16 v[58:61], v[164:167], v[190:193], v[58:61]
	v_mfma_f32_16x16x32_bf16 v[50:53], v[156:159], v[198:201], v[50:53]
	v_mfma_f32_16x16x32_bf16 v[42:45], v[164:167], v[198:201], v[42:45]
	v_mfma_f32_16x16x32_bf16 v[34:37], v[156:159], v[206:209], v[34:37]
	v_mfma_f32_16x16x32_bf16 v[26:29], v[164:167], v[206:209], v[26:29]
	v_mfma_f32_16x16x32_bf16 v[18:21], v[156:159], v[214:217], v[18:21]
	v_mfma_f32_16x16x32_bf16 v[10:13], v[164:167], v[214:217], v[10:13]
	v_mfma_f32_16x16x32_bf16 v[54:57], v[168:171], v[186:189], v[54:57]
	v_mfma_f32_16x16x32_bf16 v[46:49], v[178:181], v[186:189], v[46:49]
	v_mfma_f32_16x16x32_bf16 v[38:41], v[168:171], v[194:197], v[38:41]
	v_mfma_f32_16x16x32_bf16 v[30:33], v[178:181], v[194:197], v[30:33]
	v_mfma_f32_16x16x32_bf16 v[22:25], v[168:171], v[202:205], v[22:25]
	v_mfma_f32_16x16x32_bf16 v[14:17], v[178:181], v[202:205], v[14:17]
	v_mfma_f32_16x16x32_bf16 v[6:9], v[168:171], v[210:213], v[6:9]
	v_mfma_f32_16x16x32_bf16 v[2:5], v[178:181], v[210:213], v[2:5]
	v_mfma_f32_16x16x32_bf16 v[54:57], v[172:175], v[190:193], v[54:57]
	v_mfma_f32_16x16x32_bf16 v[46:49], v[182:185], v[190:193], v[46:49]
	v_mfma_f32_16x16x32_bf16 v[38:41], v[172:175], v[198:201], v[38:41]
	v_mfma_f32_16x16x32_bf16 v[30:33], v[182:185], v[198:201], v[30:33]
	v_mfma_f32_16x16x32_bf16 v[22:25], v[172:175], v[206:209], v[22:25]
	v_mfma_f32_16x16x32_bf16 v[14:17], v[182:185], v[206:209], v[14:17]
	v_mfma_f32_16x16x32_bf16 v[6:9], v[172:175], v[214:217], v[6:9]
	s_setprio 0
	v_mfma_f32_16x16x32_bf16 v[2:5], v[182:185], v[214:217], v[2:5]
	s_barrier
	s_add_i32 s51, 0, 0x18000
	v_add_u32_e32 v144, s51, v147
	s_add_i32 s52, 0, 0x1c000
	ds_read_b128 v[152:155], v144
	ds_read_b128 v[156:159], v144 offset:1024
	ds_read_b128 v[160:163], v144 offset:2048
	ds_read_b128 v[164:167], v144 offset:3072
	v_add_u32_e32 v144, s52, v147
	ds_read_b128 v[168:171], v144
	ds_read_b128 v[172:175], v144 offset:1024
	ds_read_b128 v[178:181], v144 offset:2048
	ds_read_b128 v[182:185], v144 offset:3072
	s_add_u32 s2, s2, 0x4000
	s_addc_u32 s3, s3, 0
	s_mov_b32 m0, s31
	v_lshl_add_u64 v[144:145], s[2:3], 0, v[130:131]
	ds_read_b128 v[186:189], v151 offset:32768
	ds_read_b128 v[190:193], v151 offset:33792
	ds_read_b128 v[194:197], v151 offset:34816
	ds_read_b128 v[198:201], v151 offset:35840
	ds_read_b128 v[202:205], v151 offset:36864
	ds_read_b128 v[206:209], v151 offset:37888
	ds_read_b128 v[210:213], v151 offset:38912
	ds_read_b128 v[214:217], v151 offset:39936
	global_load_lds_dwordx4 v[144:145], off
	v_lshl_add_u64 v[144:145], s[2:3], 0, v[134:135]
	s_mov_b32 m0, s34
	s_nop 0
	global_load_lds_dwordx4 v[144:145], off
	s_waitcnt vmcnt(8)
	s_waitcnt lgkmcnt(0)
	s_setprio 1
	s_barrier
	v_mfma_f32_16x16x32_bf16 v[126:129], v[152:155], v[186:189], v[126:129]
	v_mfma_f32_16x16x32_bf16 v[122:125], v[160:163], v[186:189], v[122:125]
	v_mfma_f32_16x16x32_bf16 v[114:117], v[152:155], v[194:197], v[114:117]
	v_mfma_f32_16x16x32_bf16 v[106:109], v[160:163], v[194:197], v[106:109]
	v_mfma_f32_16x16x32_bf16 v[98:101], v[152:155], v[202:205], v[98:101]
	v_mfma_f32_16x16x32_bf16 v[90:93], v[160:163], v[202:205], v[90:93]
	v_mfma_f32_16x16x32_bf16 v[82:85], v[152:155], v[210:213], v[82:85]
	v_mfma_f32_16x16x32_bf16 v[74:77], v[160:163], v[210:213], v[74:77]
	v_mfma_f32_16x16x32_bf16 v[126:129], v[156:159], v[190:193], v[126:129]
	v_mfma_f32_16x16x32_bf16 v[122:125], v[164:167], v[190:193], v[122:125]
	v_mfma_f32_16x16x32_bf16 v[114:117], v[156:159], v[198:201], v[114:117]
	v_mfma_f32_16x16x32_bf16 v[106:109], v[164:167], v[198:201], v[106:109]
	v_mfma_f32_16x16x32_bf16 v[98:101], v[156:159], v[206:209], v[98:101]
	v_mfma_f32_16x16x32_bf16 v[90:93], v[164:167], v[206:209], v[90:93]
	v_mfma_f32_16x16x32_bf16 v[82:85], v[156:159], v[214:217], v[82:85]
	v_mfma_f32_16x16x32_bf16 v[74:77], v[164:167], v[214:217], v[74:77]
	v_mfma_f32_16x16x32_bf16 v[118:121], v[168:171], v[186:189], v[118:121]
	v_mfma_f32_16x16x32_bf16 v[110:113], v[178:181], v[186:189], v[110:113]
	v_mfma_f32_16x16x32_bf16 v[102:105], v[168:171], v[194:197], v[102:105]
	v_mfma_f32_16x16x32_bf16 v[94:97], v[178:181], v[194:197], v[94:97]
	v_mfma_f32_16x16x32_bf16 v[86:89], v[168:171], v[202:205], v[86:89]
	v_mfma_f32_16x16x32_bf16 v[78:81], v[178:181], v[202:205], v[78:81]
	v_mfma_f32_16x16x32_bf16 v[70:73], v[168:171], v[210:213], v[70:73]
	v_mfma_f32_16x16x32_bf16 v[66:69], v[178:181], v[210:213], v[66:69]
	v_mfma_f32_16x16x32_bf16 v[118:121], v[172:175], v[190:193], v[118:121]
	v_mfma_f32_16x16x32_bf16 v[110:113], v[182:185], v[190:193], v[110:113]
	v_mfma_f32_16x16x32_bf16 v[102:105], v[172:175], v[198:201], v[102:105]
	v_mfma_f32_16x16x32_bf16 v[94:97], v[182:185], v[198:201], v[94:97]
	v_mfma_f32_16x16x32_bf16 v[86:89], v[172:175], v[206:209], v[86:89]
	v_mfma_f32_16x16x32_bf16 v[78:81], v[182:185], v[206:209], v[78:81]
	v_mfma_f32_16x16x32_bf16 v[70:73], v[172:175], v[214:217], v[70:73]
	s_setprio 0
	v_mfma_f32_16x16x32_bf16 v[66:69], v[182:185], v[214:217], v[66:69]
	s_barrier
	s_add_u32 s2, s22, 0x8000
	s_addc_u32 s3, s23, 0
	s_add_i32 s51, s51, s28
	v_lshl_add_u64 v[144:145], s[2:3], 0, v[132:133]
	s_mov_b32 m0, s51
	ds_read_b128 v[186:189], v151 offset:49152
	ds_read_b128 v[190:193], v151 offset:50176
	ds_read_b128 v[194:197], v151 offset:51200
	ds_read_b128 v[198:201], v151 offset:52224
	ds_read_b128 v[202:205], v151 offset:53248
	ds_read_b128 v[206:209], v151 offset:54272
	ds_read_b128 v[210:213], v151 offset:55296
	ds_read_b128 v[214:217], v151 offset:56320
	global_load_lds_dwordx4 v[144:145], off
	s_add_i32 m0, s51, 0x2000
	v_lshl_add_u64 v[144:145], s[2:3], 0, v[136:137]
	s_add_u32 s2, s22, 0xc000
	s_addc_u32 s3, s23, 0
	s_add_i32 s22, s52, s28
	global_load_lds_dwordx4 v[144:145], off
	v_lshl_add_u64 v[144:145], s[2:3], 0, v[132:133]
	s_mov_b32 m0, s22
	s_nop 0
	global_load_lds_dwordx4 v[144:145], off
	v_lshl_add_u64 v[144:145], s[2:3], 0, v[136:137]
	s_add_i32 m0, s22, 0x2000
	s_nop 0
	global_load_lds_dwordx4 v[144:145], off
	v_lshl_add_u64 v[144:145], s[20:21], 0, v[130:131]
	s_mov_b32 m0, s36
	s_nop 0
	global_load_lds_dwordx4 v[144:145], off
	v_lshl_add_u64 v[144:145], s[20:21], 0, v[134:135]
	s_mov_b32 m0, s37
	s_nop 0
	global_load_lds_dwordx4 v[144:145], off
	s_waitcnt vmcnt(8)
	s_waitcnt lgkmcnt(0)
	s_setprio 1
	s_barrier
	v_mfma_f32_16x16x32_bf16 v[62:65], v[152:155], v[186:189], v[62:65]
	v_mfma_f32_16x16x32_bf16 v[58:61], v[160:163], v[186:189], v[58:61]
	v_mfma_f32_16x16x32_bf16 v[50:53], v[152:155], v[194:197], v[50:53]
	v_mfma_f32_16x16x32_bf16 v[42:45], v[160:163], v[194:197], v[42:45]
	v_mfma_f32_16x16x32_bf16 v[34:37], v[152:155], v[202:205], v[34:37]
	v_mfma_f32_16x16x32_bf16 v[26:29], v[160:163], v[202:205], v[26:29]
	v_mfma_f32_16x16x32_bf16 v[18:21], v[152:155], v[210:213], v[18:21]
	v_mfma_f32_16x16x32_bf16 v[10:13], v[160:163], v[210:213], v[10:13]
	v_mfma_f32_16x16x32_bf16 v[62:65], v[156:159], v[190:193], v[62:65]
	v_mfma_f32_16x16x32_bf16 v[58:61], v[164:167], v[190:193], v[58:61]
	v_mfma_f32_16x16x32_bf16 v[50:53], v[156:159], v[198:201], v[50:53]
	v_mfma_f32_16x16x32_bf16 v[42:45], v[164:167], v[198:201], v[42:45]
	v_mfma_f32_16x16x32_bf16 v[34:37], v[156:159], v[206:209], v[34:37]
	v_mfma_f32_16x16x32_bf16 v[26:29], v[164:167], v[206:209], v[26:29]
	v_mfma_f32_16x16x32_bf16 v[18:21], v[156:159], v[214:217], v[18:21]
	v_mfma_f32_16x16x32_bf16 v[10:13], v[164:167], v[214:217], v[10:13]
	v_mfma_f32_16x16x32_bf16 v[54:57], v[168:171], v[186:189], v[54:57]
	v_mfma_f32_16x16x32_bf16 v[46:49], v[178:181], v[186:189], v[46:49]
	v_mfma_f32_16x16x32_bf16 v[38:41], v[168:171], v[194:197], v[38:41]
	v_mfma_f32_16x16x32_bf16 v[30:33], v[178:181], v[194:197], v[30:33]
	v_mfma_f32_16x16x32_bf16 v[22:25], v[168:171], v[202:205], v[22:25]
	v_mfma_f32_16x16x32_bf16 v[14:17], v[178:181], v[202:205], v[14:17]
	v_mfma_f32_16x16x32_bf16 v[6:9], v[168:171], v[210:213], v[6:9]
	v_mfma_f32_16x16x32_bf16 v[2:5], v[178:181], v[210:213], v[2:5]
	v_mfma_f32_16x16x32_bf16 v[54:57], v[172:175], v[190:193], v[54:57]
	v_mfma_f32_16x16x32_bf16 v[46:49], v[182:185], v[190:193], v[46:49]
	v_mfma_f32_16x16x32_bf16 v[38:41], v[172:175], v[198:201], v[38:41]
	v_mfma_f32_16x16x32_bf16 v[30:33], v[182:185], v[198:201], v[30:33]
	v_mfma_f32_16x16x32_bf16 v[22:25], v[172:175], v[206:209], v[22:25]
	v_mfma_f32_16x16x32_bf16 v[14:17], v[182:185], v[206:209], v[14:17]
	v_mfma_f32_16x16x32_bf16 v[6:9], v[172:175], v[214:217], v[6:9]
	s_setprio 0
	v_mfma_f32_16x16x32_bf16 v[2:5], v[182:185], v[214:217], v[2:5]
	s_barrier
	s_add_i32 s50, s50, 2
	s_add_u32 s18, s18, 0x10000
	s_addc_u32 s19, s19, 0
	s_add_u32 s48, s48, 0x10000
	s_addc_u32 s49, s49, 0
	s_cmp_gt_u32 s50, 41
	s_cbranch_scc0 .LBB0_495

.Lpk555_peel:
	ds_read_b128 v[154:157], v151
	ds_read_b128 v[158:161], v151 offset:1024
	ds_read_b128 v[162:165], v151 offset:2048
	ds_read_b128 v[166:169], v151 offset:3072
	ds_read_b128 v[170:173], v152
	ds_read_b128 v[178:181], v152 offset:1024
	ds_read_b128 v[182:185], v152 offset:2048
	ds_read_b128 v[186:189], v152 offset:3072
	s_add_u32 s2, s26, 0xfffc0080
	s_addc_u32 s3, s27, -1
	s_cmp_eq_u32 s52, 12
	s_cselect_b32 s3, s11, s3
	s_cselect_b32 s2, s13, s2
	s_cselect_b32 s29, s48, s51
	s_cselect_b32 s28, s49, s50
	v_lshl_add_u64 v[144:145], s[26:27], 0, v[138:139]
	s_add_i32 m0, s37, 0xc000
	ds_read_b128 v[190:193], v153
	ds_read_b128 v[194:197], v153 offset:1024
	ds_read_b128 v[198:201], v153 offset:2048
	ds_read_b128 v[202:205], v153 offset:3072
	ds_read_b128 v[206:209], v153 offset:4096
	ds_read_b128 v[210:213], v153 offset:5120
	ds_read_b128 v[214:217], v153 offset:6144
	ds_read_b128 v[218:221], v153 offset:7168
	global_load_lds_dwordx4 v[144:145], off
	v_lshl_add_u64 v[144:145], s[26:27], 0, v[140:141]
	s_add_i32 m0, s37, 0xe000
	s_nop 0
	global_load_lds_dwordx4 v[144:145], off
	s_waitcnt vmcnt(8)
	s_waitcnt lgkmcnt(0)
	s_setprio 1
	s_barrier
	v_mfma_f32_16x16x32_bf16 v[126:129], v[154:157], v[190:193], 0
	v_mfma_f32_16x16x32_bf16 v[122:125], v[162:165], v[190:193], 0
	v_mfma_f32_16x16x32_bf16 v[114:117], v[154:157], v[198:201], 0
	v_mfma_f32_16x16x32_bf16 v[106:109], v[162:165], v[198:201], 0
	v_mfma_f32_16x16x32_bf16 v[98:101], v[154:157], v[206:209], 0
	v_mfma_f32_16x16x32_bf16 v[90:93], v[162:165], v[206:209], 0
	v_mfma_f32_16x16x32_bf16 v[82:85], v[154:157], v[214:217], 0
	v_mfma_f32_16x16x32_bf16 v[74:77], v[162:165], v[214:217], 0
	v_mfma_f32_16x16x32_bf16 v[126:129], v[158:161], v[194:197], v[126:129]
	v_mfma_f32_16x16x32_bf16 v[122:125], v[166:169], v[194:197], v[122:125]
	v_mfma_f32_16x16x32_bf16 v[114:117], v[158:161], v[202:205], v[114:117]
	v_mfma_f32_16x16x32_bf16 v[106:109], v[166:169], v[202:205], v[106:109]
	v_mfma_f32_16x16x32_bf16 v[98:101], v[158:161], v[210:213], v[98:101]
	v_mfma_f32_16x16x32_bf16 v[90:93], v[166:169], v[210:213], v[90:93]
	v_mfma_f32_16x16x32_bf16 v[82:85], v[158:161], v[218:221], v[82:85]
	v_mfma_f32_16x16x32_bf16 v[74:77], v[166:169], v[218:221], v[74:77]
	v_mfma_f32_16x16x32_bf16 v[118:121], v[170:173], v[190:193], 0
	v_mfma_f32_16x16x32_bf16 v[110:113], v[182:185], v[190:193], 0
	v_mfma_f32_16x16x32_bf16 v[102:105], v[170:173], v[198:201], 0
	v_mfma_f32_16x16x32_bf16 v[94:97], v[182:185], v[198:201], 0
	v_mfma_f32_16x16x32_bf16 v[86:89], v[170:173], v[206:209], 0
	v_mfma_f32_16x16x32_bf16 v[78:81], v[182:185], v[206:209], 0
	v_mfma_f32_16x16x32_bf16 v[70:73], v[170:173], v[214:217], 0
	v_mfma_f32_16x16x32_bf16 v[66:69], v[182:185], v[214:217], 0
	v_mfma_f32_16x16x32_bf16 v[118:121], v[178:181], v[194:197], v[118:121]
	v_mfma_f32_16x16x32_bf16 v[110:113], v[186:189], v[194:197], v[110:113]
	v_mfma_f32_16x16x32_bf16 v[102:105], v[178:181], v[202:205], v[102:105]
	v_mfma_f32_16x16x32_bf16 v[94:97], v[186:189], v[202:205], v[94:97]
	v_mfma_f32_16x16x32_bf16 v[86:89], v[178:181], v[210:213], v[86:89]
	v_mfma_f32_16x16x32_bf16 v[78:81], v[186:189], v[210:213], v[78:81]
	v_mfma_f32_16x16x32_bf16 v[70:73], v[178:181], v[218:221], v[70:73]
	s_setprio 0
	v_mfma_f32_16x16x32_bf16 v[66:69], v[186:189], v[218:221], v[66:69]
	s_barrier
	s_add_i32 s53, s44, s34
	v_lshl_add_u64 v[144:145], s[28:29], 0, v[134:135]
	s_mov_b32 m0, s53
	ds_read_b128 v[190:193], v153 offset:16384
	ds_read_b128 v[194:197], v153 offset:17408
	ds_read_b128 v[198:201], v153 offset:18432
	ds_read_b128 v[202:205], v153 offset:19456
	ds_read_b128 v[206:209], v153 offset:20480
	ds_read_b128 v[210:213], v153 offset:21504
	ds_read_b128 v[214:217], v153 offset:22528
	ds_read_b128 v[218:221], v153 offset:23552
	global_load_lds_dwordx4 v[144:145], off
	s_add_i32 m0, s53, 0x2000
	s_add_u32 s54, s28, 0x40000
	v_lshl_add_u64 v[174:175], s[28:29], 0, v[130:131]
	s_addc_u32 s55, s29, 0
	s_add_i32 s53, s45, s34
	global_load_lds_dwordx4 v[174:175], off
	v_lshl_add_u64 v[222:223], s[54:55], 0, v[134:135]
	s_mov_b32 m0, s53
	v_lshl_add_u64 v[224:225], s[2:3], 0, v[132:133]
	global_load_lds_dwordx4 v[222:223], off
	v_lshl_add_u64 v[222:223], s[54:55], 0, v[130:131]
	s_add_i32 m0, s53, 0x2000
	s_nop 0
	global_load_lds_dwordx4 v[222:223], off
	v_lshl_add_u64 v[222:223], s[2:3], 0, v[136:137]
	s_mov_b32 m0, s37
	s_nop 0
	global_load_lds_dwordx4 v[222:223], off
	s_mov_b32 m0, s25
	s_nop 0
	global_load_lds_dwordx4 v[224:225], off
	s_waitcnt vmcnt(8)
	s_waitcnt lgkmcnt(0)
	s_setprio 1
	s_barrier
	v_mfma_f32_16x16x32_bf16 v[62:65], v[154:157], v[190:193], 0
	v_mfma_f32_16x16x32_bf16 v[58:61], v[162:165], v[190:193], 0
	v_mfma_f32_16x16x32_bf16 v[50:53], v[154:157], v[198:201], 0
	v_mfma_f32_16x16x32_bf16 v[42:45], v[162:165], v[198:201], 0
	v_mfma_f32_16x16x32_bf16 v[34:37], v[154:157], v[206:209], 0
	v_mfma_f32_16x16x32_bf16 v[26:29], v[162:165], v[206:209], 0
	v_mfma_f32_16x16x32_bf16 v[18:21], v[154:157], v[214:217], 0
	v_mfma_f32_16x16x32_bf16 v[10:13], v[162:165], v[214:217], 0
	v_mfma_f32_16x16x32_bf16 v[62:65], v[158:161], v[194:197], v[62:65]
	v_mfma_f32_16x16x32_bf16 v[58:61], v[166:169], v[194:197], v[58:61]
	v_mfma_f32_16x16x32_bf16 v[50:53], v[158:161], v[202:205], v[50:53]
	v_mfma_f32_16x16x32_bf16 v[42:45], v[166:169], v[202:205], v[42:45]
	v_mfma_f32_16x16x32_bf16 v[34:37], v[158:161], v[210:213], v[34:37]
	v_mfma_f32_16x16x32_bf16 v[26:29], v[166:169], v[210:213], v[26:29]
	v_mfma_f32_16x16x32_bf16 v[18:21], v[158:161], v[218:221], v[18:21]
	v_mfma_f32_16x16x32_bf16 v[10:13], v[166:169], v[218:221], v[10:13]
	v_mfma_f32_16x16x32_bf16 v[54:57], v[170:173], v[190:193], 0
	v_mfma_f32_16x16x32_bf16 v[46:49], v[182:185], v[190:193], 0
	v_mfma_f32_16x16x32_bf16 v[38:41], v[170:173], v[198:201], 0
	v_mfma_f32_16x16x32_bf16 v[30:33], v[182:185], v[198:201], 0
	v_mfma_f32_16x16x32_bf16 v[22:25], v[170:173], v[206:209], 0
	v_mfma_f32_16x16x32_bf16 v[14:17], v[182:185], v[206:209], 0
	v_mfma_f32_16x16x32_bf16 v[6:9], v[170:173], v[214:217], 0
	v_mfma_f32_16x16x32_bf16 v[2:5], v[182:185], v[214:217], 0
	v_mfma_f32_16x16x32_bf16 v[54:57], v[178:181], v[194:197], v[54:57]
	v_mfma_f32_16x16x32_bf16 v[46:49], v[186:189], v[194:197], v[46:49]
	v_mfma_f32_16x16x32_bf16 v[38:41], v[178:181], v[202:205], v[38:41]
	v_mfma_f32_16x16x32_bf16 v[30:33], v[186:189], v[202:205], v[30:33]
	v_mfma_f32_16x16x32_bf16 v[22:25], v[178:181], v[210:213], v[22:25]
	v_mfma_f32_16x16x32_bf16 v[14:17], v[186:189], v[210:213], v[14:17]
	v_mfma_f32_16x16x32_bf16 v[6:9], v[178:181], v[218:221], v[6:9]
	s_setprio 0
	v_mfma_f32_16x16x32_bf16 v[2:5], v[186:189], v[218:221], v[2:5]
	s_barrier
	s_add_i32 s53, 0, 0x18000
	s_add_i32 s54, 0, 0x1c000
	v_add_u32_e32 v166, s53, v149
	v_add_u32_e32 v176, s54, v149
	ds_read_b128 v[154:157], v166
	ds_read_b128 v[158:161], v166 offset:1024
	ds_read_b128 v[162:165], v166 offset:2048
	ds_read_b128 v[166:169], v166 offset:3072
	ds_read_b128 v[170:173], v176
	ds_read_b128 v[178:181], v176 offset:1024
	ds_read_b128 v[182:185], v176 offset:2048
	ds_read_b128 v[186:189], v176 offset:3072
	s_add_u32 s2, s2, 0x40000
	s_addc_u32 s3, s3, 0
	s_mov_b32 m0, s38
	v_lshl_add_u64 v[226:227], s[2:3], 0, v[136:137]
	ds_read_b128 v[190:193], v153 offset:32768
	ds_read_b128 v[194:197], v153 offset:33792
	ds_read_b128 v[198:201], v153 offset:34816
	ds_read_b128 v[202:205], v153 offset:35840
	ds_read_b128 v[206:209], v153 offset:36864
	ds_read_b128 v[210:213], v153 offset:37888
	ds_read_b128 v[214:217], v153 offset:38912
	ds_read_b128 v[218:221], v153 offset:39936
	global_load_lds_dwordx4 v[226:227], off
	v_lshl_add_u64 v[226:227], s[2:3], 0, v[132:133]
	s_mov_b32 m0, s39
	s_nop 0
	global_load_lds_dwordx4 v[226:227], off
	s_waitcnt vmcnt(8)
	s_waitcnt lgkmcnt(0)
	s_setprio 1
	s_barrier
	v_mfma_f32_16x16x32_bf16 v[126:129], v[154:157], v[190:193], v[126:129]
	v_mfma_f32_16x16x32_bf16 v[122:125], v[162:165], v[190:193], v[122:125]
	v_mfma_f32_16x16x32_bf16 v[114:117], v[154:157], v[198:201], v[114:117]
	v_mfma_f32_16x16x32_bf16 v[106:109], v[162:165], v[198:201], v[106:109]
	v_mfma_f32_16x16x32_bf16 v[98:101], v[154:157], v[206:209], v[98:101]
	v_mfma_f32_16x16x32_bf16 v[90:93], v[162:165], v[206:209], v[90:93]
	v_mfma_f32_16x16x32_bf16 v[82:85], v[154:157], v[214:217], v[82:85]
	v_mfma_f32_16x16x32_bf16 v[74:77], v[162:165], v[214:217], v[74:77]
	v_mfma_f32_16x16x32_bf16 v[126:129], v[158:161], v[194:197], v[126:129]
	v_mfma_f32_16x16x32_bf16 v[122:125], v[166:169], v[194:197], v[122:125]
	v_mfma_f32_16x16x32_bf16 v[114:117], v[158:161], v[202:205], v[114:117]
	v_mfma_f32_16x16x32_bf16 v[106:109], v[166:169], v[202:205], v[106:109]
	v_mfma_f32_16x16x32_bf16 v[98:101], v[158:161], v[210:213], v[98:101]
	v_mfma_f32_16x16x32_bf16 v[90:93], v[166:169], v[210:213], v[90:93]
	v_mfma_f32_16x16x32_bf16 v[82:85], v[158:161], v[218:221], v[82:85]
	v_mfma_f32_16x16x32_bf16 v[74:77], v[166:169], v[218:221], v[74:77]
	v_mfma_f32_16x16x32_bf16 v[118:121], v[170:173], v[190:193], v[118:121]
	v_mfma_f32_16x16x32_bf16 v[110:113], v[182:185], v[190:193], v[110:113]
	v_mfma_f32_16x16x32_bf16 v[102:105], v[170:173], v[198:201], v[102:105]
	v_mfma_f32_16x16x32_bf16 v[94:97], v[182:185], v[198:201], v[94:97]
	v_mfma_f32_16x16x32_bf16 v[86:89], v[170:173], v[206:209], v[86:89]
	v_mfma_f32_16x16x32_bf16 v[78:81], v[182:185], v[206:209], v[78:81]
	v_mfma_f32_16x16x32_bf16 v[70:73], v[170:173], v[214:217], v[70:73]
	v_mfma_f32_16x16x32_bf16 v[66:69], v[182:185], v[214:217], v[66:69]
	v_mfma_f32_16x16x32_bf16 v[118:121], v[178:181], v[194:197], v[118:121]
	v_mfma_f32_16x16x32_bf16 v[110:113], v[186:189], v[194:197], v[110:113]
	v_mfma_f32_16x16x32_bf16 v[102:105], v[178:181], v[202:205], v[102:105]
	v_mfma_f32_16x16x32_bf16 v[94:97], v[186:189], v[202:205], v[94:97]
	v_mfma_f32_16x16x32_bf16 v[86:89], v[178:181], v[210:213], v[86:89]
	v_mfma_f32_16x16x32_bf16 v[78:81], v[186:189], v[210:213], v[78:81]
	v_mfma_f32_16x16x32_bf16 v[70:73], v[178:181], v[218:221], v[70:73]
	s_setprio 0
	v_mfma_f32_16x16x32_bf16 v[66:69], v[186:189], v[218:221], v[66:69]
	s_barrier
	s_add_i32 s2, s53, s34
	v_lshl_add_u64 v[144:145], v[144:145], 0, s[6:7]
	s_mov_b32 m0, s2
	ds_read_b128 v[190:193], v153 offset:49152
	ds_read_b128 v[194:197], v153 offset:50176
	ds_read_b128 v[198:201], v153 offset:51200
	ds_read_b128 v[202:205], v153 offset:52224
	ds_read_b128 v[206:209], v153 offset:53248
	ds_read_b128 v[210:213], v153 offset:54272
	ds_read_b128 v[214:217], v153 offset:55296
	ds_read_b128 v[218:221], v153 offset:56320
	global_load_lds_dwordx4 v[144:145], off
	s_add_i32 m0, s2, 0x2000
	s_add_u32 s2, s28, 0x40080
	v_lshl_add_u64 v[144:145], v[174:175], 0, s[6:7]
	s_addc_u32 s3, s29, 0
	s_add_i32 s28, s54, s34
	global_load_lds_dwordx4 v[144:145], off
	v_lshl_add_u64 v[144:145], s[2:3], 0, v[134:135]
	s_mov_b32 m0, s28
	s_nop 0
	global_load_lds_dwordx4 v[144:145], off
	v_lshl_add_u64 v[144:145], s[2:3], 0, v[130:131]
	s_add_i32 m0, s28, 0x2000
	s_nop 0
	global_load_lds_dwordx4 v[144:145], off
	v_lshl_add_u64 v[144:145], v[222:223], 0, s[6:7]
	s_mov_b32 m0, s41
	s_nop 0
	global_load_lds_dwordx4 v[144:145], off
	v_lshl_add_u64 v[144:145], v[224:225], 0, s[6:7]
	s_mov_b32 m0, s42
	s_nop 0
	global_load_lds_dwordx4 v[144:145], off
	s_waitcnt vmcnt(8)
	s_waitcnt lgkmcnt(0)
	s_setprio 1
	s_barrier
	v_mfma_f32_16x16x32_bf16 v[62:65], v[154:157], v[190:193], v[62:65]
	v_mfma_f32_16x16x32_bf16 v[58:61], v[162:165], v[190:193], v[58:61]
	v_mfma_f32_16x16x32_bf16 v[50:53], v[154:157], v[198:201], v[50:53]
	v_mfma_f32_16x16x32_bf16 v[42:45], v[162:165], v[198:201], v[42:45]
	v_mfma_f32_16x16x32_bf16 v[34:37], v[154:157], v[206:209], v[34:37]
	v_mfma_f32_16x16x32_bf16 v[26:29], v[162:165], v[206:209], v[26:29]
	v_mfma_f32_16x16x32_bf16 v[18:21], v[154:157], v[214:217], v[18:21]
	v_mfma_f32_16x16x32_bf16 v[10:13], v[162:165], v[214:217], v[10:13]
	v_mfma_f32_16x16x32_bf16 v[62:65], v[158:161], v[194:197], v[62:65]
	v_mfma_f32_16x16x32_bf16 v[58:61], v[166:169], v[194:197], v[58:61]
	v_mfma_f32_16x16x32_bf16 v[50:53], v[158:161], v[202:205], v[50:53]
	v_mfma_f32_16x16x32_bf16 v[42:45], v[166:169], v[202:205], v[42:45]
	v_mfma_f32_16x16x32_bf16 v[34:37], v[158:161], v[210:213], v[34:37]
	v_mfma_f32_16x16x32_bf16 v[26:29], v[166:169], v[210:213], v[26:29]
	v_mfma_f32_16x16x32_bf16 v[18:21], v[158:161], v[218:221], v[18:21]
	v_mfma_f32_16x16x32_bf16 v[10:13], v[166:169], v[218:221], v[10:13]
	v_mfma_f32_16x16x32_bf16 v[54:57], v[170:173], v[190:193], v[54:57]
	v_mfma_f32_16x16x32_bf16 v[46:49], v[182:185], v[190:193], v[46:49]
	v_mfma_f32_16x16x32_bf16 v[38:41], v[170:173], v[198:201], v[38:41]
	v_mfma_f32_16x16x32_bf16 v[30:33], v[182:185], v[198:201], v[30:33]
	v_mfma_f32_16x16x32_bf16 v[22:25], v[170:173], v[206:209], v[22:25]
	v_mfma_f32_16x16x32_bf16 v[14:17], v[182:185], v[206:209], v[14:17]
	v_mfma_f32_16x16x32_bf16 v[6:9], v[170:173], v[214:217], v[6:9]
	v_mfma_f32_16x16x32_bf16 v[2:5], v[182:185], v[214:217], v[2:5]
	v_mfma_f32_16x16x32_bf16 v[54:57], v[178:181], v[194:197], v[54:57]
	v_mfma_f32_16x16x32_bf16 v[46:49], v[186:189], v[194:197], v[46:49]
	v_mfma_f32_16x16x32_bf16 v[38:41], v[178:181], v[202:205], v[38:41]
	v_mfma_f32_16x16x32_bf16 v[30:33], v[186:189], v[202:205], v[30:33]
	v_mfma_f32_16x16x32_bf16 v[22:25], v[178:181], v[210:213], v[22:25]
	v_mfma_f32_16x16x32_bf16 v[14:17], v[186:189], v[210:213], v[14:17]
	v_mfma_f32_16x16x32_bf16 v[6:9], v[178:181], v[218:221], v[6:9]
	s_setprio 0
	v_mfma_f32_16x16x32_bf16 v[2:5], v[186:189], v[218:221], v[2:5]
	s_barrier
	s_add_i32 s52, s52, 2
	s_add_u32 s26, s26, 0x100
	s_addc_u32 s27, s27, 0
	s_add_u32 s50, s50, 0x100
	s_addc_u32 s51, s51, 0
	s_cmp_gt_u32 s52, 13
	s_cbranch_scc0 .LBB0_555
	s_branch .Lpk555_exit
.LBB0_555:
	ds_read_b128 v[154:157], v151
	ds_read_b128 v[158:161], v151 offset:1024
	ds_read_b128 v[162:165], v151 offset:2048
	ds_read_b128 v[166:169], v151 offset:3072
	ds_read_b128 v[170:173], v152
	ds_read_b128 v[178:181], v152 offset:1024
	ds_read_b128 v[182:185], v152 offset:2048
	ds_read_b128 v[186:189], v152 offset:3072
	s_add_u32 s2, s26, 0xfffc0080
	s_addc_u32 s3, s27, -1
	s_cmp_eq_u32 s52, 12
	s_cselect_b32 s3, s11, s3
	s_cselect_b32 s2, s13, s2
	s_cselect_b32 s29, s48, s51
	s_cselect_b32 s28, s49, s50
	v_lshl_add_u64 v[144:145], s[26:27], 0, v[138:139]
	s_add_i32 m0, s37, 0xc000
	ds_read_b128 v[190:193], v153
	ds_read_b128 v[194:197], v153 offset:1024
	ds_read_b128 v[198:201], v153 offset:2048
	ds_read_b128 v[202:205], v153 offset:3072
	ds_read_b128 v[206:209], v153 offset:4096
	ds_read_b128 v[210:213], v153 offset:5120
	ds_read_b128 v[214:217], v153 offset:6144
	ds_read_b128 v[218:221], v153 offset:7168
	global_load_lds_dwordx4 v[144:145], off
	v_lshl_add_u64 v[144:145], s[26:27], 0, v[140:141]
	s_add_i32 m0, s37, 0xe000
	s_nop 0
	global_load_lds_dwordx4 v[144:145], off
	s_waitcnt vmcnt(8)
	s_waitcnt lgkmcnt(0)
	s_setprio 1
	s_barrier
	v_mfma_f32_16x16x32_bf16 v[126:129], v[154:157], v[190:193], v[126:129]
	v_mfma_f32_16x16x32_bf16 v[122:125], v[162:165], v[190:193], v[122:125]
	v_mfma_f32_16x16x32_bf16 v[114:117], v[154:157], v[198:201], v[114:117]
	v_mfma_f32_16x16x32_bf16 v[106:109], v[162:165], v[198:201], v[106:109]
	v_mfma_f32_16x16x32_bf16 v[98:101], v[154:157], v[206:209], v[98:101]
	v_mfma_f32_16x16x32_bf16 v[90:93], v[162:165], v[206:209], v[90:93]
	v_mfma_f32_16x16x32_bf16 v[82:85], v[154:157], v[214:217], v[82:85]
	v_mfma_f32_16x16x32_bf16 v[74:77], v[162:165], v[214:217], v[74:77]
	v_mfma_f32_16x16x32_bf16 v[126:129], v[158:161], v[194:197], v[126:129]
	v_mfma_f32_16x16x32_bf16 v[122:125], v[166:169], v[194:197], v[122:125]
	v_mfma_f32_16x16x32_bf16 v[114:117], v[158:161], v[202:205], v[114:117]
	v_mfma_f32_16x16x32_bf16 v[106:109], v[166:169], v[202:205], v[106:109]
	v_mfma_f32_16x16x32_bf16 v[98:101], v[158:161], v[210:213], v[98:101]
	v_mfma_f32_16x16x32_bf16 v[90:93], v[166:169], v[210:213], v[90:93]
	v_mfma_f32_16x16x32_bf16 v[82:85], v[158:161], v[218:221], v[82:85]
	v_mfma_f32_16x16x32_bf16 v[74:77], v[166:169], v[218:221], v[74:77]
	v_mfma_f32_16x16x32_bf16 v[118:121], v[170:173], v[190:193], v[118:121]
	v_mfma_f32_16x16x32_bf16 v[110:113], v[182:185], v[190:193], v[110:113]
	v_mfma_f32_16x16x32_bf16 v[102:105], v[170:173], v[198:201], v[102:105]
	v_mfma_f32_16x16x32_bf16 v[94:97], v[182:185], v[198:201], v[94:97]
	v_mfma_f32_16x16x32_bf16 v[86:89], v[170:173], v[206:209], v[86:89]
	v_mfma_f32_16x16x32_bf16 v[78:81], v[182:185], v[206:209], v[78:81]
	v_mfma_f32_16x16x32_bf16 v[70:73], v[170:173], v[214:217], v[70:73]
	v_mfma_f32_16x16x32_bf16 v[66:69], v[182:185], v[214:217], v[66:69]
	v_mfma_f32_16x16x32_bf16 v[118:121], v[178:181], v[194:197], v[118:121]
	v_mfma_f32_16x16x32_bf16 v[110:113], v[186:189], v[194:197], v[110:113]
	v_mfma_f32_16x16x32_bf16 v[102:105], v[178:181], v[202:205], v[102:105]
	v_mfma_f32_16x16x32_bf16 v[94:97], v[186:189], v[202:205], v[94:97]
	v_mfma_f32_16x16x32_bf16 v[86:89], v[178:181], v[210:213], v[86:89]
	v_mfma_f32_16x16x32_bf16 v[78:81], v[186:189], v[210:213], v[78:81]
	v_mfma_f32_16x16x32_bf16 v[70:73], v[178:181], v[218:221], v[70:73]
	s_setprio 0
	v_mfma_f32_16x16x32_bf16 v[66:69], v[186:189], v[218:221], v[66:69]
	s_barrier
	s_add_i32 s53, s44, s34
	v_lshl_add_u64 v[144:145], s[28:29], 0, v[134:135]
	s_mov_b32 m0, s53
	ds_read_b128 v[190:193], v153 offset:16384
	ds_read_b128 v[194:197], v153 offset:17408
	ds_read_b128 v[198:201], v153 offset:18432
	ds_read_b128 v[202:205], v153 offset:19456
	ds_read_b128 v[206:209], v153 offset:20480
	ds_read_b128 v[210:213], v153 offset:21504
	ds_read_b128 v[214:217], v153 offset:22528
	ds_read_b128 v[218:221], v153 offset:23552
	global_load_lds_dwordx4 v[144:145], off
	s_add_i32 m0, s53, 0x2000
	s_add_u32 s54, s28, 0x40000
	v_lshl_add_u64 v[174:175], s[28:29], 0, v[130:131]
	s_addc_u32 s55, s29, 0
	s_add_i32 s53, s45, s34
	global_load_lds_dwordx4 v[174:175], off
	v_lshl_add_u64 v[222:223], s[54:55], 0, v[134:135]
	s_mov_b32 m0, s53
	v_lshl_add_u64 v[224:225], s[2:3], 0, v[132:133]
	global_load_lds_dwordx4 v[222:223], off
	v_lshl_add_u64 v[222:223], s[54:55], 0, v[130:131]
	s_add_i32 m0, s53, 0x2000
	s_nop 0
	global_load_lds_dwordx4 v[222:223], off
	v_lshl_add_u64 v[222:223], s[2:3], 0, v[136:137]
	s_mov_b32 m0, s37
	s_nop 0
	global_load_lds_dwordx4 v[222:223], off
	s_mov_b32 m0, s25
	s_nop 0
	global_load_lds_dwordx4 v[224:225], off
	s_waitcnt vmcnt(8)
	s_waitcnt lgkmcnt(0)
	s_setprio 1
	s_barrier
	v_mfma_f32_16x16x32_bf16 v[62:65], v[154:157], v[190:193], v[62:65]
	v_mfma_f32_16x16x32_bf16 v[58:61], v[162:165], v[190:193], v[58:61]
	v_mfma_f32_16x16x32_bf16 v[50:53], v[154:157], v[198:201], v[50:53]
	v_mfma_f32_16x16x32_bf16 v[42:45], v[162:165], v[198:201], v[42:45]
	v_mfma_f32_16x16x32_bf16 v[34:37], v[154:157], v[206:209], v[34:37]
	v_mfma_f32_16x16x32_bf16 v[26:29], v[162:165], v[206:209], v[26:29]
	v_mfma_f32_16x16x32_bf16 v[18:21], v[154:157], v[214:217], v[18:21]
	v_mfma_f32_16x16x32_bf16 v[10:13], v[162:165], v[214:217], v[10:13]
	v_mfma_f32_16x16x32_bf16 v[62:65], v[158:161], v[194:197], v[62:65]
	v_mfma_f32_16x16x32_bf16 v[58:61], v[166:169], v[194:197], v[58:61]
	v_mfma_f32_16x16x32_bf16 v[50:53], v[158:161], v[202:205], v[50:53]
	v_mfma_f32_16x16x32_bf16 v[42:45], v[166:169], v[202:205], v[42:45]
	v_mfma_f32_16x16x32_bf16 v[34:37], v[158:161], v[210:213], v[34:37]
	v_mfma_f32_16x16x32_bf16 v[26:29], v[166:169], v[210:213], v[26:29]
	v_mfma_f32_16x16x32_bf16 v[18:21], v[158:161], v[218:221], v[18:21]
	v_mfma_f32_16x16x32_bf16 v[10:13], v[166:169], v[218:221], v[10:13]
	v_mfma_f32_16x16x32_bf16 v[54:57], v[170:173], v[190:193], v[54:57]
	v_mfma_f32_16x16x32_bf16 v[46:49], v[182:185], v[190:193], v[46:49]
	v_mfma_f32_16x16x32_bf16 v[38:41], v[170:173], v[198:201], v[38:41]
	v_mfma_f32_16x16x32_bf16 v[30:33], v[182:185], v[198:201], v[30:33]
	v_mfma_f32_16x16x32_bf16 v[22:25], v[170:173], v[206:209], v[22:25]
	v_mfma_f32_16x16x32_bf16 v[14:17], v[182:185], v[206:209], v[14:17]
	v_mfma_f32_16x16x32_bf16 v[6:9], v[170:173], v[214:217], v[6:9]
	v_mfma_f32_16x16x32_bf16 v[2:5], v[182:185], v[214:217], v[2:5]
	v_mfma_f32_16x16x32_bf16 v[54:57], v[178:181], v[194:197], v[54:57]
	v_mfma_f32_16x16x32_bf16 v[46:49], v[186:189], v[194:197], v[46:49]
	v_mfma_f32_16x16x32_bf16 v[38:41], v[178:181], v[202:205], v[38:41]
	v_mfma_f32_16x16x32_bf16 v[30:33], v[186:189], v[202:205], v[30:33]
	v_mfma_f32_16x16x32_bf16 v[22:25], v[178:181], v[210:213], v[22:25]
	v_mfma_f32_16x16x32_bf16 v[14:17], v[186:189], v[210:213], v[14:17]
	v_mfma_f32_16x16x32_bf16 v[6:9], v[178:181], v[218:221], v[6:9]
	s_setprio 0
	v_mfma_f32_16x16x32_bf16 v[2:5], v[186:189], v[218:221], v[2:5]
	s_barrier
	s_add_i32 s53, 0, 0x18000
	s_add_i32 s54, 0, 0x1c000
	v_add_u32_e32 v166, s53, v149
	v_add_u32_e32 v176, s54, v149
	ds_read_b128 v[154:157], v166
	ds_read_b128 v[158:161], v166 offset:1024
	ds_read_b128 v[162:165], v166 offset:2048
	ds_read_b128 v[166:169], v166 offset:3072
	ds_read_b128 v[170:173], v176
	ds_read_b128 v[178:181], v176 offset:1024
	ds_read_b128 v[182:185], v176 offset:2048
	ds_read_b128 v[186:189], v176 offset:3072
	s_add_u32 s2, s2, 0x40000
	s_addc_u32 s3, s3, 0
	s_mov_b32 m0, s38
	v_lshl_add_u64 v[226:227], s[2:3], 0, v[136:137]
	ds_read_b128 v[190:193], v153 offset:32768
	ds_read_b128 v[194:197], v153 offset:33792
	ds_read_b128 v[198:201], v153 offset:34816
	ds_read_b128 v[202:205], v153 offset:35840
	ds_read_b128 v[206:209], v153 offset:36864
	ds_read_b128 v[210:213], v153 offset:37888
	ds_read_b128 v[214:217], v153 offset:38912
	ds_read_b128 v[218:221], v153 offset:39936
	global_load_lds_dwordx4 v[226:227], off
	v_lshl_add_u64 v[226:227], s[2:3], 0, v[132:133]
	s_mov_b32 m0, s39
	s_nop 0
	global_load_lds_dwordx4 v[226:227], off
	s_waitcnt vmcnt(8)
	s_waitcnt lgkmcnt(0)
	s_setprio 1
	s_barrier
	v_mfma_f32_16x16x32_bf16 v[126:129], v[154:157], v[190:193], v[126:129]
	v_mfma_f32_16x16x32_bf16 v[122:125], v[162:165], v[190:193], v[122:125]
	v_mfma_f32_16x16x32_bf16 v[114:117], v[154:157], v[198:201], v[114:117]
	v_mfma_f32_16x16x32_bf16 v[106:109], v[162:165], v[198:201], v[106:109]
	v_mfma_f32_16x16x32_bf16 v[98:101], v[154:157], v[206:209], v[98:101]
	v_mfma_f32_16x16x32_bf16 v[90:93], v[162:165], v[206:209], v[90:93]
	v_mfma_f32_16x16x32_bf16 v[82:85], v[154:157], v[214:217], v[82:85]
	v_mfma_f32_16x16x32_bf16 v[74:77], v[162:165], v[214:217], v[74:77]
	v_mfma_f32_16x16x32_bf16 v[126:129], v[158:161], v[194:197], v[126:129]
	v_mfma_f32_16x16x32_bf16 v[122:125], v[166:169], v[194:197], v[122:125]
	v_mfma_f32_16x16x32_bf16 v[114:117], v[158:161], v[202:205], v[114:117]
	v_mfma_f32_16x16x32_bf16 v[106:109], v[166:169], v[202:205], v[106:109]
	v_mfma_f32_16x16x32_bf16 v[98:101], v[158:161], v[210:213], v[98:101]
	v_mfma_f32_16x16x32_bf16 v[90:93], v[166:169], v[210:213], v[90:93]
	v_mfma_f32_16x16x32_bf16 v[82:85], v[158:161], v[218:221], v[82:85]
	v_mfma_f32_16x16x32_bf16 v[74:77], v[166:169], v[218:221], v[74:77]
	v_mfma_f32_16x16x32_bf16 v[118:121], v[170:173], v[190:193], v[118:121]
	v_mfma_f32_16x16x32_bf16 v[110:113], v[182:185], v[190:193], v[110:113]
	v_mfma_f32_16x16x32_bf16 v[102:105], v[170:173], v[198:201], v[102:105]
	v_mfma_f32_16x16x32_bf16 v[94:97], v[182:185], v[198:201], v[94:97]
	v_mfma_f32_16x16x32_bf16 v[86:89], v[170:173], v[206:209], v[86:89]
	v_mfma_f32_16x16x32_bf16 v[78:81], v[182:185], v[206:209], v[78:81]
	v_mfma_f32_16x16x32_bf16 v[70:73], v[170:173], v[214:217], v[70:73]
	v_mfma_f32_16x16x32_bf16 v[66:69], v[182:185], v[214:217], v[66:69]
	v_mfma_f32_16x16x32_bf16 v[118:121], v[178:181], v[194:197], v[118:121]
	v_mfma_f32_16x16x32_bf16 v[110:113], v[186:189], v[194:197], v[110:113]
	v_mfma_f32_16x16x32_bf16 v[102:105], v[178:181], v[202:205], v[102:105]
	v_mfma_f32_16x16x32_bf16 v[94:97], v[186:189], v[202:205], v[94:97]
	v_mfma_f32_16x16x32_bf16 v[86:89], v[178:181], v[210:213], v[86:89]
	v_mfma_f32_16x16x32_bf16 v[78:81], v[186:189], v[210:213], v[78:81]
	v_mfma_f32_16x16x32_bf16 v[70:73], v[178:181], v[218:221], v[70:73]
	s_setprio 0
	v_mfma_f32_16x16x32_bf16 v[66:69], v[186:189], v[218:221], v[66:69]
	s_barrier
	s_add_i32 s2, s53, s34
	v_lshl_add_u64 v[144:145], v[144:145], 0, s[6:7]
	s_mov_b32 m0, s2
	ds_read_b128 v[190:193], v153 offset:49152
	ds_read_b128 v[194:197], v153 offset:50176
	ds_read_b128 v[198:201], v153 offset:51200
	ds_read_b128 v[202:205], v153 offset:52224
	ds_read_b128 v[206:209], v153 offset:53248
	ds_read_b128 v[210:213], v153 offset:54272
	ds_read_b128 v[214:217], v153 offset:55296
	ds_read_b128 v[218:221], v153 offset:56320
	global_load_lds_dwordx4 v[144:145], off
	s_add_i32 m0, s2, 0x2000
	s_add_u32 s2, s28, 0x40080
	v_lshl_add_u64 v[144:145], v[174:175], 0, s[6:7]
	s_addc_u32 s3, s29, 0
	s_add_i32 s28, s54, s34
	global_load_lds_dwordx4 v[144:145], off
	v_lshl_add_u64 v[144:145], s[2:3], 0, v[134:135]
	s_mov_b32 m0, s28
	s_nop 0
	global_load_lds_dwordx4 v[144:145], off
	v_lshl_add_u64 v[144:145], s[2:3], 0, v[130:131]
	s_add_i32 m0, s28, 0x2000
	s_nop 0
	global_load_lds_dwordx4 v[144:145], off
	v_lshl_add_u64 v[144:145], v[222:223], 0, s[6:7]
	s_mov_b32 m0, s41
	s_nop 0
	global_load_lds_dwordx4 v[144:145], off
	v_lshl_add_u64 v[144:145], v[224:225], 0, s[6:7]
	s_mov_b32 m0, s42
	s_nop 0
	global_load_lds_dwordx4 v[144:145], off
	s_waitcnt vmcnt(8)
	s_waitcnt lgkmcnt(0)
	s_setprio 1
	s_barrier
	v_mfma_f32_16x16x32_bf16 v[62:65], v[154:157], v[190:193], v[62:65]
	v_mfma_f32_16x16x32_bf16 v[58:61], v[162:165], v[190:193], v[58:61]
	v_mfma_f32_16x16x32_bf16 v[50:53], v[154:157], v[198:201], v[50:53]
	v_mfma_f32_16x16x32_bf16 v[42:45], v[162:165], v[198:201], v[42:45]
	v_mfma_f32_16x16x32_bf16 v[34:37], v[154:157], v[206:209], v[34:37]
	v_mfma_f32_16x16x32_bf16 v[26:29], v[162:165], v[206:209], v[26:29]
	v_mfma_f32_16x16x32_bf16 v[18:21], v[154:157], v[214:217], v[18:21]
	v_mfma_f32_16x16x32_bf16 v[10:13], v[162:165], v[214:217], v[10:13]
	v_mfma_f32_16x16x32_bf16 v[62:65], v[158:161], v[194:197], v[62:65]
	v_mfma_f32_16x16x32_bf16 v[58:61], v[166:169], v[194:197], v[58:61]
	v_mfma_f32_16x16x32_bf16 v[50:53], v[158:161], v[202:205], v[50:53]
	v_mfma_f32_16x16x32_bf16 v[42:45], v[166:169], v[202:205], v[42:45]
	v_mfma_f32_16x16x32_bf16 v[34:37], v[158:161], v[210:213], v[34:37]
	v_mfma_f32_16x16x32_bf16 v[26:29], v[166:169], v[210:213], v[26:29]
	v_mfma_f32_16x16x32_bf16 v[18:21], v[158:161], v[218:221], v[18:21]
	v_mfma_f32_16x16x32_bf16 v[10:13], v[166:169], v[218:221], v[10:13]
	v_mfma_f32_16x16x32_bf16 v[54:57], v[170:173], v[190:193], v[54:57]
	v_mfma_f32_16x16x32_bf16 v[46:49], v[182:185], v[190:193], v[46:49]
	v_mfma_f32_16x16x32_bf16 v[38:41], v[170:173], v[198:201], v[38:41]
	v_mfma_f32_16x16x32_bf16 v[30:33], v[182:185], v[198:201], v[30:33]
	v_mfma_f32_16x16x32_bf16 v[22:25], v[170:173], v[206:209], v[22:25]
	v_mfma_f32_16x16x32_bf16 v[14:17], v[182:185], v[206:209], v[14:17]
	v_mfma_f32_16x16x32_bf16 v[6:9], v[170:173], v[214:217], v[6:9]
	v_mfma_f32_16x16x32_bf16 v[2:5], v[182:185], v[214:217], v[2:5]
	v_mfma_f32_16x16x32_bf16 v[54:57], v[178:181], v[194:197], v[54:57]
	v_mfma_f32_16x16x32_bf16 v[46:49], v[186:189], v[194:197], v[46:49]
	v_mfma_f32_16x16x32_bf16 v[38:41], v[178:181], v[202:205], v[38:41]
	v_mfma_f32_16x16x32_bf16 v[30:33], v[186:189], v[202:205], v[30:33]
	v_mfma_f32_16x16x32_bf16 v[22:25], v[178:181], v[210:213], v[22:25]
	v_mfma_f32_16x16x32_bf16 v[14:17], v[186:189], v[210:213], v[14:17]
	v_mfma_f32_16x16x32_bf16 v[6:9], v[178:181], v[218:221], v[6:9]
	s_setprio 0
	v_mfma_f32_16x16x32_bf16 v[2:5], v[186:189], v[218:221], v[2:5]
	s_barrier
	s_add_i32 s52, s52, 2
	s_add_u32 s26, s26, 0x100
	s_addc_u32 s27, s27, 0
	s_add_u32 s50, s50, 0x100
	s_addc_u32 s51, s51, 0
	s_cmp_gt_u32 s52, 13
	s_cbranch_scc0 .LBB0_555

.LBB0_646:
	ds_read_b128 v[152:155], v146
	ds_read_b128 v[156:159], v146 offset:1024
	ds_read_b128 v[160:163], v146 offset:2048
	ds_read_b128 v[164:167], v146 offset:3072
	ds_read_b128 v[168:171], v147
	ds_read_b128 v[172:175], v147 offset:1024
	ds_read_b128 v[178:181], v147 offset:2048
	ds_read_b128 v[182:185], v147 offset:3072
	s_add_u32 s2, s10, s12
	s_addc_u32 s3, s11, s13
	s_add_u32 s2, s2, 0x3400100
	s_addc_u32 s3, s3, 0
	s_add_u32 s14, s24, s12
	s_addc_u32 s15, s25, s13
	s_cmpk_eq_i32 s12, 0x700
	s_cselect_b32 s3, s7, s3
	s_cselect_b32 s2, s6, s2
	s_cselect_b32 s15, s5, s15
	s_cselect_b32 s14, s4, s14
	s_mov_b32 m0, s27
	v_lshl_add_u64 v[218:219], v[138:139], 0, s[12:13]
	ds_read_b128 v[186:189], v148
	ds_read_b128 v[190:193], v148 offset:1024
	ds_read_b128 v[194:197], v148 offset:2048
	ds_read_b128 v[198:201], v148 offset:3072
	ds_read_b128 v[202:205], v148 offset:4096
	ds_read_b128 v[206:209], v148 offset:5120
	ds_read_b128 v[210:213], v148 offset:6144
	ds_read_b128 v[214:217], v148 offset:7168
	global_load_lds_dwordx4 v[218:219], off
	v_lshl_add_u64 v[218:219], v[140:141], 0, s[12:13]
	s_mov_b32 m0, s28
	s_nop 0
	global_load_lds_dwordx4 v[218:219], off
	s_waitcnt vmcnt(8)
	s_waitcnt lgkmcnt(0)
	s_setprio 1
	s_barrier
	v_mfma_f32_16x16x32_bf16 v[126:129], v[152:155], v[186:189], v[126:129]
	v_mfma_f32_16x16x32_bf16 v[122:125], v[160:163], v[186:189], v[122:125]
	v_mfma_f32_16x16x32_bf16 v[114:117], v[152:155], v[194:197], v[114:117]
	v_mfma_f32_16x16x32_bf16 v[106:109], v[160:163], v[194:197], v[106:109]
	v_mfma_f32_16x16x32_bf16 v[98:101], v[152:155], v[202:205], v[98:101]
	v_mfma_f32_16x16x32_bf16 v[90:93], v[160:163], v[202:205], v[90:93]
	v_mfma_f32_16x16x32_bf16 v[82:85], v[152:155], v[210:213], v[82:85]
	v_mfma_f32_16x16x32_bf16 v[74:77], v[160:163], v[210:213], v[74:77]
	v_mfma_f32_16x16x32_bf16 v[126:129], v[156:159], v[190:193], v[126:129]
	v_mfma_f32_16x16x32_bf16 v[122:125], v[164:167], v[190:193], v[122:125]
	v_mfma_f32_16x16x32_bf16 v[114:117], v[156:159], v[198:201], v[114:117]
	v_mfma_f32_16x16x32_bf16 v[106:109], v[164:167], v[198:201], v[106:109]
	v_mfma_f32_16x16x32_bf16 v[98:101], v[156:159], v[206:209], v[98:101]
	v_mfma_f32_16x16x32_bf16 v[90:93], v[164:167], v[206:209], v[90:93]
	v_mfma_f32_16x16x32_bf16 v[82:85], v[156:159], v[214:217], v[82:85]
	v_mfma_f32_16x16x32_bf16 v[74:77], v[164:167], v[214:217], v[74:77]
	v_mfma_f32_16x16x32_bf16 v[118:121], v[168:171], v[186:189], v[118:121]
	v_mfma_f32_16x16x32_bf16 v[110:113], v[178:181], v[186:189], v[110:113]
	v_mfma_f32_16x16x32_bf16 v[102:105], v[168:171], v[194:197], v[102:105]
	v_mfma_f32_16x16x32_bf16 v[94:97], v[178:181], v[194:197], v[94:97]
	v_mfma_f32_16x16x32_bf16 v[86:89], v[168:171], v[202:205], v[86:89]
	v_mfma_f32_16x16x32_bf16 v[78:81], v[178:181], v[202:205], v[78:81]
	v_mfma_f32_16x16x32_bf16 v[70:73], v[168:171], v[210:213], v[70:73]
	v_mfma_f32_16x16x32_bf16 v[66:69], v[178:181], v[210:213], v[66:69]
	v_mfma_f32_16x16x32_bf16 v[118:121], v[172:175], v[190:193], v[118:121]
	v_mfma_f32_16x16x32_bf16 v[110:113], v[182:185], v[190:193], v[110:113]
	v_mfma_f32_16x16x32_bf16 v[102:105], v[172:175], v[198:201], v[102:105]
	v_mfma_f32_16x16x32_bf16 v[94:97], v[182:185], v[198:201], v[94:97]
	v_mfma_f32_16x16x32_bf16 v[86:89], v[172:175], v[206:209], v[86:89]
	v_mfma_f32_16x16x32_bf16 v[78:81], v[182:185], v[206:209], v[78:81]
	v_mfma_f32_16x16x32_bf16 v[70:73], v[172:175], v[214:217], v[70:73]
	s_setprio 0
	v_mfma_f32_16x16x32_bf16 v[66:69], v[182:185], v[214:217], v[66:69]
	s_barrier
	s_mov_b32 m0, s29
	v_lshl_add_u64 v[218:219], s[14:15], 0, v[134:135]
	s_add_u32 s40, s14, 0x40000
	ds_read_b128 v[186:189], v148 offset:16384
	ds_read_b128 v[190:193], v148 offset:17408
	ds_read_b128 v[194:197], v148 offset:18432
	ds_read_b128 v[198:201], v148 offset:19456
	ds_read_b128 v[202:205], v148 offset:20480
	ds_read_b128 v[206:209], v148 offset:21504
	ds_read_b128 v[210:213], v148 offset:22528
	ds_read_b128 v[214:217], v148 offset:23552
	global_load_lds_dwordx4 v[218:219], off
	v_lshl_add_u64 v[220:221], s[14:15], 0, v[130:131]
	s_mov_b32 m0, s30
	s_addc_u32 s41, s15, 0
	global_load_lds_dwordx4 v[220:221], off
	v_lshl_add_u64 v[222:223], s[40:41], 0, v[134:135]
	s_mov_b32 m0, s31
	v_lshl_add_u64 v[224:225], s[2:3], 0, v[132:133]
	global_load_lds_dwordx4 v[222:223], off
	v_lshl_add_u64 v[222:223], s[40:41], 0, v[130:131]
	s_mov_b32 m0, s34
	s_nop 0
	global_load_lds_dwordx4 v[222:223], off
	v_lshl_add_u64 v[222:223], s[2:3], 0, v[136:137]
	s_mov_b32 m0, s18
	s_nop 0
	global_load_lds_dwordx4 v[222:223], off
	s_mov_b32 m0, s1
	s_nop 0
	global_load_lds_dwordx4 v[224:225], off
	s_waitcnt vmcnt(8)
	s_waitcnt lgkmcnt(0)
	s_setprio 1
	s_barrier
	v_mfma_f32_16x16x32_bf16 v[62:65], v[152:155], v[186:189], v[62:65]
	v_mfma_f32_16x16x32_bf16 v[58:61], v[160:163], v[186:189], v[58:61]
	v_mfma_f32_16x16x32_bf16 v[50:53], v[152:155], v[194:197], v[50:53]
	v_mfma_f32_16x16x32_bf16 v[42:45], v[160:163], v[194:197], v[42:45]
	v_mfma_f32_16x16x32_bf16 v[34:37], v[152:155], v[202:205], v[34:37]
	v_mfma_f32_16x16x32_bf16 v[26:29], v[160:163], v[202:205], v[26:29]
	v_mfma_f32_16x16x32_bf16 v[18:21], v[152:155], v[210:213], v[18:21]
	v_mfma_f32_16x16x32_bf16 v[10:13], v[160:163], v[210:213], v[10:13]
	v_mfma_f32_16x16x32_bf16 v[62:65], v[156:159], v[190:193], v[62:65]
	v_mfma_f32_16x16x32_bf16 v[58:61], v[164:167], v[190:193], v[58:61]
	v_mfma_f32_16x16x32_bf16 v[50:53], v[156:159], v[198:201], v[50:53]
	v_mfma_f32_16x16x32_bf16 v[42:45], v[164:167], v[198:201], v[42:45]
	v_mfma_f32_16x16x32_bf16 v[34:37], v[156:159], v[206:209], v[34:37]
	v_mfma_f32_16x16x32_bf16 v[26:29], v[164:167], v[206:209], v[26:29]
	v_mfma_f32_16x16x32_bf16 v[18:21], v[156:159], v[214:217], v[18:21]
	v_mfma_f32_16x16x32_bf16 v[10:13], v[164:167], v[214:217], v[10:13]
	v_mfma_f32_16x16x32_bf16 v[54:57], v[168:171], v[186:189], v[54:57]
	v_mfma_f32_16x16x32_bf16 v[46:49], v[178:181], v[186:189], v[46:49]
	v_mfma_f32_16x16x32_bf16 v[38:41], v[168:171], v[194:197], v[38:41]
	v_mfma_f32_16x16x32_bf16 v[30:33], v[178:181], v[194:197], v[30:33]
	v_mfma_f32_16x16x32_bf16 v[22:25], v[168:171], v[202:205], v[22:25]
	v_mfma_f32_16x16x32_bf16 v[14:17], v[178:181], v[202:205], v[14:17]
	v_mfma_f32_16x16x32_bf16 v[6:9], v[168:171], v[210:213], v[6:9]
	v_mfma_f32_16x16x32_bf16 v[2:5], v[178:181], v[210:213], v[2:5]
	v_mfma_f32_16x16x32_bf16 v[54:57], v[172:175], v[190:193], v[54:57]
	v_mfma_f32_16x16x32_bf16 v[46:49], v[182:185], v[190:193], v[46:49]
	v_mfma_f32_16x16x32_bf16 v[38:41], v[172:175], v[198:201], v[38:41]
	v_mfma_f32_16x16x32_bf16 v[30:33], v[182:185], v[198:201], v[30:33]
	v_mfma_f32_16x16x32_bf16 v[22:25], v[172:175], v[206:209], v[22:25]
	v_mfma_f32_16x16x32_bf16 v[14:17], v[182:185], v[206:209], v[14:17]
	v_mfma_f32_16x16x32_bf16 v[6:9], v[172:175], v[214:217], v[6:9]
	s_setprio 0
	v_mfma_f32_16x16x32_bf16 v[2:5], v[182:185], v[214:217], v[2:5]
	s_barrier
	ds_read_b128 v[152:155], v149
	ds_read_b128 v[156:159], v149 offset:1024
	ds_read_b128 v[160:163], v149 offset:2048
	ds_read_b128 v[164:167], v149 offset:3072
	ds_read_b128 v[168:171], v150
	ds_read_b128 v[172:175], v150 offset:1024
	ds_read_b128 v[178:181], v150 offset:2048
	ds_read_b128 v[182:185], v150 offset:3072
	s_add_u32 s2, s2, 0x40000
	s_addc_u32 s3, s3, 0
	s_mov_b32 m0, s19
	v_lshl_add_u64 v[226:227], s[2:3], 0, v[136:137]
	ds_read_b128 v[186:189], v148 offset:32768
	ds_read_b128 v[190:193], v148 offset:33792
	ds_read_b128 v[194:197], v148 offset:34816
	ds_read_b128 v[198:201], v148 offset:35840
	ds_read_b128 v[202:205], v148 offset:36864
	ds_read_b128 v[206:209], v148 offset:37888
	ds_read_b128 v[210:213], v148 offset:38912
	ds_read_b128 v[214:217], v148 offset:39936
	global_load_lds_dwordx4 v[226:227], off
	v_lshl_add_u64 v[226:227], s[2:3], 0, v[132:133]
	s_mov_b32 m0, s20
	s_nop 0
	global_load_lds_dwordx4 v[226:227], off
	s_waitcnt vmcnt(8)
	s_waitcnt lgkmcnt(0)
	s_setprio 1
	s_barrier
	v_mfma_f32_16x16x32_bf16 v[126:129], v[152:155], v[186:189], v[126:129]
	v_mfma_f32_16x16x32_bf16 v[122:125], v[160:163], v[186:189], v[122:125]
	v_mfma_f32_16x16x32_bf16 v[114:117], v[152:155], v[194:197], v[114:117]
	v_mfma_f32_16x16x32_bf16 v[106:109], v[160:163], v[194:197], v[106:109]
	v_mfma_f32_16x16x32_bf16 v[98:101], v[152:155], v[202:205], v[98:101]
	v_mfma_f32_16x16x32_bf16 v[90:93], v[160:163], v[202:205], v[90:93]
	v_mfma_f32_16x16x32_bf16 v[82:85], v[152:155], v[210:213], v[82:85]
	v_mfma_f32_16x16x32_bf16 v[74:77], v[160:163], v[210:213], v[74:77]
	v_mfma_f32_16x16x32_bf16 v[126:129], v[156:159], v[190:193], v[126:129]
	v_mfma_f32_16x16x32_bf16 v[122:125], v[164:167], v[190:193], v[122:125]
	v_mfma_f32_16x16x32_bf16 v[114:117], v[156:159], v[198:201], v[114:117]
	v_mfma_f32_16x16x32_bf16 v[106:109], v[164:167], v[198:201], v[106:109]
	v_mfma_f32_16x16x32_bf16 v[98:101], v[156:159], v[206:209], v[98:101]
	v_mfma_f32_16x16x32_bf16 v[90:93], v[164:167], v[206:209], v[90:93]
	v_mfma_f32_16x16x32_bf16 v[82:85], v[156:159], v[214:217], v[82:85]
	v_mfma_f32_16x16x32_bf16 v[74:77], v[164:167], v[214:217], v[74:77]
	v_mfma_f32_16x16x32_bf16 v[118:121], v[168:171], v[186:189], v[118:121]
	v_mfma_f32_16x16x32_bf16 v[110:113], v[178:181], v[186:189], v[110:113]
	v_mfma_f32_16x16x32_bf16 v[102:105], v[168:171], v[194:197], v[102:105]
	v_mfma_f32_16x16x32_bf16 v[94:97], v[178:181], v[194:197], v[94:97]
	v_mfma_f32_16x16x32_bf16 v[86:89], v[168:171], v[202:205], v[86:89]
	v_mfma_f32_16x16x32_bf16 v[78:81], v[178:181], v[202:205], v[78:81]
	v_mfma_f32_16x16x32_bf16 v[70:73], v[168:171], v[210:213], v[70:73]
	v_mfma_f32_16x16x32_bf16 v[66:69], v[178:181], v[210:213], v[66:69]
	v_mfma_f32_16x16x32_bf16 v[118:121], v[172:175], v[190:193], v[118:121]
	v_mfma_f32_16x16x32_bf16 v[110:113], v[182:185], v[190:193], v[110:113]
	v_mfma_f32_16x16x32_bf16 v[102:105], v[172:175], v[198:201], v[102:105]
	v_mfma_f32_16x16x32_bf16 v[94:97], v[182:185], v[198:201], v[94:97]
	v_mfma_f32_16x16x32_bf16 v[86:89], v[172:175], v[206:209], v[86:89]
	v_mfma_f32_16x16x32_bf16 v[78:81], v[182:185], v[206:209], v[78:81]
	v_mfma_f32_16x16x32_bf16 v[70:73], v[172:175], v[214:217], v[70:73]
	s_setprio 0
	v_mfma_f32_16x16x32_bf16 v[66:69], v[182:185], v[214:217], v[66:69]
	s_barrier
	s_mov_b32 m0, s35
	v_lshl_add_u64 v[218:219], v[218:219], 0, s[8:9]
	s_add_u32 s2, s14, 0x40080
	ds_read_b128 v[186:189], v148 offset:49152
	ds_read_b128 v[190:193], v148 offset:50176
	ds_read_b128 v[194:197], v148 offset:51200
	ds_read_b128 v[198:201], v148 offset:52224
	ds_read_b128 v[202:205], v148 offset:53248
	ds_read_b128 v[206:209], v148 offset:54272
	ds_read_b128 v[210:213], v148 offset:55296
	ds_read_b128 v[214:217], v148 offset:56320
	global_load_lds_dwordx4 v[218:219], off
	v_lshl_add_u64 v[218:219], v[220:221], 0, s[8:9]
	s_mov_b32 m0, s36
	s_addc_u32 s3, s15, 0
	global_load_lds_dwordx4 v[218:219], off
	v_lshl_add_u64 v[218:219], s[2:3], 0, v[134:135]
	s_mov_b32 m0, s37
	s_nop 0
	global_load_lds_dwordx4 v[218:219], off
	v_lshl_add_u64 v[218:219], s[2:3], 0, v[130:131]
	s_mov_b32 m0, s38
	s_nop 0
	global_load_lds_dwordx4 v[218:219], off
	v_lshl_add_u64 v[218:219], v[222:223], 0, s[8:9]
	s_mov_b32 m0, s22
	s_nop 0
	global_load_lds_dwordx4 v[218:219], off
	v_lshl_add_u64 v[218:219], v[224:225], 0, s[8:9]
	s_mov_b32 m0, s23
	s_nop 0
	global_load_lds_dwordx4 v[218:219], off
	s_waitcnt vmcnt(8)
	s_waitcnt lgkmcnt(0)
	s_setprio 1
	s_barrier
	v_mfma_f32_16x16x32_bf16 v[62:65], v[152:155], v[186:189], v[62:65]
	v_mfma_f32_16x16x32_bf16 v[58:61], v[160:163], v[186:189], v[58:61]
	v_mfma_f32_16x16x32_bf16 v[50:53], v[152:155], v[194:197], v[50:53]
	v_mfma_f32_16x16x32_bf16 v[42:45], v[160:163], v[194:197], v[42:45]
	v_mfma_f32_16x16x32_bf16 v[34:37], v[152:155], v[202:205], v[34:37]
	v_mfma_f32_16x16x32_bf16 v[26:29], v[160:163], v[202:205], v[26:29]
	v_mfma_f32_16x16x32_bf16 v[18:21], v[152:155], v[210:213], v[18:21]
	v_mfma_f32_16x16x32_bf16 v[10:13], v[160:163], v[210:213], v[10:13]
	v_mfma_f32_16x16x32_bf16 v[62:65], v[156:159], v[190:193], v[62:65]
	v_mfma_f32_16x16x32_bf16 v[58:61], v[164:167], v[190:193], v[58:61]
	v_mfma_f32_16x16x32_bf16 v[50:53], v[156:159], v[198:201], v[50:53]
	v_mfma_f32_16x16x32_bf16 v[42:45], v[164:167], v[198:201], v[42:45]
	v_mfma_f32_16x16x32_bf16 v[34:37], v[156:159], v[206:209], v[34:37]
	v_mfma_f32_16x16x32_bf16 v[26:29], v[164:167], v[206:209], v[26:29]
	v_mfma_f32_16x16x32_bf16 v[18:21], v[156:159], v[214:217], v[18:21]
	v_mfma_f32_16x16x32_bf16 v[10:13], v[164:167], v[214:217], v[10:13]
	v_mfma_f32_16x16x32_bf16 v[54:57], v[168:171], v[186:189], v[54:57]
	v_mfma_f32_16x16x32_bf16 v[46:49], v[178:181], v[186:189], v[46:49]
	v_mfma_f32_16x16x32_bf16 v[38:41], v[168:171], v[194:197], v[38:41]
	v_mfma_f32_16x16x32_bf16 v[30:33], v[178:181], v[194:197], v[30:33]
	v_mfma_f32_16x16x32_bf16 v[22:25], v[168:171], v[202:205], v[22:25]
	v_mfma_f32_16x16x32_bf16 v[14:17], v[178:181], v[202:205], v[14:17]
	v_mfma_f32_16x16x32_bf16 v[6:9], v[168:171], v[210:213], v[6:9]
	v_mfma_f32_16x16x32_bf16 v[2:5], v[178:181], v[210:213], v[2:5]
	v_mfma_f32_16x16x32_bf16 v[54:57], v[172:175], v[190:193], v[54:57]
	v_mfma_f32_16x16x32_bf16 v[46:49], v[182:185], v[190:193], v[46:49]
	v_mfma_f32_16x16x32_bf16 v[38:41], v[172:175], v[198:201], v[38:41]
	v_mfma_f32_16x16x32_bf16 v[30:33], v[182:185], v[198:201], v[30:33]
	v_mfma_f32_16x16x32_bf16 v[22:25], v[172:175], v[206:209], v[22:25]
	v_mfma_f32_16x16x32_bf16 v[14:17], v[182:185], v[206:209], v[14:17]
	v_mfma_f32_16x16x32_bf16 v[6:9], v[172:175], v[214:217], v[6:9]
	s_setprio 0
	v_mfma_f32_16x16x32_bf16 v[2:5], v[182:185], v[214:217], v[2:5]
	s_barrier
	s_add_i32 s26, s26, 2
	s_add_u32 s12, s12, 0x100
	s_addc_u32 s13, s13, 0
	s_cmp_gt_u32 s26, 13
	s_cbranch_scc0 .LBB0_646
	s_cmpk_lt_u32 s16, 0x100
	s_mov_b32 s28, s33
	v_readlane_b32 s30, v253, 58
	s_cbranch_scc0 .LBB0_649
	s_barrier

.Lpk1098_peel:
	ds_read_b128 v[152:155], v148
	ds_read_b128 v[156:159], v148 offset:1024
	ds_read_b128 v[160:163], v148 offset:2048
	ds_read_b128 v[164:167], v148 offset:3072
	ds_read_b128 v[168:171], v149
	ds_read_b128 v[172:175], v149 offset:1024
	ds_read_b128 v[178:181], v149 offset:2048
	ds_read_b128 v[182:185], v149 offset:3072
	s_add_u32 s2, s30, 0xfffc0080
	s_addc_u32 s3, s31, -1
	s_cmp_eq_u32 s56, 12
	s_cselect_b32 s3, s15, s3
	s_cselect_b32 s2, s17, s2
	s_cselect_b32 s35, s52, s55
	s_cselect_b32 s34, s53, s54
	v_lshl_add_u64 v[144:145], s[30:31], 0, v[138:139]
	s_add_i32 m0, s40, 0xc000
	ds_read_b128 v[186:189], v150
	ds_read_b128 v[190:193], v150 offset:1024
	ds_read_b128 v[194:197], v150 offset:2048
	ds_read_b128 v[198:201], v150 offset:3072
	ds_read_b128 v[202:205], v150 offset:4096
	ds_read_b128 v[206:209], v150 offset:5120
	ds_read_b128 v[210:213], v150 offset:6144
	ds_read_b128 v[214:217], v150 offset:7168
	global_load_lds_dwordx4 v[144:145], off
	v_lshl_add_u64 v[144:145], s[30:31], 0, v[140:141]
	s_add_i32 m0, s40, 0xe000
	s_nop 0
	global_load_lds_dwordx4 v[144:145], off
	s_waitcnt vmcnt(8)
	s_waitcnt lgkmcnt(0)
	s_setprio 1
	s_barrier
	v_mfma_f32_16x16x32_bf16 v[126:129], v[152:155], v[186:189], 0
	v_mfma_f32_16x16x32_bf16 v[122:125], v[160:163], v[186:189], 0
	v_mfma_f32_16x16x32_bf16 v[114:117], v[152:155], v[194:197], 0
	v_mfma_f32_16x16x32_bf16 v[106:109], v[160:163], v[194:197], 0
	v_mfma_f32_16x16x32_bf16 v[98:101], v[152:155], v[202:205], 0
	v_mfma_f32_16x16x32_bf16 v[90:93], v[160:163], v[202:205], 0
	v_mfma_f32_16x16x32_bf16 v[82:85], v[152:155], v[210:213], 0
	v_mfma_f32_16x16x32_bf16 v[74:77], v[160:163], v[210:213], 0
	v_mfma_f32_16x16x32_bf16 v[126:129], v[156:159], v[190:193], v[126:129]
	v_mfma_f32_16x16x32_bf16 v[122:125], v[164:167], v[190:193], v[122:125]
	v_mfma_f32_16x16x32_bf16 v[114:117], v[156:159], v[198:201], v[114:117]
	v_mfma_f32_16x16x32_bf16 v[106:109], v[164:167], v[198:201], v[106:109]
	v_mfma_f32_16x16x32_bf16 v[98:101], v[156:159], v[206:209], v[98:101]
	v_mfma_f32_16x16x32_bf16 v[90:93], v[164:167], v[206:209], v[90:93]
	v_mfma_f32_16x16x32_bf16 v[82:85], v[156:159], v[214:217], v[82:85]
	v_mfma_f32_16x16x32_bf16 v[74:77], v[164:167], v[214:217], v[74:77]
	v_mfma_f32_16x16x32_bf16 v[118:121], v[168:171], v[186:189], 0
	v_mfma_f32_16x16x32_bf16 v[110:113], v[178:181], v[186:189], 0
	v_mfma_f32_16x16x32_bf16 v[102:105], v[168:171], v[194:197], 0
	v_mfma_f32_16x16x32_bf16 v[94:97], v[178:181], v[194:197], 0
	v_mfma_f32_16x16x32_bf16 v[86:89], v[168:171], v[202:205], 0
	v_mfma_f32_16x16x32_bf16 v[78:81], v[178:181], v[202:205], 0
	v_mfma_f32_16x16x32_bf16 v[70:73], v[168:171], v[210:213], 0
	v_mfma_f32_16x16x32_bf16 v[66:69], v[178:181], v[210:213], 0
	v_mfma_f32_16x16x32_bf16 v[118:121], v[172:175], v[190:193], v[118:121]
	v_mfma_f32_16x16x32_bf16 v[110:113], v[182:185], v[190:193], v[110:113]
	v_mfma_f32_16x16x32_bf16 v[102:105], v[172:175], v[198:201], v[102:105]
	v_mfma_f32_16x16x32_bf16 v[94:97], v[182:185], v[198:201], v[94:97]
	v_mfma_f32_16x16x32_bf16 v[86:89], v[172:175], v[206:209], v[86:89]
	v_mfma_f32_16x16x32_bf16 v[78:81], v[182:185], v[206:209], v[78:81]
	v_mfma_f32_16x16x32_bf16 v[70:73], v[172:175], v[214:217], v[70:73]
	s_setprio 0
	v_mfma_f32_16x16x32_bf16 v[66:69], v[182:185], v[214:217], v[66:69]
	s_barrier
	s_add_i32 s57, s47, s39
	v_lshl_add_u64 v[144:145], s[34:35], 0, v[132:133]
	s_mov_b32 m0, s57
	ds_read_b128 v[186:189], v150 offset:16384
	ds_read_b128 v[190:193], v150 offset:17408
	ds_read_b128 v[194:197], v150 offset:18432
	ds_read_b128 v[198:201], v150 offset:19456
	ds_read_b128 v[202:205], v150 offset:20480
	ds_read_b128 v[206:209], v150 offset:21504
	ds_read_b128 v[210:213], v150 offset:22528
	ds_read_b128 v[214:217], v150 offset:23552
	global_load_lds_dwordx4 v[144:145], off
	s_add_i32 m0, s57, 0x2000
	s_add_u32 s58, s34, 0x40000
	v_lshl_add_u64 v[218:219], s[34:35], 0, v[136:137]
	s_addc_u32 s59, s35, 0
	s_add_i32 s57, s48, s39
	global_load_lds_dwordx4 v[218:219], off
	v_lshl_add_u64 v[220:221], s[58:59], 0, v[132:133]
	s_mov_b32 m0, s57
	v_lshl_add_u64 v[222:223], s[2:3], 0, v[134:135]
	global_load_lds_dwordx4 v[220:221], off
	v_lshl_add_u64 v[220:221], s[58:59], 0, v[136:137]
	s_add_i32 m0, s57, 0x2000
	s_nop 0
	global_load_lds_dwordx4 v[220:221], off
	v_lshl_add_u64 v[220:221], s[2:3], 0, v[130:131]
	s_mov_b32 m0, s40
	s_nop 0
	global_load_lds_dwordx4 v[220:221], off
	s_mov_b32 m0, s29
	s_nop 0
	global_load_lds_dwordx4 v[222:223], off
	s_waitcnt vmcnt(8)
	s_waitcnt lgkmcnt(0)
	s_setprio 1
	s_barrier
	v_mfma_f32_16x16x32_bf16 v[62:65], v[152:155], v[186:189], 0
	v_mfma_f32_16x16x32_bf16 v[58:61], v[160:163], v[186:189], 0
	v_mfma_f32_16x16x32_bf16 v[50:53], v[152:155], v[194:197], 0
	v_mfma_f32_16x16x32_bf16 v[42:45], v[160:163], v[194:197], 0
	v_mfma_f32_16x16x32_bf16 v[34:37], v[152:155], v[202:205], 0
	v_mfma_f32_16x16x32_bf16 v[26:29], v[160:163], v[202:205], 0
	v_mfma_f32_16x16x32_bf16 v[18:21], v[152:155], v[210:213], 0
	v_mfma_f32_16x16x32_bf16 v[10:13], v[160:163], v[210:213], 0
	v_mfma_f32_16x16x32_bf16 v[62:65], v[156:159], v[190:193], v[62:65]
	v_mfma_f32_16x16x32_bf16 v[58:61], v[164:167], v[190:193], v[58:61]
	v_mfma_f32_16x16x32_bf16 v[50:53], v[156:159], v[198:201], v[50:53]
	v_mfma_f32_16x16x32_bf16 v[42:45], v[164:167], v[198:201], v[42:45]
	v_mfma_f32_16x16x32_bf16 v[34:37], v[156:159], v[206:209], v[34:37]
	v_mfma_f32_16x16x32_bf16 v[26:29], v[164:167], v[206:209], v[26:29]
	v_mfma_f32_16x16x32_bf16 v[18:21], v[156:159], v[214:217], v[18:21]
	v_mfma_f32_16x16x32_bf16 v[10:13], v[164:167], v[214:217], v[10:13]
	v_mfma_f32_16x16x32_bf16 v[54:57], v[168:171], v[186:189], 0
	v_mfma_f32_16x16x32_bf16 v[46:49], v[178:181], v[186:189], 0
	v_mfma_f32_16x16x32_bf16 v[38:41], v[168:171], v[194:197], 0
	v_mfma_f32_16x16x32_bf16 v[30:33], v[178:181], v[194:197], 0
	v_mfma_f32_16x16x32_bf16 v[22:25], v[168:171], v[202:205], 0
	v_mfma_f32_16x16x32_bf16 v[14:17], v[178:181], v[202:205], 0
	v_mfma_f32_16x16x32_bf16 v[6:9], v[168:171], v[210:213], 0
	v_mfma_f32_16x16x32_bf16 v[2:5], v[178:181], v[210:213], 0
	v_mfma_f32_16x16x32_bf16 v[54:57], v[172:175], v[190:193], v[54:57]
	v_mfma_f32_16x16x32_bf16 v[46:49], v[182:185], v[190:193], v[46:49]
	v_mfma_f32_16x16x32_bf16 v[38:41], v[172:175], v[198:201], v[38:41]
	v_mfma_f32_16x16x32_bf16 v[30:33], v[182:185], v[198:201], v[30:33]
	v_mfma_f32_16x16x32_bf16 v[22:25], v[172:175], v[206:209], v[22:25]
	v_mfma_f32_16x16x32_bf16 v[14:17], v[182:185], v[206:209], v[14:17]
	v_mfma_f32_16x16x32_bf16 v[6:9], v[172:175], v[214:217], v[6:9]
	s_setprio 0
	v_mfma_f32_16x16x32_bf16 v[2:5], v[182:185], v[214:217], v[2:5]
	s_barrier
	s_add_i32 s57, 0, 0x18000
	v_add_u32_e32 v151, s57, v146
	s_add_i32 s58, 0, 0x1c000
	ds_read_b128 v[152:155], v151
	ds_read_b128 v[156:159], v151 offset:1024
	ds_read_b128 v[160:163], v151 offset:2048
	ds_read_b128 v[164:167], v151 offset:3072
	v_add_u32_e32 v151, s58, v146
	ds_read_b128 v[168:171], v151
	ds_read_b128 v[172:175], v151 offset:1024
	ds_read_b128 v[178:181], v151 offset:2048
	ds_read_b128 v[182:185], v151 offset:3072
	s_add_u32 s2, s2, 0x40000
	s_addc_u32 s3, s3, 0
	s_mov_b32 m0, s41
	v_lshl_add_u64 v[224:225], s[2:3], 0, v[130:131]
	ds_read_b128 v[186:189], v150 offset:32768
	ds_read_b128 v[190:193], v150 offset:33792
	ds_read_b128 v[194:197], v150 offset:34816
	ds_read_b128 v[198:201], v150 offset:35840
	ds_read_b128 v[202:205], v150 offset:36864
	ds_read_b128 v[206:209], v150 offset:37888
	ds_read_b128 v[210:213], v150 offset:38912
	ds_read_b128 v[214:217], v150 offset:39936
	global_load_lds_dwordx4 v[224:225], off
	v_lshl_add_u64 v[224:225], s[2:3], 0, v[134:135]
	s_mov_b32 m0, s42
	s_nop 0
	global_load_lds_dwordx4 v[224:225], off
	s_waitcnt vmcnt(8)
	s_waitcnt lgkmcnt(0)
	s_setprio 1
	s_barrier
	v_mfma_f32_16x16x32_bf16 v[126:129], v[152:155], v[186:189], v[126:129]
	v_mfma_f32_16x16x32_bf16 v[122:125], v[160:163], v[186:189], v[122:125]
	v_mfma_f32_16x16x32_bf16 v[114:117], v[152:155], v[194:197], v[114:117]
	v_mfma_f32_16x16x32_bf16 v[106:109], v[160:163], v[194:197], v[106:109]
	v_mfma_f32_16x16x32_bf16 v[98:101], v[152:155], v[202:205], v[98:101]
	v_mfma_f32_16x16x32_bf16 v[90:93], v[160:163], v[202:205], v[90:93]
	v_mfma_f32_16x16x32_bf16 v[82:85], v[152:155], v[210:213], v[82:85]
	v_mfma_f32_16x16x32_bf16 v[74:77], v[160:163], v[210:213], v[74:77]
	v_mfma_f32_16x16x32_bf16 v[126:129], v[156:159], v[190:193], v[126:129]
	v_mfma_f32_16x16x32_bf16 v[122:125], v[164:167], v[190:193], v[122:125]
	v_mfma_f32_16x16x32_bf16 v[114:117], v[156:159], v[198:201], v[114:117]
	v_mfma_f32_16x16x32_bf16 v[106:109], v[164:167], v[198:201], v[106:109]
	v_mfma_f32_16x16x32_bf16 v[98:101], v[156:159], v[206:209], v[98:101]
	v_mfma_f32_16x16x32_bf16 v[90:93], v[164:167], v[206:209], v[90:93]
	v_mfma_f32_16x16x32_bf16 v[82:85], v[156:159], v[214:217], v[82:85]
	v_mfma_f32_16x16x32_bf16 v[74:77], v[164:167], v[214:217], v[74:77]
	v_mfma_f32_16x16x32_bf16 v[118:121], v[168:171], v[186:189], v[118:121]
	v_mfma_f32_16x16x32_bf16 v[110:113], v[178:181], v[186:189], v[110:113]
	v_mfma_f32_16x16x32_bf16 v[102:105], v[168:171], v[194:197], v[102:105]
	v_mfma_f32_16x16x32_bf16 v[94:97], v[178:181], v[194:197], v[94:97]
	v_mfma_f32_16x16x32_bf16 v[86:89], v[168:171], v[202:205], v[86:89]
	v_mfma_f32_16x16x32_bf16 v[78:81], v[178:181], v[202:205], v[78:81]
	v_mfma_f32_16x16x32_bf16 v[70:73], v[168:171], v[210:213], v[70:73]
	v_mfma_f32_16x16x32_bf16 v[66:69], v[178:181], v[210:213], v[66:69]
	v_mfma_f32_16x16x32_bf16 v[118:121], v[172:175], v[190:193], v[118:121]
	v_mfma_f32_16x16x32_bf16 v[110:113], v[182:185], v[190:193], v[110:113]
	v_mfma_f32_16x16x32_bf16 v[102:105], v[172:175], v[198:201], v[102:105]
	v_mfma_f32_16x16x32_bf16 v[94:97], v[182:185], v[198:201], v[94:97]
	v_mfma_f32_16x16x32_bf16 v[86:89], v[172:175], v[206:209], v[86:89]
	v_mfma_f32_16x16x32_bf16 v[78:81], v[182:185], v[206:209], v[78:81]
	v_mfma_f32_16x16x32_bf16 v[70:73], v[172:175], v[214:217], v[70:73]
	s_setprio 0
	v_mfma_f32_16x16x32_bf16 v[66:69], v[182:185], v[214:217], v[66:69]
	s_barrier
	s_add_i32 s2, s57, s39
	v_lshl_add_u64 v[144:145], v[144:145], 0, s[6:7]
	s_mov_b32 m0, s2
	ds_read_b128 v[186:189], v150 offset:49152
	ds_read_b128 v[190:193], v150 offset:50176
	ds_read_b128 v[194:197], v150 offset:51200
	ds_read_b128 v[198:201], v150 offset:52224
	ds_read_b128 v[202:205], v150 offset:53248
	ds_read_b128 v[206:209], v150 offset:54272
	ds_read_b128 v[210:213], v150 offset:55296
	ds_read_b128 v[214:217], v150 offset:56320
	global_load_lds_dwordx4 v[144:145], off
	s_add_i32 m0, s2, 0x2000
	s_add_u32 s2, s34, 0x40080
	v_lshl_add_u64 v[144:145], v[218:219], 0, s[6:7]
	s_addc_u32 s3, s35, 0
	s_add_i32 s34, s58, s39
	global_load_lds_dwordx4 v[144:145], off
	v_lshl_add_u64 v[144:145], s[2:3], 0, v[132:133]
	s_mov_b32 m0, s34
	s_nop 0
	global_load_lds_dwordx4 v[144:145], off
	v_lshl_add_u64 v[144:145], s[2:3], 0, v[136:137]
	s_add_i32 m0, s34, 0x2000
	s_nop 0
	global_load_lds_dwordx4 v[144:145], off
	v_lshl_add_u64 v[144:145], v[220:221], 0, s[6:7]
	s_mov_b32 m0, s44
	s_nop 0
	global_load_lds_dwordx4 v[144:145], off
	v_lshl_add_u64 v[144:145], v[222:223], 0, s[6:7]
	s_mov_b32 m0, s45
	s_nop 0
	global_load_lds_dwordx4 v[144:145], off
	s_waitcnt vmcnt(8)
	s_waitcnt lgkmcnt(0)
	s_setprio 1
	s_barrier
	v_mfma_f32_16x16x32_bf16 v[62:65], v[152:155], v[186:189], v[62:65]
	v_mfma_f32_16x16x32_bf16 v[58:61], v[160:163], v[186:189], v[58:61]
	v_mfma_f32_16x16x32_bf16 v[50:53], v[152:155], v[194:197], v[50:53]
	v_mfma_f32_16x16x32_bf16 v[42:45], v[160:163], v[194:197], v[42:45]
	v_mfma_f32_16x16x32_bf16 v[34:37], v[152:155], v[202:205], v[34:37]
	v_mfma_f32_16x16x32_bf16 v[26:29], v[160:163], v[202:205], v[26:29]
	v_mfma_f32_16x16x32_bf16 v[18:21], v[152:155], v[210:213], v[18:21]
	v_mfma_f32_16x16x32_bf16 v[10:13], v[160:163], v[210:213], v[10:13]
	v_mfma_f32_16x16x32_bf16 v[62:65], v[156:159], v[190:193], v[62:65]
	v_mfma_f32_16x16x32_bf16 v[58:61], v[164:167], v[190:193], v[58:61]
	v_mfma_f32_16x16x32_bf16 v[50:53], v[156:159], v[198:201], v[50:53]
	v_mfma_f32_16x16x32_bf16 v[42:45], v[164:167], v[198:201], v[42:45]
	v_mfma_f32_16x16x32_bf16 v[34:37], v[156:159], v[206:209], v[34:37]
	v_mfma_f32_16x16x32_bf16 v[26:29], v[164:167], v[206:209], v[26:29]
	v_mfma_f32_16x16x32_bf16 v[18:21], v[156:159], v[214:217], v[18:21]
	v_mfma_f32_16x16x32_bf16 v[10:13], v[164:167], v[214:217], v[10:13]
	v_mfma_f32_16x16x32_bf16 v[54:57], v[168:171], v[186:189], v[54:57]
	v_mfma_f32_16x16x32_bf16 v[46:49], v[178:181], v[186:189], v[46:49]
	v_mfma_f32_16x16x32_bf16 v[38:41], v[168:171], v[194:197], v[38:41]
	v_mfma_f32_16x16x32_bf16 v[30:33], v[178:181], v[194:197], v[30:33]
	v_mfma_f32_16x16x32_bf16 v[22:25], v[168:171], v[202:205], v[22:25]
	v_mfma_f32_16x16x32_bf16 v[14:17], v[178:181], v[202:205], v[14:17]
	v_mfma_f32_16x16x32_bf16 v[6:9], v[168:171], v[210:213], v[6:9]
	v_mfma_f32_16x16x32_bf16 v[2:5], v[178:181], v[210:213], v[2:5]
	v_mfma_f32_16x16x32_bf16 v[54:57], v[172:175], v[190:193], v[54:57]
	v_mfma_f32_16x16x32_bf16 v[46:49], v[182:185], v[190:193], v[46:49]
	v_mfma_f32_16x16x32_bf16 v[38:41], v[172:175], v[198:201], v[38:41]
	v_mfma_f32_16x16x32_bf16 v[30:33], v[182:185], v[198:201], v[30:33]
	v_mfma_f32_16x16x32_bf16 v[22:25], v[172:175], v[206:209], v[22:25]
	v_mfma_f32_16x16x32_bf16 v[14:17], v[182:185], v[206:209], v[14:17]
	v_mfma_f32_16x16x32_bf16 v[6:9], v[172:175], v[214:217], v[6:9]
	s_setprio 0
	v_mfma_f32_16x16x32_bf16 v[2:5], v[182:185], v[214:217], v[2:5]
	s_barrier
	s_add_i32 s56, s56, 2
	s_add_u32 s30, s30, 0x100
	s_addc_u32 s31, s31, 0
	s_add_u32 s54, s54, 0x100
	s_addc_u32 s55, s55, 0
	s_cmp_gt_u32 s56, 13
	s_cbranch_scc0 .LBB0_1098
	s_branch .Lpk1098_exit
.LBB0_1098:
	ds_read_b128 v[152:155], v148
	ds_read_b128 v[156:159], v148 offset:1024
	ds_read_b128 v[160:163], v148 offset:2048
	ds_read_b128 v[164:167], v148 offset:3072
	ds_read_b128 v[168:171], v149
	ds_read_b128 v[172:175], v149 offset:1024
	ds_read_b128 v[178:181], v149 offset:2048
	ds_read_b128 v[182:185], v149 offset:3072
	s_add_u32 s2, s30, 0xfffc0080
	s_addc_u32 s3, s31, -1
	s_cmp_eq_u32 s56, 12
	s_cselect_b32 s3, s15, s3
	s_cselect_b32 s2, s17, s2
	s_cselect_b32 s35, s52, s55
	s_cselect_b32 s34, s53, s54
	v_lshl_add_u64 v[144:145], s[30:31], 0, v[138:139]
	s_add_i32 m0, s40, 0xc000
	ds_read_b128 v[186:189], v150
	ds_read_b128 v[190:193], v150 offset:1024
	ds_read_b128 v[194:197], v150 offset:2048
	ds_read_b128 v[198:201], v150 offset:3072
	ds_read_b128 v[202:205], v150 offset:4096
	ds_read_b128 v[206:209], v150 offset:5120
	ds_read_b128 v[210:213], v150 offset:6144
	ds_read_b128 v[214:217], v150 offset:7168
	global_load_lds_dwordx4 v[144:145], off
	v_lshl_add_u64 v[144:145], s[30:31], 0, v[140:141]
	s_add_i32 m0, s40, 0xe000
	s_nop 0
	global_load_lds_dwordx4 v[144:145], off
	s_waitcnt vmcnt(8)
	s_waitcnt lgkmcnt(0)
	s_setprio 1
	s_barrier
	v_mfma_f32_16x16x32_bf16 v[126:129], v[152:155], v[186:189], v[126:129]
	v_mfma_f32_16x16x32_bf16 v[122:125], v[160:163], v[186:189], v[122:125]
	v_mfma_f32_16x16x32_bf16 v[114:117], v[152:155], v[194:197], v[114:117]
	v_mfma_f32_16x16x32_bf16 v[106:109], v[160:163], v[194:197], v[106:109]
	v_mfma_f32_16x16x32_bf16 v[98:101], v[152:155], v[202:205], v[98:101]
	v_mfma_f32_16x16x32_bf16 v[90:93], v[160:163], v[202:205], v[90:93]
	v_mfma_f32_16x16x32_bf16 v[82:85], v[152:155], v[210:213], v[82:85]
	v_mfma_f32_16x16x32_bf16 v[74:77], v[160:163], v[210:213], v[74:77]
	v_mfma_f32_16x16x32_bf16 v[126:129], v[156:159], v[190:193], v[126:129]
	v_mfma_f32_16x16x32_bf16 v[122:125], v[164:167], v[190:193], v[122:125]
	v_mfma_f32_16x16x32_bf16 v[114:117], v[156:159], v[198:201], v[114:117]
	v_mfma_f32_16x16x32_bf16 v[106:109], v[164:167], v[198:201], v[106:109]
	v_mfma_f32_16x16x32_bf16 v[98:101], v[156:159], v[206:209], v[98:101]
	v_mfma_f32_16x16x32_bf16 v[90:93], v[164:167], v[206:209], v[90:93]
	v_mfma_f32_16x16x32_bf16 v[82:85], v[156:159], v[214:217], v[82:85]
	v_mfma_f32_16x16x32_bf16 v[74:77], v[164:167], v[214:217], v[74:77]
	v_mfma_f32_16x16x32_bf16 v[118:121], v[168:171], v[186:189], v[118:121]
	v_mfma_f32_16x16x32_bf16 v[110:113], v[178:181], v[186:189], v[110:113]
	v_mfma_f32_16x16x32_bf16 v[102:105], v[168:171], v[194:197], v[102:105]
	v_mfma_f32_16x16x32_bf16 v[94:97], v[178:181], v[194:197], v[94:97]
	v_mfma_f32_16x16x32_bf16 v[86:89], v[168:171], v[202:205], v[86:89]
	v_mfma_f32_16x16x32_bf16 v[78:81], v[178:181], v[202:205], v[78:81]
	v_mfma_f32_16x16x32_bf16 v[70:73], v[168:171], v[210:213], v[70:73]
	v_mfma_f32_16x16x32_bf16 v[66:69], v[178:181], v[210:213], v[66:69]
	v_mfma_f32_16x16x32_bf16 v[118:121], v[172:175], v[190:193], v[118:121]
	v_mfma_f32_16x16x32_bf16 v[110:113], v[182:185], v[190:193], v[110:113]
	v_mfma_f32_16x16x32_bf16 v[102:105], v[172:175], v[198:201], v[102:105]
	v_mfma_f32_16x16x32_bf16 v[94:97], v[182:185], v[198:201], v[94:97]
	v_mfma_f32_16x16x32_bf16 v[86:89], v[172:175], v[206:209], v[86:89]
	v_mfma_f32_16x16x32_bf16 v[78:81], v[182:185], v[206:209], v[78:81]
	v_mfma_f32_16x16x32_bf16 v[70:73], v[172:175], v[214:217], v[70:73]
	s_setprio 0
	v_mfma_f32_16x16x32_bf16 v[66:69], v[182:185], v[214:217], v[66:69]
	s_barrier
	s_add_i32 s57, s47, s39
	v_lshl_add_u64 v[144:145], s[34:35], 0, v[132:133]
	s_mov_b32 m0, s57
	ds_read_b128 v[186:189], v150 offset:16384
	ds_read_b128 v[190:193], v150 offset:17408
	ds_read_b128 v[194:197], v150 offset:18432
	ds_read_b128 v[198:201], v150 offset:19456
	ds_read_b128 v[202:205], v150 offset:20480
	ds_read_b128 v[206:209], v150 offset:21504
	ds_read_b128 v[210:213], v150 offset:22528
	ds_read_b128 v[214:217], v150 offset:23552
	global_load_lds_dwordx4 v[144:145], off
	s_add_i32 m0, s57, 0x2000
	s_add_u32 s58, s34, 0x40000
	v_lshl_add_u64 v[218:219], s[34:35], 0, v[136:137]
	s_addc_u32 s59, s35, 0
	s_add_i32 s57, s48, s39
	global_load_lds_dwordx4 v[218:219], off
	v_lshl_add_u64 v[220:221], s[58:59], 0, v[132:133]
	s_mov_b32 m0, s57
	v_lshl_add_u64 v[222:223], s[2:3], 0, v[134:135]
	global_load_lds_dwordx4 v[220:221], off
	v_lshl_add_u64 v[220:221], s[58:59], 0, v[136:137]
	s_add_i32 m0, s57, 0x2000
	s_nop 0
	global_load_lds_dwordx4 v[220:221], off
	v_lshl_add_u64 v[220:221], s[2:3], 0, v[130:131]
	s_mov_b32 m0, s40
	s_nop 0
	global_load_lds_dwordx4 v[220:221], off
	s_mov_b32 m0, s29
	s_nop 0
	global_load_lds_dwordx4 v[222:223], off
	s_waitcnt vmcnt(8)
	s_waitcnt lgkmcnt(0)
	s_setprio 1
	s_barrier
	v_mfma_f32_16x16x32_bf16 v[62:65], v[152:155], v[186:189], v[62:65]
	v_mfma_f32_16x16x32_bf16 v[58:61], v[160:163], v[186:189], v[58:61]
	v_mfma_f32_16x16x32_bf16 v[50:53], v[152:155], v[194:197], v[50:53]
	v_mfma_f32_16x16x32_bf16 v[42:45], v[160:163], v[194:197], v[42:45]
	v_mfma_f32_16x16x32_bf16 v[34:37], v[152:155], v[202:205], v[34:37]
	v_mfma_f32_16x16x32_bf16 v[26:29], v[160:163], v[202:205], v[26:29]
	v_mfma_f32_16x16x32_bf16 v[18:21], v[152:155], v[210:213], v[18:21]
	v_mfma_f32_16x16x32_bf16 v[10:13], v[160:163], v[210:213], v[10:13]
	v_mfma_f32_16x16x32_bf16 v[62:65], v[156:159], v[190:193], v[62:65]
	v_mfma_f32_16x16x32_bf16 v[58:61], v[164:167], v[190:193], v[58:61]
	v_mfma_f32_16x16x32_bf16 v[50:53], v[156:159], v[198:201], v[50:53]
	v_mfma_f32_16x16x32_bf16 v[42:45], v[164:167], v[198:201], v[42:45]
	v_mfma_f32_16x16x32_bf16 v[34:37], v[156:159], v[206:209], v[34:37]
	v_mfma_f32_16x16x32_bf16 v[26:29], v[164:167], v[206:209], v[26:29]
	v_mfma_f32_16x16x32_bf16 v[18:21], v[156:159], v[214:217], v[18:21]
	v_mfma_f32_16x16x32_bf16 v[10:13], v[164:167], v[214:217], v[10:13]
	v_mfma_f32_16x16x32_bf16 v[54:57], v[168:171], v[186:189], v[54:57]
	v_mfma_f32_16x16x32_bf16 v[46:49], v[178:181], v[186:189], v[46:49]
	v_mfma_f32_16x16x32_bf16 v[38:41], v[168:171], v[194:197], v[38:41]
	v_mfma_f32_16x16x32_bf16 v[30:33], v[178:181], v[194:197], v[30:33]
	v_mfma_f32_16x16x32_bf16 v[22:25], v[168:171], v[202:205], v[22:25]
	v_mfma_f32_16x16x32_bf16 v[14:17], v[178:181], v[202:205], v[14:17]
	v_mfma_f32_16x16x32_bf16 v[6:9], v[168:171], v[210:213], v[6:9]
	v_mfma_f32_16x16x32_bf16 v[2:5], v[178:181], v[210:213], v[2:5]
	v_mfma_f32_16x16x32_bf16 v[54:57], v[172:175], v[190:193], v[54:57]
	v_mfma_f32_16x16x32_bf16 v[46:49], v[182:185], v[190:193], v[46:49]
	v_mfma_f32_16x16x32_bf16 v[38:41], v[172:175], v[198:201], v[38:41]
	v_mfma_f32_16x16x32_bf16 v[30:33], v[182:185], v[198:201], v[30:33]
	v_mfma_f32_16x16x32_bf16 v[22:25], v[172:175], v[206:209], v[22:25]
	v_mfma_f32_16x16x32_bf16 v[14:17], v[182:185], v[206:209], v[14:17]
	v_mfma_f32_16x16x32_bf16 v[6:9], v[172:175], v[214:217], v[6:9]
	s_setprio 0
	v_mfma_f32_16x16x32_bf16 v[2:5], v[182:185], v[214:217], v[2:5]
	s_barrier
	s_add_i32 s57, 0, 0x18000
	v_add_u32_e32 v151, s57, v146
	s_add_i32 s58, 0, 0x1c000
	ds_read_b128 v[152:155], v151
	ds_read_b128 v[156:159], v151 offset:1024
	ds_read_b128 v[160:163], v151 offset:2048
	ds_read_b128 v[164:167], v151 offset:3072
	v_add_u32_e32 v151, s58, v146
	ds_read_b128 v[168:171], v151
	ds_read_b128 v[172:175], v151 offset:1024
	ds_read_b128 v[178:181], v151 offset:2048
	ds_read_b128 v[182:185], v151 offset:3072
	s_add_u32 s2, s2, 0x40000
	s_addc_u32 s3, s3, 0
	s_mov_b32 m0, s41
	v_lshl_add_u64 v[224:225], s[2:3], 0, v[130:131]
	ds_read_b128 v[186:189], v150 offset:32768
	ds_read_b128 v[190:193], v150 offset:33792
	ds_read_b128 v[194:197], v150 offset:34816
	ds_read_b128 v[198:201], v150 offset:35840
	ds_read_b128 v[202:205], v150 offset:36864
	ds_read_b128 v[206:209], v150 offset:37888
	ds_read_b128 v[210:213], v150 offset:38912
	ds_read_b128 v[214:217], v150 offset:39936
	global_load_lds_dwordx4 v[224:225], off
	v_lshl_add_u64 v[224:225], s[2:3], 0, v[134:135]
	s_mov_b32 m0, s42
	s_nop 0
	global_load_lds_dwordx4 v[224:225], off
	s_waitcnt vmcnt(8)
	s_waitcnt lgkmcnt(0)
	s_setprio 1
	s_barrier
	v_mfma_f32_16x16x32_bf16 v[126:129], v[152:155], v[186:189], v[126:129]
	v_mfma_f32_16x16x32_bf16 v[122:125], v[160:163], v[186:189], v[122:125]
	v_mfma_f32_16x16x32_bf16 v[114:117], v[152:155], v[194:197], v[114:117]
	v_mfma_f32_16x16x32_bf16 v[106:109], v[160:163], v[194:197], v[106:109]
	v_mfma_f32_16x16x32_bf16 v[98:101], v[152:155], v[202:205], v[98:101]
	v_mfma_f32_16x16x32_bf16 v[90:93], v[160:163], v[202:205], v[90:93]
	v_mfma_f32_16x16x32_bf16 v[82:85], v[152:155], v[210:213], v[82:85]
	v_mfma_f32_16x16x32_bf16 v[74:77], v[160:163], v[210:213], v[74:77]
	v_mfma_f32_16x16x32_bf16 v[126:129], v[156:159], v[190:193], v[126:129]
	v_mfma_f32_16x16x32_bf16 v[122:125], v[164:167], v[190:193], v[122:125]
	v_mfma_f32_16x16x32_bf16 v[114:117], v[156:159], v[198:201], v[114:117]
	v_mfma_f32_16x16x32_bf16 v[106:109], v[164:167], v[198:201], v[106:109]
	v_mfma_f32_16x16x32_bf16 v[98:101], v[156:159], v[206:209], v[98:101]
	v_mfma_f32_16x16x32_bf16 v[90:93], v[164:167], v[206:209], v[90:93]
	v_mfma_f32_16x16x32_bf16 v[82:85], v[156:159], v[214:217], v[82:85]
	v_mfma_f32_16x16x32_bf16 v[74:77], v[164:167], v[214:217], v[74:77]
	v_mfma_f32_16x16x32_bf16 v[118:121], v[168:171], v[186:189], v[118:121]
	v_mfma_f32_16x16x32_bf16 v[110:113], v[178:181], v[186:189], v[110:113]
	v_mfma_f32_16x16x32_bf16 v[102:105], v[168:171], v[194:197], v[102:105]
	v_mfma_f32_16x16x32_bf16 v[94:97], v[178:181], v[194:197], v[94:97]
	v_mfma_f32_16x16x32_bf16 v[86:89], v[168:171], v[202:205], v[86:89]
	v_mfma_f32_16x16x32_bf16 v[78:81], v[178:181], v[202:205], v[78:81]
	v_mfma_f32_16x16x32_bf16 v[70:73], v[168:171], v[210:213], v[70:73]
	v_mfma_f32_16x16x32_bf16 v[66:69], v[178:181], v[210:213], v[66:69]
	v_mfma_f32_16x16x32_bf16 v[118:121], v[172:175], v[190:193], v[118:121]
	v_mfma_f32_16x16x32_bf16 v[110:113], v[182:185], v[190:193], v[110:113]
	v_mfma_f32_16x16x32_bf16 v[102:105], v[172:175], v[198:201], v[102:105]
	v_mfma_f32_16x16x32_bf16 v[94:97], v[182:185], v[198:201], v[94:97]
	v_mfma_f32_16x16x32_bf16 v[86:89], v[172:175], v[206:209], v[86:89]
	v_mfma_f32_16x16x32_bf16 v[78:81], v[182:185], v[206:209], v[78:81]
	v_mfma_f32_16x16x32_bf16 v[70:73], v[172:175], v[214:217], v[70:73]
	s_setprio 0
	v_mfma_f32_16x16x32_bf16 v[66:69], v[182:185], v[214:217], v[66:69]
	s_barrier
	s_add_i32 s2, s57, s39
	v_lshl_add_u64 v[144:145], v[144:145], 0, s[6:7]
	s_mov_b32 m0, s2
	ds_read_b128 v[186:189], v150 offset:49152
	ds_read_b128 v[190:193], v150 offset:50176
	ds_read_b128 v[194:197], v150 offset:51200
	ds_read_b128 v[198:201], v150 offset:52224
	ds_read_b128 v[202:205], v150 offset:53248
	ds_read_b128 v[206:209], v150 offset:54272
	ds_read_b128 v[210:213], v150 offset:55296
	ds_read_b128 v[214:217], v150 offset:56320
	global_load_lds_dwordx4 v[144:145], off
	s_add_i32 m0, s2, 0x2000
	s_add_u32 s2, s34, 0x40080
	v_lshl_add_u64 v[144:145], v[218:219], 0, s[6:7]
	s_addc_u32 s3, s35, 0
	s_add_i32 s34, s58, s39
	global_load_lds_dwordx4 v[144:145], off
	v_lshl_add_u64 v[144:145], s[2:3], 0, v[132:133]
	s_mov_b32 m0, s34
	s_nop 0
	global_load_lds_dwordx4 v[144:145], off
	v_lshl_add_u64 v[144:145], s[2:3], 0, v[136:137]
	s_add_i32 m0, s34, 0x2000
	s_nop 0
	global_load_lds_dwordx4 v[144:145], off
	v_lshl_add_u64 v[144:145], v[220:221], 0, s[6:7]
	s_mov_b32 m0, s44
	s_nop 0
	global_load_lds_dwordx4 v[144:145], off
	v_lshl_add_u64 v[144:145], v[222:223], 0, s[6:7]
	s_mov_b32 m0, s45
	s_nop 0
	global_load_lds_dwordx4 v[144:145], off
	s_waitcnt vmcnt(8)
	s_waitcnt lgkmcnt(0)
	s_setprio 1
	s_barrier
	v_mfma_f32_16x16x32_bf16 v[62:65], v[152:155], v[186:189], v[62:65]
	v_mfma_f32_16x16x32_bf16 v[58:61], v[160:163], v[186:189], v[58:61]
	v_mfma_f32_16x16x32_bf16 v[50:53], v[152:155], v[194:197], v[50:53]
	v_mfma_f32_16x16x32_bf16 v[42:45], v[160:163], v[194:197], v[42:45]
	v_mfma_f32_16x16x32_bf16 v[34:37], v[152:155], v[202:205], v[34:37]
	v_mfma_f32_16x16x32_bf16 v[26:29], v[160:163], v[202:205], v[26:29]
	v_mfma_f32_16x16x32_bf16 v[18:21], v[152:155], v[210:213], v[18:21]
	v_mfma_f32_16x16x32_bf16 v[10:13], v[160:163], v[210:213], v[10:13]
	v_mfma_f32_16x16x32_bf16 v[62:65], v[156:159], v[190:193], v[62:65]
	v_mfma_f32_16x16x32_bf16 v[58:61], v[164:167], v[190:193], v[58:61]
	v_mfma_f32_16x16x32_bf16 v[50:53], v[156:159], v[198:201], v[50:53]
	v_mfma_f32_16x16x32_bf16 v[42:45], v[164:167], v[198:201], v[42:45]
	v_mfma_f32_16x16x32_bf16 v[34:37], v[156:159], v[206:209], v[34:37]
	v_mfma_f32_16x16x32_bf16 v[26:29], v[164:167], v[206:209], v[26:29]
	v_mfma_f32_16x16x32_bf16 v[18:21], v[156:159], v[214:217], v[18:21]
	v_mfma_f32_16x16x32_bf16 v[10:13], v[164:167], v[214:217], v[10:13]
	v_mfma_f32_16x16x32_bf16 v[54:57], v[168:171], v[186:189], v[54:57]
	v_mfma_f32_16x16x32_bf16 v[46:49], v[178:181], v[186:189], v[46:49]
	v_mfma_f32_16x16x32_bf16 v[38:41], v[168:171], v[194:197], v[38:41]
	v_mfma_f32_16x16x32_bf16 v[30:33], v[178:181], v[194:197], v[30:33]
	v_mfma_f32_16x16x32_bf16 v[22:25], v[168:171], v[202:205], v[22:25]
	v_mfma_f32_16x16x32_bf16 v[14:17], v[178:181], v[202:205], v[14:17]
	v_mfma_f32_16x16x32_bf16 v[6:9], v[168:171], v[210:213], v[6:9]
	v_mfma_f32_16x16x32_bf16 v[2:5], v[178:181], v[210:213], v[2:5]
	v_mfma_f32_16x16x32_bf16 v[54:57], v[172:175], v[190:193], v[54:57]
	v_mfma_f32_16x16x32_bf16 v[46:49], v[182:185], v[190:193], v[46:49]
	v_mfma_f32_16x16x32_bf16 v[38:41], v[172:175], v[198:201], v[38:41]
	v_mfma_f32_16x16x32_bf16 v[30:33], v[182:185], v[198:201], v[30:33]
	v_mfma_f32_16x16x32_bf16 v[22:25], v[172:175], v[206:209], v[22:25]
	v_mfma_f32_16x16x32_bf16 v[14:17], v[182:185], v[206:209], v[14:17]
	v_mfma_f32_16x16x32_bf16 v[6:9], v[172:175], v[214:217], v[6:9]
	s_setprio 0
	v_mfma_f32_16x16x32_bf16 v[2:5], v[182:185], v[214:217], v[2:5]
	s_barrier
	s_add_i32 s56, s56, 2
	s_add_u32 s30, s30, 0x100
	s_addc_u32 s31, s31, 0
	s_add_u32 s54, s54, 0x100
	s_addc_u32 s55, s55, 0
	s_cmp_gt_u32 s56, 13
	s_cbranch_scc0 .LBB0_1098

.LBB0_1137:
	s_add_i32 s26, 0, 0x18000
	s_add_i32 s3, s26, s18
	s_mov_b64 s[24:25], 0x80
	v_lshl_add_u64 v[4:5], v[26:27], 0, s[24:25]
	s_mov_b32 m0, s3
	s_add_i32 s5, s3, 0x2000
	s_waitcnt vmcnt(2)
	s_barrier
	global_load_lds_dwordx4 v[4:5], off
	v_lshl_add_u64 v[6:7], v[28:29], 0, s[24:25]
	s_mov_b32 m0, s5
	s_add_i32 s4, s15, 0x8000
	global_load_lds_dwordx4 v[6:7], off
	v_lshl_add_u64 v[2:3], v[20:21], 0, s[24:25]
	s_mov_b32 m0, s4
	s_add_i32 s9, s15, 0xa000
	s_add_i32 s27, 0, 0x1c000
	global_load_lds_dwordx4 v[2:3], off
	v_lshl_add_u64 v[8:9], v[22:23], 0, s[24:25]
	s_mov_b32 m0, s9
	s_add_i32 s13, s27, s18
	global_load_lds_dwordx4 v[8:9], off
	v_lshl_add_u64 v[10:11], v[24:25], 0, s[24:25]
	s_mov_b32 m0, s13
	s_add_i32 s14, s13, 0x2000
	global_load_lds_dwordx4 v[10:11], off
	v_lshl_add_u64 v[12:13], v[18:19], 0, s[24:25]
	s_mov_b32 m0, s14
	v_and_b32_e32 v30, 15, v0
	global_load_lds_dwordx4 v[12:13], off
	v_lshlrev_b32_e32 v31, 1, v1
	v_lshlrev_b32_e32 v32, 2, v0
	v_lshl_or_b32 v130, s17, 6, v30
	v_lshl_or_b32 v30, v30, 6, v31
	s_lshl_b32 s2, s17, 13
	v_and_b32_e32 v32, 32, v32
	v_bitop3_b32 v62, v30, s2, v32 bitop3:0xde
	s_lshl_b32 s2, s19, 5
	s_and_b32 s2, s2, 0x60
	v_lshlrev_b32_e32 v30, 6, v0
	s_movk_i32 s17, 0x3c0
	v_and_or_b32 v30, v30, s17, v31
	s_lshl_b32 s17, s2, 7
	v_bitop3_b32 v63, s17, v30, v32 bitop3:0xf6
	s_add_i32 s29, 0, 0x10000
	s_add_i32 s28, 0, 0x14000
	v_add_u32_e32 v176, s29, v63
	s_waitcnt vmcnt(6)
	s_barrier
	v_add_u32_e32 v131, s28, v63
	ds_read_b128 v[30:33], v176
	ds_read_b128 v[34:37], v176 offset:1024
	ds_read_b128 v[38:41], v176 offset:2048
	ds_read_b128 v[42:45], v176 offset:3072
	ds_read_b128 v[46:49], v131
	ds_read_b128 v[50:53], v131 offset:1024
	ds_read_b128 v[54:57], v131 offset:2048
	ds_read_b128 v[58:61], v131 offset:3072
	s_add_i32 s20, s29, s18
	s_add_i32 s18, s28, s18
	s_add_i32 s22, s15, 0xc000
	s_add_i32 s21, s15, 0xe000
	s_add_i32 s19, s20, 0x2000
	s_add_i32 s17, s18, 0x2000
	s_cmpk_gt_u32 s23, 0xff
	v_add_u32_e32 v242, 0, v62
	v_add_u32_e32 v238, s27, v63
	v_add_u32_e32 v239, s26, v63
	s_mov_b32 m0, s22
	v_lshl_add_u64 v[94:95], v[14:15], 0, s[24:25]
	ds_read_b128 v[62:65], v242
	ds_read_b128 v[66:69], v242 offset:1024
	ds_read_b128 v[70:73], v242 offset:2048
	ds_read_b128 v[74:77], v242 offset:3072
	ds_read_b128 v[78:81], v242 offset:4096
	ds_read_b128 v[82:85], v242 offset:5120
	ds_read_b128 v[86:89], v242 offset:6144
	ds_read_b128 v[90:93], v242 offset:7168
	global_load_lds_dwordx4 v[94:95], off
	v_lshl_add_u64 v[94:95], v[16:17], 0, s[24:25]
	s_mov_b32 m0, s21
	s_nop 0
	global_load_lds_dwordx4 v[94:95], off
	s_waitcnt vmcnt(8)
	s_waitcnt lgkmcnt(0)
	s_setprio 1
	s_barrier
	v_mfma_f32_16x16x32_bf16 v[94:97], v[30:33], v[62:65], 0
	v_mfma_f32_16x16x32_bf16 v[98:101], v[38:41], v[62:65], 0
	v_mfma_f32_16x16x32_bf16 v[102:105], v[30:33], v[70:73], 0
	v_mfma_f32_16x16x32_bf16 v[106:109], v[38:41], v[70:73], 0
	v_mfma_f32_16x16x32_bf16 v[110:113], v[30:33], v[78:81], 0
	v_mfma_f32_16x16x32_bf16 v[114:117], v[38:41], v[78:81], 0
	v_mfma_f32_16x16x32_bf16 v[118:121], v[30:33], v[86:89], 0
	v_mfma_f32_16x16x32_bf16 v[122:125], v[38:41], v[86:89], 0
	v_mfma_f32_16x16x32_bf16 v[94:97], v[34:37], v[66:69], v[94:97]
	v_mfma_f32_16x16x32_bf16 v[98:101], v[42:45], v[66:69], v[98:101]
	v_mfma_f32_16x16x32_bf16 v[102:105], v[34:37], v[74:77], v[102:105]
	v_mfma_f32_16x16x32_bf16 v[106:109], v[42:45], v[74:77], v[106:109]
	v_mfma_f32_16x16x32_bf16 v[110:113], v[34:37], v[82:85], v[110:113]
	v_mfma_f32_16x16x32_bf16 v[114:117], v[42:45], v[82:85], v[114:117]
	v_mfma_f32_16x16x32_bf16 v[118:121], v[34:37], v[90:93], v[118:121]
	v_mfma_f32_16x16x32_bf16 v[122:125], v[42:45], v[90:93], v[122:125]
	v_mfma_f32_16x16x32_bf16 v[126:129], v[46:49], v[62:65], 0
	v_mfma_f32_16x16x32_bf16 v[62:65], v[54:57], v[62:65], 0
	v_mfma_f32_16x16x32_bf16 v[126:129], v[50:53], v[66:69], v[126:129]
	v_mfma_f32_16x16x32_bf16 v[62:65], v[58:61], v[66:69], v[62:65]
	v_mfma_f32_16x16x32_bf16 v[66:69], v[46:49], v[70:73], 0
	v_mfma_f32_16x16x32_bf16 v[70:73], v[54:57], v[70:73], 0
	v_mfma_f32_16x16x32_bf16 v[66:69], v[50:53], v[74:77], v[66:69]
	v_mfma_f32_16x16x32_bf16 v[70:73], v[58:61], v[74:77], v[70:73]
	v_mfma_f32_16x16x32_bf16 v[74:77], v[46:49], v[78:81], 0
	v_mfma_f32_16x16x32_bf16 v[78:81], v[54:57], v[78:81], 0
	v_mfma_f32_16x16x32_bf16 v[74:77], v[50:53], v[82:85], v[74:77]
	v_mfma_f32_16x16x32_bf16 v[78:81], v[58:61], v[82:85], v[78:81]
	v_mfma_f32_16x16x32_bf16 v[82:85], v[46:49], v[86:89], 0
	v_mfma_f32_16x16x32_bf16 v[86:89], v[54:57], v[86:89], 0
	v_mfma_f32_16x16x32_bf16 v[82:85], v[50:53], v[90:93], v[82:85]
	s_setprio 0
	v_mfma_f32_16x16x32_bf16 v[86:89], v[58:61], v[90:93], v[86:89]
	s_barrier
	s_mov_b64 s[24:25], 0x100
	s_mov_b32 m0, s20
	v_lshl_add_u64 v[160:161], v[26:27], 0, s[24:25]
	ds_read_b128 v[90:93], v242 offset:16384
	ds_read_b128 v[132:135], v242 offset:17408
	ds_read_b128 v[136:139], v242 offset:18432
	ds_read_b128 v[140:143], v242 offset:19456
	ds_read_b128 v[144:147], v242 offset:20480
	ds_read_b128 v[148:151], v242 offset:21504
	ds_read_b128 v[152:155], v242 offset:22528
	ds_read_b128 v[156:159], v242 offset:23552
	global_load_lds_dwordx4 v[160:161], off
	v_lshl_add_u64 v[160:161], v[28:29], 0, s[24:25]
	s_mov_b32 m0, s19
	s_nop 0
	global_load_lds_dwordx4 v[160:161], off
	v_lshl_add_u64 v[160:161], v[24:25], 0, s[24:25]
	s_mov_b32 m0, s18
	s_nop 0
	global_load_lds_dwordx4 v[160:161], off
	v_lshl_add_u64 v[160:161], v[18:19], 0, s[24:25]
	s_mov_b32 m0, s17
	s_nop 0
	global_load_lds_dwordx4 v[160:161], off
	v_lshl_add_u64 v[160:161], v[20:21], 0, s[24:25]
	s_mov_b32 m0, s15
	s_nop 0
	global_load_lds_dwordx4 v[160:161], off
	v_lshl_add_u64 v[160:161], v[22:23], 0, s[24:25]
	s_mov_b32 m0, s16
	s_nop 0
	global_load_lds_dwordx4 v[160:161], off
	s_waitcnt vmcnt(8)
	s_waitcnt lgkmcnt(0)
	s_setprio 1
	s_barrier
	v_mfma_f32_16x16x32_bf16 v[160:163], v[30:33], v[90:93], 0
	v_mfma_f32_16x16x32_bf16 v[168:171], v[30:33], v[136:139], 0
	v_mfma_f32_16x16x32_bf16 v[178:181], v[30:33], v[144:147], 0
	v_mfma_f32_16x16x32_bf16 v[30:33], v[30:33], v[152:155], 0
	v_mfma_f32_16x16x32_bf16 v[160:163], v[34:37], v[132:135], v[160:163]
	v_mfma_f32_16x16x32_bf16 v[168:171], v[34:37], v[140:143], v[168:171]
	v_mfma_f32_16x16x32_bf16 v[178:181], v[34:37], v[148:151], v[178:181]
	v_mfma_f32_16x16x32_bf16 v[30:33], v[34:37], v[156:159], v[30:33]
	v_mfma_f32_16x16x32_bf16 v[34:37], v[38:41], v[152:155], 0
	v_mfma_f32_16x16x32_bf16 v[164:167], v[38:41], v[90:93], 0
	v_mfma_f32_16x16x32_bf16 v[172:175], v[38:41], v[136:139], 0
	v_mfma_f32_16x16x32_bf16 v[182:185], v[38:41], v[144:147], 0
	v_mfma_f32_16x16x32_bf16 v[34:37], v[42:45], v[156:159], v[34:37]
	v_mfma_f32_16x16x32_bf16 v[164:167], v[42:45], v[132:135], v[164:167]
	v_mfma_f32_16x16x32_bf16 v[172:175], v[42:45], v[140:143], v[172:175]
	v_mfma_f32_16x16x32_bf16 v[182:185], v[42:45], v[148:151], v[182:185]
	v_mfma_f32_16x16x32_bf16 v[38:41], v[46:49], v[90:93], 0
	v_mfma_f32_16x16x32_bf16 v[42:45], v[54:57], v[90:93], 0
	v_mfma_f32_16x16x32_bf16 v[38:41], v[50:53], v[132:135], v[38:41]
	v_mfma_f32_16x16x32_bf16 v[42:45], v[58:61], v[132:135], v[42:45]
	v_mfma_f32_16x16x32_bf16 v[90:93], v[46:49], v[136:139], 0
	v_mfma_f32_16x16x32_bf16 v[132:135], v[54:57], v[136:139], 0
	v_mfma_f32_16x16x32_bf16 v[136:139], v[46:49], v[144:147], 0
	v_mfma_f32_16x16x32_bf16 v[46:49], v[46:49], v[152:155], 0
	v_mfma_f32_16x16x32_bf16 v[90:93], v[50:53], v[140:143], v[90:93]
	v_mfma_f32_16x16x32_bf16 v[136:139], v[50:53], v[148:151], v[136:139]
	v_mfma_f32_16x16x32_bf16 v[46:49], v[50:53], v[156:159], v[46:49]
	v_mfma_f32_16x16x32_bf16 v[50:53], v[54:57], v[152:155], 0
	v_mfma_f32_16x16x32_bf16 v[132:135], v[58:61], v[140:143], v[132:135]
	v_mfma_f32_16x16x32_bf16 v[140:143], v[54:57], v[144:147], 0
	v_mfma_f32_16x16x32_bf16 v[50:53], v[58:61], v[156:159], v[50:53]
	s_setprio 0
	v_mfma_f32_16x16x32_bf16 v[140:143], v[58:61], v[148:151], v[140:143]
	s_barrier
	ds_read_b128 v[54:57], v239
	ds_read_b128 v[58:61], v239 offset:1024
	ds_read_b128 v[144:147], v239 offset:2048
	ds_read_b128 v[148:151], v239 offset:3072
	ds_read_b128 v[152:155], v238
	ds_read_b128 v[156:159], v238 offset:1024
	ds_read_b128 v[186:189], v238 offset:2048
	ds_read_b128 v[190:193], v238 offset:3072
	s_mov_b32 m0, s11
	v_lshl_add_u64 v[226:227], v[14:15], 0, s[24:25]
	ds_read_b128 v[194:197], v242 offset:32768
	ds_read_b128 v[198:201], v242 offset:33792
	ds_read_b128 v[202:205], v242 offset:34816
	ds_read_b128 v[206:209], v242 offset:35840
	ds_read_b128 v[210:213], v242 offset:36864
	ds_read_b128 v[214:217], v242 offset:37888
	ds_read_b128 v[218:221], v242 offset:38912
	ds_read_b128 v[222:225], v242 offset:39936
	global_load_lds_dwordx4 v[226:227], off
	v_lshl_add_u64 v[226:227], v[16:17], 0, s[24:25]
	s_mov_b32 m0, s12
	s_nop 0
	global_load_lds_dwordx4 v[226:227], off
	s_waitcnt vmcnt(8)
	s_waitcnt lgkmcnt(0)
	s_setprio 1
	s_barrier
	v_mfma_f32_16x16x32_bf16 v[94:97], v[54:57], v[194:197], v[94:97]
	v_mfma_f32_16x16x32_bf16 v[98:101], v[144:147], v[194:197], v[98:101]
	v_mfma_f32_16x16x32_bf16 v[102:105], v[54:57], v[202:205], v[102:105]
	v_mfma_f32_16x16x32_bf16 v[106:109], v[144:147], v[202:205], v[106:109]
	v_mfma_f32_16x16x32_bf16 v[110:113], v[54:57], v[210:213], v[110:113]
	v_mfma_f32_16x16x32_bf16 v[114:117], v[144:147], v[210:213], v[114:117]
	v_mfma_f32_16x16x32_bf16 v[118:121], v[54:57], v[218:221], v[118:121]
	v_mfma_f32_16x16x32_bf16 v[122:125], v[144:147], v[218:221], v[122:125]
	v_mfma_f32_16x16x32_bf16 v[94:97], v[58:61], v[198:201], v[94:97]
	v_mfma_f32_16x16x32_bf16 v[98:101], v[148:151], v[198:201], v[98:101]
	v_mfma_f32_16x16x32_bf16 v[102:105], v[58:61], v[206:209], v[102:105]
	v_mfma_f32_16x16x32_bf16 v[106:109], v[148:151], v[206:209], v[106:109]
	v_mfma_f32_16x16x32_bf16 v[110:113], v[58:61], v[214:217], v[110:113]
	v_mfma_f32_16x16x32_bf16 v[114:117], v[148:151], v[214:217], v[114:117]
	v_mfma_f32_16x16x32_bf16 v[118:121], v[58:61], v[222:225], v[118:121]
	v_mfma_f32_16x16x32_bf16 v[122:125], v[148:151], v[222:225], v[122:125]
	v_mfma_f32_16x16x32_bf16 v[126:129], v[152:155], v[194:197], v[126:129]
	v_mfma_f32_16x16x32_bf16 v[62:65], v[186:189], v[194:197], v[62:65]
	v_mfma_f32_16x16x32_bf16 v[66:69], v[152:155], v[202:205], v[66:69]
	v_mfma_f32_16x16x32_bf16 v[70:73], v[186:189], v[202:205], v[70:73]
	v_mfma_f32_16x16x32_bf16 v[74:77], v[152:155], v[210:213], v[74:77]
	v_mfma_f32_16x16x32_bf16 v[78:81], v[186:189], v[210:213], v[78:81]
	v_mfma_f32_16x16x32_bf16 v[82:85], v[152:155], v[218:221], v[82:85]
	v_mfma_f32_16x16x32_bf16 v[86:89], v[186:189], v[218:221], v[86:89]
	v_mfma_f32_16x16x32_bf16 v[126:129], v[156:159], v[198:201], v[126:129]
	v_mfma_f32_16x16x32_bf16 v[62:65], v[190:193], v[198:201], v[62:65]
	v_mfma_f32_16x16x32_bf16 v[66:69], v[156:159], v[206:209], v[66:69]
	v_mfma_f32_16x16x32_bf16 v[70:73], v[190:193], v[206:209], v[70:73]
	v_mfma_f32_16x16x32_bf16 v[74:77], v[156:159], v[214:217], v[74:77]
	v_mfma_f32_16x16x32_bf16 v[78:81], v[190:193], v[214:217], v[78:81]
	v_mfma_f32_16x16x32_bf16 v[82:85], v[156:159], v[222:225], v[82:85]
	s_setprio 0
	v_mfma_f32_16x16x32_bf16 v[86:89], v[190:193], v[222:225], v[86:89]
	s_barrier
	s_mov_b64 s[24:25], 0x180
	s_mov_b32 m0, s3
	v_lshl_add_u64 v[226:227], v[26:27], 0, s[24:25]
	ds_read_b128 v[194:197], v242 offset:49152
	ds_read_b128 v[198:201], v242 offset:50176
	ds_read_b128 v[202:205], v242 offset:51200
	ds_read_b128 v[206:209], v242 offset:52224
	ds_read_b128 v[210:213], v242 offset:53248
	ds_read_b128 v[214:217], v242 offset:54272
	ds_read_b128 v[218:221], v242 offset:55296
	ds_read_b128 v[222:225], v242 offset:56320
	global_load_lds_dwordx4 v[226:227], off
	v_lshl_add_u64 v[226:227], v[28:29], 0, s[24:25]
	s_mov_b32 m0, s5
	s_nop 0
	global_load_lds_dwordx4 v[226:227], off
	v_lshl_add_u64 v[226:227], v[24:25], 0, s[24:25]
	s_mov_b32 m0, s13
	s_nop 0
	global_load_lds_dwordx4 v[226:227], off
	v_lshl_add_u64 v[226:227], v[18:19], 0, s[24:25]
	s_mov_b32 m0, s14
	s_nop 0
	global_load_lds_dwordx4 v[226:227], off
	v_lshl_add_u64 v[226:227], v[20:21], 0, s[24:25]
	s_mov_b32 m0, s4
	s_nop 0
	global_load_lds_dwordx4 v[226:227], off
	v_lshl_add_u64 v[226:227], v[22:23], 0, s[24:25]
	s_mov_b32 m0, s9
	s_nop 0
	global_load_lds_dwordx4 v[226:227], off
	s_waitcnt vmcnt(8)
	s_waitcnt lgkmcnt(0)
	s_setprio 1
	s_barrier
	v_mfma_f32_16x16x32_bf16 v[30:33], v[54:57], v[218:221], v[30:33]
	v_mfma_f32_16x16x32_bf16 v[34:37], v[144:147], v[218:221], v[34:37]
	v_mfma_f32_16x16x32_bf16 v[160:163], v[54:57], v[194:197], v[160:163]
	v_mfma_f32_16x16x32_bf16 v[164:167], v[144:147], v[194:197], v[164:167]
	v_mfma_f32_16x16x32_bf16 v[168:171], v[54:57], v[202:205], v[168:171]
	v_mfma_f32_16x16x32_bf16 v[172:175], v[144:147], v[202:205], v[172:175]
	v_mfma_f32_16x16x32_bf16 v[178:181], v[54:57], v[210:213], v[178:181]
	v_mfma_f32_16x16x32_bf16 v[182:185], v[144:147], v[210:213], v[182:185]
	v_mfma_f32_16x16x32_bf16 v[30:33], v[58:61], v[222:225], v[30:33]
	v_mfma_f32_16x16x32_bf16 v[34:37], v[148:151], v[222:225], v[34:37]
	v_mfma_f32_16x16x32_bf16 v[160:163], v[58:61], v[198:201], v[160:163]
	v_mfma_f32_16x16x32_bf16 v[164:167], v[148:151], v[198:201], v[164:167]
	v_mfma_f32_16x16x32_bf16 v[168:171], v[58:61], v[206:209], v[168:171]
	v_mfma_f32_16x16x32_bf16 v[172:175], v[148:151], v[206:209], v[172:175]
	v_mfma_f32_16x16x32_bf16 v[178:181], v[58:61], v[214:217], v[178:181]
	v_mfma_f32_16x16x32_bf16 v[182:185], v[148:151], v[214:217], v[182:185]
	v_mfma_f32_16x16x32_bf16 v[38:41], v[152:155], v[194:197], v[38:41]
	v_mfma_f32_16x16x32_bf16 v[42:45], v[186:189], v[194:197], v[42:45]
	v_mfma_f32_16x16x32_bf16 v[54:57], v[152:155], v[202:205], v[90:93]
	v_mfma_f32_16x16x32_bf16 v[58:61], v[186:189], v[202:205], v[132:135]
	v_mfma_f32_16x16x32_bf16 v[90:93], v[152:155], v[210:213], v[136:139]
	v_mfma_f32_16x16x32_bf16 v[46:49], v[152:155], v[218:221], v[46:49]
	v_mfma_f32_16x16x32_bf16 v[50:53], v[186:189], v[218:221], v[50:53]
	v_mfma_f32_16x16x32_bf16 v[38:41], v[156:159], v[198:201], v[38:41]
	v_mfma_f32_16x16x32_bf16 v[42:45], v[190:193], v[198:201], v[42:45]
	v_mfma_f32_16x16x32_bf16 v[54:57], v[156:159], v[206:209], v[54:57]
	v_mfma_f32_16x16x32_bf16 v[58:61], v[190:193], v[206:209], v[58:61]
	v_mfma_f32_16x16x32_bf16 v[90:93], v[156:159], v[214:217], v[90:93]
	v_mfma_f32_16x16x32_bf16 v[132:135], v[186:189], v[210:213], v[140:143]
	v_mfma_f32_16x16x32_bf16 v[46:49], v[156:159], v[222:225], v[46:49]
	v_mfma_f32_16x16x32_bf16 v[50:53], v[190:193], v[222:225], v[50:53]
	s_setprio 0
	v_mfma_f32_16x16x32_bf16 v[132:135], v[190:193], v[214:217], v[132:135]
	s_barrier
	ds_read_b128 v[136:139], v176
	ds_read_b128 v[140:143], v176 offset:1024
	ds_read_b128 v[144:147], v176 offset:2048
	ds_read_b128 v[148:151], v176 offset:3072
	ds_read_b128 v[152:155], v131
	ds_read_b128 v[156:159], v131 offset:1024
	ds_read_b128 v[186:189], v131 offset:2048
	ds_read_b128 v[190:193], v131 offset:3072
	s_mov_b32 m0, s22
	v_lshl_add_u64 v[226:227], v[14:15], 0, s[24:25]
	ds_read_b128 v[194:197], v242
	ds_read_b128 v[198:201], v242 offset:1024
	ds_read_b128 v[202:205], v242 offset:2048
	ds_read_b128 v[206:209], v242 offset:3072
	ds_read_b128 v[210:213], v242 offset:4096
	ds_read_b128 v[214:217], v242 offset:5120
	ds_read_b128 v[218:221], v242 offset:6144
	ds_read_b128 v[222:225], v242 offset:7168
	global_load_lds_dwordx4 v[226:227], off
	v_lshl_add_u64 v[226:227], v[16:17], 0, s[24:25]
	s_mov_b32 m0, s21
	s_nop 0
	global_load_lds_dwordx4 v[226:227], off
	s_waitcnt vmcnt(8)
	s_waitcnt lgkmcnt(0)
	s_setprio 1
	s_barrier
	v_mfma_f32_16x16x32_bf16 v[110:113], v[136:139], v[210:213], v[110:113]
	v_mfma_f32_16x16x32_bf16 v[226:229], v[140:143], v[214:217], v[110:113]
	v_mfma_f32_16x16x32_bf16 v[110:113], v[144:147], v[210:213], v[114:117]
	v_mfma_f32_16x16x32_bf16 v[94:97], v[136:139], v[194:197], v[94:97]
	v_mfma_f32_16x16x32_bf16 v[98:101], v[144:147], v[194:197], v[98:101]
	v_mfma_f32_16x16x32_bf16 v[102:105], v[136:139], v[202:205], v[102:105]
	v_mfma_f32_16x16x32_bf16 v[106:109], v[144:147], v[202:205], v[106:109]
	v_mfma_f32_16x16x32_bf16 v[114:117], v[148:151], v[214:217], v[110:113]
	v_mfma_f32_16x16x32_bf16 v[110:113], v[136:139], v[218:221], v[118:121]
	v_mfma_f32_16x16x32_bf16 v[94:97], v[140:143], v[198:201], v[94:97]
	v_mfma_f32_16x16x32_bf16 v[98:101], v[148:151], v[198:201], v[98:101]
	v_mfma_f32_16x16x32_bf16 v[102:105], v[140:143], v[206:209], v[102:105]
	v_mfma_f32_16x16x32_bf16 v[106:109], v[148:151], v[206:209], v[106:109]
	v_mfma_f32_16x16x32_bf16 v[118:121], v[140:143], v[222:225], v[110:113]
	v_mfma_f32_16x16x32_bf16 v[110:113], v[144:147], v[218:221], v[122:125]
	v_mfma_f32_16x16x32_bf16 v[230:233], v[148:151], v[222:225], v[110:113]
	v_mfma_f32_16x16x32_bf16 v[74:77], v[152:155], v[210:213], v[74:77]
	v_mfma_f32_16x16x32_bf16 v[110:113], v[152:155], v[194:197], v[126:129]
	v_mfma_f32_16x16x32_bf16 v[62:65], v[186:189], v[194:197], v[62:65]
	v_mfma_f32_16x16x32_bf16 v[194:197], v[156:159], v[214:217], v[74:77]
	v_mfma_f32_16x16x32_bf16 v[74:77], v[186:189], v[210:213], v[78:81]
	v_mfma_f32_16x16x32_bf16 v[234:237], v[156:159], v[198:201], v[110:113]
	v_mfma_f32_16x16x32_bf16 v[62:65], v[190:193], v[198:201], v[62:65]
	v_mfma_f32_16x16x32_bf16 v[66:69], v[152:155], v[202:205], v[66:69]
	v_mfma_f32_16x16x32_bf16 v[70:73], v[186:189], v[202:205], v[70:73]
	v_mfma_f32_16x16x32_bf16 v[198:201], v[190:193], v[214:217], v[74:77]
	v_mfma_f32_16x16x32_bf16 v[74:77], v[152:155], v[218:221], v[82:85]
	v_mfma_f32_16x16x32_bf16 v[66:69], v[156:159], v[206:209], v[66:69]
	v_mfma_f32_16x16x32_bf16 v[70:73], v[190:193], v[206:209], v[70:73]
	v_mfma_f32_16x16x32_bf16 v[202:205], v[156:159], v[222:225], v[74:77]
	v_mfma_f32_16x16x32_bf16 v[74:77], v[186:189], v[218:221], v[86:89]
	s_setprio 0
	v_mfma_f32_16x16x32_bf16 v[206:209], v[190:193], v[222:225], v[74:77]
	s_barrier
	s_mov_b32 m0, s20
	s_nop 3
	ds_read_b128 v[74:77], v242 offset:16384
	ds_read_b128 v[78:81], v242 offset:17408
	ds_read_b128 v[82:85], v242 offset:18432
	ds_read_b128 v[86:89], v242 offset:19456
	ds_read_b128 v[110:113], v242 offset:20480
	ds_read_b128 v[122:125], v242 offset:21504
	ds_read_b128 v[126:129], v242 offset:22528
	ds_read_b128 v[210:213], v242 offset:23552
	global_load_lds_dwordx4 v[26:27], off
	s_mov_b32 m0, s19
	s_nop 0
	global_load_lds_dwordx4 v[28:29], off
	s_mov_b32 m0, s18
	s_nop 0
	global_load_lds_dwordx4 v[24:25], off
	s_mov_b32 m0, s17
	s_nop 0
	global_load_lds_dwordx4 v[18:19], off
	s_mov_b32 m0, s15
	s_nop 0
	global_load_lds_dwordx4 v[20:21], off
	s_mov_b32 m0, s16
	s_nop 0
	global_load_lds_dwordx4 v[22:23], off
	s_waitcnt vmcnt(8)
	s_waitcnt lgkmcnt(0)
	s_setprio 1
	s_barrier
	v_mfma_f32_16x16x32_bf16 v[30:33], v[136:139], v[126:129], v[30:33]
	v_mfma_f32_16x16x32_bf16 v[18:21], v[136:139], v[74:77], v[160:163]
	v_mfma_f32_16x16x32_bf16 v[22:25], v[144:147], v[74:77], v[164:167]
	v_mfma_f32_16x16x32_bf16 v[26:29], v[136:139], v[82:85], v[168:171]
	v_mfma_f32_16x16x32_bf16 v[164:167], v[136:139], v[110:113], v[178:181]
	v_mfma_f32_16x16x32_bf16 v[136:139], v[140:143], v[210:213], v[30:33]
	v_mfma_f32_16x16x32_bf16 v[30:33], v[144:147], v[126:129], v[34:37]
	v_mfma_f32_16x16x32_bf16 v[18:21], v[140:143], v[78:81], v[18:21]
	v_mfma_f32_16x16x32_bf16 v[22:25], v[148:151], v[78:81], v[22:25]
	v_mfma_f32_16x16x32_bf16 v[26:29], v[140:143], v[86:89], v[26:29]
	v_mfma_f32_16x16x32_bf16 v[160:163], v[144:147], v[82:85], v[172:175]
	v_mfma_f32_16x16x32_bf16 v[168:171], v[144:147], v[110:113], v[182:185]
	v_mfma_f32_16x16x32_bf16 v[34:37], v[148:151], v[210:213], v[30:33]
	v_mfma_f32_16x16x32_bf16 v[160:163], v[148:151], v[86:89], v[160:163]
	v_mfma_f32_16x16x32_bf16 v[164:167], v[140:143], v[122:125], v[164:167]
	v_mfma_f32_16x16x32_bf16 v[168:171], v[148:151], v[122:125], v[168:171]
	v_mfma_f32_16x16x32_bf16 v[30:33], v[152:155], v[74:77], v[38:41]
	v_mfma_f32_16x16x32_bf16 v[38:41], v[156:159], v[78:81], v[30:33]
	v_mfma_f32_16x16x32_bf16 v[30:33], v[186:189], v[74:77], v[42:45]
	v_mfma_f32_16x16x32_bf16 v[140:143], v[190:193], v[78:81], v[30:33]
	v_mfma_f32_16x16x32_bf16 v[30:33], v[152:155], v[82:85], v[54:57]
	v_mfma_f32_16x16x32_bf16 v[144:147], v[156:159], v[86:89], v[30:33]
	v_mfma_f32_16x16x32_bf16 v[30:33], v[186:189], v[82:85], v[58:61]
	v_mfma_f32_16x16x32_bf16 v[148:151], v[190:193], v[86:89], v[30:33]
	v_mfma_f32_16x16x32_bf16 v[30:33], v[152:155], v[110:113], v[90:93]
	v_mfma_f32_16x16x32_bf16 v[172:175], v[156:159], v[122:125], v[30:33]
	v_mfma_f32_16x16x32_bf16 v[30:33], v[186:189], v[110:113], v[132:135]
	v_mfma_f32_16x16x32_bf16 v[132:135], v[190:193], v[122:125], v[30:33]
	v_mfma_f32_16x16x32_bf16 v[30:33], v[152:155], v[126:129], v[46:49]
	v_mfma_f32_16x16x32_bf16 v[152:155], v[156:159], v[210:213], v[30:33]
	v_mfma_f32_16x16x32_bf16 v[30:33], v[186:189], v[126:129], v[50:53]
	s_setprio 0
	v_mfma_f32_16x16x32_bf16 v[156:159], v[190:193], v[210:213], v[30:33]
	s_barrier
	ds_read_b128 v[50:53], v239
	ds_read_b128 v[54:57], v239 offset:1024
	ds_read_b128 v[178:181], v239 offset:2048
	ds_read_b128 v[182:185], v239 offset:3072
	ds_read_b128 v[186:189], v238
	ds_read_b128 v[190:193], v238 offset:1024
	ds_read_b128 v[210:213], v238 offset:2048
	ds_read_b128 v[214:217], v238 offset:3072
	s_mov_b32 m0, s11
	ds_read_b128 v[30:33], v242 offset:32768
	ds_read_b128 v[42:45], v242 offset:33792
	ds_read_b128 v[46:49], v242 offset:34816
	ds_read_b128 v[58:61], v242 offset:35840
	ds_read_b128 v[82:85], v242 offset:36864
	ds_read_b128 v[218:221], v242 offset:37888
	ds_read_b128 v[222:225], v242 offset:38912
	ds_read_b128 v[238:241], v242 offset:39936
	global_load_lds_dwordx4 v[14:15], off
	s_mov_b32 m0, s12
	s_nop 0
	global_load_lds_dwordx4 v[16:17], off
	s_waitcnt vmcnt(8)
	s_waitcnt lgkmcnt(0)
	s_setprio 1
	s_barrier
	v_mfma_f32_16x16x32_bf16 v[14:17], v[50:53], v[30:33], v[94:97]
	v_mfma_f32_16x16x32_bf16 v[126:129], v[54:57], v[42:45], v[14:17]
	v_mfma_f32_16x16x32_bf16 v[14:17], v[178:181], v[30:33], v[98:101]
	v_mfma_f32_16x16x32_bf16 v[122:125], v[182:185], v[42:45], v[14:17]
	v_mfma_f32_16x16x32_bf16 v[14:17], v[50:53], v[46:49], v[102:105]
	v_mfma_f32_16x16x32_bf16 v[110:113], v[54:57], v[58:61], v[14:17]
	v_mfma_f32_16x16x32_bf16 v[14:17], v[178:181], v[46:49], v[106:109]
	v_mfma_f32_16x16x32_bf16 v[106:109], v[182:185], v[58:61], v[14:17]
	v_mfma_f32_16x16x32_bf16 v[14:17], v[50:53], v[82:85], v[226:229]
	v_mfma_f32_16x16x32_bf16 v[94:97], v[54:57], v[218:221], v[14:17]
	v_mfma_f32_16x16x32_bf16 v[14:17], v[178:181], v[82:85], v[114:117]
	v_mfma_f32_16x16x32_bf16 v[90:93], v[182:185], v[218:221], v[14:17]
	v_mfma_f32_16x16x32_bf16 v[14:17], v[50:53], v[222:225], v[118:121]
	v_mfma_f32_16x16x32_bf16 v[78:81], v[54:57], v[238:241], v[14:17]
	v_mfma_f32_16x16x32_bf16 v[14:17], v[178:181], v[222:225], v[230:233]
	v_mfma_f32_16x16x32_bf16 v[74:77], v[182:185], v[238:241], v[14:17]
	v_mfma_f32_16x16x32_bf16 v[14:17], v[186:189], v[30:33], v[234:237]
	v_mfma_f32_16x16x32_bf16 v[118:121], v[190:193], v[42:45], v[14:17]
	v_mfma_f32_16x16x32_bf16 v[14:17], v[210:213], v[30:33], v[62:65]
	v_mfma_f32_16x16x32_bf16 v[114:117], v[214:217], v[42:45], v[14:17]
	v_mfma_f32_16x16x32_bf16 v[14:17], v[186:189], v[46:49], v[66:69]
	v_mfma_f32_16x16x32_bf16 v[102:105], v[190:193], v[58:61], v[14:17]
	v_mfma_f32_16x16x32_bf16 v[14:17], v[210:213], v[46:49], v[70:73]
	v_mfma_f32_16x16x32_bf16 v[98:101], v[214:217], v[58:61], v[14:17]
	v_mfma_f32_16x16x32_bf16 v[14:17], v[186:189], v[82:85], v[194:197]
	v_mfma_f32_16x16x32_bf16 v[86:89], v[190:193], v[218:221], v[14:17]
	v_mfma_f32_16x16x32_bf16 v[14:17], v[210:213], v[82:85], v[198:201]
	v_mfma_f32_16x16x32_bf16 v[82:85], v[214:217], v[218:221], v[14:17]
	v_mfma_f32_16x16x32_bf16 v[14:17], v[186:189], v[222:225], v[202:205]
	v_mfma_f32_16x16x32_bf16 v[66:69], v[190:193], v[238:241], v[14:17]
	v_mfma_f32_16x16x32_bf16 v[14:17], v[210:213], v[222:225], v[206:209]
	s_setprio 0
	v_mfma_f32_16x16x32_bf16 v[58:61], v[214:217], v[238:241], v[14:17]
	s_barrier
	s_mov_b32 m0, s3
	ds_read_b128 v[194:197], v242 offset:49152
	ds_read_b128 v[198:201], v242 offset:50176
	ds_read_b128 v[202:205], v242 offset:51200
	ds_read_b128 v[206:209], v242 offset:52224
	ds_read_b128 v[218:221], v242 offset:53248
	ds_read_b128 v[222:225], v242 offset:54272
	ds_read_b128 v[226:229], v242 offset:55296
	ds_read_b128 v[230:233], v242 offset:56320
	global_load_lds_dwordx4 v[4:5], off
	s_mov_b32 m0, s5
	s_nop 0
	global_load_lds_dwordx4 v[6:7], off
	s_mov_b32 m0, s13
	s_nop 0
	global_load_lds_dwordx4 v[10:11], off
	s_mov_b32 m0, s14
	s_nop 0
	global_load_lds_dwordx4 v[12:13], off
	s_mov_b32 m0, s4
	s_nop 0
	global_load_lds_dwordx4 v[2:3], off
	s_mov_b32 m0, s9
	s_nop 0
	global_load_lds_dwordx4 v[8:9], off
	s_waitcnt vmcnt(8)
	s_waitcnt lgkmcnt(0)
	s_setprio 1
	s_barrier
	v_mfma_f32_16x16x32_bf16 v[2:5], v[50:53], v[194:197], v[18:21]
	v_mfma_f32_16x16x32_bf16 v[70:73], v[54:57], v[198:201], v[2:5]
	v_mfma_f32_16x16x32_bf16 v[2:5], v[178:181], v[194:197], v[22:25]
	v_mfma_f32_16x16x32_bf16 v[62:65], v[182:185], v[198:201], v[2:5]
	v_mfma_f32_16x16x32_bf16 v[2:5], v[50:53], v[202:205], v[26:29]
	v_mfma_f32_16x16x32_bf16 v[46:49], v[54:57], v[206:209], v[2:5]
	v_mfma_f32_16x16x32_bf16 v[2:5], v[178:181], v[202:205], v[160:163]
	v_mfma_f32_16x16x32_bf16 v[42:45], v[182:185], v[206:209], v[2:5]
	v_mfma_f32_16x16x32_bf16 v[2:5], v[50:53], v[218:221], v[164:167]
	v_mfma_f32_16x16x32_bf16 v[30:33], v[54:57], v[222:225], v[2:5]
	v_mfma_f32_16x16x32_bf16 v[2:5], v[178:181], v[218:221], v[168:171]
	v_mfma_f32_16x16x32_bf16 v[26:29], v[182:185], v[222:225], v[2:5]
	v_mfma_f32_16x16x32_bf16 v[2:5], v[50:53], v[226:229], v[136:139]
	v_mfma_f32_16x16x32_bf16 v[14:17], v[54:57], v[230:233], v[2:5]
	v_mfma_f32_16x16x32_bf16 v[2:5], v[178:181], v[226:229], v[34:37]
	v_mfma_f32_16x16x32_bf16 v[10:13], v[182:185], v[230:233], v[2:5]
	v_mfma_f32_16x16x32_bf16 v[2:5], v[186:189], v[194:197], v[38:41]
	v_mfma_f32_16x16x32_bf16 v[54:57], v[190:193], v[198:201], v[2:5]
	v_mfma_f32_16x16x32_bf16 v[2:5], v[210:213], v[194:197], v[140:143]
	v_mfma_f32_16x16x32_bf16 v[50:53], v[214:217], v[198:201], v[2:5]
	v_mfma_f32_16x16x32_bf16 v[2:5], v[186:189], v[202:205], v[144:147]
	v_mfma_f32_16x16x32_bf16 v[38:41], v[190:193], v[206:209], v[2:5]
	v_mfma_f32_16x16x32_bf16 v[2:5], v[210:213], v[202:205], v[148:151]
	v_mfma_f32_16x16x32_bf16 v[34:37], v[214:217], v[206:209], v[2:5]
	v_mfma_f32_16x16x32_bf16 v[2:5], v[186:189], v[218:221], v[172:175]
	v_mfma_f32_16x16x32_bf16 v[22:25], v[190:193], v[222:225], v[2:5]
	v_mfma_f32_16x16x32_bf16 v[2:5], v[210:213], v[218:221], v[132:135]
	v_mfma_f32_16x16x32_bf16 v[18:21], v[214:217], v[222:225], v[2:5]
	v_mfma_f32_16x16x32_bf16 v[2:5], v[186:189], v[226:229], v[152:155]
	v_mfma_f32_16x16x32_bf16 v[6:9], v[190:193], v[230:233], v[2:5]
	v_mfma_f32_16x16x32_bf16 v[2:5], v[210:213], v[226:229], v[156:159]
	s_setprio 0
	v_mfma_f32_16x16x32_bf16 v[2:5], v[214:217], v[230:233], v[2:5]
	s_barrier
	s_cbranch_scc1 .LBB0_1139
	s_barrier

.Lpk1179_peel:
	ds_read_b128 v[144:147], v158
	ds_read_b128 v[164:167], v158 offset:1024
	ds_read_b128 v[168:171], v158 offset:2048
	ds_read_b128 v[172:175], v158 offset:3072
	ds_read_b128 v[178:181], v159
	ds_read_b128 v[182:185], v159 offset:1024
	ds_read_b128 v[186:189], v159 offset:2048
	ds_read_b128 v[190:193], v159 offset:3072
	s_add_u32 s2, s36, 0xfffc0080
	s_addc_u32 s3, s37, -1
	s_cmp_eq_u32 s61, 12
	s_cselect_b32 s3, s19, s3
	s_cselect_b32 s2, s21, s2
	s_cselect_b32 s39, s57, s60
	s_cselect_b32 s38, s58, s59
	v_lshl_add_u64 v[226:227], s[36:37], 0, v[138:139]
	s_add_i32 m0, s42, 0xc000
	ds_read_b128 v[194:197], v160
	ds_read_b128 v[198:201], v160 offset:1024
	ds_read_b128 v[202:205], v160 offset:2048
	ds_read_b128 v[206:209], v160 offset:3072
	ds_read_b128 v[210:213], v160 offset:4096
	ds_read_b128 v[214:217], v160 offset:5120
	ds_read_b128 v[218:221], v160 offset:6144
	ds_read_b128 v[222:225], v160 offset:7168
	global_load_lds_dwordx4 v[226:227], off
	v_lshl_add_u64 v[226:227], s[36:37], 0, v[140:141]
	s_add_i32 m0, s42, 0xe000
	s_nop 0
	global_load_lds_dwordx4 v[226:227], off
	s_waitcnt vmcnt(8)
	s_waitcnt lgkmcnt(0)
	s_setprio 1
	s_barrier
	v_mfma_f32_16x16x32_bf16 v[126:129], v[144:147], v[194:197], 0
	v_mfma_f32_16x16x32_bf16 v[122:125], v[168:171], v[194:197], 0
	v_mfma_f32_16x16x32_bf16 v[114:117], v[144:147], v[202:205], 0
	v_mfma_f32_16x16x32_bf16 v[106:109], v[168:171], v[202:205], 0
	v_mfma_f32_16x16x32_bf16 v[98:101], v[144:147], v[210:213], 0
	v_mfma_f32_16x16x32_bf16 v[90:93], v[168:171], v[210:213], 0
	v_mfma_f32_16x16x32_bf16 v[82:85], v[144:147], v[218:221], 0
	v_mfma_f32_16x16x32_bf16 v[74:77], v[168:171], v[218:221], 0
	v_mfma_f32_16x16x32_bf16 v[126:129], v[164:167], v[198:201], v[126:129]
	v_mfma_f32_16x16x32_bf16 v[122:125], v[172:175], v[198:201], v[122:125]
	v_mfma_f32_16x16x32_bf16 v[114:117], v[164:167], v[206:209], v[114:117]
	v_mfma_f32_16x16x32_bf16 v[106:109], v[172:175], v[206:209], v[106:109]
	v_mfma_f32_16x16x32_bf16 v[98:101], v[164:167], v[214:217], v[98:101]
	v_mfma_f32_16x16x32_bf16 v[90:93], v[172:175], v[214:217], v[90:93]
	v_mfma_f32_16x16x32_bf16 v[82:85], v[164:167], v[222:225], v[82:85]
	v_mfma_f32_16x16x32_bf16 v[74:77], v[172:175], v[222:225], v[74:77]
	v_mfma_f32_16x16x32_bf16 v[118:121], v[178:181], v[194:197], 0
	v_mfma_f32_16x16x32_bf16 v[110:113], v[186:189], v[194:197], 0
	v_mfma_f32_16x16x32_bf16 v[102:105], v[178:181], v[202:205], 0
	v_mfma_f32_16x16x32_bf16 v[94:97], v[186:189], v[202:205], 0
	v_mfma_f32_16x16x32_bf16 v[86:89], v[178:181], v[210:213], 0
	v_mfma_f32_16x16x32_bf16 v[78:81], v[186:189], v[210:213], 0
	v_mfma_f32_16x16x32_bf16 v[70:73], v[178:181], v[218:221], 0
	v_mfma_f32_16x16x32_bf16 v[66:69], v[186:189], v[218:221], 0
	v_mfma_f32_16x16x32_bf16 v[118:121], v[182:185], v[198:201], v[118:121]
	v_mfma_f32_16x16x32_bf16 v[110:113], v[190:193], v[198:201], v[110:113]
	v_mfma_f32_16x16x32_bf16 v[102:105], v[182:185], v[206:209], v[102:105]
	v_mfma_f32_16x16x32_bf16 v[94:97], v[190:193], v[206:209], v[94:97]
	v_mfma_f32_16x16x32_bf16 v[86:89], v[182:185], v[214:217], v[86:89]
	v_mfma_f32_16x16x32_bf16 v[78:81], v[190:193], v[214:217], v[78:81]
	v_mfma_f32_16x16x32_bf16 v[70:73], v[182:185], v[222:225], v[70:73]
	s_setprio 0
	v_mfma_f32_16x16x32_bf16 v[66:69], v[190:193], v[222:225], v[66:69]
	s_barrier
	s_add_i32 s62, s51, s41
	v_lshl_add_u64 v[226:227], s[38:39], 0, v[132:133]
	s_mov_b32 m0, s62
	ds_read_b128 v[194:197], v160 offset:16384
	ds_read_b128 v[198:201], v160 offset:17408
	ds_read_b128 v[202:205], v160 offset:18432
	ds_read_b128 v[206:209], v160 offset:19456
	ds_read_b128 v[210:213], v160 offset:20480
	ds_read_b128 v[214:217], v160 offset:21504
	ds_read_b128 v[218:221], v160 offset:22528
	ds_read_b128 v[222:225], v160 offset:23552
	global_load_lds_dwordx4 v[226:227], off
	s_add_i32 m0, s62, 0x2000
	s_add_u32 s62, s38, 0x40000
	v_lshl_add_u64 v[228:229], s[38:39], 0, v[136:137]
	s_addc_u32 s63, s39, 0
	s_add_i32 s64, s52, s41
	global_load_lds_dwordx4 v[228:229], off
	v_lshl_add_u64 v[230:231], s[62:63], 0, v[132:133]
	s_mov_b32 m0, s64
	v_lshl_add_u64 v[232:233], s[2:3], 0, v[134:135]
	global_load_lds_dwordx4 v[230:231], off
	v_lshl_add_u64 v[230:231], s[62:63], 0, v[136:137]
	s_add_i32 m0, s64, 0x2000
	s_nop 0
	global_load_lds_dwordx4 v[230:231], off
	v_lshl_add_u64 v[230:231], s[2:3], 0, v[130:131]
	s_mov_b32 m0, s42
	s_nop 0
	global_load_lds_dwordx4 v[230:231], off
	s_mov_b32 m0, s43
	s_nop 0
	global_load_lds_dwordx4 v[232:233], off
	s_waitcnt vmcnt(8)
	s_waitcnt lgkmcnt(0)
	s_setprio 1
	s_barrier
	v_mfma_f32_16x16x32_bf16 v[62:65], v[144:147], v[194:197], 0
	v_mfma_f32_16x16x32_bf16 v[58:61], v[168:171], v[194:197], 0
	v_mfma_f32_16x16x32_bf16 v[50:53], v[144:147], v[202:205], 0
	v_mfma_f32_16x16x32_bf16 v[42:45], v[168:171], v[202:205], 0
	v_mfma_f32_16x16x32_bf16 v[34:37], v[144:147], v[210:213], 0
	v_mfma_f32_16x16x32_bf16 v[26:29], v[168:171], v[210:213], 0
	v_mfma_f32_16x16x32_bf16 v[18:21], v[144:147], v[218:221], 0
	v_mfma_f32_16x16x32_bf16 v[10:13], v[168:171], v[218:221], 0
	v_mfma_f32_16x16x32_bf16 v[62:65], v[164:167], v[198:201], v[62:65]
	v_mfma_f32_16x16x32_bf16 v[58:61], v[172:175], v[198:201], v[58:61]
	v_mfma_f32_16x16x32_bf16 v[50:53], v[164:167], v[206:209], v[50:53]
	v_mfma_f32_16x16x32_bf16 v[42:45], v[172:175], v[206:209], v[42:45]
	v_mfma_f32_16x16x32_bf16 v[34:37], v[164:167], v[214:217], v[34:37]
	v_mfma_f32_16x16x32_bf16 v[26:29], v[172:175], v[214:217], v[26:29]
	v_mfma_f32_16x16x32_bf16 v[18:21], v[164:167], v[222:225], v[18:21]
	v_mfma_f32_16x16x32_bf16 v[10:13], v[172:175], v[222:225], v[10:13]
	v_mfma_f32_16x16x32_bf16 v[54:57], v[178:181], v[194:197], 0
	v_mfma_f32_16x16x32_bf16 v[46:49], v[186:189], v[194:197], 0
	v_mfma_f32_16x16x32_bf16 v[38:41], v[178:181], v[202:205], 0
	v_mfma_f32_16x16x32_bf16 v[30:33], v[186:189], v[202:205], 0
	v_mfma_f32_16x16x32_bf16 v[22:25], v[178:181], v[210:213], 0
	v_mfma_f32_16x16x32_bf16 v[14:17], v[186:189], v[210:213], 0
	v_mfma_f32_16x16x32_bf16 v[6:9], v[178:181], v[218:221], 0
	v_mfma_f32_16x16x32_bf16 v[2:5], v[186:189], v[218:221], 0
	v_mfma_f32_16x16x32_bf16 v[54:57], v[182:185], v[198:201], v[54:57]
	v_mfma_f32_16x16x32_bf16 v[46:49], v[190:193], v[198:201], v[46:49]
	v_mfma_f32_16x16x32_bf16 v[38:41], v[182:185], v[206:209], v[38:41]
	v_mfma_f32_16x16x32_bf16 v[30:33], v[190:193], v[206:209], v[30:33]
	v_mfma_f32_16x16x32_bf16 v[22:25], v[182:185], v[214:217], v[22:25]
	v_mfma_f32_16x16x32_bf16 v[14:17], v[190:193], v[214:217], v[14:17]
	v_mfma_f32_16x16x32_bf16 v[6:9], v[182:185], v[222:225], v[6:9]
	s_setprio 0
	v_mfma_f32_16x16x32_bf16 v[2:5], v[190:193], v[222:225], v[2:5]
	s_barrier
	s_add_i32 s62, 0, 0x18000
	v_add_u32_e32 v163, s62, v148
	s_add_i32 s63, 0, 0x1c000
	ds_read_b128 v[144:147], v163
	ds_read_b128 v[164:167], v163 offset:1024
	ds_read_b128 v[168:171], v163 offset:2048
	ds_read_b128 v[172:175], v163 offset:3072
	v_add_u32_e32 v163, s63, v148
	ds_read_b128 v[178:181], v163
	ds_read_b128 v[182:185], v163 offset:1024
	ds_read_b128 v[186:189], v163 offset:2048
	ds_read_b128 v[190:193], v163 offset:3072
	s_add_u32 s2, s2, 0x40000
	s_addc_u32 s3, s3, 0
	s_mov_b32 m0, s44
	v_lshl_add_u64 v[234:235], s[2:3], 0, v[130:131]
	ds_read_b128 v[194:197], v160 offset:32768
	ds_read_b128 v[198:201], v160 offset:33792
	ds_read_b128 v[202:205], v160 offset:34816
	ds_read_b128 v[206:209], v160 offset:35840
	ds_read_b128 v[210:213], v160 offset:36864
	ds_read_b128 v[214:217], v160 offset:37888
	ds_read_b128 v[218:221], v160 offset:38912
	ds_read_b128 v[222:225], v160 offset:39936
	global_load_lds_dwordx4 v[234:235], off
	v_lshl_add_u64 v[234:235], s[2:3], 0, v[134:135]
	s_mov_b32 m0, s45
	s_nop 0
	global_load_lds_dwordx4 v[234:235], off
	s_waitcnt vmcnt(8)
	s_waitcnt lgkmcnt(0)
	s_setprio 1
	s_barrier
	v_mfma_f32_16x16x32_bf16 v[126:129], v[144:147], v[194:197], v[126:129]
	v_mfma_f32_16x16x32_bf16 v[122:125], v[168:171], v[194:197], v[122:125]
	v_mfma_f32_16x16x32_bf16 v[114:117], v[144:147], v[202:205], v[114:117]
	v_mfma_f32_16x16x32_bf16 v[106:109], v[168:171], v[202:205], v[106:109]
	v_mfma_f32_16x16x32_bf16 v[98:101], v[144:147], v[210:213], v[98:101]
	v_mfma_f32_16x16x32_bf16 v[90:93], v[168:171], v[210:213], v[90:93]
	v_mfma_f32_16x16x32_bf16 v[82:85], v[144:147], v[218:221], v[82:85]
	v_mfma_f32_16x16x32_bf16 v[74:77], v[168:171], v[218:221], v[74:77]
	v_mfma_f32_16x16x32_bf16 v[126:129], v[164:167], v[198:201], v[126:129]
	v_mfma_f32_16x16x32_bf16 v[122:125], v[172:175], v[198:201], v[122:125]
	v_mfma_f32_16x16x32_bf16 v[114:117], v[164:167], v[206:209], v[114:117]
	v_mfma_f32_16x16x32_bf16 v[106:109], v[172:175], v[206:209], v[106:109]
	v_mfma_f32_16x16x32_bf16 v[98:101], v[164:167], v[214:217], v[98:101]
	v_mfma_f32_16x16x32_bf16 v[90:93], v[172:175], v[214:217], v[90:93]
	v_mfma_f32_16x16x32_bf16 v[82:85], v[164:167], v[222:225], v[82:85]
	v_mfma_f32_16x16x32_bf16 v[74:77], v[172:175], v[222:225], v[74:77]
	v_mfma_f32_16x16x32_bf16 v[118:121], v[178:181], v[194:197], v[118:121]
	v_mfma_f32_16x16x32_bf16 v[110:113], v[186:189], v[194:197], v[110:113]
	v_mfma_f32_16x16x32_bf16 v[102:105], v[178:181], v[202:205], v[102:105]
	v_mfma_f32_16x16x32_bf16 v[94:97], v[186:189], v[202:205], v[94:97]
	v_mfma_f32_16x16x32_bf16 v[86:89], v[178:181], v[210:213], v[86:89]
	v_mfma_f32_16x16x32_bf16 v[78:81], v[186:189], v[210:213], v[78:81]
	v_mfma_f32_16x16x32_bf16 v[70:73], v[178:181], v[218:221], v[70:73]
	v_mfma_f32_16x16x32_bf16 v[66:69], v[186:189], v[218:221], v[66:69]
	v_mfma_f32_16x16x32_bf16 v[118:121], v[182:185], v[198:201], v[118:121]
	v_mfma_f32_16x16x32_bf16 v[110:113], v[190:193], v[198:201], v[110:113]
	v_mfma_f32_16x16x32_bf16 v[102:105], v[182:185], v[206:209], v[102:105]
	v_mfma_f32_16x16x32_bf16 v[94:97], v[190:193], v[206:209], v[94:97]
	v_mfma_f32_16x16x32_bf16 v[86:89], v[182:185], v[214:217], v[86:89]
	v_mfma_f32_16x16x32_bf16 v[78:81], v[190:193], v[214:217], v[78:81]
	v_mfma_f32_16x16x32_bf16 v[70:73], v[182:185], v[222:225], v[70:73]
	s_setprio 0
	v_mfma_f32_16x16x32_bf16 v[66:69], v[190:193], v[222:225], v[66:69]
	s_barrier
	s_add_i32 s2, s62, s41
	v_lshl_add_u64 v[226:227], v[226:227], 0, s[10:11]
	s_mov_b32 m0, s2
	ds_read_b128 v[194:197], v160 offset:49152
	ds_read_b128 v[198:201], v160 offset:50176
	ds_read_b128 v[202:205], v160 offset:51200
	ds_read_b128 v[206:209], v160 offset:52224
	ds_read_b128 v[210:213], v160 offset:53248
	ds_read_b128 v[214:217], v160 offset:54272
	ds_read_b128 v[218:221], v160 offset:55296
	ds_read_b128 v[222:225], v160 offset:56320
	global_load_lds_dwordx4 v[226:227], off
	s_add_i32 m0, s2, 0x2000
	s_add_u32 s2, s38, 0x40080
	v_lshl_add_u64 v[226:227], v[228:229], 0, s[10:11]
	s_addc_u32 s3, s39, 0
	s_add_i32 s38, s63, s41
	global_load_lds_dwordx4 v[226:227], off
	v_lshl_add_u64 v[226:227], s[2:3], 0, v[132:133]
	s_mov_b32 m0, s38
	s_nop 0
	global_load_lds_dwordx4 v[226:227], off
	v_lshl_add_u64 v[226:227], s[2:3], 0, v[136:137]
	s_add_i32 m0, s38, 0x2000
	s_nop 0
	global_load_lds_dwordx4 v[226:227], off
	v_lshl_add_u64 v[226:227], v[230:231], 0, s[10:11]
	s_mov_b32 m0, s47
	s_nop 0
	global_load_lds_dwordx4 v[226:227], off
	v_lshl_add_u64 v[226:227], v[232:233], 0, s[10:11]
	s_mov_b32 m0, s48
	s_nop 0
	global_load_lds_dwordx4 v[226:227], off
	s_waitcnt vmcnt(8)
	s_waitcnt lgkmcnt(0)
	s_setprio 1
	s_barrier
	v_mfma_f32_16x16x32_bf16 v[62:65], v[144:147], v[194:197], v[62:65]
	v_mfma_f32_16x16x32_bf16 v[58:61], v[168:171], v[194:197], v[58:61]
	v_mfma_f32_16x16x32_bf16 v[50:53], v[144:147], v[202:205], v[50:53]
	v_mfma_f32_16x16x32_bf16 v[42:45], v[168:171], v[202:205], v[42:45]
	v_mfma_f32_16x16x32_bf16 v[34:37], v[144:147], v[210:213], v[34:37]
	v_mfma_f32_16x16x32_bf16 v[26:29], v[168:171], v[210:213], v[26:29]
	v_mfma_f32_16x16x32_bf16 v[18:21], v[144:147], v[218:221], v[18:21]
	v_mfma_f32_16x16x32_bf16 v[10:13], v[168:171], v[218:221], v[10:13]
	v_mfma_f32_16x16x32_bf16 v[62:65], v[164:167], v[198:201], v[62:65]
	v_mfma_f32_16x16x32_bf16 v[58:61], v[172:175], v[198:201], v[58:61]
	v_mfma_f32_16x16x32_bf16 v[50:53], v[164:167], v[206:209], v[50:53]
	v_mfma_f32_16x16x32_bf16 v[42:45], v[172:175], v[206:209], v[42:45]
	v_mfma_f32_16x16x32_bf16 v[34:37], v[164:167], v[214:217], v[34:37]
	v_mfma_f32_16x16x32_bf16 v[26:29], v[172:175], v[214:217], v[26:29]
	v_mfma_f32_16x16x32_bf16 v[18:21], v[164:167], v[222:225], v[18:21]
	v_mfma_f32_16x16x32_bf16 v[10:13], v[172:175], v[222:225], v[10:13]
	v_mfma_f32_16x16x32_bf16 v[54:57], v[178:181], v[194:197], v[54:57]
	v_mfma_f32_16x16x32_bf16 v[46:49], v[186:189], v[194:197], v[46:49]
	v_mfma_f32_16x16x32_bf16 v[38:41], v[178:181], v[202:205], v[38:41]
	v_mfma_f32_16x16x32_bf16 v[30:33], v[186:189], v[202:205], v[30:33]
	v_mfma_f32_16x16x32_bf16 v[22:25], v[178:181], v[210:213], v[22:25]
	v_mfma_f32_16x16x32_bf16 v[14:17], v[186:189], v[210:213], v[14:17]
	v_mfma_f32_16x16x32_bf16 v[6:9], v[178:181], v[218:221], v[6:9]
	v_mfma_f32_16x16x32_bf16 v[2:5], v[186:189], v[218:221], v[2:5]
	v_mfma_f32_16x16x32_bf16 v[54:57], v[182:185], v[198:201], v[54:57]
	v_mfma_f32_16x16x32_bf16 v[46:49], v[190:193], v[198:201], v[46:49]
	v_mfma_f32_16x16x32_bf16 v[38:41], v[182:185], v[206:209], v[38:41]
	v_mfma_f32_16x16x32_bf16 v[30:33], v[190:193], v[206:209], v[30:33]
	v_mfma_f32_16x16x32_bf16 v[22:25], v[182:185], v[214:217], v[22:25]
	v_mfma_f32_16x16x32_bf16 v[14:17], v[190:193], v[214:217], v[14:17]
	v_mfma_f32_16x16x32_bf16 v[6:9], v[182:185], v[222:225], v[6:9]
	s_setprio 0
	v_mfma_f32_16x16x32_bf16 v[2:5], v[190:193], v[222:225], v[2:5]
	s_barrier
	s_add_i32 s61, s61, 2
	s_add_u32 s36, s36, 0x100
	s_addc_u32 s37, s37, 0
	s_add_u32 s59, s59, 0x100
	s_addc_u32 s60, s60, 0
	s_cmp_gt_u32 s61, 13
	s_cbranch_scc0 .LBB0_1179
	s_branch .Lpk1179_exit
.LBB0_1179:
	ds_read_b128 v[144:147], v158
	ds_read_b128 v[164:167], v158 offset:1024
	ds_read_b128 v[168:171], v158 offset:2048
	ds_read_b128 v[172:175], v158 offset:3072
	ds_read_b128 v[178:181], v159
	ds_read_b128 v[182:185], v159 offset:1024
	ds_read_b128 v[186:189], v159 offset:2048
	ds_read_b128 v[190:193], v159 offset:3072
	s_add_u32 s2, s36, 0xfffc0080
	s_addc_u32 s3, s37, -1
	s_cmp_eq_u32 s61, 12
	s_cselect_b32 s3, s19, s3
	s_cselect_b32 s2, s21, s2
	s_cselect_b32 s39, s57, s60
	s_cselect_b32 s38, s58, s59
	v_lshl_add_u64 v[226:227], s[36:37], 0, v[138:139]
	s_add_i32 m0, s42, 0xc000
	ds_read_b128 v[194:197], v160
	ds_read_b128 v[198:201], v160 offset:1024
	ds_read_b128 v[202:205], v160 offset:2048
	ds_read_b128 v[206:209], v160 offset:3072
	ds_read_b128 v[210:213], v160 offset:4096
	ds_read_b128 v[214:217], v160 offset:5120
	ds_read_b128 v[218:221], v160 offset:6144
	ds_read_b128 v[222:225], v160 offset:7168
	global_load_lds_dwordx4 v[226:227], off
	v_lshl_add_u64 v[226:227], s[36:37], 0, v[140:141]
	s_add_i32 m0, s42, 0xe000
	s_nop 0
	global_load_lds_dwordx4 v[226:227], off
	s_waitcnt vmcnt(8)
	s_waitcnt lgkmcnt(0)
	s_setprio 1
	s_barrier
	v_mfma_f32_16x16x32_bf16 v[126:129], v[144:147], v[194:197], v[126:129]
	v_mfma_f32_16x16x32_bf16 v[122:125], v[168:171], v[194:197], v[122:125]
	v_mfma_f32_16x16x32_bf16 v[114:117], v[144:147], v[202:205], v[114:117]
	v_mfma_f32_16x16x32_bf16 v[106:109], v[168:171], v[202:205], v[106:109]
	v_mfma_f32_16x16x32_bf16 v[98:101], v[144:147], v[210:213], v[98:101]
	v_mfma_f32_16x16x32_bf16 v[90:93], v[168:171], v[210:213], v[90:93]
	v_mfma_f32_16x16x32_bf16 v[82:85], v[144:147], v[218:221], v[82:85]
	v_mfma_f32_16x16x32_bf16 v[74:77], v[168:171], v[218:221], v[74:77]
	v_mfma_f32_16x16x32_bf16 v[126:129], v[164:167], v[198:201], v[126:129]
	v_mfma_f32_16x16x32_bf16 v[122:125], v[172:175], v[198:201], v[122:125]
	v_mfma_f32_16x16x32_bf16 v[114:117], v[164:167], v[206:209], v[114:117]
	v_mfma_f32_16x16x32_bf16 v[106:109], v[172:175], v[206:209], v[106:109]
	v_mfma_f32_16x16x32_bf16 v[98:101], v[164:167], v[214:217], v[98:101]
	v_mfma_f32_16x16x32_bf16 v[90:93], v[172:175], v[214:217], v[90:93]
	v_mfma_f32_16x16x32_bf16 v[82:85], v[164:167], v[222:225], v[82:85]
	v_mfma_f32_16x16x32_bf16 v[74:77], v[172:175], v[222:225], v[74:77]
	v_mfma_f32_16x16x32_bf16 v[118:121], v[178:181], v[194:197], v[118:121]
	v_mfma_f32_16x16x32_bf16 v[110:113], v[186:189], v[194:197], v[110:113]
	v_mfma_f32_16x16x32_bf16 v[102:105], v[178:181], v[202:205], v[102:105]
	v_mfma_f32_16x16x32_bf16 v[94:97], v[186:189], v[202:205], v[94:97]
	v_mfma_f32_16x16x32_bf16 v[86:89], v[178:181], v[210:213], v[86:89]
	v_mfma_f32_16x16x32_bf16 v[78:81], v[186:189], v[210:213], v[78:81]
	v_mfma_f32_16x16x32_bf16 v[70:73], v[178:181], v[218:221], v[70:73]
	v_mfma_f32_16x16x32_bf16 v[66:69], v[186:189], v[218:221], v[66:69]
	v_mfma_f32_16x16x32_bf16 v[118:121], v[182:185], v[198:201], v[118:121]
	v_mfma_f32_16x16x32_bf16 v[110:113], v[190:193], v[198:201], v[110:113]
	v_mfma_f32_16x16x32_bf16 v[102:105], v[182:185], v[206:209], v[102:105]
	v_mfma_f32_16x16x32_bf16 v[94:97], v[190:193], v[206:209], v[94:97]
	v_mfma_f32_16x16x32_bf16 v[86:89], v[182:185], v[214:217], v[86:89]
	v_mfma_f32_16x16x32_bf16 v[78:81], v[190:193], v[214:217], v[78:81]
	v_mfma_f32_16x16x32_bf16 v[70:73], v[182:185], v[222:225], v[70:73]
	s_setprio 0
	v_mfma_f32_16x16x32_bf16 v[66:69], v[190:193], v[222:225], v[66:69]
	s_barrier
	s_add_i32 s62, s51, s41
	v_lshl_add_u64 v[226:227], s[38:39], 0, v[132:133]
	s_mov_b32 m0, s62
	ds_read_b128 v[194:197], v160 offset:16384
	ds_read_b128 v[198:201], v160 offset:17408
	ds_read_b128 v[202:205], v160 offset:18432
	ds_read_b128 v[206:209], v160 offset:19456
	ds_read_b128 v[210:213], v160 offset:20480
	ds_read_b128 v[214:217], v160 offset:21504
	ds_read_b128 v[218:221], v160 offset:22528
	ds_read_b128 v[222:225], v160 offset:23552
	global_load_lds_dwordx4 v[226:227], off
	s_add_i32 m0, s62, 0x2000
	s_add_u32 s62, s38, 0x40000
	v_lshl_add_u64 v[228:229], s[38:39], 0, v[136:137]
	s_addc_u32 s63, s39, 0
	s_add_i32 s64, s52, s41
	global_load_lds_dwordx4 v[228:229], off
	v_lshl_add_u64 v[230:231], s[62:63], 0, v[132:133]
	s_mov_b32 m0, s64
	v_lshl_add_u64 v[232:233], s[2:3], 0, v[134:135]
	global_load_lds_dwordx4 v[230:231], off
	v_lshl_add_u64 v[230:231], s[62:63], 0, v[136:137]
	s_add_i32 m0, s64, 0x2000
	s_nop 0
	global_load_lds_dwordx4 v[230:231], off
	v_lshl_add_u64 v[230:231], s[2:3], 0, v[130:131]
	s_mov_b32 m0, s42
	s_nop 0
	global_load_lds_dwordx4 v[230:231], off
	s_mov_b32 m0, s43
	s_nop 0
	global_load_lds_dwordx4 v[232:233], off
	s_waitcnt vmcnt(8)
	s_waitcnt lgkmcnt(0)
	s_setprio 1
	s_barrier
	v_mfma_f32_16x16x32_bf16 v[62:65], v[144:147], v[194:197], v[62:65]
	v_mfma_f32_16x16x32_bf16 v[58:61], v[168:171], v[194:197], v[58:61]
	v_mfma_f32_16x16x32_bf16 v[50:53], v[144:147], v[202:205], v[50:53]
	v_mfma_f32_16x16x32_bf16 v[42:45], v[168:171], v[202:205], v[42:45]
	v_mfma_f32_16x16x32_bf16 v[34:37], v[144:147], v[210:213], v[34:37]
	v_mfma_f32_16x16x32_bf16 v[26:29], v[168:171], v[210:213], v[26:29]
	v_mfma_f32_16x16x32_bf16 v[18:21], v[144:147], v[218:221], v[18:21]
	v_mfma_f32_16x16x32_bf16 v[10:13], v[168:171], v[218:221], v[10:13]
	v_mfma_f32_16x16x32_bf16 v[62:65], v[164:167], v[198:201], v[62:65]
	v_mfma_f32_16x16x32_bf16 v[58:61], v[172:175], v[198:201], v[58:61]
	v_mfma_f32_16x16x32_bf16 v[50:53], v[164:167], v[206:209], v[50:53]
	v_mfma_f32_16x16x32_bf16 v[42:45], v[172:175], v[206:209], v[42:45]
	v_mfma_f32_16x16x32_bf16 v[34:37], v[164:167], v[214:217], v[34:37]
	v_mfma_f32_16x16x32_bf16 v[26:29], v[172:175], v[214:217], v[26:29]
	v_mfma_f32_16x16x32_bf16 v[18:21], v[164:167], v[222:225], v[18:21]
	v_mfma_f32_16x16x32_bf16 v[10:13], v[172:175], v[222:225], v[10:13]
	v_mfma_f32_16x16x32_bf16 v[54:57], v[178:181], v[194:197], v[54:57]
	v_mfma_f32_16x16x32_bf16 v[46:49], v[186:189], v[194:197], v[46:49]
	v_mfma_f32_16x16x32_bf16 v[38:41], v[178:181], v[202:205], v[38:41]
	v_mfma_f32_16x16x32_bf16 v[30:33], v[186:189], v[202:205], v[30:33]
	v_mfma_f32_16x16x32_bf16 v[22:25], v[178:181], v[210:213], v[22:25]
	v_mfma_f32_16x16x32_bf16 v[14:17], v[186:189], v[210:213], v[14:17]
	v_mfma_f32_16x16x32_bf16 v[6:9], v[178:181], v[218:221], v[6:9]
	v_mfma_f32_16x16x32_bf16 v[2:5], v[186:189], v[218:221], v[2:5]
	v_mfma_f32_16x16x32_bf16 v[54:57], v[182:185], v[198:201], v[54:57]
	v_mfma_f32_16x16x32_bf16 v[46:49], v[190:193], v[198:201], v[46:49]
	v_mfma_f32_16x16x32_bf16 v[38:41], v[182:185], v[206:209], v[38:41]
	v_mfma_f32_16x16x32_bf16 v[30:33], v[190:193], v[206:209], v[30:33]
	v_mfma_f32_16x16x32_bf16 v[22:25], v[182:185], v[214:217], v[22:25]
	v_mfma_f32_16x16x32_bf16 v[14:17], v[190:193], v[214:217], v[14:17]
	v_mfma_f32_16x16x32_bf16 v[6:9], v[182:185], v[222:225], v[6:9]
	s_setprio 0
	v_mfma_f32_16x16x32_bf16 v[2:5], v[190:193], v[222:225], v[2:5]
	s_barrier
	s_add_i32 s62, 0, 0x18000
	v_add_u32_e32 v163, s62, v148
	s_add_i32 s63, 0, 0x1c000
	ds_read_b128 v[144:147], v163
	ds_read_b128 v[164:167], v163 offset:1024
	ds_read_b128 v[168:171], v163 offset:2048
	ds_read_b128 v[172:175], v163 offset:3072
	v_add_u32_e32 v163, s63, v148
	ds_read_b128 v[178:181], v163
	ds_read_b128 v[182:185], v163 offset:1024
	ds_read_b128 v[186:189], v163 offset:2048
	ds_read_b128 v[190:193], v163 offset:3072
	s_add_u32 s2, s2, 0x40000
	s_addc_u32 s3, s3, 0
	s_mov_b32 m0, s44
	v_lshl_add_u64 v[234:235], s[2:3], 0, v[130:131]
	ds_read_b128 v[194:197], v160 offset:32768
	ds_read_b128 v[198:201], v160 offset:33792
	ds_read_b128 v[202:205], v160 offset:34816
	ds_read_b128 v[206:209], v160 offset:35840
	ds_read_b128 v[210:213], v160 offset:36864
	ds_read_b128 v[214:217], v160 offset:37888
	ds_read_b128 v[218:221], v160 offset:38912
	ds_read_b128 v[222:225], v160 offset:39936
	global_load_lds_dwordx4 v[234:235], off
	v_lshl_add_u64 v[234:235], s[2:3], 0, v[134:135]
	s_mov_b32 m0, s45
	s_nop 0
	global_load_lds_dwordx4 v[234:235], off
	s_waitcnt vmcnt(8)
	s_waitcnt lgkmcnt(0)
	s_setprio 1
	s_barrier
	v_mfma_f32_16x16x32_bf16 v[126:129], v[144:147], v[194:197], v[126:129]
	v_mfma_f32_16x16x32_bf16 v[122:125], v[168:171], v[194:197], v[122:125]
	v_mfma_f32_16x16x32_bf16 v[114:117], v[144:147], v[202:205], v[114:117]
	v_mfma_f32_16x16x32_bf16 v[106:109], v[168:171], v[202:205], v[106:109]
	v_mfma_f32_16x16x32_bf16 v[98:101], v[144:147], v[210:213], v[98:101]
	v_mfma_f32_16x16x32_bf16 v[90:93], v[168:171], v[210:213], v[90:93]
	v_mfma_f32_16x16x32_bf16 v[82:85], v[144:147], v[218:221], v[82:85]
	v_mfma_f32_16x16x32_bf16 v[74:77], v[168:171], v[218:221], v[74:77]
	v_mfma_f32_16x16x32_bf16 v[126:129], v[164:167], v[198:201], v[126:129]
	v_mfma_f32_16x16x32_bf16 v[122:125], v[172:175], v[198:201], v[122:125]
	v_mfma_f32_16x16x32_bf16 v[114:117], v[164:167], v[206:209], v[114:117]
	v_mfma_f32_16x16x32_bf16 v[106:109], v[172:175], v[206:209], v[106:109]
	v_mfma_f32_16x16x32_bf16 v[98:101], v[164:167], v[214:217], v[98:101]
	v_mfma_f32_16x16x32_bf16 v[90:93], v[172:175], v[214:217], v[90:93]
	v_mfma_f32_16x16x32_bf16 v[82:85], v[164:167], v[222:225], v[82:85]
	v_mfma_f32_16x16x32_bf16 v[74:77], v[172:175], v[222:225], v[74:77]
	v_mfma_f32_16x16x32_bf16 v[118:121], v[178:181], v[194:197], v[118:121]
	v_mfma_f32_16x16x32_bf16 v[110:113], v[186:189], v[194:197], v[110:113]
	v_mfma_f32_16x16x32_bf16 v[102:105], v[178:181], v[202:205], v[102:105]
	v_mfma_f32_16x16x32_bf16 v[94:97], v[186:189], v[202:205], v[94:97]
	v_mfma_f32_16x16x32_bf16 v[86:89], v[178:181], v[210:213], v[86:89]
	v_mfma_f32_16x16x32_bf16 v[78:81], v[186:189], v[210:213], v[78:81]
	v_mfma_f32_16x16x32_bf16 v[70:73], v[178:181], v[218:221], v[70:73]
	v_mfma_f32_16x16x32_bf16 v[66:69], v[186:189], v[218:221], v[66:69]
	v_mfma_f32_16x16x32_bf16 v[118:121], v[182:185], v[198:201], v[118:121]
	v_mfma_f32_16x16x32_bf16 v[110:113], v[190:193], v[198:201], v[110:113]
	v_mfma_f32_16x16x32_bf16 v[102:105], v[182:185], v[206:209], v[102:105]
	v_mfma_f32_16x16x32_bf16 v[94:97], v[190:193], v[206:209], v[94:97]
	v_mfma_f32_16x16x32_bf16 v[86:89], v[182:185], v[214:217], v[86:89]
	v_mfma_f32_16x16x32_bf16 v[78:81], v[190:193], v[214:217], v[78:81]
	v_mfma_f32_16x16x32_bf16 v[70:73], v[182:185], v[222:225], v[70:73]
	s_setprio 0
	v_mfma_f32_16x16x32_bf16 v[66:69], v[190:193], v[222:225], v[66:69]
	s_barrier
	s_add_i32 s2, s62, s41
	v_lshl_add_u64 v[226:227], v[226:227], 0, s[10:11]
	s_mov_b32 m0, s2
	ds_read_b128 v[194:197], v160 offset:49152
	ds_read_b128 v[198:201], v160 offset:50176
	ds_read_b128 v[202:205], v160 offset:51200
	ds_read_b128 v[206:209], v160 offset:52224
	ds_read_b128 v[210:213], v160 offset:53248
	ds_read_b128 v[214:217], v160 offset:54272
	ds_read_b128 v[218:221], v160 offset:55296
	ds_read_b128 v[222:225], v160 offset:56320
	global_load_lds_dwordx4 v[226:227], off
	s_add_i32 m0, s2, 0x2000
	s_add_u32 s2, s38, 0x40080
	v_lshl_add_u64 v[226:227], v[228:229], 0, s[10:11]
	s_addc_u32 s3, s39, 0
	s_add_i32 s38, s63, s41
	global_load_lds_dwordx4 v[226:227], off
	v_lshl_add_u64 v[226:227], s[2:3], 0, v[132:133]
	s_mov_b32 m0, s38
	s_nop 0
	global_load_lds_dwordx4 v[226:227], off
	v_lshl_add_u64 v[226:227], s[2:3], 0, v[136:137]
	s_add_i32 m0, s38, 0x2000
	s_nop 0
	global_load_lds_dwordx4 v[226:227], off
	v_lshl_add_u64 v[226:227], v[230:231], 0, s[10:11]
	s_mov_b32 m0, s47
	s_nop 0
	global_load_lds_dwordx4 v[226:227], off
	v_lshl_add_u64 v[226:227], v[232:233], 0, s[10:11]
	s_mov_b32 m0, s48
	s_nop 0
	global_load_lds_dwordx4 v[226:227], off
	s_waitcnt vmcnt(8)
	s_waitcnt lgkmcnt(0)
	s_setprio 1
	s_barrier
	v_mfma_f32_16x16x32_bf16 v[62:65], v[144:147], v[194:197], v[62:65]
	v_mfma_f32_16x16x32_bf16 v[58:61], v[168:171], v[194:197], v[58:61]
	v_mfma_f32_16x16x32_bf16 v[50:53], v[144:147], v[202:205], v[50:53]
	v_mfma_f32_16x16x32_bf16 v[42:45], v[168:171], v[202:205], v[42:45]
	v_mfma_f32_16x16x32_bf16 v[34:37], v[144:147], v[210:213], v[34:37]
	v_mfma_f32_16x16x32_bf16 v[26:29], v[168:171], v[210:213], v[26:29]
	v_mfma_f32_16x16x32_bf16 v[18:21], v[144:147], v[218:221], v[18:21]
	v_mfma_f32_16x16x32_bf16 v[10:13], v[168:171], v[218:221], v[10:13]
	v_mfma_f32_16x16x32_bf16 v[62:65], v[164:167], v[198:201], v[62:65]
	v_mfma_f32_16x16x32_bf16 v[58:61], v[172:175], v[198:201], v[58:61]
	v_mfma_f32_16x16x32_bf16 v[50:53], v[164:167], v[206:209], v[50:53]
	v_mfma_f32_16x16x32_bf16 v[42:45], v[172:175], v[206:209], v[42:45]
	v_mfma_f32_16x16x32_bf16 v[34:37], v[164:167], v[214:217], v[34:37]
	v_mfma_f32_16x16x32_bf16 v[26:29], v[172:175], v[214:217], v[26:29]
	v_mfma_f32_16x16x32_bf16 v[18:21], v[164:167], v[222:225], v[18:21]
	v_mfma_f32_16x16x32_bf16 v[10:13], v[172:175], v[222:225], v[10:13]
	v_mfma_f32_16x16x32_bf16 v[54:57], v[178:181], v[194:197], v[54:57]
	v_mfma_f32_16x16x32_bf16 v[46:49], v[186:189], v[194:197], v[46:49]
	v_mfma_f32_16x16x32_bf16 v[38:41], v[178:181], v[202:205], v[38:41]
	v_mfma_f32_16x16x32_bf16 v[30:33], v[186:189], v[202:205], v[30:33]
	v_mfma_f32_16x16x32_bf16 v[22:25], v[178:181], v[210:213], v[22:25]
	v_mfma_f32_16x16x32_bf16 v[14:17], v[186:189], v[210:213], v[14:17]
	v_mfma_f32_16x16x32_bf16 v[6:9], v[178:181], v[218:221], v[6:9]
	v_mfma_f32_16x16x32_bf16 v[2:5], v[186:189], v[218:221], v[2:5]
	v_mfma_f32_16x16x32_bf16 v[54:57], v[182:185], v[198:201], v[54:57]
	v_mfma_f32_16x16x32_bf16 v[46:49], v[190:193], v[198:201], v[46:49]
	v_mfma_f32_16x16x32_bf16 v[38:41], v[182:185], v[206:209], v[38:41]
	v_mfma_f32_16x16x32_bf16 v[30:33], v[190:193], v[206:209], v[30:33]
	v_mfma_f32_16x16x32_bf16 v[22:25], v[182:185], v[214:217], v[22:25]
	v_mfma_f32_16x16x32_bf16 v[14:17], v[190:193], v[214:217], v[14:17]
	v_mfma_f32_16x16x32_bf16 v[6:9], v[182:185], v[222:225], v[6:9]
	s_setprio 0
	v_mfma_f32_16x16x32_bf16 v[2:5], v[190:193], v[222:225], v[2:5]
	s_barrier
	s_add_i32 s61, s61, 2
	s_add_u32 s36, s36, 0x100
	s_addc_u32 s37, s37, 0
	s_add_u32 s59, s59, 0x100
	s_addc_u32 s60, s60, 0
	s_cmp_gt_u32 s61, 13
	s_cbranch_scc0 .LBB0_1179

.Lpk1239_peel:
	ds_read_b128 v[152:155], v148
	ds_read_b128 v[156:159], v148 offset:1024
	ds_read_b128 v[160:163], v148 offset:2048
	ds_read_b128 v[164:167], v148 offset:3072
	ds_read_b128 v[168:171], v149
	ds_read_b128 v[172:175], v149 offset:1024
	ds_read_b128 v[178:181], v149 offset:2048
	ds_read_b128 v[182:185], v149 offset:3072
	s_add_u32 s2, s36, 0xfffc0080
	s_addc_u32 s3, s37, -1
	s_cmp_eq_u32 s62, 12
	s_cselect_b32 s3, s19, s3
	s_cselect_b32 s2, s21, s2
	s_cselect_b32 s39, s58, s61
	s_cselect_b32 s38, s59, s60
	v_lshl_add_u64 v[144:145], s[36:37], 0, v[138:139]
	s_add_i32 m0, s44, 0xc000
	ds_read_b128 v[186:189], v150
	ds_read_b128 v[190:193], v150 offset:1024
	ds_read_b128 v[194:197], v150 offset:2048
	ds_read_b128 v[198:201], v150 offset:3072
	ds_read_b128 v[202:205], v150 offset:4096
	ds_read_b128 v[206:209], v150 offset:5120
	ds_read_b128 v[210:213], v150 offset:6144
	ds_read_b128 v[214:217], v150 offset:7168
	global_load_lds_dwordx4 v[144:145], off
	v_lshl_add_u64 v[144:145], s[36:37], 0, v[140:141]
	s_add_i32 m0, s44, 0xe000
	s_nop 0
	global_load_lds_dwordx4 v[144:145], off
	s_waitcnt vmcnt(8)
	s_waitcnt lgkmcnt(0)
	s_setprio 1
	s_barrier
	v_mfma_f32_16x16x32_bf16 v[126:129], v[152:155], v[186:189], 0
	v_mfma_f32_16x16x32_bf16 v[122:125], v[160:163], v[186:189], 0
	v_mfma_f32_16x16x32_bf16 v[114:117], v[152:155], v[194:197], 0
	v_mfma_f32_16x16x32_bf16 v[106:109], v[160:163], v[194:197], 0
	v_mfma_f32_16x16x32_bf16 v[98:101], v[152:155], v[202:205], 0
	v_mfma_f32_16x16x32_bf16 v[90:93], v[160:163], v[202:205], 0
	v_mfma_f32_16x16x32_bf16 v[82:85], v[152:155], v[210:213], 0
	v_mfma_f32_16x16x32_bf16 v[74:77], v[160:163], v[210:213], 0
	v_mfma_f32_16x16x32_bf16 v[126:129], v[156:159], v[190:193], v[126:129]
	v_mfma_f32_16x16x32_bf16 v[122:125], v[164:167], v[190:193], v[122:125]
	v_mfma_f32_16x16x32_bf16 v[114:117], v[156:159], v[198:201], v[114:117]
	v_mfma_f32_16x16x32_bf16 v[106:109], v[164:167], v[198:201], v[106:109]
	v_mfma_f32_16x16x32_bf16 v[98:101], v[156:159], v[206:209], v[98:101]
	v_mfma_f32_16x16x32_bf16 v[90:93], v[164:167], v[206:209], v[90:93]
	v_mfma_f32_16x16x32_bf16 v[82:85], v[156:159], v[214:217], v[82:85]
	v_mfma_f32_16x16x32_bf16 v[74:77], v[164:167], v[214:217], v[74:77]
	v_mfma_f32_16x16x32_bf16 v[118:121], v[168:171], v[186:189], 0
	v_mfma_f32_16x16x32_bf16 v[110:113], v[178:181], v[186:189], 0
	v_mfma_f32_16x16x32_bf16 v[102:105], v[168:171], v[194:197], 0
	v_mfma_f32_16x16x32_bf16 v[94:97], v[178:181], v[194:197], 0
	v_mfma_f32_16x16x32_bf16 v[86:89], v[168:171], v[202:205], 0
	v_mfma_f32_16x16x32_bf16 v[78:81], v[178:181], v[202:205], 0
	v_mfma_f32_16x16x32_bf16 v[70:73], v[168:171], v[210:213], 0
	v_mfma_f32_16x16x32_bf16 v[66:69], v[178:181], v[210:213], 0
	v_mfma_f32_16x16x32_bf16 v[118:121], v[172:175], v[190:193], v[118:121]
	v_mfma_f32_16x16x32_bf16 v[110:113], v[182:185], v[190:193], v[110:113]
	v_mfma_f32_16x16x32_bf16 v[102:105], v[172:175], v[198:201], v[102:105]
	v_mfma_f32_16x16x32_bf16 v[94:97], v[182:185], v[198:201], v[94:97]
	v_mfma_f32_16x16x32_bf16 v[86:89], v[172:175], v[206:209], v[86:89]
	v_mfma_f32_16x16x32_bf16 v[78:81], v[182:185], v[206:209], v[78:81]
	v_mfma_f32_16x16x32_bf16 v[70:73], v[172:175], v[214:217], v[70:73]
	s_setprio 0
	v_mfma_f32_16x16x32_bf16 v[66:69], v[182:185], v[214:217], v[66:69]
	s_barrier
	s_add_i32 s63, s51, s43
	v_lshl_add_u64 v[144:145], s[38:39], 0, v[132:133]
	s_mov_b32 m0, s63
	ds_read_b128 v[186:189], v150 offset:16384
	ds_read_b128 v[190:193], v150 offset:17408
	ds_read_b128 v[194:197], v150 offset:18432
	ds_read_b128 v[198:201], v150 offset:19456
	ds_read_b128 v[202:205], v150 offset:20480
	ds_read_b128 v[206:209], v150 offset:21504
	ds_read_b128 v[210:213], v150 offset:22528
	ds_read_b128 v[214:217], v150 offset:23552
	global_load_lds_dwordx4 v[144:145], off
	s_add_i32 m0, s63, 0x2000
	s_add_u32 s64, s38, 0x40000
	v_lshl_add_u64 v[218:219], s[38:39], 0, v[136:137]
	s_addc_u32 s65, s39, 0
	s_add_i32 s63, s52, s43
	global_load_lds_dwordx4 v[218:219], off
	v_lshl_add_u64 v[220:221], s[64:65], 0, v[132:133]
	s_mov_b32 m0, s63
	v_lshl_add_u64 v[222:223], s[2:3], 0, v[134:135]
	global_load_lds_dwordx4 v[220:221], off
	v_lshl_add_u64 v[220:221], s[64:65], 0, v[136:137]
	s_add_i32 m0, s63, 0x2000
	s_nop 0
	global_load_lds_dwordx4 v[220:221], off
	v_lshl_add_u64 v[220:221], s[2:3], 0, v[130:131]
	s_mov_b32 m0, s44
	s_nop 0
	global_load_lds_dwordx4 v[220:221], off
	s_mov_b32 m0, s35
	s_nop 0
	global_load_lds_dwordx4 v[222:223], off
	s_waitcnt vmcnt(8)
	s_waitcnt lgkmcnt(0)
	s_setprio 1
	s_barrier
	v_mfma_f32_16x16x32_bf16 v[62:65], v[152:155], v[186:189], 0
	v_mfma_f32_16x16x32_bf16 v[58:61], v[160:163], v[186:189], 0
	v_mfma_f32_16x16x32_bf16 v[50:53], v[152:155], v[194:197], 0
	v_mfma_f32_16x16x32_bf16 v[42:45], v[160:163], v[194:197], 0
	v_mfma_f32_16x16x32_bf16 v[34:37], v[152:155], v[202:205], 0
	v_mfma_f32_16x16x32_bf16 v[26:29], v[160:163], v[202:205], 0
	v_mfma_f32_16x16x32_bf16 v[18:21], v[152:155], v[210:213], 0
	v_mfma_f32_16x16x32_bf16 v[10:13], v[160:163], v[210:213], 0
	v_mfma_f32_16x16x32_bf16 v[62:65], v[156:159], v[190:193], v[62:65]
	v_mfma_f32_16x16x32_bf16 v[58:61], v[164:167], v[190:193], v[58:61]
	v_mfma_f32_16x16x32_bf16 v[50:53], v[156:159], v[198:201], v[50:53]
	v_mfma_f32_16x16x32_bf16 v[42:45], v[164:167], v[198:201], v[42:45]
	v_mfma_f32_16x16x32_bf16 v[34:37], v[156:159], v[206:209], v[34:37]
	v_mfma_f32_16x16x32_bf16 v[26:29], v[164:167], v[206:209], v[26:29]
	v_mfma_f32_16x16x32_bf16 v[18:21], v[156:159], v[214:217], v[18:21]
	v_mfma_f32_16x16x32_bf16 v[10:13], v[164:167], v[214:217], v[10:13]
	v_mfma_f32_16x16x32_bf16 v[54:57], v[168:171], v[186:189], 0
	v_mfma_f32_16x16x32_bf16 v[46:49], v[178:181], v[186:189], 0
	v_mfma_f32_16x16x32_bf16 v[38:41], v[168:171], v[194:197], 0
	v_mfma_f32_16x16x32_bf16 v[30:33], v[178:181], v[194:197], 0
	v_mfma_f32_16x16x32_bf16 v[22:25], v[168:171], v[202:205], 0
	v_mfma_f32_16x16x32_bf16 v[14:17], v[178:181], v[202:205], 0
	v_mfma_f32_16x16x32_bf16 v[6:9], v[168:171], v[210:213], 0
	v_mfma_f32_16x16x32_bf16 v[2:5], v[178:181], v[210:213], 0
	v_mfma_f32_16x16x32_bf16 v[54:57], v[172:175], v[190:193], v[54:57]
	v_mfma_f32_16x16x32_bf16 v[46:49], v[182:185], v[190:193], v[46:49]
	v_mfma_f32_16x16x32_bf16 v[38:41], v[172:175], v[198:201], v[38:41]
	v_mfma_f32_16x16x32_bf16 v[30:33], v[182:185], v[198:201], v[30:33]
	v_mfma_f32_16x16x32_bf16 v[22:25], v[172:175], v[206:209], v[22:25]
	v_mfma_f32_16x16x32_bf16 v[14:17], v[182:185], v[206:209], v[14:17]
	v_mfma_f32_16x16x32_bf16 v[6:9], v[172:175], v[214:217], v[6:9]
	s_setprio 0
	v_mfma_f32_16x16x32_bf16 v[2:5], v[182:185], v[214:217], v[2:5]
	s_barrier
	s_add_i32 s63, 0, 0x18000
	v_add_u32_e32 v151, s63, v146
	s_add_i32 s64, 0, 0x1c000
	ds_read_b128 v[152:155], v151
	ds_read_b128 v[156:159], v151 offset:1024
	ds_read_b128 v[160:163], v151 offset:2048
	ds_read_b128 v[164:167], v151 offset:3072
	v_add_u32_e32 v151, s64, v146
	ds_read_b128 v[168:171], v151
	ds_read_b128 v[172:175], v151 offset:1024
	ds_read_b128 v[178:181], v151 offset:2048
	ds_read_b128 v[182:185], v151 offset:3072
	s_add_u32 s2, s2, 0x40000
	s_addc_u32 s3, s3, 0
	s_mov_b32 m0, s45
	v_lshl_add_u64 v[224:225], s[2:3], 0, v[130:131]
	ds_read_b128 v[186:189], v150 offset:32768
	ds_read_b128 v[190:193], v150 offset:33792
	ds_read_b128 v[194:197], v150 offset:34816
	ds_read_b128 v[198:201], v150 offset:35840
	ds_read_b128 v[202:205], v150 offset:36864
	ds_read_b128 v[206:209], v150 offset:37888
	ds_read_b128 v[210:213], v150 offset:38912
	ds_read_b128 v[214:217], v150 offset:39936
	global_load_lds_dwordx4 v[224:225], off
	v_lshl_add_u64 v[224:225], s[2:3], 0, v[134:135]
	s_mov_b32 m0, s46
	s_nop 0
	global_load_lds_dwordx4 v[224:225], off
	s_waitcnt vmcnt(8)
	s_waitcnt lgkmcnt(0)
	s_setprio 1
	s_barrier
	v_mfma_f32_16x16x32_bf16 v[126:129], v[152:155], v[186:189], v[126:129]
	v_mfma_f32_16x16x32_bf16 v[122:125], v[160:163], v[186:189], v[122:125]
	v_mfma_f32_16x16x32_bf16 v[114:117], v[152:155], v[194:197], v[114:117]
	v_mfma_f32_16x16x32_bf16 v[106:109], v[160:163], v[194:197], v[106:109]
	v_mfma_f32_16x16x32_bf16 v[98:101], v[152:155], v[202:205], v[98:101]
	v_mfma_f32_16x16x32_bf16 v[90:93], v[160:163], v[202:205], v[90:93]
	v_mfma_f32_16x16x32_bf16 v[82:85], v[152:155], v[210:213], v[82:85]
	v_mfma_f32_16x16x32_bf16 v[74:77], v[160:163], v[210:213], v[74:77]
	v_mfma_f32_16x16x32_bf16 v[126:129], v[156:159], v[190:193], v[126:129]
	v_mfma_f32_16x16x32_bf16 v[122:125], v[164:167], v[190:193], v[122:125]
	v_mfma_f32_16x16x32_bf16 v[114:117], v[156:159], v[198:201], v[114:117]
	v_mfma_f32_16x16x32_bf16 v[106:109], v[164:167], v[198:201], v[106:109]
	v_mfma_f32_16x16x32_bf16 v[98:101], v[156:159], v[206:209], v[98:101]
	v_mfma_f32_16x16x32_bf16 v[90:93], v[164:167], v[206:209], v[90:93]
	v_mfma_f32_16x16x32_bf16 v[82:85], v[156:159], v[214:217], v[82:85]
	v_mfma_f32_16x16x32_bf16 v[74:77], v[164:167], v[214:217], v[74:77]
	v_mfma_f32_16x16x32_bf16 v[118:121], v[168:171], v[186:189], v[118:121]
	v_mfma_f32_16x16x32_bf16 v[110:113], v[178:181], v[186:189], v[110:113]
	v_mfma_f32_16x16x32_bf16 v[102:105], v[168:171], v[194:197], v[102:105]
	v_mfma_f32_16x16x32_bf16 v[94:97], v[178:181], v[194:197], v[94:97]
	v_mfma_f32_16x16x32_bf16 v[86:89], v[168:171], v[202:205], v[86:89]
	v_mfma_f32_16x16x32_bf16 v[78:81], v[178:181], v[202:205], v[78:81]
	v_mfma_f32_16x16x32_bf16 v[70:73], v[168:171], v[210:213], v[70:73]
	v_mfma_f32_16x16x32_bf16 v[66:69], v[178:181], v[210:213], v[66:69]
	v_mfma_f32_16x16x32_bf16 v[118:121], v[172:175], v[190:193], v[118:121]
	v_mfma_f32_16x16x32_bf16 v[110:113], v[182:185], v[190:193], v[110:113]
	v_mfma_f32_16x16x32_bf16 v[102:105], v[172:175], v[198:201], v[102:105]
	v_mfma_f32_16x16x32_bf16 v[94:97], v[182:185], v[198:201], v[94:97]
	v_mfma_f32_16x16x32_bf16 v[86:89], v[172:175], v[206:209], v[86:89]
	v_mfma_f32_16x16x32_bf16 v[78:81], v[182:185], v[206:209], v[78:81]
	v_mfma_f32_16x16x32_bf16 v[70:73], v[172:175], v[214:217], v[70:73]
	s_setprio 0
	v_mfma_f32_16x16x32_bf16 v[66:69], v[182:185], v[214:217], v[66:69]
	s_barrier
	s_add_i32 s2, s63, s43
	v_lshl_add_u64 v[144:145], v[144:145], 0, s[8:9]
	s_mov_b32 m0, s2
	ds_read_b128 v[186:189], v150 offset:49152
	ds_read_b128 v[190:193], v150 offset:50176
	ds_read_b128 v[194:197], v150 offset:51200
	ds_read_b128 v[198:201], v150 offset:52224
	ds_read_b128 v[202:205], v150 offset:53248
	ds_read_b128 v[206:209], v150 offset:54272
	ds_read_b128 v[210:213], v150 offset:55296
	ds_read_b128 v[214:217], v150 offset:56320
	global_load_lds_dwordx4 v[144:145], off
	s_add_i32 m0, s2, 0x2000
	s_add_u32 s2, s38, 0x40080
	v_lshl_add_u64 v[144:145], v[218:219], 0, s[8:9]
	s_addc_u32 s3, s39, 0
	s_add_i32 s38, s64, s43
	global_load_lds_dwordx4 v[144:145], off
	v_lshl_add_u64 v[144:145], s[2:3], 0, v[132:133]
	s_mov_b32 m0, s38
	s_nop 0
	global_load_lds_dwordx4 v[144:145], off
	v_lshl_add_u64 v[144:145], s[2:3], 0, v[136:137]
	s_add_i32 m0, s38, 0x2000
	s_nop 0
	global_load_lds_dwordx4 v[144:145], off
	v_lshl_add_u64 v[144:145], v[220:221], 0, s[8:9]
	s_mov_b32 m0, s48
	s_nop 0
	global_load_lds_dwordx4 v[144:145], off
	v_lshl_add_u64 v[144:145], v[222:223], 0, s[8:9]
	s_mov_b32 m0, s49
	s_nop 0
	global_load_lds_dwordx4 v[144:145], off
	s_waitcnt vmcnt(8)
	s_waitcnt lgkmcnt(0)
	s_setprio 1
	s_barrier
	v_mfma_f32_16x16x32_bf16 v[62:65], v[152:155], v[186:189], v[62:65]
	v_mfma_f32_16x16x32_bf16 v[58:61], v[160:163], v[186:189], v[58:61]
	v_mfma_f32_16x16x32_bf16 v[50:53], v[152:155], v[194:197], v[50:53]
	v_mfma_f32_16x16x32_bf16 v[42:45], v[160:163], v[194:197], v[42:45]
	v_mfma_f32_16x16x32_bf16 v[34:37], v[152:155], v[202:205], v[34:37]
	v_mfma_f32_16x16x32_bf16 v[26:29], v[160:163], v[202:205], v[26:29]
	v_mfma_f32_16x16x32_bf16 v[18:21], v[152:155], v[210:213], v[18:21]
	v_mfma_f32_16x16x32_bf16 v[10:13], v[160:163], v[210:213], v[10:13]
	v_mfma_f32_16x16x32_bf16 v[62:65], v[156:159], v[190:193], v[62:65]
	v_mfma_f32_16x16x32_bf16 v[58:61], v[164:167], v[190:193], v[58:61]
	v_mfma_f32_16x16x32_bf16 v[50:53], v[156:159], v[198:201], v[50:53]
	v_mfma_f32_16x16x32_bf16 v[42:45], v[164:167], v[198:201], v[42:45]
	v_mfma_f32_16x16x32_bf16 v[34:37], v[156:159], v[206:209], v[34:37]
	v_mfma_f32_16x16x32_bf16 v[26:29], v[164:167], v[206:209], v[26:29]
	v_mfma_f32_16x16x32_bf16 v[18:21], v[156:159], v[214:217], v[18:21]
	v_mfma_f32_16x16x32_bf16 v[10:13], v[164:167], v[214:217], v[10:13]
	v_mfma_f32_16x16x32_bf16 v[54:57], v[168:171], v[186:189], v[54:57]
	v_mfma_f32_16x16x32_bf16 v[46:49], v[178:181], v[186:189], v[46:49]
	v_mfma_f32_16x16x32_bf16 v[38:41], v[168:171], v[194:197], v[38:41]
	v_mfma_f32_16x16x32_bf16 v[30:33], v[178:181], v[194:197], v[30:33]
	v_mfma_f32_16x16x32_bf16 v[22:25], v[168:171], v[202:205], v[22:25]
	v_mfma_f32_16x16x32_bf16 v[14:17], v[178:181], v[202:205], v[14:17]
	v_mfma_f32_16x16x32_bf16 v[6:9], v[168:171], v[210:213], v[6:9]
	v_mfma_f32_16x16x32_bf16 v[2:5], v[178:181], v[210:213], v[2:5]
	v_mfma_f32_16x16x32_bf16 v[54:57], v[172:175], v[190:193], v[54:57]
	v_mfma_f32_16x16x32_bf16 v[46:49], v[182:185], v[190:193], v[46:49]
	v_mfma_f32_16x16x32_bf16 v[38:41], v[172:175], v[198:201], v[38:41]
	v_mfma_f32_16x16x32_bf16 v[30:33], v[182:185], v[198:201], v[30:33]
	v_mfma_f32_16x16x32_bf16 v[22:25], v[172:175], v[206:209], v[22:25]
	v_mfma_f32_16x16x32_bf16 v[14:17], v[182:185], v[206:209], v[14:17]
	v_mfma_f32_16x16x32_bf16 v[6:9], v[172:175], v[214:217], v[6:9]
	s_setprio 0
	v_mfma_f32_16x16x32_bf16 v[2:5], v[182:185], v[214:217], v[2:5]
	s_barrier
	s_add_i32 s62, s62, 2
	s_add_u32 s36, s36, 0x100
	s_addc_u32 s37, s37, 0
	s_add_u32 s60, s60, 0x100
	s_addc_u32 s61, s61, 0
	s_cmp_gt_u32 s62, 13
	s_cbranch_scc0 .LBB0_1239
	s_branch .Lpk1239_exit
.LBB0_1239:
	ds_read_b128 v[152:155], v148
	ds_read_b128 v[156:159], v148 offset:1024
	ds_read_b128 v[160:163], v148 offset:2048
	ds_read_b128 v[164:167], v148 offset:3072
	ds_read_b128 v[168:171], v149
	ds_read_b128 v[172:175], v149 offset:1024
	ds_read_b128 v[178:181], v149 offset:2048
	ds_read_b128 v[182:185], v149 offset:3072
	s_add_u32 s2, s36, 0xfffc0080
	s_addc_u32 s3, s37, -1
	s_cmp_eq_u32 s62, 12
	s_cselect_b32 s3, s19, s3
	s_cselect_b32 s2, s21, s2
	s_cselect_b32 s39, s58, s61
	s_cselect_b32 s38, s59, s60
	v_lshl_add_u64 v[144:145], s[36:37], 0, v[138:139]
	s_add_i32 m0, s44, 0xc000
	ds_read_b128 v[186:189], v150
	ds_read_b128 v[190:193], v150 offset:1024
	ds_read_b128 v[194:197], v150 offset:2048
	ds_read_b128 v[198:201], v150 offset:3072
	ds_read_b128 v[202:205], v150 offset:4096
	ds_read_b128 v[206:209], v150 offset:5120
	ds_read_b128 v[210:213], v150 offset:6144
	ds_read_b128 v[214:217], v150 offset:7168
	global_load_lds_dwordx4 v[144:145], off
	v_lshl_add_u64 v[144:145], s[36:37], 0, v[140:141]
	s_add_i32 m0, s44, 0xe000
	s_nop 0
	global_load_lds_dwordx4 v[144:145], off
	s_waitcnt vmcnt(8)
	s_waitcnt lgkmcnt(0)
	s_setprio 1
	s_barrier
	v_mfma_f32_16x16x32_bf16 v[126:129], v[152:155], v[186:189], v[126:129]
	v_mfma_f32_16x16x32_bf16 v[122:125], v[160:163], v[186:189], v[122:125]
	v_mfma_f32_16x16x32_bf16 v[114:117], v[152:155], v[194:197], v[114:117]
	v_mfma_f32_16x16x32_bf16 v[106:109], v[160:163], v[194:197], v[106:109]
	v_mfma_f32_16x16x32_bf16 v[98:101], v[152:155], v[202:205], v[98:101]
	v_mfma_f32_16x16x32_bf16 v[90:93], v[160:163], v[202:205], v[90:93]
	v_mfma_f32_16x16x32_bf16 v[82:85], v[152:155], v[210:213], v[82:85]
	v_mfma_f32_16x16x32_bf16 v[74:77], v[160:163], v[210:213], v[74:77]
	v_mfma_f32_16x16x32_bf16 v[126:129], v[156:159], v[190:193], v[126:129]
	v_mfma_f32_16x16x32_bf16 v[122:125], v[164:167], v[190:193], v[122:125]
	v_mfma_f32_16x16x32_bf16 v[114:117], v[156:159], v[198:201], v[114:117]
	v_mfma_f32_16x16x32_bf16 v[106:109], v[164:167], v[198:201], v[106:109]
	v_mfma_f32_16x16x32_bf16 v[98:101], v[156:159], v[206:209], v[98:101]
	v_mfma_f32_16x16x32_bf16 v[90:93], v[164:167], v[206:209], v[90:93]
	v_mfma_f32_16x16x32_bf16 v[82:85], v[156:159], v[214:217], v[82:85]
	v_mfma_f32_16x16x32_bf16 v[74:77], v[164:167], v[214:217], v[74:77]
	v_mfma_f32_16x16x32_bf16 v[118:121], v[168:171], v[186:189], v[118:121]
	v_mfma_f32_16x16x32_bf16 v[110:113], v[178:181], v[186:189], v[110:113]
	v_mfma_f32_16x16x32_bf16 v[102:105], v[168:171], v[194:197], v[102:105]
	v_mfma_f32_16x16x32_bf16 v[94:97], v[178:181], v[194:197], v[94:97]
	v_mfma_f32_16x16x32_bf16 v[86:89], v[168:171], v[202:205], v[86:89]
	v_mfma_f32_16x16x32_bf16 v[78:81], v[178:181], v[202:205], v[78:81]
	v_mfma_f32_16x16x32_bf16 v[70:73], v[168:171], v[210:213], v[70:73]
	v_mfma_f32_16x16x32_bf16 v[66:69], v[178:181], v[210:213], v[66:69]
	v_mfma_f32_16x16x32_bf16 v[118:121], v[172:175], v[190:193], v[118:121]
	v_mfma_f32_16x16x32_bf16 v[110:113], v[182:185], v[190:193], v[110:113]
	v_mfma_f32_16x16x32_bf16 v[102:105], v[172:175], v[198:201], v[102:105]
	v_mfma_f32_16x16x32_bf16 v[94:97], v[182:185], v[198:201], v[94:97]
	v_mfma_f32_16x16x32_bf16 v[86:89], v[172:175], v[206:209], v[86:89]
	v_mfma_f32_16x16x32_bf16 v[78:81], v[182:185], v[206:209], v[78:81]
	v_mfma_f32_16x16x32_bf16 v[70:73], v[172:175], v[214:217], v[70:73]
	s_setprio 0
	v_mfma_f32_16x16x32_bf16 v[66:69], v[182:185], v[214:217], v[66:69]
	s_barrier
	s_add_i32 s63, s51, s43
	v_lshl_add_u64 v[144:145], s[38:39], 0, v[132:133]
	s_mov_b32 m0, s63
	ds_read_b128 v[186:189], v150 offset:16384
	ds_read_b128 v[190:193], v150 offset:17408
	ds_read_b128 v[194:197], v150 offset:18432
	ds_read_b128 v[198:201], v150 offset:19456
	ds_read_b128 v[202:205], v150 offset:20480
	ds_read_b128 v[206:209], v150 offset:21504
	ds_read_b128 v[210:213], v150 offset:22528
	ds_read_b128 v[214:217], v150 offset:23552
	global_load_lds_dwordx4 v[144:145], off
	s_add_i32 m0, s63, 0x2000
	s_add_u32 s64, s38, 0x40000
	v_lshl_add_u64 v[218:219], s[38:39], 0, v[136:137]
	s_addc_u32 s65, s39, 0
	s_add_i32 s63, s52, s43
	global_load_lds_dwordx4 v[218:219], off
	v_lshl_add_u64 v[220:221], s[64:65], 0, v[132:133]
	s_mov_b32 m0, s63
	v_lshl_add_u64 v[222:223], s[2:3], 0, v[134:135]
	global_load_lds_dwordx4 v[220:221], off
	v_lshl_add_u64 v[220:221], s[64:65], 0, v[136:137]
	s_add_i32 m0, s63, 0x2000
	s_nop 0
	global_load_lds_dwordx4 v[220:221], off
	v_lshl_add_u64 v[220:221], s[2:3], 0, v[130:131]
	s_mov_b32 m0, s44
	s_nop 0
	global_load_lds_dwordx4 v[220:221], off
	s_mov_b32 m0, s35
	s_nop 0
	global_load_lds_dwordx4 v[222:223], off
	s_waitcnt vmcnt(8)
	s_waitcnt lgkmcnt(0)
	s_setprio 1
	s_barrier
	v_mfma_f32_16x16x32_bf16 v[62:65], v[152:155], v[186:189], v[62:65]
	v_mfma_f32_16x16x32_bf16 v[58:61], v[160:163], v[186:189], v[58:61]
	v_mfma_f32_16x16x32_bf16 v[50:53], v[152:155], v[194:197], v[50:53]
	v_mfma_f32_16x16x32_bf16 v[42:45], v[160:163], v[194:197], v[42:45]
	v_mfma_f32_16x16x32_bf16 v[34:37], v[152:155], v[202:205], v[34:37]
	v_mfma_f32_16x16x32_bf16 v[26:29], v[160:163], v[202:205], v[26:29]
	v_mfma_f32_16x16x32_bf16 v[18:21], v[152:155], v[210:213], v[18:21]
	v_mfma_f32_16x16x32_bf16 v[10:13], v[160:163], v[210:213], v[10:13]
	v_mfma_f32_16x16x32_bf16 v[62:65], v[156:159], v[190:193], v[62:65]
	v_mfma_f32_16x16x32_bf16 v[58:61], v[164:167], v[190:193], v[58:61]
	v_mfma_f32_16x16x32_bf16 v[50:53], v[156:159], v[198:201], v[50:53]
	v_mfma_f32_16x16x32_bf16 v[42:45], v[164:167], v[198:201], v[42:45]
	v_mfma_f32_16x16x32_bf16 v[34:37], v[156:159], v[206:209], v[34:37]
	v_mfma_f32_16x16x32_bf16 v[26:29], v[164:167], v[206:209], v[26:29]
	v_mfma_f32_16x16x32_bf16 v[18:21], v[156:159], v[214:217], v[18:21]
	v_mfma_f32_16x16x32_bf16 v[10:13], v[164:167], v[214:217], v[10:13]
	v_mfma_f32_16x16x32_bf16 v[54:57], v[168:171], v[186:189], v[54:57]
	v_mfma_f32_16x16x32_bf16 v[46:49], v[178:181], v[186:189], v[46:49]
	v_mfma_f32_16x16x32_bf16 v[38:41], v[168:171], v[194:197], v[38:41]
	v_mfma_f32_16x16x32_bf16 v[30:33], v[178:181], v[194:197], v[30:33]
	v_mfma_f32_16x16x32_bf16 v[22:25], v[168:171], v[202:205], v[22:25]
	v_mfma_f32_16x16x32_bf16 v[14:17], v[178:181], v[202:205], v[14:17]
	v_mfma_f32_16x16x32_bf16 v[6:9], v[168:171], v[210:213], v[6:9]
	v_mfma_f32_16x16x32_bf16 v[2:5], v[178:181], v[210:213], v[2:5]
	v_mfma_f32_16x16x32_bf16 v[54:57], v[172:175], v[190:193], v[54:57]
	v_mfma_f32_16x16x32_bf16 v[46:49], v[182:185], v[190:193], v[46:49]
	v_mfma_f32_16x16x32_bf16 v[38:41], v[172:175], v[198:201], v[38:41]
	v_mfma_f32_16x16x32_bf16 v[30:33], v[182:185], v[198:201], v[30:33]
	v_mfma_f32_16x16x32_bf16 v[22:25], v[172:175], v[206:209], v[22:25]
	v_mfma_f32_16x16x32_bf16 v[14:17], v[182:185], v[206:209], v[14:17]
	v_mfma_f32_16x16x32_bf16 v[6:9], v[172:175], v[214:217], v[6:9]
	s_setprio 0
	v_mfma_f32_16x16x32_bf16 v[2:5], v[182:185], v[214:217], v[2:5]
	s_barrier
	s_add_i32 s63, 0, 0x18000
	v_add_u32_e32 v151, s63, v146
	s_add_i32 s64, 0, 0x1c000
	ds_read_b128 v[152:155], v151
	ds_read_b128 v[156:159], v151 offset:1024
	ds_read_b128 v[160:163], v151 offset:2048
	ds_read_b128 v[164:167], v151 offset:3072
	v_add_u32_e32 v151, s64, v146
	ds_read_b128 v[168:171], v151
	ds_read_b128 v[172:175], v151 offset:1024
	ds_read_b128 v[178:181], v151 offset:2048
	ds_read_b128 v[182:185], v151 offset:3072
	s_add_u32 s2, s2, 0x40000
	s_addc_u32 s3, s3, 0
	s_mov_b32 m0, s45
	v_lshl_add_u64 v[224:225], s[2:3], 0, v[130:131]
	ds_read_b128 v[186:189], v150 offset:32768
	ds_read_b128 v[190:193], v150 offset:33792
	ds_read_b128 v[194:197], v150 offset:34816
	ds_read_b128 v[198:201], v150 offset:35840
	ds_read_b128 v[202:205], v150 offset:36864
	ds_read_b128 v[206:209], v150 offset:37888
	ds_read_b128 v[210:213], v150 offset:38912
	ds_read_b128 v[214:217], v150 offset:39936
	global_load_lds_dwordx4 v[224:225], off
	v_lshl_add_u64 v[224:225], s[2:3], 0, v[134:135]
	s_mov_b32 m0, s46
	s_nop 0
	global_load_lds_dwordx4 v[224:225], off
	s_waitcnt vmcnt(8)
	s_waitcnt lgkmcnt(0)
	s_setprio 1
	s_barrier
	v_mfma_f32_16x16x32_bf16 v[126:129], v[152:155], v[186:189], v[126:129]
	v_mfma_f32_16x16x32_bf16 v[122:125], v[160:163], v[186:189], v[122:125]
	v_mfma_f32_16x16x32_bf16 v[114:117], v[152:155], v[194:197], v[114:117]
	v_mfma_f32_16x16x32_bf16 v[106:109], v[160:163], v[194:197], v[106:109]
	v_mfma_f32_16x16x32_bf16 v[98:101], v[152:155], v[202:205], v[98:101]
	v_mfma_f32_16x16x32_bf16 v[90:93], v[160:163], v[202:205], v[90:93]
	v_mfma_f32_16x16x32_bf16 v[82:85], v[152:155], v[210:213], v[82:85]
	v_mfma_f32_16x16x32_bf16 v[74:77], v[160:163], v[210:213], v[74:77]
	v_mfma_f32_16x16x32_bf16 v[126:129], v[156:159], v[190:193], v[126:129]
	v_mfma_f32_16x16x32_bf16 v[122:125], v[164:167], v[190:193], v[122:125]
	v_mfma_f32_16x16x32_bf16 v[114:117], v[156:159], v[198:201], v[114:117]
	v_mfma_f32_16x16x32_bf16 v[106:109], v[164:167], v[198:201], v[106:109]
	v_mfma_f32_16x16x32_bf16 v[98:101], v[156:159], v[206:209], v[98:101]
	v_mfma_f32_16x16x32_bf16 v[90:93], v[164:167], v[206:209], v[90:93]
	v_mfma_f32_16x16x32_bf16 v[82:85], v[156:159], v[214:217], v[82:85]
	v_mfma_f32_16x16x32_bf16 v[74:77], v[164:167], v[214:217], v[74:77]
	v_mfma_f32_16x16x32_bf16 v[118:121], v[168:171], v[186:189], v[118:121]
	v_mfma_f32_16x16x32_bf16 v[110:113], v[178:181], v[186:189], v[110:113]
	v_mfma_f32_16x16x32_bf16 v[102:105], v[168:171], v[194:197], v[102:105]
	v_mfma_f32_16x16x32_bf16 v[94:97], v[178:181], v[194:197], v[94:97]
	v_mfma_f32_16x16x32_bf16 v[86:89], v[168:171], v[202:205], v[86:89]
	v_mfma_f32_16x16x32_bf16 v[78:81], v[178:181], v[202:205], v[78:81]
	v_mfma_f32_16x16x32_bf16 v[70:73], v[168:171], v[210:213], v[70:73]
	v_mfma_f32_16x16x32_bf16 v[66:69], v[178:181], v[210:213], v[66:69]
	v_mfma_f32_16x16x32_bf16 v[118:121], v[172:175], v[190:193], v[118:121]
	v_mfma_f32_16x16x32_bf16 v[110:113], v[182:185], v[190:193], v[110:113]
	v_mfma_f32_16x16x32_bf16 v[102:105], v[172:175], v[198:201], v[102:105]
	v_mfma_f32_16x16x32_bf16 v[94:97], v[182:185], v[198:201], v[94:97]
	v_mfma_f32_16x16x32_bf16 v[86:89], v[172:175], v[206:209], v[86:89]
	v_mfma_f32_16x16x32_bf16 v[78:81], v[182:185], v[206:209], v[78:81]
	v_mfma_f32_16x16x32_bf16 v[70:73], v[172:175], v[214:217], v[70:73]
	s_setprio 0
	v_mfma_f32_16x16x32_bf16 v[66:69], v[182:185], v[214:217], v[66:69]
	s_barrier
	s_add_i32 s2, s63, s43
	v_lshl_add_u64 v[144:145], v[144:145], 0, s[8:9]
	s_mov_b32 m0, s2
	ds_read_b128 v[186:189], v150 offset:49152
	ds_read_b128 v[190:193], v150 offset:50176
	ds_read_b128 v[194:197], v150 offset:51200
	ds_read_b128 v[198:201], v150 offset:52224
	ds_read_b128 v[202:205], v150 offset:53248
	ds_read_b128 v[206:209], v150 offset:54272
	ds_read_b128 v[210:213], v150 offset:55296
	ds_read_b128 v[214:217], v150 offset:56320
	global_load_lds_dwordx4 v[144:145], off
	s_add_i32 m0, s2, 0x2000
	s_add_u32 s2, s38, 0x40080
	v_lshl_add_u64 v[144:145], v[218:219], 0, s[8:9]
	s_addc_u32 s3, s39, 0
	s_add_i32 s38, s64, s43
	global_load_lds_dwordx4 v[144:145], off
	v_lshl_add_u64 v[144:145], s[2:3], 0, v[132:133]
	s_mov_b32 m0, s38
	s_nop 0
	global_load_lds_dwordx4 v[144:145], off
	v_lshl_add_u64 v[144:145], s[2:3], 0, v[136:137]
	s_add_i32 m0, s38, 0x2000
	s_nop 0
	global_load_lds_dwordx4 v[144:145], off
	v_lshl_add_u64 v[144:145], v[220:221], 0, s[8:9]
	s_mov_b32 m0, s48
	s_nop 0
	global_load_lds_dwordx4 v[144:145], off
	v_lshl_add_u64 v[144:145], v[222:223], 0, s[8:9]
	s_mov_b32 m0, s49
	s_nop 0
	global_load_lds_dwordx4 v[144:145], off
	s_waitcnt vmcnt(8)
	s_waitcnt lgkmcnt(0)
	s_setprio 1
	s_barrier
	v_mfma_f32_16x16x32_bf16 v[62:65], v[152:155], v[186:189], v[62:65]
	v_mfma_f32_16x16x32_bf16 v[58:61], v[160:163], v[186:189], v[58:61]
	v_mfma_f32_16x16x32_bf16 v[50:53], v[152:155], v[194:197], v[50:53]
	v_mfma_f32_16x16x32_bf16 v[42:45], v[160:163], v[194:197], v[42:45]
	v_mfma_f32_16x16x32_bf16 v[34:37], v[152:155], v[202:205], v[34:37]
	v_mfma_f32_16x16x32_bf16 v[26:29], v[160:163], v[202:205], v[26:29]
	v_mfma_f32_16x16x32_bf16 v[18:21], v[152:155], v[210:213], v[18:21]
	v_mfma_f32_16x16x32_bf16 v[10:13], v[160:163], v[210:213], v[10:13]
	v_mfma_f32_16x16x32_bf16 v[62:65], v[156:159], v[190:193], v[62:65]
	v_mfma_f32_16x16x32_bf16 v[58:61], v[164:167], v[190:193], v[58:61]
	v_mfma_f32_16x16x32_bf16 v[50:53], v[156:159], v[198:201], v[50:53]
	v_mfma_f32_16x16x32_bf16 v[42:45], v[164:167], v[198:201], v[42:45]
	v_mfma_f32_16x16x32_bf16 v[34:37], v[156:159], v[206:209], v[34:37]
	v_mfma_f32_16x16x32_bf16 v[26:29], v[164:167], v[206:209], v[26:29]
	v_mfma_f32_16x16x32_bf16 v[18:21], v[156:159], v[214:217], v[18:21]
	v_mfma_f32_16x16x32_bf16 v[10:13], v[164:167], v[214:217], v[10:13]
	v_mfma_f32_16x16x32_bf16 v[54:57], v[168:171], v[186:189], v[54:57]
	v_mfma_f32_16x16x32_bf16 v[46:49], v[178:181], v[186:189], v[46:49]
	v_mfma_f32_16x16x32_bf16 v[38:41], v[168:171], v[194:197], v[38:41]
	v_mfma_f32_16x16x32_bf16 v[30:33], v[178:181], v[194:197], v[30:33]
	v_mfma_f32_16x16x32_bf16 v[22:25], v[168:171], v[202:205], v[22:25]
	v_mfma_f32_16x16x32_bf16 v[14:17], v[178:181], v[202:205], v[14:17]
	v_mfma_f32_16x16x32_bf16 v[6:9], v[168:171], v[210:213], v[6:9]
	v_mfma_f32_16x16x32_bf16 v[2:5], v[178:181], v[210:213], v[2:5]
	v_mfma_f32_16x16x32_bf16 v[54:57], v[172:175], v[190:193], v[54:57]
	v_mfma_f32_16x16x32_bf16 v[46:49], v[182:185], v[190:193], v[46:49]
	v_mfma_f32_16x16x32_bf16 v[38:41], v[172:175], v[198:201], v[38:41]
	v_mfma_f32_16x16x32_bf16 v[30:33], v[182:185], v[198:201], v[30:33]
	v_mfma_f32_16x16x32_bf16 v[22:25], v[172:175], v[206:209], v[22:25]
	v_mfma_f32_16x16x32_bf16 v[14:17], v[182:185], v[206:209], v[14:17]
	v_mfma_f32_16x16x32_bf16 v[6:9], v[172:175], v[214:217], v[6:9]
	s_setprio 0
	v_mfma_f32_16x16x32_bf16 v[2:5], v[182:185], v[214:217], v[2:5]
	s_barrier
	s_add_i32 s62, s62, 2
	s_add_u32 s36, s36, 0x100
	s_addc_u32 s37, s37, 0
	s_add_u32 s60, s60, 0x100
	s_addc_u32 s61, s61, 0
	s_cmp_gt_u32 s62, 13
	s_cbranch_scc0 .LBB0_1239

.Lpk1303_peel:
	ds_read_b128 v[166:169], v139
	ds_read_b128 v[170:173], v139 offset:1024
	ds_read_b128 v[178:181], v139 offset:2048
	ds_read_b128 v[182:185], v139 offset:3072
	ds_read_b128 v[186:189], v163
	ds_read_b128 v[190:193], v163 offset:1024
	ds_read_b128 v[194:197], v163 offset:2048
	ds_read_b128 v[198:201], v163 offset:3072
	s_add_u32 s2, s26, 0xfffc0080
	s_addc_u32 s3, s27, -1
	s_cmp_eq_u32 s55, 12
	s_cselect_b32 s3, s11, s3
	s_cselect_b32 s2, s13, s2
	s_cselect_b32 s29, s47, s54
	s_cselect_b32 s28, s52, s53
	v_lshl_add_u64 v[148:149], s[26:27], 0, v[142:143]
	s_add_i32 m0, s34, 0xc000
	ds_read_b128 v[202:205], v164
	ds_read_b128 v[206:209], v164 offset:1024
	ds_read_b128 v[210:213], v164 offset:2048
	ds_read_b128 v[214:217], v164 offset:3072
	ds_read_b128 v[218:221], v164 offset:4096
	ds_read_b128 v[222:225], v164 offset:5120
	ds_read_b128 v[226:229], v164 offset:6144
	ds_read_b128 v[230:233], v164 offset:7168
	global_load_lds_dwordx4 v[148:149], off
	v_lshl_add_u64 v[148:149], s[26:27], 0, v[144:145]
	s_add_i32 m0, s34, 0xe000
	s_nop 0
	global_load_lds_dwordx4 v[148:149], off
	s_waitcnt vmcnt(8)
	s_waitcnt lgkmcnt(0)
	s_setprio 1
	s_barrier
	v_mfma_f32_16x16x32_bf16 v[126:129], v[166:169], v[202:205], 0
	v_mfma_f32_16x16x32_bf16 v[122:125], v[178:181], v[202:205], 0
	v_mfma_f32_16x16x32_bf16 v[110:113], v[166:169], v[210:213], 0
	v_mfma_f32_16x16x32_bf16 v[106:109], v[178:181], v[210:213], 0
	v_mfma_f32_16x16x32_bf16 v[94:97], v[166:169], v[218:221], 0
	v_mfma_f32_16x16x32_bf16 v[90:93], v[178:181], v[218:221], 0
	v_mfma_f32_16x16x32_bf16 v[78:81], v[166:169], v[226:229], 0
	v_mfma_f32_16x16x32_bf16 v[74:77], v[178:181], v[226:229], 0
	v_mfma_f32_16x16x32_bf16 v[126:129], v[170:173], v[206:209], v[126:129]
	v_mfma_f32_16x16x32_bf16 v[122:125], v[182:185], v[206:209], v[122:125]
	v_mfma_f32_16x16x32_bf16 v[110:113], v[170:173], v[214:217], v[110:113]
	v_mfma_f32_16x16x32_bf16 v[106:109], v[182:185], v[214:217], v[106:109]
	v_mfma_f32_16x16x32_bf16 v[94:97], v[170:173], v[222:225], v[94:97]
	v_mfma_f32_16x16x32_bf16 v[90:93], v[182:185], v[222:225], v[90:93]
	v_mfma_f32_16x16x32_bf16 v[78:81], v[170:173], v[230:233], v[78:81]
	v_mfma_f32_16x16x32_bf16 v[74:77], v[182:185], v[230:233], v[74:77]
	v_mfma_f32_16x16x32_bf16 v[118:121], v[186:189], v[202:205], 0
	v_mfma_f32_16x16x32_bf16 v[114:117], v[194:197], v[202:205], 0
	v_mfma_f32_16x16x32_bf16 v[102:105], v[186:189], v[210:213], 0
	v_mfma_f32_16x16x32_bf16 v[98:101], v[194:197], v[210:213], 0
	v_mfma_f32_16x16x32_bf16 v[86:89], v[186:189], v[218:221], 0
	v_mfma_f32_16x16x32_bf16 v[82:85], v[194:197], v[218:221], 0
	v_mfma_f32_16x16x32_bf16 v[70:73], v[186:189], v[226:229], 0
	v_mfma_f32_16x16x32_bf16 v[66:69], v[194:197], v[226:229], 0
	v_mfma_f32_16x16x32_bf16 v[118:121], v[190:193], v[206:209], v[118:121]
	v_mfma_f32_16x16x32_bf16 v[114:117], v[198:201], v[206:209], v[114:117]
	v_mfma_f32_16x16x32_bf16 v[102:105], v[190:193], v[214:217], v[102:105]
	v_mfma_f32_16x16x32_bf16 v[98:101], v[198:201], v[214:217], v[98:101]
	v_mfma_f32_16x16x32_bf16 v[86:89], v[190:193], v[222:225], v[86:89]
	v_mfma_f32_16x16x32_bf16 v[82:85], v[198:201], v[222:225], v[82:85]
	v_mfma_f32_16x16x32_bf16 v[70:73], v[190:193], v[230:233], v[70:73]
	s_setprio 0
	v_mfma_f32_16x16x32_bf16 v[66:69], v[198:201], v[230:233], v[66:69]
	s_barrier
	s_add_i32 s56, s42, s30
	v_lshl_add_u64 v[148:149], s[28:29], 0, v[132:133]
	s_mov_b32 m0, s56
	ds_read_b128 v[202:205], v164 offset:16384
	ds_read_b128 v[206:209], v164 offset:17408
	ds_read_b128 v[210:213], v164 offset:18432
	ds_read_b128 v[214:217], v164 offset:19456
	ds_read_b128 v[218:221], v164 offset:20480
	ds_read_b128 v[222:225], v164 offset:21504
	ds_read_b128 v[226:229], v164 offset:22528
	ds_read_b128 v[230:233], v164 offset:23552
	global_load_lds_dwordx4 v[148:149], off
	s_add_i32 m0, s56, 0x2000
	s_add_u32 s56, s28, 0x40000
	v_lshl_add_u64 v[174:175], s[28:29], 0, v[136:137]
	s_addc_u32 s57, s29, 0
	s_add_i32 s58, s43, s30
	global_load_lds_dwordx4 v[174:175], off
	v_lshl_add_u64 v[234:235], s[56:57], 0, v[132:133]
	s_mov_b32 m0, s58
	v_lshl_add_u64 v[236:237], s[2:3], 0, v[134:135]
	global_load_lds_dwordx4 v[234:235], off
	v_lshl_add_u64 v[234:235], s[56:57], 0, v[136:137]
	s_add_i32 m0, s58, 0x2000
	s_nop 0
	global_load_lds_dwordx4 v[234:235], off
	v_lshl_add_u64 v[234:235], s[2:3], 0, v[130:131]
	s_mov_b32 m0, s34
	s_nop 0
	global_load_lds_dwordx4 v[234:235], off
	s_mov_b32 m0, s25
	s_nop 0
	global_load_lds_dwordx4 v[236:237], off
	s_waitcnt vmcnt(8)
	s_waitcnt lgkmcnt(0)
	s_setprio 1
	s_barrier
	v_mfma_f32_16x16x32_bf16 v[62:65], v[166:169], v[202:205], 0
	v_mfma_f32_16x16x32_bf16 v[58:61], v[178:181], v[202:205], 0
	v_mfma_f32_16x16x32_bf16 v[46:49], v[166:169], v[210:213], 0
	v_mfma_f32_16x16x32_bf16 v[42:45], v[178:181], v[210:213], 0
	v_mfma_f32_16x16x32_bf16 v[30:33], v[166:169], v[218:221], 0
	v_mfma_f32_16x16x32_bf16 v[26:29], v[178:181], v[218:221], 0
	v_mfma_f32_16x16x32_bf16 v[14:17], v[166:169], v[226:229], 0
	v_mfma_f32_16x16x32_bf16 v[10:13], v[178:181], v[226:229], 0
	v_mfma_f32_16x16x32_bf16 v[62:65], v[170:173], v[206:209], v[62:65]
	v_mfma_f32_16x16x32_bf16 v[58:61], v[182:185], v[206:209], v[58:61]
	v_mfma_f32_16x16x32_bf16 v[46:49], v[170:173], v[214:217], v[46:49]
	v_mfma_f32_16x16x32_bf16 v[42:45], v[182:185], v[214:217], v[42:45]
	v_mfma_f32_16x16x32_bf16 v[30:33], v[170:173], v[222:225], v[30:33]
	v_mfma_f32_16x16x32_bf16 v[26:29], v[182:185], v[222:225], v[26:29]
	v_mfma_f32_16x16x32_bf16 v[14:17], v[170:173], v[230:233], v[14:17]
	v_mfma_f32_16x16x32_bf16 v[10:13], v[182:185], v[230:233], v[10:13]
	v_mfma_f32_16x16x32_bf16 v[54:57], v[186:189], v[202:205], 0
	v_mfma_f32_16x16x32_bf16 v[50:53], v[194:197], v[202:205], 0
	v_mfma_f32_16x16x32_bf16 v[38:41], v[186:189], v[210:213], 0
	v_mfma_f32_16x16x32_bf16 v[34:37], v[194:197], v[210:213], 0
	v_mfma_f32_16x16x32_bf16 v[22:25], v[186:189], v[218:221], 0
	v_mfma_f32_16x16x32_bf16 v[18:21], v[194:197], v[218:221], 0
	v_mfma_f32_16x16x32_bf16 v[6:9], v[186:189], v[226:229], 0
	v_mfma_f32_16x16x32_bf16 v[2:5], v[194:197], v[226:229], 0
	v_mfma_f32_16x16x32_bf16 v[54:57], v[190:193], v[206:209], v[54:57]
	v_mfma_f32_16x16x32_bf16 v[50:53], v[198:201], v[206:209], v[50:53]
	v_mfma_f32_16x16x32_bf16 v[38:41], v[190:193], v[214:217], v[38:41]
	v_mfma_f32_16x16x32_bf16 v[34:37], v[198:201], v[214:217], v[34:37]
	v_mfma_f32_16x16x32_bf16 v[22:25], v[190:193], v[222:225], v[22:25]
	v_mfma_f32_16x16x32_bf16 v[18:21], v[198:201], v[222:225], v[18:21]
	v_mfma_f32_16x16x32_bf16 v[6:9], v[190:193], v[230:233], v[6:9]
	s_setprio 0
	v_mfma_f32_16x16x32_bf16 v[2:5], v[198:201], v[230:233], v[2:5]
	s_barrier
	s_add_i32 s56, 0, 0x18000
	v_add_u32_e32 v165, s56, v162
	s_add_i32 s57, 0, 0x1c000
	ds_read_b128 v[166:169], v165
	ds_read_b128 v[170:173], v165 offset:1024
	ds_read_b128 v[178:181], v165 offset:2048
	ds_read_b128 v[182:185], v165 offset:3072
	v_add_u32_e32 v165, s57, v162
	ds_read_b128 v[186:189], v165
	ds_read_b128 v[190:193], v165 offset:1024
	ds_read_b128 v[194:197], v165 offset:2048
	ds_read_b128 v[198:201], v165 offset:3072
	s_add_u32 s2, s2, 0x40000
	s_addc_u32 s3, s3, 0
	s_mov_b32 m0, s35
	v_lshl_add_u64 v[238:239], s[2:3], 0, v[130:131]
	ds_read_b128 v[202:205], v164 offset:32768
	ds_read_b128 v[206:209], v164 offset:33792
	ds_read_b128 v[210:213], v164 offset:34816
	ds_read_b128 v[214:217], v164 offset:35840
	ds_read_b128 v[218:221], v164 offset:36864
	ds_read_b128 v[222:225], v164 offset:37888
	ds_read_b128 v[226:229], v164 offset:38912
	ds_read_b128 v[230:233], v164 offset:39936
	global_load_lds_dwordx4 v[238:239], off
	v_lshl_add_u64 v[238:239], s[2:3], 0, v[134:135]
	s_mov_b32 m0, s36
	s_nop 0
	global_load_lds_dwordx4 v[238:239], off
	s_waitcnt vmcnt(8)
	s_waitcnt lgkmcnt(0)
	s_setprio 1
	s_barrier
	v_mfma_f32_16x16x32_bf16 v[126:129], v[166:169], v[202:205], v[126:129]
	v_mfma_f32_16x16x32_bf16 v[122:125], v[178:181], v[202:205], v[122:125]
	v_mfma_f32_16x16x32_bf16 v[110:113], v[166:169], v[210:213], v[110:113]
	v_mfma_f32_16x16x32_bf16 v[106:109], v[178:181], v[210:213], v[106:109]
	v_mfma_f32_16x16x32_bf16 v[94:97], v[166:169], v[218:221], v[94:97]
	v_mfma_f32_16x16x32_bf16 v[90:93], v[178:181], v[218:221], v[90:93]
	v_mfma_f32_16x16x32_bf16 v[78:81], v[166:169], v[226:229], v[78:81]
	v_mfma_f32_16x16x32_bf16 v[74:77], v[178:181], v[226:229], v[74:77]
	v_mfma_f32_16x16x32_bf16 v[126:129], v[170:173], v[206:209], v[126:129]
	v_mfma_f32_16x16x32_bf16 v[122:125], v[182:185], v[206:209], v[122:125]
	v_mfma_f32_16x16x32_bf16 v[110:113], v[170:173], v[214:217], v[110:113]
	v_mfma_f32_16x16x32_bf16 v[106:109], v[182:185], v[214:217], v[106:109]
	v_mfma_f32_16x16x32_bf16 v[94:97], v[170:173], v[222:225], v[94:97]
	v_mfma_f32_16x16x32_bf16 v[90:93], v[182:185], v[222:225], v[90:93]
	v_mfma_f32_16x16x32_bf16 v[78:81], v[170:173], v[230:233], v[78:81]
	v_mfma_f32_16x16x32_bf16 v[74:77], v[182:185], v[230:233], v[74:77]
	v_mfma_f32_16x16x32_bf16 v[118:121], v[186:189], v[202:205], v[118:121]
	v_mfma_f32_16x16x32_bf16 v[114:117], v[194:197], v[202:205], v[114:117]
	v_mfma_f32_16x16x32_bf16 v[102:105], v[186:189], v[210:213], v[102:105]
	v_mfma_f32_16x16x32_bf16 v[98:101], v[194:197], v[210:213], v[98:101]
	v_mfma_f32_16x16x32_bf16 v[86:89], v[186:189], v[218:221], v[86:89]
	v_mfma_f32_16x16x32_bf16 v[82:85], v[194:197], v[218:221], v[82:85]
	v_mfma_f32_16x16x32_bf16 v[70:73], v[186:189], v[226:229], v[70:73]
	v_mfma_f32_16x16x32_bf16 v[66:69], v[194:197], v[226:229], v[66:69]
	v_mfma_f32_16x16x32_bf16 v[118:121], v[190:193], v[206:209], v[118:121]
	v_mfma_f32_16x16x32_bf16 v[114:117], v[198:201], v[206:209], v[114:117]
	v_mfma_f32_16x16x32_bf16 v[102:105], v[190:193], v[214:217], v[102:105]
	v_mfma_f32_16x16x32_bf16 v[98:101], v[198:201], v[214:217], v[98:101]
	v_mfma_f32_16x16x32_bf16 v[86:89], v[190:193], v[222:225], v[86:89]
	v_mfma_f32_16x16x32_bf16 v[82:85], v[198:201], v[222:225], v[82:85]
	v_mfma_f32_16x16x32_bf16 v[70:73], v[190:193], v[230:233], v[70:73]
	s_setprio 0
	v_mfma_f32_16x16x32_bf16 v[66:69], v[198:201], v[230:233], v[66:69]
	s_barrier
	s_add_i32 s2, s56, s30
	v_lshl_add_u64 v[148:149], v[148:149], 0, s[6:7]
	s_mov_b32 m0, s2
	ds_read_b128 v[202:205], v164 offset:49152
	ds_read_b128 v[206:209], v164 offset:50176
	ds_read_b128 v[210:213], v164 offset:51200
	ds_read_b128 v[214:217], v164 offset:52224
	ds_read_b128 v[218:221], v164 offset:53248
	ds_read_b128 v[222:225], v164 offset:54272
	ds_read_b128 v[226:229], v164 offset:55296
	ds_read_b128 v[230:233], v164 offset:56320
	global_load_lds_dwordx4 v[148:149], off
	s_add_i32 m0, s2, 0x2000
	s_add_u32 s2, s28, 0x40080
	v_lshl_add_u64 v[148:149], v[174:175], 0, s[6:7]
	s_addc_u32 s3, s29, 0
	s_add_i32 s28, s57, s30
	global_load_lds_dwordx4 v[148:149], off
	v_lshl_add_u64 v[148:149], s[2:3], 0, v[132:133]
	s_mov_b32 m0, s28
	s_nop 0
	global_load_lds_dwordx4 v[148:149], off
	v_lshl_add_u64 v[148:149], s[2:3], 0, v[136:137]
	s_add_i32 m0, s28, 0x2000
	s_nop 0
	global_load_lds_dwordx4 v[148:149], off
	v_lshl_add_u64 v[148:149], v[234:235], 0, s[6:7]
	s_mov_b32 m0, s39
	s_nop 0
	global_load_lds_dwordx4 v[148:149], off
	v_lshl_add_u64 v[148:149], v[236:237], 0, s[6:7]
	s_mov_b32 m0, s40
	s_nop 0
	global_load_lds_dwordx4 v[148:149], off
	s_waitcnt vmcnt(8)
	s_waitcnt lgkmcnt(0)
	s_setprio 1
	s_barrier
	v_mfma_f32_16x16x32_bf16 v[62:65], v[166:169], v[202:205], v[62:65]
	v_mfma_f32_16x16x32_bf16 v[58:61], v[178:181], v[202:205], v[58:61]
	v_mfma_f32_16x16x32_bf16 v[46:49], v[166:169], v[210:213], v[46:49]
	v_mfma_f32_16x16x32_bf16 v[42:45], v[178:181], v[210:213], v[42:45]
	v_mfma_f32_16x16x32_bf16 v[30:33], v[166:169], v[218:221], v[30:33]
	v_mfma_f32_16x16x32_bf16 v[26:29], v[178:181], v[218:221], v[26:29]
	v_mfma_f32_16x16x32_bf16 v[14:17], v[166:169], v[226:229], v[14:17]
	v_mfma_f32_16x16x32_bf16 v[10:13], v[178:181], v[226:229], v[10:13]
	v_mfma_f32_16x16x32_bf16 v[62:65], v[170:173], v[206:209], v[62:65]
	v_mfma_f32_16x16x32_bf16 v[58:61], v[182:185], v[206:209], v[58:61]
	v_mfma_f32_16x16x32_bf16 v[46:49], v[170:173], v[214:217], v[46:49]
	v_mfma_f32_16x16x32_bf16 v[42:45], v[182:185], v[214:217], v[42:45]
	v_mfma_f32_16x16x32_bf16 v[30:33], v[170:173], v[222:225], v[30:33]
	v_mfma_f32_16x16x32_bf16 v[26:29], v[182:185], v[222:225], v[26:29]
	v_mfma_f32_16x16x32_bf16 v[14:17], v[170:173], v[230:233], v[14:17]
	v_mfma_f32_16x16x32_bf16 v[10:13], v[182:185], v[230:233], v[10:13]
	v_mfma_f32_16x16x32_bf16 v[54:57], v[186:189], v[202:205], v[54:57]
	v_mfma_f32_16x16x32_bf16 v[50:53], v[194:197], v[202:205], v[50:53]
	v_mfma_f32_16x16x32_bf16 v[38:41], v[186:189], v[210:213], v[38:41]
	v_mfma_f32_16x16x32_bf16 v[34:37], v[194:197], v[210:213], v[34:37]
	v_mfma_f32_16x16x32_bf16 v[22:25], v[186:189], v[218:221], v[22:25]
	v_mfma_f32_16x16x32_bf16 v[18:21], v[194:197], v[218:221], v[18:21]
	v_mfma_f32_16x16x32_bf16 v[6:9], v[186:189], v[226:229], v[6:9]
	v_mfma_f32_16x16x32_bf16 v[2:5], v[194:197], v[226:229], v[2:5]
	v_mfma_f32_16x16x32_bf16 v[54:57], v[190:193], v[206:209], v[54:57]
	v_mfma_f32_16x16x32_bf16 v[50:53], v[198:201], v[206:209], v[50:53]
	v_mfma_f32_16x16x32_bf16 v[38:41], v[190:193], v[214:217], v[38:41]
	v_mfma_f32_16x16x32_bf16 v[34:37], v[198:201], v[214:217], v[34:37]
	v_mfma_f32_16x16x32_bf16 v[22:25], v[190:193], v[222:225], v[22:25]
	v_mfma_f32_16x16x32_bf16 v[18:21], v[198:201], v[222:225], v[18:21]
	v_mfma_f32_16x16x32_bf16 v[6:9], v[190:193], v[230:233], v[6:9]
	s_setprio 0
	v_mfma_f32_16x16x32_bf16 v[2:5], v[198:201], v[230:233], v[2:5]
	s_barrier
	s_add_i32 s55, s55, 2
	s_add_u32 s26, s26, 0x100
	s_addc_u32 s27, s27, 0
	s_add_u32 s53, s53, 0x100
	s_addc_u32 s54, s54, 0
	s_cmp_gt_u32 s55, 13
	s_cbranch_scc0 .LBB0_1303
	s_branch .Lpk1303_exit
.LBB0_1303:
	ds_read_b128 v[166:169], v139
	ds_read_b128 v[170:173], v139 offset:1024
	ds_read_b128 v[178:181], v139 offset:2048
	ds_read_b128 v[182:185], v139 offset:3072
	ds_read_b128 v[186:189], v163
	ds_read_b128 v[190:193], v163 offset:1024
	ds_read_b128 v[194:197], v163 offset:2048
	ds_read_b128 v[198:201], v163 offset:3072
	s_add_u32 s2, s26, 0xfffc0080
	s_addc_u32 s3, s27, -1
	s_cmp_eq_u32 s55, 12
	s_cselect_b32 s3, s11, s3
	s_cselect_b32 s2, s13, s2
	s_cselect_b32 s29, s47, s54
	s_cselect_b32 s28, s52, s53
	v_lshl_add_u64 v[148:149], s[26:27], 0, v[142:143]
	s_add_i32 m0, s34, 0xc000
	ds_read_b128 v[202:205], v164
	ds_read_b128 v[206:209], v164 offset:1024
	ds_read_b128 v[210:213], v164 offset:2048
	ds_read_b128 v[214:217], v164 offset:3072
	ds_read_b128 v[218:221], v164 offset:4096
	ds_read_b128 v[222:225], v164 offset:5120
	ds_read_b128 v[226:229], v164 offset:6144
	ds_read_b128 v[230:233], v164 offset:7168
	global_load_lds_dwordx4 v[148:149], off
	v_lshl_add_u64 v[148:149], s[26:27], 0, v[144:145]
	s_add_i32 m0, s34, 0xe000
	s_nop 0
	global_load_lds_dwordx4 v[148:149], off
	s_waitcnt vmcnt(8)
	s_waitcnt lgkmcnt(0)
	s_setprio 1
	s_barrier
	v_mfma_f32_16x16x32_bf16 v[126:129], v[166:169], v[202:205], v[126:129]
	v_mfma_f32_16x16x32_bf16 v[122:125], v[178:181], v[202:205], v[122:125]
	v_mfma_f32_16x16x32_bf16 v[110:113], v[166:169], v[210:213], v[110:113]
	v_mfma_f32_16x16x32_bf16 v[106:109], v[178:181], v[210:213], v[106:109]
	v_mfma_f32_16x16x32_bf16 v[94:97], v[166:169], v[218:221], v[94:97]
	v_mfma_f32_16x16x32_bf16 v[90:93], v[178:181], v[218:221], v[90:93]
	v_mfma_f32_16x16x32_bf16 v[78:81], v[166:169], v[226:229], v[78:81]
	v_mfma_f32_16x16x32_bf16 v[74:77], v[178:181], v[226:229], v[74:77]
	v_mfma_f32_16x16x32_bf16 v[126:129], v[170:173], v[206:209], v[126:129]
	v_mfma_f32_16x16x32_bf16 v[122:125], v[182:185], v[206:209], v[122:125]
	v_mfma_f32_16x16x32_bf16 v[110:113], v[170:173], v[214:217], v[110:113]
	v_mfma_f32_16x16x32_bf16 v[106:109], v[182:185], v[214:217], v[106:109]
	v_mfma_f32_16x16x32_bf16 v[94:97], v[170:173], v[222:225], v[94:97]
	v_mfma_f32_16x16x32_bf16 v[90:93], v[182:185], v[222:225], v[90:93]
	v_mfma_f32_16x16x32_bf16 v[78:81], v[170:173], v[230:233], v[78:81]
	v_mfma_f32_16x16x32_bf16 v[74:77], v[182:185], v[230:233], v[74:77]
	v_mfma_f32_16x16x32_bf16 v[118:121], v[186:189], v[202:205], v[118:121]
	v_mfma_f32_16x16x32_bf16 v[114:117], v[194:197], v[202:205], v[114:117]
	v_mfma_f32_16x16x32_bf16 v[102:105], v[186:189], v[210:213], v[102:105]
	v_mfma_f32_16x16x32_bf16 v[98:101], v[194:197], v[210:213], v[98:101]
	v_mfma_f32_16x16x32_bf16 v[86:89], v[186:189], v[218:221], v[86:89]
	v_mfma_f32_16x16x32_bf16 v[82:85], v[194:197], v[218:221], v[82:85]
	v_mfma_f32_16x16x32_bf16 v[70:73], v[186:189], v[226:229], v[70:73]
	v_mfma_f32_16x16x32_bf16 v[66:69], v[194:197], v[226:229], v[66:69]
	v_mfma_f32_16x16x32_bf16 v[118:121], v[190:193], v[206:209], v[118:121]
	v_mfma_f32_16x16x32_bf16 v[114:117], v[198:201], v[206:209], v[114:117]
	v_mfma_f32_16x16x32_bf16 v[102:105], v[190:193], v[214:217], v[102:105]
	v_mfma_f32_16x16x32_bf16 v[98:101], v[198:201], v[214:217], v[98:101]
	v_mfma_f32_16x16x32_bf16 v[86:89], v[190:193], v[222:225], v[86:89]
	v_mfma_f32_16x16x32_bf16 v[82:85], v[198:201], v[222:225], v[82:85]
	v_mfma_f32_16x16x32_bf16 v[70:73], v[190:193], v[230:233], v[70:73]
	s_setprio 0
	v_mfma_f32_16x16x32_bf16 v[66:69], v[198:201], v[230:233], v[66:69]
	s_barrier
	s_add_i32 s56, s42, s30
	v_lshl_add_u64 v[148:149], s[28:29], 0, v[132:133]
	s_mov_b32 m0, s56
	ds_read_b128 v[202:205], v164 offset:16384
	ds_read_b128 v[206:209], v164 offset:17408
	ds_read_b128 v[210:213], v164 offset:18432
	ds_read_b128 v[214:217], v164 offset:19456
	ds_read_b128 v[218:221], v164 offset:20480
	ds_read_b128 v[222:225], v164 offset:21504
	ds_read_b128 v[226:229], v164 offset:22528
	ds_read_b128 v[230:233], v164 offset:23552
	global_load_lds_dwordx4 v[148:149], off
	s_add_i32 m0, s56, 0x2000
	s_add_u32 s56, s28, 0x40000
	v_lshl_add_u64 v[174:175], s[28:29], 0, v[136:137]
	s_addc_u32 s57, s29, 0
	s_add_i32 s58, s43, s30
	global_load_lds_dwordx4 v[174:175], off
	v_lshl_add_u64 v[234:235], s[56:57], 0, v[132:133]
	s_mov_b32 m0, s58
	v_lshl_add_u64 v[236:237], s[2:3], 0, v[134:135]
	global_load_lds_dwordx4 v[234:235], off
	v_lshl_add_u64 v[234:235], s[56:57], 0, v[136:137]
	s_add_i32 m0, s58, 0x2000
	s_nop 0
	global_load_lds_dwordx4 v[234:235], off
	v_lshl_add_u64 v[234:235], s[2:3], 0, v[130:131]
	s_mov_b32 m0, s34
	s_nop 0
	global_load_lds_dwordx4 v[234:235], off
	s_mov_b32 m0, s25
	s_nop 0
	global_load_lds_dwordx4 v[236:237], off
	s_waitcnt vmcnt(8)
	s_waitcnt lgkmcnt(0)
	s_setprio 1
	s_barrier
	v_mfma_f32_16x16x32_bf16 v[62:65], v[166:169], v[202:205], v[62:65]
	v_mfma_f32_16x16x32_bf16 v[58:61], v[178:181], v[202:205], v[58:61]
	v_mfma_f32_16x16x32_bf16 v[46:49], v[166:169], v[210:213], v[46:49]
	v_mfma_f32_16x16x32_bf16 v[42:45], v[178:181], v[210:213], v[42:45]
	v_mfma_f32_16x16x32_bf16 v[30:33], v[166:169], v[218:221], v[30:33]
	v_mfma_f32_16x16x32_bf16 v[26:29], v[178:181], v[218:221], v[26:29]
	v_mfma_f32_16x16x32_bf16 v[14:17], v[166:169], v[226:229], v[14:17]
	v_mfma_f32_16x16x32_bf16 v[10:13], v[178:181], v[226:229], v[10:13]
	v_mfma_f32_16x16x32_bf16 v[62:65], v[170:173], v[206:209], v[62:65]
	v_mfma_f32_16x16x32_bf16 v[58:61], v[182:185], v[206:209], v[58:61]
	v_mfma_f32_16x16x32_bf16 v[46:49], v[170:173], v[214:217], v[46:49]
	v_mfma_f32_16x16x32_bf16 v[42:45], v[182:185], v[214:217], v[42:45]
	v_mfma_f32_16x16x32_bf16 v[30:33], v[170:173], v[222:225], v[30:33]
	v_mfma_f32_16x16x32_bf16 v[26:29], v[182:185], v[222:225], v[26:29]
	v_mfma_f32_16x16x32_bf16 v[14:17], v[170:173], v[230:233], v[14:17]
	v_mfma_f32_16x16x32_bf16 v[10:13], v[182:185], v[230:233], v[10:13]
	v_mfma_f32_16x16x32_bf16 v[54:57], v[186:189], v[202:205], v[54:57]
	v_mfma_f32_16x16x32_bf16 v[50:53], v[194:197], v[202:205], v[50:53]
	v_mfma_f32_16x16x32_bf16 v[38:41], v[186:189], v[210:213], v[38:41]
	v_mfma_f32_16x16x32_bf16 v[34:37], v[194:197], v[210:213], v[34:37]
	v_mfma_f32_16x16x32_bf16 v[22:25], v[186:189], v[218:221], v[22:25]
	v_mfma_f32_16x16x32_bf16 v[18:21], v[194:197], v[218:221], v[18:21]
	v_mfma_f32_16x16x32_bf16 v[6:9], v[186:189], v[226:229], v[6:9]
	v_mfma_f32_16x16x32_bf16 v[2:5], v[194:197], v[226:229], v[2:5]
	v_mfma_f32_16x16x32_bf16 v[54:57], v[190:193], v[206:209], v[54:57]
	v_mfma_f32_16x16x32_bf16 v[50:53], v[198:201], v[206:209], v[50:53]
	v_mfma_f32_16x16x32_bf16 v[38:41], v[190:193], v[214:217], v[38:41]
	v_mfma_f32_16x16x32_bf16 v[34:37], v[198:201], v[214:217], v[34:37]
	v_mfma_f32_16x16x32_bf16 v[22:25], v[190:193], v[222:225], v[22:25]
	v_mfma_f32_16x16x32_bf16 v[18:21], v[198:201], v[222:225], v[18:21]
	v_mfma_f32_16x16x32_bf16 v[6:9], v[190:193], v[230:233], v[6:9]
	s_setprio 0
	v_mfma_f32_16x16x32_bf16 v[2:5], v[198:201], v[230:233], v[2:5]
	s_barrier
	s_add_i32 s56, 0, 0x18000
	v_add_u32_e32 v165, s56, v162
	s_add_i32 s57, 0, 0x1c000
	ds_read_b128 v[166:169], v165
	ds_read_b128 v[170:173], v165 offset:1024
	ds_read_b128 v[178:181], v165 offset:2048
	ds_read_b128 v[182:185], v165 offset:3072
	v_add_u32_e32 v165, s57, v162
	ds_read_b128 v[186:189], v165
	ds_read_b128 v[190:193], v165 offset:1024
	ds_read_b128 v[194:197], v165 offset:2048
	ds_read_b128 v[198:201], v165 offset:3072
	s_add_u32 s2, s2, 0x40000
	s_addc_u32 s3, s3, 0
	s_mov_b32 m0, s35
	v_lshl_add_u64 v[238:239], s[2:3], 0, v[130:131]
	ds_read_b128 v[202:205], v164 offset:32768
	ds_read_b128 v[206:209], v164 offset:33792
	ds_read_b128 v[210:213], v164 offset:34816
	ds_read_b128 v[214:217], v164 offset:35840
	ds_read_b128 v[218:221], v164 offset:36864
	ds_read_b128 v[222:225], v164 offset:37888
	ds_read_b128 v[226:229], v164 offset:38912
	ds_read_b128 v[230:233], v164 offset:39936
	global_load_lds_dwordx4 v[238:239], off
	v_lshl_add_u64 v[238:239], s[2:3], 0, v[134:135]
	s_mov_b32 m0, s36
	s_nop 0
	global_load_lds_dwordx4 v[238:239], off
	s_waitcnt vmcnt(8)
	s_waitcnt lgkmcnt(0)
	s_setprio 1
	s_barrier
	v_mfma_f32_16x16x32_bf16 v[126:129], v[166:169], v[202:205], v[126:129]
	v_mfma_f32_16x16x32_bf16 v[122:125], v[178:181], v[202:205], v[122:125]
	v_mfma_f32_16x16x32_bf16 v[110:113], v[166:169], v[210:213], v[110:113]
	v_mfma_f32_16x16x32_bf16 v[106:109], v[178:181], v[210:213], v[106:109]
	v_mfma_f32_16x16x32_bf16 v[94:97], v[166:169], v[218:221], v[94:97]
	v_mfma_f32_16x16x32_bf16 v[90:93], v[178:181], v[218:221], v[90:93]
	v_mfma_f32_16x16x32_bf16 v[78:81], v[166:169], v[226:229], v[78:81]
	v_mfma_f32_16x16x32_bf16 v[74:77], v[178:181], v[226:229], v[74:77]
	v_mfma_f32_16x16x32_bf16 v[126:129], v[170:173], v[206:209], v[126:129]
	v_mfma_f32_16x16x32_bf16 v[122:125], v[182:185], v[206:209], v[122:125]
	v_mfma_f32_16x16x32_bf16 v[110:113], v[170:173], v[214:217], v[110:113]
	v_mfma_f32_16x16x32_bf16 v[106:109], v[182:185], v[214:217], v[106:109]
	v_mfma_f32_16x16x32_bf16 v[94:97], v[170:173], v[222:225], v[94:97]
	v_mfma_f32_16x16x32_bf16 v[90:93], v[182:185], v[222:225], v[90:93]
	v_mfma_f32_16x16x32_bf16 v[78:81], v[170:173], v[230:233], v[78:81]
	v_mfma_f32_16x16x32_bf16 v[74:77], v[182:185], v[230:233], v[74:77]
	v_mfma_f32_16x16x32_bf16 v[118:121], v[186:189], v[202:205], v[118:121]
	v_mfma_f32_16x16x32_bf16 v[114:117], v[194:197], v[202:205], v[114:117]
	v_mfma_f32_16x16x32_bf16 v[102:105], v[186:189], v[210:213], v[102:105]
	v_mfma_f32_16x16x32_bf16 v[98:101], v[194:197], v[210:213], v[98:101]
	v_mfma_f32_16x16x32_bf16 v[86:89], v[186:189], v[218:221], v[86:89]
	v_mfma_f32_16x16x32_bf16 v[82:85], v[194:197], v[218:221], v[82:85]
	v_mfma_f32_16x16x32_bf16 v[70:73], v[186:189], v[226:229], v[70:73]
	v_mfma_f32_16x16x32_bf16 v[66:69], v[194:197], v[226:229], v[66:69]
	v_mfma_f32_16x16x32_bf16 v[118:121], v[190:193], v[206:209], v[118:121]
	v_mfma_f32_16x16x32_bf16 v[114:117], v[198:201], v[206:209], v[114:117]
	v_mfma_f32_16x16x32_bf16 v[102:105], v[190:193], v[214:217], v[102:105]
	v_mfma_f32_16x16x32_bf16 v[98:101], v[198:201], v[214:217], v[98:101]
	v_mfma_f32_16x16x32_bf16 v[86:89], v[190:193], v[222:225], v[86:89]
	v_mfma_f32_16x16x32_bf16 v[82:85], v[198:201], v[222:225], v[82:85]
	v_mfma_f32_16x16x32_bf16 v[70:73], v[190:193], v[230:233], v[70:73]
	s_setprio 0
	v_mfma_f32_16x16x32_bf16 v[66:69], v[198:201], v[230:233], v[66:69]
	s_barrier
	s_add_i32 s2, s56, s30
	v_lshl_add_u64 v[148:149], v[148:149], 0, s[6:7]
	s_mov_b32 m0, s2
	ds_read_b128 v[202:205], v164 offset:49152
	ds_read_b128 v[206:209], v164 offset:50176
	ds_read_b128 v[210:213], v164 offset:51200
	ds_read_b128 v[214:217], v164 offset:52224
	ds_read_b128 v[218:221], v164 offset:53248
	ds_read_b128 v[222:225], v164 offset:54272
	ds_read_b128 v[226:229], v164 offset:55296
	ds_read_b128 v[230:233], v164 offset:56320
	global_load_lds_dwordx4 v[148:149], off
	s_add_i32 m0, s2, 0x2000
	s_add_u32 s2, s28, 0x40080
	v_lshl_add_u64 v[148:149], v[174:175], 0, s[6:7]
	s_addc_u32 s3, s29, 0
	s_add_i32 s28, s57, s30
	global_load_lds_dwordx4 v[148:149], off
	v_lshl_add_u64 v[148:149], s[2:3], 0, v[132:133]
	s_mov_b32 m0, s28
	s_nop 0
	global_load_lds_dwordx4 v[148:149], off
	v_lshl_add_u64 v[148:149], s[2:3], 0, v[136:137]
	s_add_i32 m0, s28, 0x2000
	s_nop 0
	global_load_lds_dwordx4 v[148:149], off
	v_lshl_add_u64 v[148:149], v[234:235], 0, s[6:7]
	s_mov_b32 m0, s39
	s_nop 0
	global_load_lds_dwordx4 v[148:149], off
	v_lshl_add_u64 v[148:149], v[236:237], 0, s[6:7]
	s_mov_b32 m0, s40
	s_nop 0
	global_load_lds_dwordx4 v[148:149], off
	s_waitcnt vmcnt(8)
	s_waitcnt lgkmcnt(0)
	s_setprio 1
	s_barrier
	v_mfma_f32_16x16x32_bf16 v[62:65], v[166:169], v[202:205], v[62:65]
	v_mfma_f32_16x16x32_bf16 v[58:61], v[178:181], v[202:205], v[58:61]
	v_mfma_f32_16x16x32_bf16 v[46:49], v[166:169], v[210:213], v[46:49]
	v_mfma_f32_16x16x32_bf16 v[42:45], v[178:181], v[210:213], v[42:45]
	v_mfma_f32_16x16x32_bf16 v[30:33], v[166:169], v[218:221], v[30:33]
	v_mfma_f32_16x16x32_bf16 v[26:29], v[178:181], v[218:221], v[26:29]
	v_mfma_f32_16x16x32_bf16 v[14:17], v[166:169], v[226:229], v[14:17]
	v_mfma_f32_16x16x32_bf16 v[10:13], v[178:181], v[226:229], v[10:13]
	v_mfma_f32_16x16x32_bf16 v[62:65], v[170:173], v[206:209], v[62:65]
	v_mfma_f32_16x16x32_bf16 v[58:61], v[182:185], v[206:209], v[58:61]
	v_mfma_f32_16x16x32_bf16 v[46:49], v[170:173], v[214:217], v[46:49]
	v_mfma_f32_16x16x32_bf16 v[42:45], v[182:185], v[214:217], v[42:45]
	v_mfma_f32_16x16x32_bf16 v[30:33], v[170:173], v[222:225], v[30:33]
	v_mfma_f32_16x16x32_bf16 v[26:29], v[182:185], v[222:225], v[26:29]
	v_mfma_f32_16x16x32_bf16 v[14:17], v[170:173], v[230:233], v[14:17]
	v_mfma_f32_16x16x32_bf16 v[10:13], v[182:185], v[230:233], v[10:13]
	v_mfma_f32_16x16x32_bf16 v[54:57], v[186:189], v[202:205], v[54:57]
	v_mfma_f32_16x16x32_bf16 v[50:53], v[194:197], v[202:205], v[50:53]
	v_mfma_f32_16x16x32_bf16 v[38:41], v[186:189], v[210:213], v[38:41]
	v_mfma_f32_16x16x32_bf16 v[34:37], v[194:197], v[210:213], v[34:37]
	v_mfma_f32_16x16x32_bf16 v[22:25], v[186:189], v[218:221], v[22:25]
	v_mfma_f32_16x16x32_bf16 v[18:21], v[194:197], v[218:221], v[18:21]
	v_mfma_f32_16x16x32_bf16 v[6:9], v[186:189], v[226:229], v[6:9]
	v_mfma_f32_16x16x32_bf16 v[2:5], v[194:197], v[226:229], v[2:5]
	v_mfma_f32_16x16x32_bf16 v[54:57], v[190:193], v[206:209], v[54:57]
	v_mfma_f32_16x16x32_bf16 v[50:53], v[198:201], v[206:209], v[50:53]
	v_mfma_f32_16x16x32_bf16 v[38:41], v[190:193], v[214:217], v[38:41]
	v_mfma_f32_16x16x32_bf16 v[34:37], v[198:201], v[214:217], v[34:37]
	v_mfma_f32_16x16x32_bf16 v[22:25], v[190:193], v[222:225], v[22:25]
	v_mfma_f32_16x16x32_bf16 v[18:21], v[198:201], v[222:225], v[18:21]
	v_mfma_f32_16x16x32_bf16 v[6:9], v[190:193], v[230:233], v[6:9]
	s_setprio 0
	v_mfma_f32_16x16x32_bf16 v[2:5], v[198:201], v[230:233], v[2:5]
	s_barrier
	s_add_i32 s55, s55, 2
	s_add_u32 s26, s26, 0x100
	s_addc_u32 s27, s27, 0
	s_add_u32 s53, s53, 0x100
	s_addc_u32 s54, s54, 0
	s_cmp_gt_u32 s55, 13
	s_cbranch_scc0 .LBB0_1303

.LBB0_1386:
	ds_read_b128 v[160:163], v133
	ds_read_b128 v[164:167], v133 offset:1024
	ds_read_b128 v[168:171], v133 offset:2048
	ds_read_b128 v[172:175], v133 offset:3072
	ds_read_b128 v[178:181], v135
	ds_read_b128 v[182:185], v135 offset:1024
	ds_read_b128 v[186:189], v135 offset:2048
	ds_read_b128 v[190:193], v135 offset:3072
	s_cmp_lg_u32 s8, 0x160000
	s_cselect_b32 s13, s8, 0
	s_cselect_b32 s12, s9, 0
	s_add_u32 s2, s6, s13
	s_addc_u32 s3, s7, s12
	s_add_u32 s14, s0, s13
	s_addc_u32 s15, s1, s12
	s_add_u32 s12, s2, 0x8000
	s_addc_u32 s13, s3, 0
	v_lshl_add_u64 v[226:227], v[148:149], 0, s[8:9]
	s_mov_b32 m0, s27
	v_lshl_add_u64 v[226:227], v[226:227], 0, s[10:11]
	ds_read_b128 v[194:197], v137
	ds_read_b128 v[198:201], v137 offset:1024
	ds_read_b128 v[202:205], v137 offset:2048
	ds_read_b128 v[206:209], v137 offset:3072
	ds_read_b128 v[210:213], v137 offset:4096
	ds_read_b128 v[214:217], v137 offset:5120
	ds_read_b128 v[218:221], v137 offset:6144
	ds_read_b128 v[222:225], v137 offset:7168
	global_load_lds_dwordx4 v[226:227], off
	v_lshl_add_u64 v[226:227], v[150:151], 0, s[8:9]
	v_lshl_add_u64 v[226:227], v[226:227], 0, s[10:11]
	s_mov_b32 m0, s28
	s_nop 0
	global_load_lds_dwordx4 v[226:227], off
	s_waitcnt vmcnt(8)
	s_waitcnt lgkmcnt(0)
	s_setprio 1
	s_barrier
	v_mfma_f32_16x16x32_bf16 v[126:129], v[160:163], v[194:197], v[126:129]
	v_mfma_f32_16x16x32_bf16 v[122:125], v[168:171], v[194:197], v[122:125]
	v_mfma_f32_16x16x32_bf16 v[114:117], v[160:163], v[202:205], v[114:117]
	v_mfma_f32_16x16x32_bf16 v[106:109], v[168:171], v[202:205], v[106:109]
	v_mfma_f32_16x16x32_bf16 v[98:101], v[160:163], v[210:213], v[98:101]
	v_mfma_f32_16x16x32_bf16 v[90:93], v[168:171], v[210:213], v[90:93]
	v_mfma_f32_16x16x32_bf16 v[82:85], v[160:163], v[218:221], v[82:85]
	v_mfma_f32_16x16x32_bf16 v[74:77], v[168:171], v[218:221], v[74:77]
	v_mfma_f32_16x16x32_bf16 v[126:129], v[164:167], v[198:201], v[126:129]
	v_mfma_f32_16x16x32_bf16 v[122:125], v[172:175], v[198:201], v[122:125]
	v_mfma_f32_16x16x32_bf16 v[114:117], v[164:167], v[206:209], v[114:117]
	v_mfma_f32_16x16x32_bf16 v[106:109], v[172:175], v[206:209], v[106:109]
	v_mfma_f32_16x16x32_bf16 v[98:101], v[164:167], v[214:217], v[98:101]
	v_mfma_f32_16x16x32_bf16 v[90:93], v[172:175], v[214:217], v[90:93]
	v_mfma_f32_16x16x32_bf16 v[82:85], v[164:167], v[222:225], v[82:85]
	v_mfma_f32_16x16x32_bf16 v[74:77], v[172:175], v[222:225], v[74:77]
	v_mfma_f32_16x16x32_bf16 v[118:121], v[178:181], v[194:197], v[118:121]
	v_mfma_f32_16x16x32_bf16 v[110:113], v[186:189], v[194:197], v[110:113]
	v_mfma_f32_16x16x32_bf16 v[102:105], v[178:181], v[202:205], v[102:105]
	v_mfma_f32_16x16x32_bf16 v[94:97], v[186:189], v[202:205], v[94:97]
	v_mfma_f32_16x16x32_bf16 v[86:89], v[178:181], v[210:213], v[86:89]
	v_mfma_f32_16x16x32_bf16 v[78:81], v[186:189], v[210:213], v[78:81]
	v_mfma_f32_16x16x32_bf16 v[70:73], v[178:181], v[218:221], v[70:73]
	v_mfma_f32_16x16x32_bf16 v[66:69], v[186:189], v[218:221], v[66:69]
	v_mfma_f32_16x16x32_bf16 v[118:121], v[182:185], v[198:201], v[118:121]
	v_mfma_f32_16x16x32_bf16 v[110:113], v[190:193], v[198:201], v[110:113]
	v_mfma_f32_16x16x32_bf16 v[102:105], v[182:185], v[206:209], v[102:105]
	v_mfma_f32_16x16x32_bf16 v[94:97], v[190:193], v[206:209], v[94:97]
	v_mfma_f32_16x16x32_bf16 v[86:89], v[182:185], v[214:217], v[86:89]
	v_mfma_f32_16x16x32_bf16 v[78:81], v[190:193], v[214:217], v[78:81]
	v_mfma_f32_16x16x32_bf16 v[70:73], v[182:185], v[222:225], v[70:73]
	s_setprio 0
	v_mfma_f32_16x16x32_bf16 v[66:69], v[190:193], v[222:225], v[66:69]
	s_barrier
	s_mov_b32 m0, s29
	v_lshl_add_u64 v[226:227], s[14:15], 0, v[142:143]
	s_add_u32 s40, s14, 0x4000
	ds_read_b128 v[194:197], v137 offset:16384
	ds_read_b128 v[198:201], v137 offset:17408
	ds_read_b128 v[202:205], v137 offset:18432
	ds_read_b128 v[206:209], v137 offset:19456
	ds_read_b128 v[210:213], v137 offset:20480
	ds_read_b128 v[214:217], v137 offset:21504
	ds_read_b128 v[218:221], v137 offset:22528
	ds_read_b128 v[222:225], v137 offset:23552
	global_load_lds_dwordx4 v[226:227], off
	v_lshl_add_u64 v[226:227], s[14:15], 0, v[146:147]
	s_mov_b32 m0, s30
	s_addc_u32 s41, s15, 0
	global_load_lds_dwordx4 v[226:227], off
	v_lshl_add_u64 v[226:227], s[40:41], 0, v[142:143]
	s_mov_b32 m0, s31
	s_nop 0
	global_load_lds_dwordx4 v[226:227], off
	v_lshl_add_u64 v[226:227], s[40:41], 0, v[146:147]
	s_mov_b32 m0, s34
	s_nop 0
	global_load_lds_dwordx4 v[226:227], off
	v_lshl_add_u64 v[226:227], s[2:3], 0, v[140:141]
	s_mov_b32 m0, s19
	s_nop 0
	global_load_lds_dwordx4 v[226:227], off
	v_lshl_add_u64 v[226:227], s[2:3], 0, v[144:145]
	s_mov_b32 m0, s20
	s_nop 0
	global_load_lds_dwordx4 v[226:227], off
	s_waitcnt vmcnt(8)
	s_waitcnt lgkmcnt(0)
	s_setprio 1
	s_barrier
	v_mfma_f32_16x16x32_bf16 v[62:65], v[160:163], v[194:197], v[62:65]
	v_mfma_f32_16x16x32_bf16 v[58:61], v[168:171], v[194:197], v[58:61]
	v_mfma_f32_16x16x32_bf16 v[50:53], v[160:163], v[202:205], v[50:53]
	v_mfma_f32_16x16x32_bf16 v[42:45], v[168:171], v[202:205], v[42:45]
	v_mfma_f32_16x16x32_bf16 v[34:37], v[160:163], v[210:213], v[34:37]
	v_mfma_f32_16x16x32_bf16 v[26:29], v[168:171], v[210:213], v[26:29]
	v_mfma_f32_16x16x32_bf16 v[18:21], v[160:163], v[218:221], v[18:21]
	v_mfma_f32_16x16x32_bf16 v[10:13], v[168:171], v[218:221], v[10:13]
	v_mfma_f32_16x16x32_bf16 v[62:65], v[164:167], v[198:201], v[62:65]
	v_mfma_f32_16x16x32_bf16 v[58:61], v[172:175], v[198:201], v[58:61]
	v_mfma_f32_16x16x32_bf16 v[50:53], v[164:167], v[206:209], v[50:53]
	v_mfma_f32_16x16x32_bf16 v[42:45], v[172:175], v[206:209], v[42:45]
	v_mfma_f32_16x16x32_bf16 v[34:37], v[164:167], v[214:217], v[34:37]
	v_mfma_f32_16x16x32_bf16 v[26:29], v[172:175], v[214:217], v[26:29]
	v_mfma_f32_16x16x32_bf16 v[18:21], v[164:167], v[222:225], v[18:21]
	v_mfma_f32_16x16x32_bf16 v[10:13], v[172:175], v[222:225], v[10:13]
	v_mfma_f32_16x16x32_bf16 v[54:57], v[178:181], v[194:197], v[54:57]
	v_mfma_f32_16x16x32_bf16 v[46:49], v[186:189], v[194:197], v[46:49]
	v_mfma_f32_16x16x32_bf16 v[38:41], v[178:181], v[202:205], v[38:41]
	v_mfma_f32_16x16x32_bf16 v[30:33], v[186:189], v[202:205], v[30:33]
	v_mfma_f32_16x16x32_bf16 v[22:25], v[178:181], v[210:213], v[22:25]
	v_mfma_f32_16x16x32_bf16 v[14:17], v[186:189], v[210:213], v[14:17]
	v_mfma_f32_16x16x32_bf16 v[6:9], v[178:181], v[218:221], v[6:9]
	v_mfma_f32_16x16x32_bf16 v[2:5], v[186:189], v[218:221], v[2:5]
	v_mfma_f32_16x16x32_bf16 v[54:57], v[182:185], v[198:201], v[54:57]
	v_mfma_f32_16x16x32_bf16 v[46:49], v[190:193], v[198:201], v[46:49]
	v_mfma_f32_16x16x32_bf16 v[38:41], v[182:185], v[206:209], v[38:41]
	v_mfma_f32_16x16x32_bf16 v[30:33], v[190:193], v[206:209], v[30:33]
	v_mfma_f32_16x16x32_bf16 v[22:25], v[182:185], v[214:217], v[22:25]
	v_mfma_f32_16x16x32_bf16 v[14:17], v[190:193], v[214:217], v[14:17]
	v_mfma_f32_16x16x32_bf16 v[6:9], v[182:185], v[222:225], v[6:9]
	s_setprio 0
	v_mfma_f32_16x16x32_bf16 v[2:5], v[190:193], v[222:225], v[2:5]
	s_barrier
	ds_read_b128 v[160:163], v139
	ds_read_b128 v[164:167], v139 offset:1024
	ds_read_b128 v[168:171], v139 offset:2048
	ds_read_b128 v[172:175], v139 offset:3072
	ds_read_b128 v[178:181], v158
	ds_read_b128 v[182:185], v158 offset:1024
	ds_read_b128 v[186:189], v158 offset:2048
	ds_read_b128 v[190:193], v158 offset:3072
	s_add_u32 s2, s2, 0x4000
	s_addc_u32 s3, s3, 0
	s_mov_b32 m0, s21
	v_lshl_add_u64 v[226:227], s[2:3], 0, v[140:141]
	ds_read_b128 v[194:197], v137 offset:32768
	ds_read_b128 v[198:201], v137 offset:33792
	ds_read_b128 v[202:205], v137 offset:34816
	ds_read_b128 v[206:209], v137 offset:35840
	ds_read_b128 v[210:213], v137 offset:36864
	ds_read_b128 v[214:217], v137 offset:37888
	ds_read_b128 v[218:221], v137 offset:38912
	ds_read_b128 v[222:225], v137 offset:39936
	global_load_lds_dwordx4 v[226:227], off
	v_lshl_add_u64 v[226:227], s[2:3], 0, v[144:145]
	s_mov_b32 m0, s22
	s_nop 0
	global_load_lds_dwordx4 v[226:227], off
	s_waitcnt vmcnt(8)
	s_waitcnt lgkmcnt(0)
	s_setprio 1
	s_barrier
	v_mfma_f32_16x16x32_bf16 v[126:129], v[160:163], v[194:197], v[126:129]
	v_mfma_f32_16x16x32_bf16 v[122:125], v[168:171], v[194:197], v[122:125]
	v_mfma_f32_16x16x32_bf16 v[114:117], v[160:163], v[202:205], v[114:117]
	v_mfma_f32_16x16x32_bf16 v[106:109], v[168:171], v[202:205], v[106:109]
	v_mfma_f32_16x16x32_bf16 v[98:101], v[160:163], v[210:213], v[98:101]
	v_mfma_f32_16x16x32_bf16 v[90:93], v[168:171], v[210:213], v[90:93]
	v_mfma_f32_16x16x32_bf16 v[82:85], v[160:163], v[218:221], v[82:85]
	v_mfma_f32_16x16x32_bf16 v[74:77], v[168:171], v[218:221], v[74:77]
	v_mfma_f32_16x16x32_bf16 v[126:129], v[164:167], v[198:201], v[126:129]
	v_mfma_f32_16x16x32_bf16 v[122:125], v[172:175], v[198:201], v[122:125]
	v_mfma_f32_16x16x32_bf16 v[114:117], v[164:167], v[206:209], v[114:117]
	v_mfma_f32_16x16x32_bf16 v[106:109], v[172:175], v[206:209], v[106:109]
	v_mfma_f32_16x16x32_bf16 v[98:101], v[164:167], v[214:217], v[98:101]
	v_mfma_f32_16x16x32_bf16 v[90:93], v[172:175], v[214:217], v[90:93]
	v_mfma_f32_16x16x32_bf16 v[82:85], v[164:167], v[222:225], v[82:85]
	v_mfma_f32_16x16x32_bf16 v[74:77], v[172:175], v[222:225], v[74:77]
	v_mfma_f32_16x16x32_bf16 v[118:121], v[178:181], v[194:197], v[118:121]
	v_mfma_f32_16x16x32_bf16 v[110:113], v[186:189], v[194:197], v[110:113]
	v_mfma_f32_16x16x32_bf16 v[102:105], v[178:181], v[202:205], v[102:105]
	v_mfma_f32_16x16x32_bf16 v[94:97], v[186:189], v[202:205], v[94:97]
	v_mfma_f32_16x16x32_bf16 v[86:89], v[178:181], v[210:213], v[86:89]
	v_mfma_f32_16x16x32_bf16 v[78:81], v[186:189], v[210:213], v[78:81]
	v_mfma_f32_16x16x32_bf16 v[70:73], v[178:181], v[218:221], v[70:73]
	v_mfma_f32_16x16x32_bf16 v[66:69], v[186:189], v[218:221], v[66:69]
	v_mfma_f32_16x16x32_bf16 v[118:121], v[182:185], v[198:201], v[118:121]
	v_mfma_f32_16x16x32_bf16 v[110:113], v[190:193], v[198:201], v[110:113]
	v_mfma_f32_16x16x32_bf16 v[102:105], v[182:185], v[206:209], v[102:105]
	v_mfma_f32_16x16x32_bf16 v[94:97], v[190:193], v[206:209], v[94:97]
	v_mfma_f32_16x16x32_bf16 v[86:89], v[182:185], v[214:217], v[86:89]
	v_mfma_f32_16x16x32_bf16 v[78:81], v[190:193], v[214:217], v[78:81]
	v_mfma_f32_16x16x32_bf16 v[70:73], v[182:185], v[222:225], v[70:73]
	s_setprio 0
	v_mfma_f32_16x16x32_bf16 v[66:69], v[190:193], v[222:225], v[66:69]
	s_barrier
	s_add_u32 s2, s14, 0x8000
	s_addc_u32 s3, s15, 0
	s_mov_b32 m0, s35
	v_lshl_add_u64 v[226:227], s[2:3], 0, v[142:143]
	ds_read_b128 v[194:197], v137 offset:49152
	ds_read_b128 v[198:201], v137 offset:50176
	ds_read_b128 v[202:205], v137 offset:51200
	ds_read_b128 v[206:209], v137 offset:52224
	ds_read_b128 v[210:213], v137 offset:53248
	ds_read_b128 v[214:217], v137 offset:54272
	ds_read_b128 v[218:221], v137 offset:55296
	ds_read_b128 v[222:225], v137 offset:56320
	global_load_lds_dwordx4 v[226:227], off
	v_lshl_add_u64 v[226:227], s[2:3], 0, v[146:147]
	s_add_u32 s2, s14, 0xc000
	s_mov_b32 m0, s36
	s_addc_u32 s3, s15, 0
	global_load_lds_dwordx4 v[226:227], off
	v_lshl_add_u64 v[226:227], s[2:3], 0, v[142:143]
	s_mov_b32 m0, s37
	s_nop 0
	global_load_lds_dwordx4 v[226:227], off
	v_lshl_add_u64 v[226:227], s[2:3], 0, v[146:147]
	s_mov_b32 m0, s38
	s_nop 0
	global_load_lds_dwordx4 v[226:227], off
	v_lshl_add_u64 v[226:227], s[12:13], 0, v[140:141]
	s_mov_b32 m0, s24
	s_nop 0
	global_load_lds_dwordx4 v[226:227], off
	v_lshl_add_u64 v[226:227], s[12:13], 0, v[144:145]
	s_mov_b32 m0, s25
	s_nop 0
	global_load_lds_dwordx4 v[226:227], off
	s_waitcnt vmcnt(8)
	s_waitcnt lgkmcnt(0)
	s_setprio 1
	s_barrier
	v_mfma_f32_16x16x32_bf16 v[62:65], v[160:163], v[194:197], v[62:65]
	v_mfma_f32_16x16x32_bf16 v[58:61], v[168:171], v[194:197], v[58:61]
	v_mfma_f32_16x16x32_bf16 v[50:53], v[160:163], v[202:205], v[50:53]
	v_mfma_f32_16x16x32_bf16 v[42:45], v[168:171], v[202:205], v[42:45]
	v_mfma_f32_16x16x32_bf16 v[34:37], v[160:163], v[210:213], v[34:37]
	v_mfma_f32_16x16x32_bf16 v[26:29], v[168:171], v[210:213], v[26:29]
	v_mfma_f32_16x16x32_bf16 v[18:21], v[160:163], v[218:221], v[18:21]
	v_mfma_f32_16x16x32_bf16 v[10:13], v[168:171], v[218:221], v[10:13]
	v_mfma_f32_16x16x32_bf16 v[62:65], v[164:167], v[198:201], v[62:65]
	v_mfma_f32_16x16x32_bf16 v[58:61], v[172:175], v[198:201], v[58:61]
	v_mfma_f32_16x16x32_bf16 v[50:53], v[164:167], v[206:209], v[50:53]
	v_mfma_f32_16x16x32_bf16 v[42:45], v[172:175], v[206:209], v[42:45]
	v_mfma_f32_16x16x32_bf16 v[34:37], v[164:167], v[214:217], v[34:37]
	v_mfma_f32_16x16x32_bf16 v[26:29], v[172:175], v[214:217], v[26:29]
	v_mfma_f32_16x16x32_bf16 v[18:21], v[164:167], v[222:225], v[18:21]
	v_mfma_f32_16x16x32_bf16 v[10:13], v[172:175], v[222:225], v[10:13]
	v_mfma_f32_16x16x32_bf16 v[54:57], v[178:181], v[194:197], v[54:57]
	v_mfma_f32_16x16x32_bf16 v[46:49], v[186:189], v[194:197], v[46:49]
	v_mfma_f32_16x16x32_bf16 v[38:41], v[178:181], v[202:205], v[38:41]
	v_mfma_f32_16x16x32_bf16 v[30:33], v[186:189], v[202:205], v[30:33]
	v_mfma_f32_16x16x32_bf16 v[22:25], v[178:181], v[210:213], v[22:25]
	v_mfma_f32_16x16x32_bf16 v[14:17], v[186:189], v[210:213], v[14:17]
	v_mfma_f32_16x16x32_bf16 v[6:9], v[178:181], v[218:221], v[6:9]
	v_mfma_f32_16x16x32_bf16 v[2:5], v[186:189], v[218:221], v[2:5]
	v_mfma_f32_16x16x32_bf16 v[54:57], v[182:185], v[198:201], v[54:57]
	v_mfma_f32_16x16x32_bf16 v[46:49], v[190:193], v[198:201], v[46:49]
	v_mfma_f32_16x16x32_bf16 v[38:41], v[182:185], v[206:209], v[38:41]
	v_mfma_f32_16x16x32_bf16 v[30:33], v[190:193], v[206:209], v[30:33]
	v_mfma_f32_16x16x32_bf16 v[22:25], v[182:185], v[214:217], v[22:25]
	v_mfma_f32_16x16x32_bf16 v[14:17], v[190:193], v[214:217], v[14:17]
	v_mfma_f32_16x16x32_bf16 v[6:9], v[182:185], v[222:225], v[6:9]
	s_setprio 0
	v_mfma_f32_16x16x32_bf16 v[2:5], v[190:193], v[222:225], v[2:5]
	s_barrier
	s_add_i32 s26, s26, 2
	s_add_u32 s8, s8, 0x10000
	s_addc_u32 s9, s9, 0
	s_cmp_gt_u32 s26, 41
	s_cbranch_scc0 .LBB0_1386
	s_cmpk_lt_u32 s16, 0x100
	s_cbranch_scc0 .LBB0_1389
	s_barrier

.Lpk1400_peel:
	ds_read_b128 v[152:155], v1
	ds_read_b128 v[156:159], v1 offset:1024
	ds_read_b128 v[160:163], v1 offset:2048
	ds_read_b128 v[164:167], v1 offset:3072
	ds_read_b128 v[168:171], v149
	ds_read_b128 v[172:175], v149 offset:1024
	ds_read_b128 v[178:181], v149 offset:2048
	ds_read_b128 v[182:185], v149 offset:3072
	s_add_u32 s2, s28, 0xfffc0080
	s_addc_u32 s3, s29, -1
	s_cmp_eq_u32 s55, 12
	s_cselect_b32 s3, s11, s3
	s_cselect_b32 s2, s13, s2
	s_cselect_b32 s31, s47, s54
	s_cselect_b32 s30, s52, s53
	v_lshl_add_u64 v[146:147], s[28:29], 0, v[140:141]
	s_add_i32 m0, s25, 0xc000
	ds_read_b128 v[186:189], v150
	ds_read_b128 v[190:193], v150 offset:1024
	ds_read_b128 v[194:197], v150 offset:2048
	ds_read_b128 v[198:201], v150 offset:3072
	ds_read_b128 v[202:205], v150 offset:4096
	ds_read_b128 v[206:209], v150 offset:5120
	ds_read_b128 v[210:213], v150 offset:6144
	ds_read_b128 v[214:217], v150 offset:7168
	global_load_lds_dwordx4 v[146:147], off
	v_lshl_add_u64 v[146:147], s[28:29], 0, v[142:143]
	s_add_i32 m0, s25, 0xe000
	s_nop 0
	global_load_lds_dwordx4 v[146:147], off
	s_waitcnt vmcnt(8)
	s_waitcnt lgkmcnt(0)
	s_setprio 1
	s_barrier
	v_mfma_f32_16x16x32_bf16 v[126:129], v[152:155], v[186:189], 0
	v_mfma_f32_16x16x32_bf16 v[122:125], v[160:163], v[186:189], 0
	v_mfma_f32_16x16x32_bf16 v[110:113], v[152:155], v[194:197], 0
	v_mfma_f32_16x16x32_bf16 v[106:109], v[160:163], v[194:197], 0
	v_mfma_f32_16x16x32_bf16 v[94:97], v[152:155], v[202:205], 0
	v_mfma_f32_16x16x32_bf16 v[90:93], v[160:163], v[202:205], 0
	v_mfma_f32_16x16x32_bf16 v[78:81], v[152:155], v[210:213], 0
	v_mfma_f32_16x16x32_bf16 v[74:77], v[160:163], v[210:213], 0
	v_mfma_f32_16x16x32_bf16 v[126:129], v[156:159], v[190:193], v[126:129]
	v_mfma_f32_16x16x32_bf16 v[122:125], v[164:167], v[190:193], v[122:125]
	v_mfma_f32_16x16x32_bf16 v[110:113], v[156:159], v[198:201], v[110:113]
	v_mfma_f32_16x16x32_bf16 v[106:109], v[164:167], v[198:201], v[106:109]
	v_mfma_f32_16x16x32_bf16 v[94:97], v[156:159], v[206:209], v[94:97]
	v_mfma_f32_16x16x32_bf16 v[90:93], v[164:167], v[206:209], v[90:93]
	v_mfma_f32_16x16x32_bf16 v[78:81], v[156:159], v[214:217], v[78:81]
	v_mfma_f32_16x16x32_bf16 v[74:77], v[164:167], v[214:217], v[74:77]
	v_mfma_f32_16x16x32_bf16 v[118:121], v[168:171], v[186:189], 0
	v_mfma_f32_16x16x32_bf16 v[114:117], v[178:181], v[186:189], 0
	v_mfma_f32_16x16x32_bf16 v[102:105], v[168:171], v[194:197], 0
	v_mfma_f32_16x16x32_bf16 v[98:101], v[178:181], v[194:197], 0
	v_mfma_f32_16x16x32_bf16 v[86:89], v[168:171], v[202:205], 0
	v_mfma_f32_16x16x32_bf16 v[82:85], v[178:181], v[202:205], 0
	v_mfma_f32_16x16x32_bf16 v[70:73], v[168:171], v[210:213], 0
	v_mfma_f32_16x16x32_bf16 v[66:69], v[178:181], v[210:213], 0
	v_mfma_f32_16x16x32_bf16 v[118:121], v[172:175], v[190:193], v[118:121]
	v_mfma_f32_16x16x32_bf16 v[114:117], v[182:185], v[190:193], v[114:117]
	v_mfma_f32_16x16x32_bf16 v[102:105], v[172:175], v[198:201], v[102:105]
	v_mfma_f32_16x16x32_bf16 v[98:101], v[182:185], v[198:201], v[98:101]
	v_mfma_f32_16x16x32_bf16 v[86:89], v[172:175], v[206:209], v[86:89]
	v_mfma_f32_16x16x32_bf16 v[82:85], v[182:185], v[206:209], v[82:85]
	v_mfma_f32_16x16x32_bf16 v[70:73], v[172:175], v[214:217], v[70:73]
	s_setprio 0
	v_mfma_f32_16x16x32_bf16 v[66:69], v[182:185], v[214:217], v[66:69]
	s_barrier
	s_add_i32 s56, s43, s34
	v_lshl_add_u64 v[146:147], s[30:31], 0, v[132:133]
	s_mov_b32 m0, s56
	ds_read_b128 v[186:189], v150 offset:16384
	ds_read_b128 v[190:193], v150 offset:17408
	ds_read_b128 v[194:197], v150 offset:18432
	ds_read_b128 v[198:201], v150 offset:19456
	ds_read_b128 v[202:205], v150 offset:20480
	ds_read_b128 v[206:209], v150 offset:21504
	ds_read_b128 v[210:213], v150 offset:22528
	ds_read_b128 v[214:217], v150 offset:23552
	global_load_lds_dwordx4 v[146:147], off
	s_add_i32 m0, s56, 0x2000
	s_add_u32 s56, s30, 0x40000
	v_lshl_add_u64 v[218:219], s[30:31], 0, v[136:137]
	s_addc_u32 s57, s31, 0
	s_add_i32 s58, s44, s34
	global_load_lds_dwordx4 v[218:219], off
	v_lshl_add_u64 v[220:221], s[56:57], 0, v[132:133]
	s_mov_b32 m0, s58
	v_lshl_add_u64 v[222:223], s[2:3], 0, v[134:135]
	global_load_lds_dwordx4 v[220:221], off
	v_lshl_add_u64 v[220:221], s[56:57], 0, v[136:137]
	s_add_i32 m0, s58, 0x2000
	s_nop 0
	global_load_lds_dwordx4 v[220:221], off
	v_lshl_add_u64 v[220:221], s[2:3], 0, v[130:131]
	s_mov_b32 m0, s25
	s_nop 0
	global_load_lds_dwordx4 v[220:221], off
	s_mov_b32 m0, s27
	s_nop 0
	global_load_lds_dwordx4 v[222:223], off
	s_waitcnt vmcnt(8)
	s_waitcnt lgkmcnt(0)
	s_setprio 1
	s_barrier
	v_mfma_f32_16x16x32_bf16 v[62:65], v[152:155], v[186:189], 0
	v_mfma_f32_16x16x32_bf16 v[58:61], v[160:163], v[186:189], 0
	v_mfma_f32_16x16x32_bf16 v[46:49], v[152:155], v[194:197], 0
	v_mfma_f32_16x16x32_bf16 v[42:45], v[160:163], v[194:197], 0
	v_mfma_f32_16x16x32_bf16 v[30:33], v[152:155], v[202:205], 0
	v_mfma_f32_16x16x32_bf16 v[26:29], v[160:163], v[202:205], 0
	v_mfma_f32_16x16x32_bf16 v[14:17], v[152:155], v[210:213], 0
	v_mfma_f32_16x16x32_bf16 v[10:13], v[160:163], v[210:213], 0
	v_mfma_f32_16x16x32_bf16 v[62:65], v[156:159], v[190:193], v[62:65]
	v_mfma_f32_16x16x32_bf16 v[58:61], v[164:167], v[190:193], v[58:61]
	v_mfma_f32_16x16x32_bf16 v[46:49], v[156:159], v[198:201], v[46:49]
	v_mfma_f32_16x16x32_bf16 v[42:45], v[164:167], v[198:201], v[42:45]
	v_mfma_f32_16x16x32_bf16 v[30:33], v[156:159], v[206:209], v[30:33]
	v_mfma_f32_16x16x32_bf16 v[26:29], v[164:167], v[206:209], v[26:29]
	v_mfma_f32_16x16x32_bf16 v[14:17], v[156:159], v[214:217], v[14:17]
	v_mfma_f32_16x16x32_bf16 v[10:13], v[164:167], v[214:217], v[10:13]
	v_mfma_f32_16x16x32_bf16 v[54:57], v[168:171], v[186:189], 0
	v_mfma_f32_16x16x32_bf16 v[50:53], v[178:181], v[186:189], 0
	v_mfma_f32_16x16x32_bf16 v[38:41], v[168:171], v[194:197], 0
	v_mfma_f32_16x16x32_bf16 v[34:37], v[178:181], v[194:197], 0
	v_mfma_f32_16x16x32_bf16 v[22:25], v[168:171], v[202:205], 0
	v_mfma_f32_16x16x32_bf16 v[18:21], v[178:181], v[202:205], 0
	v_mfma_f32_16x16x32_bf16 v[6:9], v[168:171], v[210:213], 0
	v_mfma_f32_16x16x32_bf16 v[2:5], v[178:181], v[210:213], 0
	v_mfma_f32_16x16x32_bf16 v[54:57], v[172:175], v[190:193], v[54:57]
	v_mfma_f32_16x16x32_bf16 v[50:53], v[182:185], v[190:193], v[50:53]
	v_mfma_f32_16x16x32_bf16 v[38:41], v[172:175], v[198:201], v[38:41]
	v_mfma_f32_16x16x32_bf16 v[34:37], v[182:185], v[198:201], v[34:37]
	v_mfma_f32_16x16x32_bf16 v[22:25], v[172:175], v[206:209], v[22:25]
	v_mfma_f32_16x16x32_bf16 v[18:21], v[182:185], v[206:209], v[18:21]
	v_mfma_f32_16x16x32_bf16 v[6:9], v[172:175], v[214:217], v[6:9]
	s_setprio 0
	v_mfma_f32_16x16x32_bf16 v[2:5], v[182:185], v[214:217], v[2:5]
	s_barrier
	s_add_i32 s56, 0, 0x18000
	v_add_u32_e32 v151, s56, v148
	s_add_i32 s57, 0, 0x1c000
	ds_read_b128 v[152:155], v151
	ds_read_b128 v[156:159], v151 offset:1024
	ds_read_b128 v[160:163], v151 offset:2048
	ds_read_b128 v[164:167], v151 offset:3072
	v_add_u32_e32 v151, s57, v148
	ds_read_b128 v[168:171], v151
	ds_read_b128 v[172:175], v151 offset:1024
	ds_read_b128 v[178:181], v151 offset:2048
	ds_read_b128 v[182:185], v151 offset:3072
	s_add_u32 s2, s2, 0x40000
	s_addc_u32 s3, s3, 0
	s_mov_b32 m0, s36
	v_lshl_add_u64 v[224:225], s[2:3], 0, v[130:131]
	ds_read_b128 v[186:189], v150 offset:32768
	ds_read_b128 v[190:193], v150 offset:33792
	ds_read_b128 v[194:197], v150 offset:34816
	ds_read_b128 v[198:201], v150 offset:35840
	ds_read_b128 v[202:205], v150 offset:36864
	ds_read_b128 v[206:209], v150 offset:37888
	ds_read_b128 v[210:213], v150 offset:38912
	ds_read_b128 v[214:217], v150 offset:39936
	global_load_lds_dwordx4 v[224:225], off
	v_lshl_add_u64 v[224:225], s[2:3], 0, v[134:135]
	s_mov_b32 m0, s37
	s_nop 0
	global_load_lds_dwordx4 v[224:225], off
	s_waitcnt vmcnt(8)
	s_waitcnt lgkmcnt(0)
	s_setprio 1
	s_barrier
	v_mfma_f32_16x16x32_bf16 v[126:129], v[152:155], v[186:189], v[126:129]
	v_mfma_f32_16x16x32_bf16 v[122:125], v[160:163], v[186:189], v[122:125]
	v_mfma_f32_16x16x32_bf16 v[110:113], v[152:155], v[194:197], v[110:113]
	v_mfma_f32_16x16x32_bf16 v[106:109], v[160:163], v[194:197], v[106:109]
	v_mfma_f32_16x16x32_bf16 v[94:97], v[152:155], v[202:205], v[94:97]
	v_mfma_f32_16x16x32_bf16 v[90:93], v[160:163], v[202:205], v[90:93]
	v_mfma_f32_16x16x32_bf16 v[78:81], v[152:155], v[210:213], v[78:81]
	v_mfma_f32_16x16x32_bf16 v[74:77], v[160:163], v[210:213], v[74:77]
	v_mfma_f32_16x16x32_bf16 v[126:129], v[156:159], v[190:193], v[126:129]
	v_mfma_f32_16x16x32_bf16 v[122:125], v[164:167], v[190:193], v[122:125]
	v_mfma_f32_16x16x32_bf16 v[110:113], v[156:159], v[198:201], v[110:113]
	v_mfma_f32_16x16x32_bf16 v[106:109], v[164:167], v[198:201], v[106:109]
	v_mfma_f32_16x16x32_bf16 v[94:97], v[156:159], v[206:209], v[94:97]
	v_mfma_f32_16x16x32_bf16 v[90:93], v[164:167], v[206:209], v[90:93]
	v_mfma_f32_16x16x32_bf16 v[78:81], v[156:159], v[214:217], v[78:81]
	v_mfma_f32_16x16x32_bf16 v[74:77], v[164:167], v[214:217], v[74:77]
	v_mfma_f32_16x16x32_bf16 v[118:121], v[168:171], v[186:189], v[118:121]
	v_mfma_f32_16x16x32_bf16 v[114:117], v[178:181], v[186:189], v[114:117]
	v_mfma_f32_16x16x32_bf16 v[102:105], v[168:171], v[194:197], v[102:105]
	v_mfma_f32_16x16x32_bf16 v[98:101], v[178:181], v[194:197], v[98:101]
	v_mfma_f32_16x16x32_bf16 v[86:89], v[168:171], v[202:205], v[86:89]
	v_mfma_f32_16x16x32_bf16 v[82:85], v[178:181], v[202:205], v[82:85]
	v_mfma_f32_16x16x32_bf16 v[70:73], v[168:171], v[210:213], v[70:73]
	v_mfma_f32_16x16x32_bf16 v[66:69], v[178:181], v[210:213], v[66:69]
	v_mfma_f32_16x16x32_bf16 v[118:121], v[172:175], v[190:193], v[118:121]
	v_mfma_f32_16x16x32_bf16 v[114:117], v[182:185], v[190:193], v[114:117]
	v_mfma_f32_16x16x32_bf16 v[102:105], v[172:175], v[198:201], v[102:105]
	v_mfma_f32_16x16x32_bf16 v[98:101], v[182:185], v[198:201], v[98:101]
	v_mfma_f32_16x16x32_bf16 v[86:89], v[172:175], v[206:209], v[86:89]
	v_mfma_f32_16x16x32_bf16 v[82:85], v[182:185], v[206:209], v[82:85]
	v_mfma_f32_16x16x32_bf16 v[70:73], v[172:175], v[214:217], v[70:73]
	s_setprio 0
	v_mfma_f32_16x16x32_bf16 v[66:69], v[182:185], v[214:217], v[66:69]
	s_barrier
	s_add_i32 s2, s56, s34
	v_lshl_add_u64 v[146:147], v[146:147], 0, s[6:7]
	s_mov_b32 m0, s2
	ds_read_b128 v[186:189], v150 offset:49152
	ds_read_b128 v[190:193], v150 offset:50176
	ds_read_b128 v[194:197], v150 offset:51200
	ds_read_b128 v[198:201], v150 offset:52224
	ds_read_b128 v[202:205], v150 offset:53248
	ds_read_b128 v[206:209], v150 offset:54272
	ds_read_b128 v[210:213], v150 offset:55296
	ds_read_b128 v[214:217], v150 offset:56320
	global_load_lds_dwordx4 v[146:147], off
	s_add_i32 m0, s2, 0x2000
	s_add_u32 s2, s30, 0x40080
	v_lshl_add_u64 v[146:147], v[218:219], 0, s[6:7]
	s_addc_u32 s3, s31, 0
	s_add_i32 s30, s57, s34
	global_load_lds_dwordx4 v[146:147], off
	v_lshl_add_u64 v[146:147], s[2:3], 0, v[132:133]
	s_mov_b32 m0, s30
	s_nop 0
	global_load_lds_dwordx4 v[146:147], off
	v_lshl_add_u64 v[146:147], s[2:3], 0, v[136:137]
	s_add_i32 m0, s30, 0x2000
	s_nop 0
	global_load_lds_dwordx4 v[146:147], off
	v_lshl_add_u64 v[146:147], v[220:221], 0, s[6:7]
	s_mov_b32 m0, s40
	s_nop 0
	global_load_lds_dwordx4 v[146:147], off
	v_lshl_add_u64 v[146:147], v[222:223], 0, s[6:7]
	s_mov_b32 m0, s41
	s_nop 0
	global_load_lds_dwordx4 v[146:147], off
	s_waitcnt vmcnt(8)
	s_waitcnt lgkmcnt(0)
	s_setprio 1
	s_barrier
	v_mfma_f32_16x16x32_bf16 v[62:65], v[152:155], v[186:189], v[62:65]
	v_mfma_f32_16x16x32_bf16 v[58:61], v[160:163], v[186:189], v[58:61]
	v_mfma_f32_16x16x32_bf16 v[46:49], v[152:155], v[194:197], v[46:49]
	v_mfma_f32_16x16x32_bf16 v[42:45], v[160:163], v[194:197], v[42:45]
	v_mfma_f32_16x16x32_bf16 v[30:33], v[152:155], v[202:205], v[30:33]
	v_mfma_f32_16x16x32_bf16 v[26:29], v[160:163], v[202:205], v[26:29]
	v_mfma_f32_16x16x32_bf16 v[14:17], v[152:155], v[210:213], v[14:17]
	v_mfma_f32_16x16x32_bf16 v[10:13], v[160:163], v[210:213], v[10:13]
	v_mfma_f32_16x16x32_bf16 v[62:65], v[156:159], v[190:193], v[62:65]
	v_mfma_f32_16x16x32_bf16 v[58:61], v[164:167], v[190:193], v[58:61]
	v_mfma_f32_16x16x32_bf16 v[46:49], v[156:159], v[198:201], v[46:49]
	v_mfma_f32_16x16x32_bf16 v[42:45], v[164:167], v[198:201], v[42:45]
	v_mfma_f32_16x16x32_bf16 v[30:33], v[156:159], v[206:209], v[30:33]
	v_mfma_f32_16x16x32_bf16 v[26:29], v[164:167], v[206:209], v[26:29]
	v_mfma_f32_16x16x32_bf16 v[14:17], v[156:159], v[214:217], v[14:17]
	v_mfma_f32_16x16x32_bf16 v[10:13], v[164:167], v[214:217], v[10:13]
	v_mfma_f32_16x16x32_bf16 v[54:57], v[168:171], v[186:189], v[54:57]
	v_mfma_f32_16x16x32_bf16 v[50:53], v[178:181], v[186:189], v[50:53]
	v_mfma_f32_16x16x32_bf16 v[38:41], v[168:171], v[194:197], v[38:41]
	v_mfma_f32_16x16x32_bf16 v[34:37], v[178:181], v[194:197], v[34:37]
	v_mfma_f32_16x16x32_bf16 v[22:25], v[168:171], v[202:205], v[22:25]
	v_mfma_f32_16x16x32_bf16 v[18:21], v[178:181], v[202:205], v[18:21]
	v_mfma_f32_16x16x32_bf16 v[6:9], v[168:171], v[210:213], v[6:9]
	v_mfma_f32_16x16x32_bf16 v[2:5], v[178:181], v[210:213], v[2:5]
	v_mfma_f32_16x16x32_bf16 v[54:57], v[172:175], v[190:193], v[54:57]
	v_mfma_f32_16x16x32_bf16 v[50:53], v[182:185], v[190:193], v[50:53]
	v_mfma_f32_16x16x32_bf16 v[38:41], v[172:175], v[198:201], v[38:41]
	v_mfma_f32_16x16x32_bf16 v[34:37], v[182:185], v[198:201], v[34:37]
	v_mfma_f32_16x16x32_bf16 v[22:25], v[172:175], v[206:209], v[22:25]
	v_mfma_f32_16x16x32_bf16 v[18:21], v[182:185], v[206:209], v[18:21]
	v_mfma_f32_16x16x32_bf16 v[6:9], v[172:175], v[214:217], v[6:9]
	s_setprio 0
	v_mfma_f32_16x16x32_bf16 v[2:5], v[182:185], v[214:217], v[2:5]
	s_barrier
	s_add_i32 s55, s55, 2
	s_add_u32 s28, s28, 0x100
	s_addc_u32 s29, s29, 0
	s_add_u32 s53, s53, 0x100
	s_addc_u32 s54, s54, 0
	s_cmp_gt_u32 s55, 13
	s_cbranch_scc0 .LBB0_1400
	s_branch .Lpk1400_exit
.LBB0_1400:
	ds_read_b128 v[152:155], v1
	ds_read_b128 v[156:159], v1 offset:1024
	ds_read_b128 v[160:163], v1 offset:2048
	ds_read_b128 v[164:167], v1 offset:3072
	ds_read_b128 v[168:171], v149
	ds_read_b128 v[172:175], v149 offset:1024
	ds_read_b128 v[178:181], v149 offset:2048
	ds_read_b128 v[182:185], v149 offset:3072
	s_add_u32 s2, s28, 0xfffc0080
	s_addc_u32 s3, s29, -1
	s_cmp_eq_u32 s55, 12
	s_cselect_b32 s3, s11, s3
	s_cselect_b32 s2, s13, s2
	s_cselect_b32 s31, s47, s54
	s_cselect_b32 s30, s52, s53
	v_lshl_add_u64 v[146:147], s[28:29], 0, v[140:141]
	s_add_i32 m0, s25, 0xc000
	ds_read_b128 v[186:189], v150
	ds_read_b128 v[190:193], v150 offset:1024
	ds_read_b128 v[194:197], v150 offset:2048
	ds_read_b128 v[198:201], v150 offset:3072
	ds_read_b128 v[202:205], v150 offset:4096
	ds_read_b128 v[206:209], v150 offset:5120
	ds_read_b128 v[210:213], v150 offset:6144
	ds_read_b128 v[214:217], v150 offset:7168
	global_load_lds_dwordx4 v[146:147], off
	v_lshl_add_u64 v[146:147], s[28:29], 0, v[142:143]
	s_add_i32 m0, s25, 0xe000
	s_nop 0
	global_load_lds_dwordx4 v[146:147], off
	s_waitcnt vmcnt(8)
	s_waitcnt lgkmcnt(0)
	s_setprio 1
	s_barrier
	v_mfma_f32_16x16x32_bf16 v[126:129], v[152:155], v[186:189], v[126:129]
	v_mfma_f32_16x16x32_bf16 v[122:125], v[160:163], v[186:189], v[122:125]
	v_mfma_f32_16x16x32_bf16 v[110:113], v[152:155], v[194:197], v[110:113]
	v_mfma_f32_16x16x32_bf16 v[106:109], v[160:163], v[194:197], v[106:109]
	v_mfma_f32_16x16x32_bf16 v[94:97], v[152:155], v[202:205], v[94:97]
	v_mfma_f32_16x16x32_bf16 v[90:93], v[160:163], v[202:205], v[90:93]
	v_mfma_f32_16x16x32_bf16 v[78:81], v[152:155], v[210:213], v[78:81]
	v_mfma_f32_16x16x32_bf16 v[74:77], v[160:163], v[210:213], v[74:77]
	v_mfma_f32_16x16x32_bf16 v[126:129], v[156:159], v[190:193], v[126:129]
	v_mfma_f32_16x16x32_bf16 v[122:125], v[164:167], v[190:193], v[122:125]
	v_mfma_f32_16x16x32_bf16 v[110:113], v[156:159], v[198:201], v[110:113]
	v_mfma_f32_16x16x32_bf16 v[106:109], v[164:167], v[198:201], v[106:109]
	v_mfma_f32_16x16x32_bf16 v[94:97], v[156:159], v[206:209], v[94:97]
	v_mfma_f32_16x16x32_bf16 v[90:93], v[164:167], v[206:209], v[90:93]
	v_mfma_f32_16x16x32_bf16 v[78:81], v[156:159], v[214:217], v[78:81]
	v_mfma_f32_16x16x32_bf16 v[74:77], v[164:167], v[214:217], v[74:77]
	v_mfma_f32_16x16x32_bf16 v[118:121], v[168:171], v[186:189], v[118:121]
	v_mfma_f32_16x16x32_bf16 v[114:117], v[178:181], v[186:189], v[114:117]
	v_mfma_f32_16x16x32_bf16 v[102:105], v[168:171], v[194:197], v[102:105]
	v_mfma_f32_16x16x32_bf16 v[98:101], v[178:181], v[194:197], v[98:101]
	v_mfma_f32_16x16x32_bf16 v[86:89], v[168:171], v[202:205], v[86:89]
	v_mfma_f32_16x16x32_bf16 v[82:85], v[178:181], v[202:205], v[82:85]
	v_mfma_f32_16x16x32_bf16 v[70:73], v[168:171], v[210:213], v[70:73]
	v_mfma_f32_16x16x32_bf16 v[66:69], v[178:181], v[210:213], v[66:69]
	v_mfma_f32_16x16x32_bf16 v[118:121], v[172:175], v[190:193], v[118:121]
	v_mfma_f32_16x16x32_bf16 v[114:117], v[182:185], v[190:193], v[114:117]
	v_mfma_f32_16x16x32_bf16 v[102:105], v[172:175], v[198:201], v[102:105]
	v_mfma_f32_16x16x32_bf16 v[98:101], v[182:185], v[198:201], v[98:101]
	v_mfma_f32_16x16x32_bf16 v[86:89], v[172:175], v[206:209], v[86:89]
	v_mfma_f32_16x16x32_bf16 v[82:85], v[182:185], v[206:209], v[82:85]
	v_mfma_f32_16x16x32_bf16 v[70:73], v[172:175], v[214:217], v[70:73]
	s_setprio 0
	v_mfma_f32_16x16x32_bf16 v[66:69], v[182:185], v[214:217], v[66:69]
	s_barrier
	s_add_i32 s56, s43, s34
	v_lshl_add_u64 v[146:147], s[30:31], 0, v[132:133]
	s_mov_b32 m0, s56
	ds_read_b128 v[186:189], v150 offset:16384
	ds_read_b128 v[190:193], v150 offset:17408
	ds_read_b128 v[194:197], v150 offset:18432
	ds_read_b128 v[198:201], v150 offset:19456
	ds_read_b128 v[202:205], v150 offset:20480
	ds_read_b128 v[206:209], v150 offset:21504
	ds_read_b128 v[210:213], v150 offset:22528
	ds_read_b128 v[214:217], v150 offset:23552
	global_load_lds_dwordx4 v[146:147], off
	s_add_i32 m0, s56, 0x2000
	s_add_u32 s56, s30, 0x40000
	v_lshl_add_u64 v[218:219], s[30:31], 0, v[136:137]
	s_addc_u32 s57, s31, 0
	s_add_i32 s58, s44, s34
	global_load_lds_dwordx4 v[218:219], off
	v_lshl_add_u64 v[220:221], s[56:57], 0, v[132:133]
	s_mov_b32 m0, s58
	v_lshl_add_u64 v[222:223], s[2:3], 0, v[134:135]
	global_load_lds_dwordx4 v[220:221], off
	v_lshl_add_u64 v[220:221], s[56:57], 0, v[136:137]
	s_add_i32 m0, s58, 0x2000
	s_nop 0
	global_load_lds_dwordx4 v[220:221], off
	v_lshl_add_u64 v[220:221], s[2:3], 0, v[130:131]
	s_mov_b32 m0, s25
	s_nop 0
	global_load_lds_dwordx4 v[220:221], off
	s_mov_b32 m0, s27
	s_nop 0
	global_load_lds_dwordx4 v[222:223], off
	s_waitcnt vmcnt(8)
	s_waitcnt lgkmcnt(0)
	s_setprio 1
	s_barrier
	v_mfma_f32_16x16x32_bf16 v[62:65], v[152:155], v[186:189], v[62:65]
	v_mfma_f32_16x16x32_bf16 v[58:61], v[160:163], v[186:189], v[58:61]
	v_mfma_f32_16x16x32_bf16 v[46:49], v[152:155], v[194:197], v[46:49]
	v_mfma_f32_16x16x32_bf16 v[42:45], v[160:163], v[194:197], v[42:45]
	v_mfma_f32_16x16x32_bf16 v[30:33], v[152:155], v[202:205], v[30:33]
	v_mfma_f32_16x16x32_bf16 v[26:29], v[160:163], v[202:205], v[26:29]
	v_mfma_f32_16x16x32_bf16 v[14:17], v[152:155], v[210:213], v[14:17]
	v_mfma_f32_16x16x32_bf16 v[10:13], v[160:163], v[210:213], v[10:13]
	v_mfma_f32_16x16x32_bf16 v[62:65], v[156:159], v[190:193], v[62:65]
	v_mfma_f32_16x16x32_bf16 v[58:61], v[164:167], v[190:193], v[58:61]
	v_mfma_f32_16x16x32_bf16 v[46:49], v[156:159], v[198:201], v[46:49]
	v_mfma_f32_16x16x32_bf16 v[42:45], v[164:167], v[198:201], v[42:45]
	v_mfma_f32_16x16x32_bf16 v[30:33], v[156:159], v[206:209], v[30:33]
	v_mfma_f32_16x16x32_bf16 v[26:29], v[164:167], v[206:209], v[26:29]
	v_mfma_f32_16x16x32_bf16 v[14:17], v[156:159], v[214:217], v[14:17]
	v_mfma_f32_16x16x32_bf16 v[10:13], v[164:167], v[214:217], v[10:13]
	v_mfma_f32_16x16x32_bf16 v[54:57], v[168:171], v[186:189], v[54:57]
	v_mfma_f32_16x16x32_bf16 v[50:53], v[178:181], v[186:189], v[50:53]
	v_mfma_f32_16x16x32_bf16 v[38:41], v[168:171], v[194:197], v[38:41]
	v_mfma_f32_16x16x32_bf16 v[34:37], v[178:181], v[194:197], v[34:37]
	v_mfma_f32_16x16x32_bf16 v[22:25], v[168:171], v[202:205], v[22:25]
	v_mfma_f32_16x16x32_bf16 v[18:21], v[178:181], v[202:205], v[18:21]
	v_mfma_f32_16x16x32_bf16 v[6:9], v[168:171], v[210:213], v[6:9]
	v_mfma_f32_16x16x32_bf16 v[2:5], v[178:181], v[210:213], v[2:5]
	v_mfma_f32_16x16x32_bf16 v[54:57], v[172:175], v[190:193], v[54:57]
	v_mfma_f32_16x16x32_bf16 v[50:53], v[182:185], v[190:193], v[50:53]
	v_mfma_f32_16x16x32_bf16 v[38:41], v[172:175], v[198:201], v[38:41]
	v_mfma_f32_16x16x32_bf16 v[34:37], v[182:185], v[198:201], v[34:37]
	v_mfma_f32_16x16x32_bf16 v[22:25], v[172:175], v[206:209], v[22:25]
	v_mfma_f32_16x16x32_bf16 v[18:21], v[182:185], v[206:209], v[18:21]
	v_mfma_f32_16x16x32_bf16 v[6:9], v[172:175], v[214:217], v[6:9]
	s_setprio 0
	v_mfma_f32_16x16x32_bf16 v[2:5], v[182:185], v[214:217], v[2:5]
	s_barrier
	s_add_i32 s56, 0, 0x18000
	v_add_u32_e32 v151, s56, v148
	s_add_i32 s57, 0, 0x1c000
	ds_read_b128 v[152:155], v151
	ds_read_b128 v[156:159], v151 offset:1024
	ds_read_b128 v[160:163], v151 offset:2048
	ds_read_b128 v[164:167], v151 offset:3072
	v_add_u32_e32 v151, s57, v148
	ds_read_b128 v[168:171], v151
	ds_read_b128 v[172:175], v151 offset:1024
	ds_read_b128 v[178:181], v151 offset:2048
	ds_read_b128 v[182:185], v151 offset:3072
	s_add_u32 s2, s2, 0x40000
	s_addc_u32 s3, s3, 0
	s_mov_b32 m0, s36
	v_lshl_add_u64 v[224:225], s[2:3], 0, v[130:131]
	ds_read_b128 v[186:189], v150 offset:32768
	ds_read_b128 v[190:193], v150 offset:33792
	ds_read_b128 v[194:197], v150 offset:34816
	ds_read_b128 v[198:201], v150 offset:35840
	ds_read_b128 v[202:205], v150 offset:36864
	ds_read_b128 v[206:209], v150 offset:37888
	ds_read_b128 v[210:213], v150 offset:38912
	ds_read_b128 v[214:217], v150 offset:39936
	global_load_lds_dwordx4 v[224:225], off
	v_lshl_add_u64 v[224:225], s[2:3], 0, v[134:135]
	s_mov_b32 m0, s37
	s_nop 0
	global_load_lds_dwordx4 v[224:225], off
	s_waitcnt vmcnt(8)
	s_waitcnt lgkmcnt(0)
	s_setprio 1
	s_barrier
	v_mfma_f32_16x16x32_bf16 v[126:129], v[152:155], v[186:189], v[126:129]
	v_mfma_f32_16x16x32_bf16 v[122:125], v[160:163], v[186:189], v[122:125]
	v_mfma_f32_16x16x32_bf16 v[110:113], v[152:155], v[194:197], v[110:113]
	v_mfma_f32_16x16x32_bf16 v[106:109], v[160:163], v[194:197], v[106:109]
	v_mfma_f32_16x16x32_bf16 v[94:97], v[152:155], v[202:205], v[94:97]
	v_mfma_f32_16x16x32_bf16 v[90:93], v[160:163], v[202:205], v[90:93]
	v_mfma_f32_16x16x32_bf16 v[78:81], v[152:155], v[210:213], v[78:81]
	v_mfma_f32_16x16x32_bf16 v[74:77], v[160:163], v[210:213], v[74:77]
	v_mfma_f32_16x16x32_bf16 v[126:129], v[156:159], v[190:193], v[126:129]
	v_mfma_f32_16x16x32_bf16 v[122:125], v[164:167], v[190:193], v[122:125]
	v_mfma_f32_16x16x32_bf16 v[110:113], v[156:159], v[198:201], v[110:113]
	v_mfma_f32_16x16x32_bf16 v[106:109], v[164:167], v[198:201], v[106:109]
	v_mfma_f32_16x16x32_bf16 v[94:97], v[156:159], v[206:209], v[94:97]
	v_mfma_f32_16x16x32_bf16 v[90:93], v[164:167], v[206:209], v[90:93]
	v_mfma_f32_16x16x32_bf16 v[78:81], v[156:159], v[214:217], v[78:81]
	v_mfma_f32_16x16x32_bf16 v[74:77], v[164:167], v[214:217], v[74:77]
	v_mfma_f32_16x16x32_bf16 v[118:121], v[168:171], v[186:189], v[118:121]
	v_mfma_f32_16x16x32_bf16 v[114:117], v[178:181], v[186:189], v[114:117]
	v_mfma_f32_16x16x32_bf16 v[102:105], v[168:171], v[194:197], v[102:105]
	v_mfma_f32_16x16x32_bf16 v[98:101], v[178:181], v[194:197], v[98:101]
	v_mfma_f32_16x16x32_bf16 v[86:89], v[168:171], v[202:205], v[86:89]
	v_mfma_f32_16x16x32_bf16 v[82:85], v[178:181], v[202:205], v[82:85]
	v_mfma_f32_16x16x32_bf16 v[70:73], v[168:171], v[210:213], v[70:73]
	v_mfma_f32_16x16x32_bf16 v[66:69], v[178:181], v[210:213], v[66:69]
	v_mfma_f32_16x16x32_bf16 v[118:121], v[172:175], v[190:193], v[118:121]
	v_mfma_f32_16x16x32_bf16 v[114:117], v[182:185], v[190:193], v[114:117]
	v_mfma_f32_16x16x32_bf16 v[102:105], v[172:175], v[198:201], v[102:105]
	v_mfma_f32_16x16x32_bf16 v[98:101], v[182:185], v[198:201], v[98:101]
	v_mfma_f32_16x16x32_bf16 v[86:89], v[172:175], v[206:209], v[86:89]
	v_mfma_f32_16x16x32_bf16 v[82:85], v[182:185], v[206:209], v[82:85]
	v_mfma_f32_16x16x32_bf16 v[70:73], v[172:175], v[214:217], v[70:73]
	s_setprio 0
	v_mfma_f32_16x16x32_bf16 v[66:69], v[182:185], v[214:217], v[66:69]
	s_barrier
	s_add_i32 s2, s56, s34
	v_lshl_add_u64 v[146:147], v[146:147], 0, s[6:7]
	s_mov_b32 m0, s2
	ds_read_b128 v[186:189], v150 offset:49152
	ds_read_b128 v[190:193], v150 offset:50176
	ds_read_b128 v[194:197], v150 offset:51200
	ds_read_b128 v[198:201], v150 offset:52224
	ds_read_b128 v[202:205], v150 offset:53248
	ds_read_b128 v[206:209], v150 offset:54272
	ds_read_b128 v[210:213], v150 offset:55296
	ds_read_b128 v[214:217], v150 offset:56320
	global_load_lds_dwordx4 v[146:147], off
	s_add_i32 m0, s2, 0x2000
	s_add_u32 s2, s30, 0x40080
	v_lshl_add_u64 v[146:147], v[218:219], 0, s[6:7]
	s_addc_u32 s3, s31, 0
	s_add_i32 s30, s57, s34
	global_load_lds_dwordx4 v[146:147], off
	v_lshl_add_u64 v[146:147], s[2:3], 0, v[132:133]
	s_mov_b32 m0, s30
	s_nop 0
	global_load_lds_dwordx4 v[146:147], off
	v_lshl_add_u64 v[146:147], s[2:3], 0, v[136:137]
	s_add_i32 m0, s30, 0x2000
	s_nop 0
	global_load_lds_dwordx4 v[146:147], off
	v_lshl_add_u64 v[146:147], v[220:221], 0, s[6:7]
	s_mov_b32 m0, s40
	s_nop 0
	global_load_lds_dwordx4 v[146:147], off
	v_lshl_add_u64 v[146:147], v[222:223], 0, s[6:7]
	s_mov_b32 m0, s41
	s_nop 0
	global_load_lds_dwordx4 v[146:147], off
	s_waitcnt vmcnt(8)
	s_waitcnt lgkmcnt(0)
	s_setprio 1
	s_barrier
	v_mfma_f32_16x16x32_bf16 v[62:65], v[152:155], v[186:189], v[62:65]
	v_mfma_f32_16x16x32_bf16 v[58:61], v[160:163], v[186:189], v[58:61]
	v_mfma_f32_16x16x32_bf16 v[46:49], v[152:155], v[194:197], v[46:49]
	v_mfma_f32_16x16x32_bf16 v[42:45], v[160:163], v[194:197], v[42:45]
	v_mfma_f32_16x16x32_bf16 v[30:33], v[152:155], v[202:205], v[30:33]
	v_mfma_f32_16x16x32_bf16 v[26:29], v[160:163], v[202:205], v[26:29]
	v_mfma_f32_16x16x32_bf16 v[14:17], v[152:155], v[210:213], v[14:17]
	v_mfma_f32_16x16x32_bf16 v[10:13], v[160:163], v[210:213], v[10:13]
	v_mfma_f32_16x16x32_bf16 v[62:65], v[156:159], v[190:193], v[62:65]
	v_mfma_f32_16x16x32_bf16 v[58:61], v[164:167], v[190:193], v[58:61]
	v_mfma_f32_16x16x32_bf16 v[46:49], v[156:159], v[198:201], v[46:49]
	v_mfma_f32_16x16x32_bf16 v[42:45], v[164:167], v[198:201], v[42:45]
	v_mfma_f32_16x16x32_bf16 v[30:33], v[156:159], v[206:209], v[30:33]
	v_mfma_f32_16x16x32_bf16 v[26:29], v[164:167], v[206:209], v[26:29]
	v_mfma_f32_16x16x32_bf16 v[14:17], v[156:159], v[214:217], v[14:17]
	v_mfma_f32_16x16x32_bf16 v[10:13], v[164:167], v[214:217], v[10:13]
	v_mfma_f32_16x16x32_bf16 v[54:57], v[168:171], v[186:189], v[54:57]
	v_mfma_f32_16x16x32_bf16 v[50:53], v[178:181], v[186:189], v[50:53]
	v_mfma_f32_16x16x32_bf16 v[38:41], v[168:171], v[194:197], v[38:41]
	v_mfma_f32_16x16x32_bf16 v[34:37], v[178:181], v[194:197], v[34:37]
	v_mfma_f32_16x16x32_bf16 v[22:25], v[168:171], v[202:205], v[22:25]
	v_mfma_f32_16x16x32_bf16 v[18:21], v[178:181], v[202:205], v[18:21]
	v_mfma_f32_16x16x32_bf16 v[6:9], v[168:171], v[210:213], v[6:9]
	v_mfma_f32_16x16x32_bf16 v[2:5], v[178:181], v[210:213], v[2:5]
	v_mfma_f32_16x16x32_bf16 v[54:57], v[172:175], v[190:193], v[54:57]
	v_mfma_f32_16x16x32_bf16 v[50:53], v[182:185], v[190:193], v[50:53]
	v_mfma_f32_16x16x32_bf16 v[38:41], v[172:175], v[198:201], v[38:41]
	v_mfma_f32_16x16x32_bf16 v[34:37], v[182:185], v[198:201], v[34:37]
	v_mfma_f32_16x16x32_bf16 v[22:25], v[172:175], v[206:209], v[22:25]
	v_mfma_f32_16x16x32_bf16 v[18:21], v[182:185], v[206:209], v[18:21]
	v_mfma_f32_16x16x32_bf16 v[6:9], v[172:175], v[214:217], v[6:9]
	s_setprio 0
	v_mfma_f32_16x16x32_bf16 v[2:5], v[182:185], v[214:217], v[2:5]
	s_barrier
	s_add_i32 s55, s55, 2
	s_add_u32 s28, s28, 0x100
	s_addc_u32 s29, s29, 0
	s_add_u32 s53, s53, 0x100
	s_addc_u32 s54, s54, 0
	s_cmp_gt_u32 s55, 13
	s_cbranch_scc0 .LBB0_1400

.Lpk1444_peel:
	ds_read_b128 v[152:155], v148
	ds_read_b128 v[156:159], v148 offset:1024
	ds_read_b128 v[160:163], v148 offset:2048
	ds_read_b128 v[164:167], v148 offset:3072
	ds_read_b128 v[168:171], v149
	ds_read_b128 v[172:175], v149 offset:1024
	ds_read_b128 v[178:181], v149 offset:2048
	ds_read_b128 v[182:185], v149 offset:3072
	s_add_u32 s2, s26, 0x4000
	s_addc_u32 s3, s27, 0
	s_cmp_eq_u32 s62, 40
	s_cselect_b32 s2, s57, s2
	s_cselect_b32 s3, s56, s3
	s_cselect_b32 s31, s58, s61
	s_cselect_b32 s30, s59, s60
	s_add_u32 s28, s2, 0x8000
	s_addc_u32 s29, s3, 0
	v_lshl_add_u64 v[144:145], s[26:27], 0, v[138:139]
	s_add_i32 m0, s39, 0xc000
	ds_read_b128 v[186:189], v150
	ds_read_b128 v[190:193], v150 offset:1024
	ds_read_b128 v[194:197], v150 offset:2048
	ds_read_b128 v[198:201], v150 offset:3072
	ds_read_b128 v[202:205], v150 offset:4096
	ds_read_b128 v[206:209], v150 offset:5120
	ds_read_b128 v[210:213], v150 offset:6144
	ds_read_b128 v[214:217], v150 offset:7168
	global_load_lds_dwordx4 v[144:145], off
	v_lshl_add_u64 v[144:145], s[26:27], 0, v[140:141]
	s_add_i32 m0, s39, 0xe000
	s_nop 0
	global_load_lds_dwordx4 v[144:145], off
	s_waitcnt vmcnt(8)
	s_waitcnt lgkmcnt(0)
	s_setprio 1
	s_barrier
	v_mfma_f32_16x16x32_bf16 v[126:129], v[152:155], v[186:189], 0
	v_mfma_f32_16x16x32_bf16 v[122:125], v[160:163], v[186:189], 0
	v_mfma_f32_16x16x32_bf16 v[114:117], v[152:155], v[194:197], 0
	v_mfma_f32_16x16x32_bf16 v[106:109], v[160:163], v[194:197], 0
	v_mfma_f32_16x16x32_bf16 v[98:101], v[152:155], v[202:205], 0
	v_mfma_f32_16x16x32_bf16 v[90:93], v[160:163], v[202:205], 0
	v_mfma_f32_16x16x32_bf16 v[82:85], v[152:155], v[210:213], 0
	v_mfma_f32_16x16x32_bf16 v[74:77], v[160:163], v[210:213], 0
	v_mfma_f32_16x16x32_bf16 v[126:129], v[156:159], v[190:193], v[126:129]
	v_mfma_f32_16x16x32_bf16 v[122:125], v[164:167], v[190:193], v[122:125]
	v_mfma_f32_16x16x32_bf16 v[114:117], v[156:159], v[198:201], v[114:117]
	v_mfma_f32_16x16x32_bf16 v[106:109], v[164:167], v[198:201], v[106:109]
	v_mfma_f32_16x16x32_bf16 v[98:101], v[156:159], v[206:209], v[98:101]
	v_mfma_f32_16x16x32_bf16 v[90:93], v[164:167], v[206:209], v[90:93]
	v_mfma_f32_16x16x32_bf16 v[82:85], v[156:159], v[214:217], v[82:85]
	v_mfma_f32_16x16x32_bf16 v[74:77], v[164:167], v[214:217], v[74:77]
	v_mfma_f32_16x16x32_bf16 v[118:121], v[168:171], v[186:189], 0
	v_mfma_f32_16x16x32_bf16 v[110:113], v[178:181], v[186:189], 0
	v_mfma_f32_16x16x32_bf16 v[102:105], v[168:171], v[194:197], 0
	v_mfma_f32_16x16x32_bf16 v[94:97], v[178:181], v[194:197], 0
	v_mfma_f32_16x16x32_bf16 v[86:89], v[168:171], v[202:205], 0
	v_mfma_f32_16x16x32_bf16 v[78:81], v[178:181], v[202:205], 0
	v_mfma_f32_16x16x32_bf16 v[70:73], v[168:171], v[210:213], 0
	v_mfma_f32_16x16x32_bf16 v[66:69], v[178:181], v[210:213], 0
	v_mfma_f32_16x16x32_bf16 v[118:121], v[172:175], v[190:193], v[118:121]
	v_mfma_f32_16x16x32_bf16 v[110:113], v[182:185], v[190:193], v[110:113]
	v_mfma_f32_16x16x32_bf16 v[102:105], v[172:175], v[198:201], v[102:105]
	v_mfma_f32_16x16x32_bf16 v[94:97], v[182:185], v[198:201], v[94:97]
	v_mfma_f32_16x16x32_bf16 v[86:89], v[172:175], v[206:209], v[86:89]
	v_mfma_f32_16x16x32_bf16 v[78:81], v[182:185], v[206:209], v[78:81]
	v_mfma_f32_16x16x32_bf16 v[70:73], v[172:175], v[214:217], v[70:73]
	s_setprio 0
	v_mfma_f32_16x16x32_bf16 v[66:69], v[182:185], v[214:217], v[66:69]
	s_barrier
	s_add_i32 s63, s46, s38
	v_lshl_add_u64 v[144:145], s[30:31], 0, v[132:133]
	s_mov_b32 m0, s63
	ds_read_b128 v[186:189], v150 offset:16384
	ds_read_b128 v[190:193], v150 offset:17408
	ds_read_b128 v[194:197], v150 offset:18432
	ds_read_b128 v[198:201], v150 offset:19456
	ds_read_b128 v[202:205], v150 offset:20480
	ds_read_b128 v[206:209], v150 offset:21504
	ds_read_b128 v[210:213], v150 offset:22528
	ds_read_b128 v[214:217], v150 offset:23552
	global_load_lds_dwordx4 v[144:145], off
	s_add_i32 m0, s63, 0x2000
	s_add_u32 s64, s30, 0x4000
	v_lshl_add_u64 v[144:145], s[30:31], 0, v[136:137]
	s_addc_u32 s65, s31, 0
	s_add_i32 s63, s47, s38
	global_load_lds_dwordx4 v[144:145], off
	v_lshl_add_u64 v[144:145], s[64:65], 0, v[132:133]
	s_mov_b32 m0, s63
	s_nop 0
	global_load_lds_dwordx4 v[144:145], off
	v_lshl_add_u64 v[144:145], s[64:65], 0, v[136:137]
	s_add_i32 m0, s63, 0x2000
	s_nop 0
	global_load_lds_dwordx4 v[144:145], off
	v_lshl_add_u64 v[144:145], s[2:3], 0, v[130:131]
	s_mov_b32 m0, s39
	s_nop 0
	global_load_lds_dwordx4 v[144:145], off
	v_lshl_add_u64 v[144:145], s[2:3], 0, v[134:135]
	s_mov_b32 m0, s40
	s_nop 0
	global_load_lds_dwordx4 v[144:145], off
	s_waitcnt vmcnt(8)
	s_waitcnt lgkmcnt(0)
	s_setprio 1
	s_barrier
	v_mfma_f32_16x16x32_bf16 v[62:65], v[152:155], v[186:189], 0
	v_mfma_f32_16x16x32_bf16 v[58:61], v[160:163], v[186:189], 0
	v_mfma_f32_16x16x32_bf16 v[50:53], v[152:155], v[194:197], 0
	v_mfma_f32_16x16x32_bf16 v[42:45], v[160:163], v[194:197], 0
	v_mfma_f32_16x16x32_bf16 v[34:37], v[152:155], v[202:205], 0
	v_mfma_f32_16x16x32_bf16 v[26:29], v[160:163], v[202:205], 0
	v_mfma_f32_16x16x32_bf16 v[18:21], v[152:155], v[210:213], 0
	v_mfma_f32_16x16x32_bf16 v[10:13], v[160:163], v[210:213], 0
	v_mfma_f32_16x16x32_bf16 v[62:65], v[156:159], v[190:193], v[62:65]
	v_mfma_f32_16x16x32_bf16 v[58:61], v[164:167], v[190:193], v[58:61]
	v_mfma_f32_16x16x32_bf16 v[50:53], v[156:159], v[198:201], v[50:53]
	v_mfma_f32_16x16x32_bf16 v[42:45], v[164:167], v[198:201], v[42:45]
	v_mfma_f32_16x16x32_bf16 v[34:37], v[156:159], v[206:209], v[34:37]
	v_mfma_f32_16x16x32_bf16 v[26:29], v[164:167], v[206:209], v[26:29]
	v_mfma_f32_16x16x32_bf16 v[18:21], v[156:159], v[214:217], v[18:21]
	v_mfma_f32_16x16x32_bf16 v[10:13], v[164:167], v[214:217], v[10:13]
	v_mfma_f32_16x16x32_bf16 v[54:57], v[168:171], v[186:189], 0
	v_mfma_f32_16x16x32_bf16 v[46:49], v[178:181], v[186:189], 0
	v_mfma_f32_16x16x32_bf16 v[38:41], v[168:171], v[194:197], 0
	v_mfma_f32_16x16x32_bf16 v[30:33], v[178:181], v[194:197], 0
	v_mfma_f32_16x16x32_bf16 v[22:25], v[168:171], v[202:205], 0
	v_mfma_f32_16x16x32_bf16 v[14:17], v[178:181], v[202:205], 0
	v_mfma_f32_16x16x32_bf16 v[6:9], v[168:171], v[210:213], 0
	v_mfma_f32_16x16x32_bf16 v[2:5], v[178:181], v[210:213], 0
	v_mfma_f32_16x16x32_bf16 v[54:57], v[172:175], v[190:193], v[54:57]
	v_mfma_f32_16x16x32_bf16 v[46:49], v[182:185], v[190:193], v[46:49]
	v_mfma_f32_16x16x32_bf16 v[38:41], v[172:175], v[198:201], v[38:41]
	v_mfma_f32_16x16x32_bf16 v[30:33], v[182:185], v[198:201], v[30:33]
	v_mfma_f32_16x16x32_bf16 v[22:25], v[172:175], v[206:209], v[22:25]
	v_mfma_f32_16x16x32_bf16 v[14:17], v[182:185], v[206:209], v[14:17]
	v_mfma_f32_16x16x32_bf16 v[6:9], v[172:175], v[214:217], v[6:9]
	s_setprio 0
	v_mfma_f32_16x16x32_bf16 v[2:5], v[182:185], v[214:217], v[2:5]
	s_barrier
	s_add_i32 s63, 0, 0x18000
	v_add_u32_e32 v144, s63, v146
	s_add_i32 s64, 0, 0x1c000
	ds_read_b128 v[152:155], v144
	ds_read_b128 v[156:159], v144 offset:1024
	ds_read_b128 v[160:163], v144 offset:2048
	ds_read_b128 v[164:167], v144 offset:3072
	v_add_u32_e32 v144, s64, v146
	ds_read_b128 v[168:171], v144
	ds_read_b128 v[172:175], v144 offset:1024
	ds_read_b128 v[178:181], v144 offset:2048
	ds_read_b128 v[182:185], v144 offset:3072
	s_add_u32 s2, s2, 0x4000
	s_addc_u32 s3, s3, 0
	s_mov_b32 m0, s41
	v_lshl_add_u64 v[144:145], s[2:3], 0, v[130:131]
	ds_read_b128 v[186:189], v150 offset:32768
	ds_read_b128 v[190:193], v150 offset:33792
	ds_read_b128 v[194:197], v150 offset:34816
	ds_read_b128 v[198:201], v150 offset:35840
	ds_read_b128 v[202:205], v150 offset:36864
	ds_read_b128 v[206:209], v150 offset:37888
	ds_read_b128 v[210:213], v150 offset:38912
	ds_read_b128 v[214:217], v150 offset:39936
	global_load_lds_dwordx4 v[144:145], off
	v_lshl_add_u64 v[144:145], s[2:3], 0, v[134:135]
	s_mov_b32 m0, s42
	s_nop 0
	global_load_lds_dwordx4 v[144:145], off
	s_waitcnt vmcnt(8)
	s_waitcnt lgkmcnt(0)
	s_setprio 1
	s_barrier
	v_mfma_f32_16x16x32_bf16 v[126:129], v[152:155], v[186:189], v[126:129]
	v_mfma_f32_16x16x32_bf16 v[122:125], v[160:163], v[186:189], v[122:125]
	v_mfma_f32_16x16x32_bf16 v[114:117], v[152:155], v[194:197], v[114:117]
	v_mfma_f32_16x16x32_bf16 v[106:109], v[160:163], v[194:197], v[106:109]
	v_mfma_f32_16x16x32_bf16 v[98:101], v[152:155], v[202:205], v[98:101]
	v_mfma_f32_16x16x32_bf16 v[90:93], v[160:163], v[202:205], v[90:93]
	v_mfma_f32_16x16x32_bf16 v[82:85], v[152:155], v[210:213], v[82:85]
	v_mfma_f32_16x16x32_bf16 v[74:77], v[160:163], v[210:213], v[74:77]
	v_mfma_f32_16x16x32_bf16 v[126:129], v[156:159], v[190:193], v[126:129]
	v_mfma_f32_16x16x32_bf16 v[122:125], v[164:167], v[190:193], v[122:125]
	v_mfma_f32_16x16x32_bf16 v[114:117], v[156:159], v[198:201], v[114:117]
	v_mfma_f32_16x16x32_bf16 v[106:109], v[164:167], v[198:201], v[106:109]
	v_mfma_f32_16x16x32_bf16 v[98:101], v[156:159], v[206:209], v[98:101]
	v_mfma_f32_16x16x32_bf16 v[90:93], v[164:167], v[206:209], v[90:93]
	v_mfma_f32_16x16x32_bf16 v[82:85], v[156:159], v[214:217], v[82:85]
	v_mfma_f32_16x16x32_bf16 v[74:77], v[164:167], v[214:217], v[74:77]
	v_mfma_f32_16x16x32_bf16 v[118:121], v[168:171], v[186:189], v[118:121]
	v_mfma_f32_16x16x32_bf16 v[110:113], v[178:181], v[186:189], v[110:113]
	v_mfma_f32_16x16x32_bf16 v[102:105], v[168:171], v[194:197], v[102:105]
	v_mfma_f32_16x16x32_bf16 v[94:97], v[178:181], v[194:197], v[94:97]
	v_mfma_f32_16x16x32_bf16 v[86:89], v[168:171], v[202:205], v[86:89]
	v_mfma_f32_16x16x32_bf16 v[78:81], v[178:181], v[202:205], v[78:81]
	v_mfma_f32_16x16x32_bf16 v[70:73], v[168:171], v[210:213], v[70:73]
	v_mfma_f32_16x16x32_bf16 v[66:69], v[178:181], v[210:213], v[66:69]
	v_mfma_f32_16x16x32_bf16 v[118:121], v[172:175], v[190:193], v[118:121]
	v_mfma_f32_16x16x32_bf16 v[110:113], v[182:185], v[190:193], v[110:113]
	v_mfma_f32_16x16x32_bf16 v[102:105], v[172:175], v[198:201], v[102:105]
	v_mfma_f32_16x16x32_bf16 v[94:97], v[182:185], v[198:201], v[94:97]
	v_mfma_f32_16x16x32_bf16 v[86:89], v[172:175], v[206:209], v[86:89]
	v_mfma_f32_16x16x32_bf16 v[78:81], v[182:185], v[206:209], v[78:81]
	v_mfma_f32_16x16x32_bf16 v[70:73], v[172:175], v[214:217], v[70:73]
	s_setprio 0
	v_mfma_f32_16x16x32_bf16 v[66:69], v[182:185], v[214:217], v[66:69]
	s_barrier
	s_add_u32 s2, s30, 0x8000
	s_addc_u32 s3, s31, 0
	s_add_i32 s63, s63, s38
	v_lshl_add_u64 v[144:145], s[2:3], 0, v[132:133]
	s_mov_b32 m0, s63
	ds_read_b128 v[186:189], v150 offset:49152
	ds_read_b128 v[190:193], v150 offset:50176
	ds_read_b128 v[194:197], v150 offset:51200
	ds_read_b128 v[198:201], v150 offset:52224
	ds_read_b128 v[202:205], v150 offset:53248
	ds_read_b128 v[206:209], v150 offset:54272
	ds_read_b128 v[210:213], v150 offset:55296
	ds_read_b128 v[214:217], v150 offset:56320
	global_load_lds_dwordx4 v[144:145], off
	s_add_i32 m0, s63, 0x2000
	v_lshl_add_u64 v[144:145], s[2:3], 0, v[136:137]
	s_add_u32 s2, s30, 0xc000
	s_addc_u32 s3, s31, 0
	s_add_i32 s30, s64, s38
	global_load_lds_dwordx4 v[144:145], off
	v_lshl_add_u64 v[144:145], s[2:3], 0, v[132:133]
	s_mov_b32 m0, s30
	s_nop 0
	global_load_lds_dwordx4 v[144:145], off
	v_lshl_add_u64 v[144:145], s[2:3], 0, v[136:137]
	s_add_i32 m0, s30, 0x2000
	s_nop 0
	global_load_lds_dwordx4 v[144:145], off
	v_lshl_add_u64 v[144:145], s[28:29], 0, v[130:131]
	s_mov_b32 m0, s44
	s_nop 0
	global_load_lds_dwordx4 v[144:145], off
	v_lshl_add_u64 v[144:145], s[28:29], 0, v[134:135]
	s_mov_b32 m0, s45
	s_nop 0
	global_load_lds_dwordx4 v[144:145], off
	s_waitcnt vmcnt(8)
	s_waitcnt lgkmcnt(0)
	s_setprio 1
	s_barrier
	v_mfma_f32_16x16x32_bf16 v[62:65], v[152:155], v[186:189], v[62:65]
	v_mfma_f32_16x16x32_bf16 v[58:61], v[160:163], v[186:189], v[58:61]
	v_mfma_f32_16x16x32_bf16 v[50:53], v[152:155], v[194:197], v[50:53]
	v_mfma_f32_16x16x32_bf16 v[42:45], v[160:163], v[194:197], v[42:45]
	v_mfma_f32_16x16x32_bf16 v[34:37], v[152:155], v[202:205], v[34:37]
	v_mfma_f32_16x16x32_bf16 v[26:29], v[160:163], v[202:205], v[26:29]
	v_mfma_f32_16x16x32_bf16 v[18:21], v[152:155], v[210:213], v[18:21]
	v_mfma_f32_16x16x32_bf16 v[10:13], v[160:163], v[210:213], v[10:13]
	v_mfma_f32_16x16x32_bf16 v[62:65], v[156:159], v[190:193], v[62:65]
	v_mfma_f32_16x16x32_bf16 v[58:61], v[164:167], v[190:193], v[58:61]
	v_mfma_f32_16x16x32_bf16 v[50:53], v[156:159], v[198:201], v[50:53]
	v_mfma_f32_16x16x32_bf16 v[42:45], v[164:167], v[198:201], v[42:45]
	v_mfma_f32_16x16x32_bf16 v[34:37], v[156:159], v[206:209], v[34:37]
	v_mfma_f32_16x16x32_bf16 v[26:29], v[164:167], v[206:209], v[26:29]
	v_mfma_f32_16x16x32_bf16 v[18:21], v[156:159], v[214:217], v[18:21]
	v_mfma_f32_16x16x32_bf16 v[10:13], v[164:167], v[214:217], v[10:13]
	v_mfma_f32_16x16x32_bf16 v[54:57], v[168:171], v[186:189], v[54:57]
	v_mfma_f32_16x16x32_bf16 v[46:49], v[178:181], v[186:189], v[46:49]
	v_mfma_f32_16x16x32_bf16 v[38:41], v[168:171], v[194:197], v[38:41]
	v_mfma_f32_16x16x32_bf16 v[30:33], v[178:181], v[194:197], v[30:33]
	v_mfma_f32_16x16x32_bf16 v[22:25], v[168:171], v[202:205], v[22:25]
	v_mfma_f32_16x16x32_bf16 v[14:17], v[178:181], v[202:205], v[14:17]
	v_mfma_f32_16x16x32_bf16 v[6:9], v[168:171], v[210:213], v[6:9]
	v_mfma_f32_16x16x32_bf16 v[2:5], v[178:181], v[210:213], v[2:5]
	v_mfma_f32_16x16x32_bf16 v[54:57], v[172:175], v[190:193], v[54:57]
	v_mfma_f32_16x16x32_bf16 v[46:49], v[182:185], v[190:193], v[46:49]
	v_mfma_f32_16x16x32_bf16 v[38:41], v[172:175], v[198:201], v[38:41]
	v_mfma_f32_16x16x32_bf16 v[30:33], v[182:185], v[198:201], v[30:33]
	v_mfma_f32_16x16x32_bf16 v[22:25], v[172:175], v[206:209], v[22:25]
	v_mfma_f32_16x16x32_bf16 v[14:17], v[182:185], v[206:209], v[14:17]
	v_mfma_f32_16x16x32_bf16 v[6:9], v[172:175], v[214:217], v[6:9]
	s_setprio 0
	v_mfma_f32_16x16x32_bf16 v[2:5], v[182:185], v[214:217], v[2:5]
	s_barrier
	s_add_i32 s62, s62, 2
	s_add_u32 s26, s26, 0x10000
	s_addc_u32 s27, s27, 0
	s_add_u32 s60, s60, 0x10000
	s_addc_u32 s61, s61, 0
	s_cmp_gt_u32 s62, 41
	s_cbranch_scc0 .LBB0_1444
	s_branch .Lpk1444_exit
.LBB0_1444:
	ds_read_b128 v[152:155], v148
	ds_read_b128 v[156:159], v148 offset:1024
	ds_read_b128 v[160:163], v148 offset:2048
	ds_read_b128 v[164:167], v148 offset:3072
	ds_read_b128 v[168:171], v149
	ds_read_b128 v[172:175], v149 offset:1024
	ds_read_b128 v[178:181], v149 offset:2048
	ds_read_b128 v[182:185], v149 offset:3072
	s_add_u32 s2, s26, 0x4000
	s_addc_u32 s3, s27, 0
	s_cmp_eq_u32 s62, 40
	s_cselect_b32 s2, s57, s2
	s_cselect_b32 s3, s56, s3
	s_cselect_b32 s31, s58, s61
	s_cselect_b32 s30, s59, s60
	s_add_u32 s28, s2, 0x8000
	s_addc_u32 s29, s3, 0
	v_lshl_add_u64 v[144:145], s[26:27], 0, v[138:139]
	s_add_i32 m0, s39, 0xc000
	ds_read_b128 v[186:189], v150
	ds_read_b128 v[190:193], v150 offset:1024
	ds_read_b128 v[194:197], v150 offset:2048
	ds_read_b128 v[198:201], v150 offset:3072
	ds_read_b128 v[202:205], v150 offset:4096
	ds_read_b128 v[206:209], v150 offset:5120
	ds_read_b128 v[210:213], v150 offset:6144
	ds_read_b128 v[214:217], v150 offset:7168
	global_load_lds_dwordx4 v[144:145], off
	v_lshl_add_u64 v[144:145], s[26:27], 0, v[140:141]
	s_add_i32 m0, s39, 0xe000
	s_nop 0
	global_load_lds_dwordx4 v[144:145], off
	s_waitcnt vmcnt(8)
	s_waitcnt lgkmcnt(0)
	s_setprio 1
	s_barrier
	v_mfma_f32_16x16x32_bf16 v[126:129], v[152:155], v[186:189], v[126:129]
	v_mfma_f32_16x16x32_bf16 v[122:125], v[160:163], v[186:189], v[122:125]
	v_mfma_f32_16x16x32_bf16 v[114:117], v[152:155], v[194:197], v[114:117]
	v_mfma_f32_16x16x32_bf16 v[106:109], v[160:163], v[194:197], v[106:109]
	v_mfma_f32_16x16x32_bf16 v[98:101], v[152:155], v[202:205], v[98:101]
	v_mfma_f32_16x16x32_bf16 v[90:93], v[160:163], v[202:205], v[90:93]
	v_mfma_f32_16x16x32_bf16 v[82:85], v[152:155], v[210:213], v[82:85]
	v_mfma_f32_16x16x32_bf16 v[74:77], v[160:163], v[210:213], v[74:77]
	v_mfma_f32_16x16x32_bf16 v[126:129], v[156:159], v[190:193], v[126:129]
	v_mfma_f32_16x16x32_bf16 v[122:125], v[164:167], v[190:193], v[122:125]
	v_mfma_f32_16x16x32_bf16 v[114:117], v[156:159], v[198:201], v[114:117]
	v_mfma_f32_16x16x32_bf16 v[106:109], v[164:167], v[198:201], v[106:109]
	v_mfma_f32_16x16x32_bf16 v[98:101], v[156:159], v[206:209], v[98:101]
	v_mfma_f32_16x16x32_bf16 v[90:93], v[164:167], v[206:209], v[90:93]
	v_mfma_f32_16x16x32_bf16 v[82:85], v[156:159], v[214:217], v[82:85]
	v_mfma_f32_16x16x32_bf16 v[74:77], v[164:167], v[214:217], v[74:77]
	v_mfma_f32_16x16x32_bf16 v[118:121], v[168:171], v[186:189], v[118:121]
	v_mfma_f32_16x16x32_bf16 v[110:113], v[178:181], v[186:189], v[110:113]
	v_mfma_f32_16x16x32_bf16 v[102:105], v[168:171], v[194:197], v[102:105]
	v_mfma_f32_16x16x32_bf16 v[94:97], v[178:181], v[194:197], v[94:97]
	v_mfma_f32_16x16x32_bf16 v[86:89], v[168:171], v[202:205], v[86:89]
	v_mfma_f32_16x16x32_bf16 v[78:81], v[178:181], v[202:205], v[78:81]
	v_mfma_f32_16x16x32_bf16 v[70:73], v[168:171], v[210:213], v[70:73]
	v_mfma_f32_16x16x32_bf16 v[66:69], v[178:181], v[210:213], v[66:69]
	v_mfma_f32_16x16x32_bf16 v[118:121], v[172:175], v[190:193], v[118:121]
	v_mfma_f32_16x16x32_bf16 v[110:113], v[182:185], v[190:193], v[110:113]
	v_mfma_f32_16x16x32_bf16 v[102:105], v[172:175], v[198:201], v[102:105]
	v_mfma_f32_16x16x32_bf16 v[94:97], v[182:185], v[198:201], v[94:97]
	v_mfma_f32_16x16x32_bf16 v[86:89], v[172:175], v[206:209], v[86:89]
	v_mfma_f32_16x16x32_bf16 v[78:81], v[182:185], v[206:209], v[78:81]
	v_mfma_f32_16x16x32_bf16 v[70:73], v[172:175], v[214:217], v[70:73]
	s_setprio 0
	v_mfma_f32_16x16x32_bf16 v[66:69], v[182:185], v[214:217], v[66:69]
	s_barrier
	s_add_i32 s63, s46, s38
	v_lshl_add_u64 v[144:145], s[30:31], 0, v[132:133]
	s_mov_b32 m0, s63
	ds_read_b128 v[186:189], v150 offset:16384
	ds_read_b128 v[190:193], v150 offset:17408
	ds_read_b128 v[194:197], v150 offset:18432
	ds_read_b128 v[198:201], v150 offset:19456
	ds_read_b128 v[202:205], v150 offset:20480
	ds_read_b128 v[206:209], v150 offset:21504
	ds_read_b128 v[210:213], v150 offset:22528
	ds_read_b128 v[214:217], v150 offset:23552
	global_load_lds_dwordx4 v[144:145], off
	s_add_i32 m0, s63, 0x2000
	s_add_u32 s64, s30, 0x4000
	v_lshl_add_u64 v[144:145], s[30:31], 0, v[136:137]
	s_addc_u32 s65, s31, 0
	s_add_i32 s63, s47, s38
	global_load_lds_dwordx4 v[144:145], off
	v_lshl_add_u64 v[144:145], s[64:65], 0, v[132:133]
	s_mov_b32 m0, s63
	s_nop 0
	global_load_lds_dwordx4 v[144:145], off
	v_lshl_add_u64 v[144:145], s[64:65], 0, v[136:137]
	s_add_i32 m0, s63, 0x2000
	s_nop 0
	global_load_lds_dwordx4 v[144:145], off
	v_lshl_add_u64 v[144:145], s[2:3], 0, v[130:131]
	s_mov_b32 m0, s39
	s_nop 0
	global_load_lds_dwordx4 v[144:145], off
	v_lshl_add_u64 v[144:145], s[2:3], 0, v[134:135]
	s_mov_b32 m0, s40
	s_nop 0
	global_load_lds_dwordx4 v[144:145], off
	s_waitcnt vmcnt(8)
	s_waitcnt lgkmcnt(0)
	s_setprio 1
	s_barrier
	v_mfma_f32_16x16x32_bf16 v[62:65], v[152:155], v[186:189], v[62:65]
	v_mfma_f32_16x16x32_bf16 v[58:61], v[160:163], v[186:189], v[58:61]
	v_mfma_f32_16x16x32_bf16 v[50:53], v[152:155], v[194:197], v[50:53]
	v_mfma_f32_16x16x32_bf16 v[42:45], v[160:163], v[194:197], v[42:45]
	v_mfma_f32_16x16x32_bf16 v[34:37], v[152:155], v[202:205], v[34:37]
	v_mfma_f32_16x16x32_bf16 v[26:29], v[160:163], v[202:205], v[26:29]
	v_mfma_f32_16x16x32_bf16 v[18:21], v[152:155], v[210:213], v[18:21]
	v_mfma_f32_16x16x32_bf16 v[10:13], v[160:163], v[210:213], v[10:13]
	v_mfma_f32_16x16x32_bf16 v[62:65], v[156:159], v[190:193], v[62:65]
	v_mfma_f32_16x16x32_bf16 v[58:61], v[164:167], v[190:193], v[58:61]
	v_mfma_f32_16x16x32_bf16 v[50:53], v[156:159], v[198:201], v[50:53]
	v_mfma_f32_16x16x32_bf16 v[42:45], v[164:167], v[198:201], v[42:45]
	v_mfma_f32_16x16x32_bf16 v[34:37], v[156:159], v[206:209], v[34:37]
	v_mfma_f32_16x16x32_bf16 v[26:29], v[164:167], v[206:209], v[26:29]
	v_mfma_f32_16x16x32_bf16 v[18:21], v[156:159], v[214:217], v[18:21]
	v_mfma_f32_16x16x32_bf16 v[10:13], v[164:167], v[214:217], v[10:13]
	v_mfma_f32_16x16x32_bf16 v[54:57], v[168:171], v[186:189], v[54:57]
	v_mfma_f32_16x16x32_bf16 v[46:49], v[178:181], v[186:189], v[46:49]
	v_mfma_f32_16x16x32_bf16 v[38:41], v[168:171], v[194:197], v[38:41]
	v_mfma_f32_16x16x32_bf16 v[30:33], v[178:181], v[194:197], v[30:33]
	v_mfma_f32_16x16x32_bf16 v[22:25], v[168:171], v[202:205], v[22:25]
	v_mfma_f32_16x16x32_bf16 v[14:17], v[178:181], v[202:205], v[14:17]
	v_mfma_f32_16x16x32_bf16 v[6:9], v[168:171], v[210:213], v[6:9]
	v_mfma_f32_16x16x32_bf16 v[2:5], v[178:181], v[210:213], v[2:5]
	v_mfma_f32_16x16x32_bf16 v[54:57], v[172:175], v[190:193], v[54:57]
	v_mfma_f32_16x16x32_bf16 v[46:49], v[182:185], v[190:193], v[46:49]
	v_mfma_f32_16x16x32_bf16 v[38:41], v[172:175], v[198:201], v[38:41]
	v_mfma_f32_16x16x32_bf16 v[30:33], v[182:185], v[198:201], v[30:33]
	v_mfma_f32_16x16x32_bf16 v[22:25], v[172:175], v[206:209], v[22:25]
	v_mfma_f32_16x16x32_bf16 v[14:17], v[182:185], v[206:209], v[14:17]
	v_mfma_f32_16x16x32_bf16 v[6:9], v[172:175], v[214:217], v[6:9]
	s_setprio 0
	v_mfma_f32_16x16x32_bf16 v[2:5], v[182:185], v[214:217], v[2:5]
	s_barrier
	s_add_i32 s63, 0, 0x18000
	v_add_u32_e32 v144, s63, v146
	s_add_i32 s64, 0, 0x1c000
	ds_read_b128 v[152:155], v144
	ds_read_b128 v[156:159], v144 offset:1024
	ds_read_b128 v[160:163], v144 offset:2048
	ds_read_b128 v[164:167], v144 offset:3072
	v_add_u32_e32 v144, s64, v146
	ds_read_b128 v[168:171], v144
	ds_read_b128 v[172:175], v144 offset:1024
	ds_read_b128 v[178:181], v144 offset:2048
	ds_read_b128 v[182:185], v144 offset:3072
	s_add_u32 s2, s2, 0x4000
	s_addc_u32 s3, s3, 0
	s_mov_b32 m0, s41
	v_lshl_add_u64 v[144:145], s[2:3], 0, v[130:131]
	ds_read_b128 v[186:189], v150 offset:32768
	ds_read_b128 v[190:193], v150 offset:33792
	ds_read_b128 v[194:197], v150 offset:34816
	ds_read_b128 v[198:201], v150 offset:35840
	ds_read_b128 v[202:205], v150 offset:36864
	ds_read_b128 v[206:209], v150 offset:37888
	ds_read_b128 v[210:213], v150 offset:38912
	ds_read_b128 v[214:217], v150 offset:39936
	global_load_lds_dwordx4 v[144:145], off
	v_lshl_add_u64 v[144:145], s[2:3], 0, v[134:135]
	s_mov_b32 m0, s42
	s_nop 0
	global_load_lds_dwordx4 v[144:145], off
	s_waitcnt vmcnt(8)
	s_waitcnt lgkmcnt(0)
	s_setprio 1
	s_barrier
	v_mfma_f32_16x16x32_bf16 v[126:129], v[152:155], v[186:189], v[126:129]
	v_mfma_f32_16x16x32_bf16 v[122:125], v[160:163], v[186:189], v[122:125]
	v_mfma_f32_16x16x32_bf16 v[114:117], v[152:155], v[194:197], v[114:117]
	v_mfma_f32_16x16x32_bf16 v[106:109], v[160:163], v[194:197], v[106:109]
	v_mfma_f32_16x16x32_bf16 v[98:101], v[152:155], v[202:205], v[98:101]
	v_mfma_f32_16x16x32_bf16 v[90:93], v[160:163], v[202:205], v[90:93]
	v_mfma_f32_16x16x32_bf16 v[82:85], v[152:155], v[210:213], v[82:85]
	v_mfma_f32_16x16x32_bf16 v[74:77], v[160:163], v[210:213], v[74:77]
	v_mfma_f32_16x16x32_bf16 v[126:129], v[156:159], v[190:193], v[126:129]
	v_mfma_f32_16x16x32_bf16 v[122:125], v[164:167], v[190:193], v[122:125]
	v_mfma_f32_16x16x32_bf16 v[114:117], v[156:159], v[198:201], v[114:117]
	v_mfma_f32_16x16x32_bf16 v[106:109], v[164:167], v[198:201], v[106:109]
	v_mfma_f32_16x16x32_bf16 v[98:101], v[156:159], v[206:209], v[98:101]
	v_mfma_f32_16x16x32_bf16 v[90:93], v[164:167], v[206:209], v[90:93]
	v_mfma_f32_16x16x32_bf16 v[82:85], v[156:159], v[214:217], v[82:85]
	v_mfma_f32_16x16x32_bf16 v[74:77], v[164:167], v[214:217], v[74:77]
	v_mfma_f32_16x16x32_bf16 v[118:121], v[168:171], v[186:189], v[118:121]
	v_mfma_f32_16x16x32_bf16 v[110:113], v[178:181], v[186:189], v[110:113]
	v_mfma_f32_16x16x32_bf16 v[102:105], v[168:171], v[194:197], v[102:105]
	v_mfma_f32_16x16x32_bf16 v[94:97], v[178:181], v[194:197], v[94:97]
	v_mfma_f32_16x16x32_bf16 v[86:89], v[168:171], v[202:205], v[86:89]
	v_mfma_f32_16x16x32_bf16 v[78:81], v[178:181], v[202:205], v[78:81]
	v_mfma_f32_16x16x32_bf16 v[70:73], v[168:171], v[210:213], v[70:73]
	v_mfma_f32_16x16x32_bf16 v[66:69], v[178:181], v[210:213], v[66:69]
	v_mfma_f32_16x16x32_bf16 v[118:121], v[172:175], v[190:193], v[118:121]
	v_mfma_f32_16x16x32_bf16 v[110:113], v[182:185], v[190:193], v[110:113]
	v_mfma_f32_16x16x32_bf16 v[102:105], v[172:175], v[198:201], v[102:105]
	v_mfma_f32_16x16x32_bf16 v[94:97], v[182:185], v[198:201], v[94:97]
	v_mfma_f32_16x16x32_bf16 v[86:89], v[172:175], v[206:209], v[86:89]
	v_mfma_f32_16x16x32_bf16 v[78:81], v[182:185], v[206:209], v[78:81]
	v_mfma_f32_16x16x32_bf16 v[70:73], v[172:175], v[214:217], v[70:73]
	s_setprio 0
	v_mfma_f32_16x16x32_bf16 v[66:69], v[182:185], v[214:217], v[66:69]
	s_barrier
	s_add_u32 s2, s30, 0x8000
	s_addc_u32 s3, s31, 0
	s_add_i32 s63, s63, s38
	v_lshl_add_u64 v[144:145], s[2:3], 0, v[132:133]
	s_mov_b32 m0, s63
	ds_read_b128 v[186:189], v150 offset:49152
	ds_read_b128 v[190:193], v150 offset:50176
	ds_read_b128 v[194:197], v150 offset:51200
	ds_read_b128 v[198:201], v150 offset:52224
	ds_read_b128 v[202:205], v150 offset:53248
	ds_read_b128 v[206:209], v150 offset:54272
	ds_read_b128 v[210:213], v150 offset:55296
	ds_read_b128 v[214:217], v150 offset:56320
	global_load_lds_dwordx4 v[144:145], off
	s_add_i32 m0, s63, 0x2000
	v_lshl_add_u64 v[144:145], s[2:3], 0, v[136:137]
	s_add_u32 s2, s30, 0xc000
	s_addc_u32 s3, s31, 0
	s_add_i32 s30, s64, s38
	global_load_lds_dwordx4 v[144:145], off
	v_lshl_add_u64 v[144:145], s[2:3], 0, v[132:133]
	s_mov_b32 m0, s30
	s_nop 0
	global_load_lds_dwordx4 v[144:145], off
	v_lshl_add_u64 v[144:145], s[2:3], 0, v[136:137]
	s_add_i32 m0, s30, 0x2000
	s_nop 0
	global_load_lds_dwordx4 v[144:145], off
	v_lshl_add_u64 v[144:145], s[28:29], 0, v[130:131]
	s_mov_b32 m0, s44
	s_nop 0
	global_load_lds_dwordx4 v[144:145], off
	v_lshl_add_u64 v[144:145], s[28:29], 0, v[134:135]
	s_mov_b32 m0, s45
	s_nop 0
	global_load_lds_dwordx4 v[144:145], off
	s_waitcnt vmcnt(8)
	s_waitcnt lgkmcnt(0)
	s_setprio 1
	s_barrier
	v_mfma_f32_16x16x32_bf16 v[62:65], v[152:155], v[186:189], v[62:65]
	v_mfma_f32_16x16x32_bf16 v[58:61], v[160:163], v[186:189], v[58:61]
	v_mfma_f32_16x16x32_bf16 v[50:53], v[152:155], v[194:197], v[50:53]
	v_mfma_f32_16x16x32_bf16 v[42:45], v[160:163], v[194:197], v[42:45]
	v_mfma_f32_16x16x32_bf16 v[34:37], v[152:155], v[202:205], v[34:37]
	v_mfma_f32_16x16x32_bf16 v[26:29], v[160:163], v[202:205], v[26:29]
	v_mfma_f32_16x16x32_bf16 v[18:21], v[152:155], v[210:213], v[18:21]
	v_mfma_f32_16x16x32_bf16 v[10:13], v[160:163], v[210:213], v[10:13]
	v_mfma_f32_16x16x32_bf16 v[62:65], v[156:159], v[190:193], v[62:65]
	v_mfma_f32_16x16x32_bf16 v[58:61], v[164:167], v[190:193], v[58:61]
	v_mfma_f32_16x16x32_bf16 v[50:53], v[156:159], v[198:201], v[50:53]
	v_mfma_f32_16x16x32_bf16 v[42:45], v[164:167], v[198:201], v[42:45]
	v_mfma_f32_16x16x32_bf16 v[34:37], v[156:159], v[206:209], v[34:37]
	v_mfma_f32_16x16x32_bf16 v[26:29], v[164:167], v[206:209], v[26:29]
	v_mfma_f32_16x16x32_bf16 v[18:21], v[156:159], v[214:217], v[18:21]
	v_mfma_f32_16x16x32_bf16 v[10:13], v[164:167], v[214:217], v[10:13]
	v_mfma_f32_16x16x32_bf16 v[54:57], v[168:171], v[186:189], v[54:57]
	v_mfma_f32_16x16x32_bf16 v[46:49], v[178:181], v[186:189], v[46:49]
	v_mfma_f32_16x16x32_bf16 v[38:41], v[168:171], v[194:197], v[38:41]
	v_mfma_f32_16x16x32_bf16 v[30:33], v[178:181], v[194:197], v[30:33]
	v_mfma_f32_16x16x32_bf16 v[22:25], v[168:171], v[202:205], v[22:25]
	v_mfma_f32_16x16x32_bf16 v[14:17], v[178:181], v[202:205], v[14:17]
	v_mfma_f32_16x16x32_bf16 v[6:9], v[168:171], v[210:213], v[6:9]
	v_mfma_f32_16x16x32_bf16 v[2:5], v[178:181], v[210:213], v[2:5]
	v_mfma_f32_16x16x32_bf16 v[54:57], v[172:175], v[190:193], v[54:57]
	v_mfma_f32_16x16x32_bf16 v[46:49], v[182:185], v[190:193], v[46:49]
	v_mfma_f32_16x16x32_bf16 v[38:41], v[172:175], v[198:201], v[38:41]
	v_mfma_f32_16x16x32_bf16 v[30:33], v[182:185], v[198:201], v[30:33]
	v_mfma_f32_16x16x32_bf16 v[22:25], v[172:175], v[206:209], v[22:25]
	v_mfma_f32_16x16x32_bf16 v[14:17], v[182:185], v[206:209], v[14:17]
	v_mfma_f32_16x16x32_bf16 v[6:9], v[172:175], v[214:217], v[6:9]
	s_setprio 0
	v_mfma_f32_16x16x32_bf16 v[2:5], v[182:185], v[214:217], v[2:5]
	s_barrier
	s_add_i32 s62, s62, 2
	s_add_u32 s26, s26, 0x10000
	s_addc_u32 s27, s27, 0
	s_add_u32 s60, s60, 0x10000
	s_addc_u32 s61, s61, 0
	s_cmp_gt_u32 s62, 41
	s_cbranch_scc0 .LBB0_1444
